# adds: all flat->global, prep alias-wait removed, F32IN EpiResidNorm residual loads prefetched 2 units ahead
# speedup vs baseline: 1.0148x; 1.0034x over previous
; __device__ __forceinline__ void phase_mod(const float* c, const float* ada_w, const float* ada_b, float* mod, unsigned char* ldsb) {
;     ...
;         const int k0 = w * 128;
; #pragma unroll 16
;         for (int k = k0; k < k0 + 128; ++k) {
;             const float wv = W[(unsigned)k * 9216];
; #pragma unroll
;             for (int b = 0; b < 8; ++b) acc[b] += cact[b * 1024 + k] * wv;
;         }
.LBB0_9:
	s_add_i32 s6, s75, s77
	v_mov_b32_e32 v4, s9
	v_lshl_add_u64 v[146:147], s[6:7], 2, v[8:9]
	ds_read_b128 v[18:21], v4
	ds_read_b128 v[22:25], v4 offset:16
	ds_read_b128 v[26:29], v4 offset:4096
	ds_read_b128 v[30:33], v4 offset:4112
	ds_read_b128 v[34:37], v4 offset:8192
	ds_read_b128 v[38:41], v4 offset:8208
	ds_read_b128 v[42:45], v4 offset:12288
	ds_read_b128 v[46:49], v4 offset:12304
	ds_read_b128 v[50:53], v4 offset:16384
	ds_read_b128 v[54:57], v4 offset:16400
	ds_read_b128 v[58:61], v4 offset:20480
	ds_read_b128 v[62:65], v4 offset:20496
	ds_read_b128 v[66:69], v4 offset:24576
	ds_read_b128 v[70:73], v4 offset:24592
	ds_read_b128 v[74:77], v4 offset:28672
	ds_read_b128 v[78:81], v4 offset:28688
	ds_read_b128 v[82:85], v4 offset:32
	ds_read_b128 v[86:89], v4 offset:48
	ds_read_b128 v[90:93], v4 offset:4128
	ds_read_b128 v[94:97], v4 offset:4144
	ds_read_b128 v[98:101], v4 offset:8224
	ds_read_b128 v[102:105], v4 offset:8240
	ds_read_b128 v[106:109], v4 offset:12320
	ds_read_b128 v[110:113], v4 offset:12336
	ds_read_b128 v[114:117], v4 offset:16416
	ds_read_b128 v[118:121], v4 offset:16432
	ds_read_b128 v[122:125], v4 offset:20512
	ds_read_b128 v[126:129], v4 offset:20528
	ds_read_b128 v[130:133], v4 offset:24608
	ds_read_b128 v[134:137], v4 offset:24624
	ds_read_b128 v[138:141], v4 offset:28704
	ds_read_b128 v[142:145], v4 offset:28720
	global_load_dword v4, v[146:147], off
	s_mov_b32 s11, s7
	s_mov_b32 s13, s7
	s_mov_b32 s15, s7
	s_mov_b32 s17, s7
	s_mov_b32 s19, s7
	s_mov_b32 s21, s7
	s_mov_b32 s23, s7
	s_mov_b32 s25, s7
	s_mov_b32 s27, s7
	s_mov_b32 s29, s7
	s_mov_b32 s31, s7
	s_mov_b32 s55, s7
	s_mov_b32 s69, s7
	s_mov_b32 s71, s7
	s_add_i32 s10, s6, 0x2400
	s_add_i32 s12, s6, 0x4800
	s_add_i32 s14, s6, 0x6c00
	s_add_i32 s16, s6, 0x9000
	s_add_i32 s18, s6, 0xb400
	s_add_i32 s20, s6, 0xd800
	s_add_i32 s22, s6, 0xfc00
	s_add_i32 s24, s6, 0x12000
	s_add_i32 s26, s6, 0x14400
	s_add_i32 s28, s6, 0x16800
	s_add_i32 s30, s6, 0x18c00
	s_add_i32 s54, s6, 0x1b000
	s_add_i32 s68, s6, 0x1d400
	s_add_i32 s70, s6, 0x1f800
	s_add_i32 s6, s6, 0x21c00
	v_lshl_add_u64 v[146:147], s[10:11], 2, v[8:9]
	v_lshl_add_u64 v[148:149], s[12:13], 2, v[8:9]
	v_lshl_add_u64 v[150:151], s[14:15], 2, v[8:9]
	v_lshl_add_u64 v[152:153], s[16:17], 2, v[8:9]
	v_lshl_add_u64 v[154:155], s[18:19], 2, v[8:9]
	v_lshl_add_u64 v[156:157], s[20:21], 2, v[8:9]
	v_lshl_add_u64 v[158:159], s[22:23], 2, v[8:9]
	v_lshl_add_u64 v[160:161], s[24:25], 2, v[8:9]
	v_lshl_add_u64 v[162:163], s[26:27], 2, v[8:9]
	v_lshl_add_u64 v[164:165], s[28:29], 2, v[8:9]
	v_lshl_add_u64 v[166:167], s[30:31], 2, v[8:9]
	v_lshl_add_u64 v[168:169], s[54:55], 2, v[8:9]
	v_lshl_add_u64 v[170:171], s[68:69], 2, v[8:9]
	v_lshl_add_u64 v[172:173], s[70:71], 2, v[8:9]
	v_lshl_add_u64 v[174:175], s[6:7], 2, v[8:9]
	global_load_dword v146, v[146:147], off
	s_nop 0
	global_load_dword v148, v[148:149], off
	s_nop 0
	global_load_dword v150, v[150:151], off
	s_nop 0
	global_load_dword v152, v[152:153], off
	s_nop 0
	global_load_dword v154, v[154:155], off
	s_nop 0
	global_load_dword v156, v[156:157], off
	s_nop 0
	global_load_dword v158, v[158:159], off
	s_nop 0
	global_load_dword v160, v[160:161], off
	s_nop 0
	global_load_dword v162, v[162:163], off
	s_nop 0
	global_load_dword v164, v[164:165], off
	s_nop 0
	global_load_dword v166, v[166:167], off
	s_nop 0
	global_load_dword v168, v[168:169], off
	s_nop 0
	global_load_dword v170, v[170:171], off
	s_nop 0
	global_load_dword v172, v[172:173], off
	s_nop 0
	global_load_dword v174, v[174:175], off
	s_waitcnt lgkmcnt(0)
	v_mov_b32_e32 v176, v18
	v_mov_b32_e32 v177, v26
	v_mov_b32_e32 v26, v19
	v_mov_b32_e32 v18, v20
	v_mov_b32_e32 v19, v28
	v_mov_b32_e32 v28, v21
	v_mov_b32_e32 v20, v34
	v_mov_b32_e32 v21, v42
	v_mov_b32_e32 v42, v35
	v_mov_b32_e32 v34, v36
	v_mov_b32_e32 v35, v44
	v_mov_b32_e32 v44, v37
	v_mov_b32_e32 v36, v50
	v_mov_b32_e32 v37, v58
	v_mov_b32_e32 v58, v51
	v_mov_b32_e32 v50, v52
	v_mov_b32_e32 v51, v60
	v_mov_b32_e32 v60, v53
	v_mov_b32_e32 v52, v66
	v_mov_b32_e32 v53, v74
	v_mov_b32_e32 v74, v67
	v_mov_b32_e32 v66, v68
	v_mov_b32_e32 v67, v76
	v_mov_b32_e32 v76, v69
	v_mov_b32_e32 v68, v22
	v_mov_b32_e32 v69, v30
	v_mov_b32_e32 v30, v23
	v_mov_b32_e32 v22, v24
	v_mov_b32_e32 v23, v32
	v_mov_b32_e32 v32, v25
	v_mov_b32_e32 v24, v38
	v_mov_b32_e32 v25, v46
	v_mov_b32_e32 v46, v39
	v_mov_b32_e32 v38, v40
	s_waitcnt vmcnt(0)
	v_pk_fma_f32 v[12:13], v[4:5], v[176:177], v[12:13] op_sel_hi:[0,1,1]
	v_pk_fma_f32 v[14:15], v[4:5], v[20:21], v[14:15] op_sel_hi:[0,1,1]
	v_pk_fma_f32 v[16:17], v[4:5], v[36:37], v[16:17] op_sel_hi:[0,1,1]
	v_pk_fma_f32 v[10:11], v[4:5], v[52:53], v[10:11] op_sel_hi:[0,1,1]
	v_mov_b32_e32 v39, v48
	v_mov_b32_e32 v48, v41
	v_mov_b32_e32 v40, v54
	v_mov_b32_e32 v41, v62
	v_mov_b32_e32 v62, v55
	v_mov_b32_e32 v54, v56
	v_mov_b32_e32 v55, v64
	v_mov_b32_e32 v64, v57
	v_mov_b32_e32 v56, v70
	v_mov_b32_e32 v57, v78
	v_mov_b32_e32 v78, v71
	v_mov_b32_e32 v70, v72
	v_mov_b32_e32 v71, v80
	v_mov_b32_e32 v80, v73
	v_mov_b32_e32 v72, v82
	v_mov_b32_e32 v73, v90
	v_mov_b32_e32 v90, v83
	v_mov_b32_e32 v82, v84
	v_mov_b32_e32 v83, v92
	v_mov_b32_e32 v92, v85
	v_mov_b32_e32 v84, v98
	v_mov_b32_e32 v85, v106
	v_mov_b32_e32 v106, v99
	v_mov_b32_e32 v98, v100
	v_mov_b32_e32 v99, v108
	v_mov_b32_e32 v108, v101
	v_mov_b32_e32 v100, v114
	s_waitcnt vmcnt(14)
	v_pk_fma_f32 v[12:13], v[146:147], v[26:27], v[12:13] op_sel_hi:[0,1,1]
	v_pk_fma_f32 v[14:15], v[146:147], v[42:43], v[14:15] op_sel_hi:[0,1,1]
	v_pk_fma_f32 v[16:17], v[146:147], v[58:59], v[16:17] op_sel_hi:[0,1,1]
	v_pk_fma_f32 v[10:11], v[146:147], v[74:75], v[10:11] op_sel_hi:[0,1,1]
	s_waitcnt vmcnt(13)
; __device__ __forceinline__ void phase_mod(const float* c, const float* ada_w, const float* ada_b, float* mod, unsigned char* ldsb) {
;     ...
;         const int k0 = w * 128;
; #pragma unroll 16
;         for (int k = k0; k < k0 + 128; ++k) {
;             const float wv = W[(unsigned)k * 9216];
; #pragma unroll
;             for (int b = 0; b < 8; ++b) acc[b] += cact[b * 1024 + k] * wv;
;         }
	v_pk_fma_f32 v[12:13], v[148:149], v[18:19], v[12:13] op_sel_hi:[0,1,1]
	v_pk_fma_f32 v[14:15], v[148:149], v[34:35], v[14:15] op_sel_hi:[0,1,1]
	v_pk_fma_f32 v[16:17], v[148:149], v[50:51], v[16:17] op_sel_hi:[0,1,1]
	v_pk_fma_f32 v[10:11], v[148:149], v[66:67], v[10:11] op_sel_hi:[0,1,1]
	s_waitcnt vmcnt(12)
	v_pk_fma_f32 v[12:13], v[150:151], v[28:29], v[12:13] op_sel_hi:[0,1,1]
	v_pk_fma_f32 v[14:15], v[150:151], v[44:45], v[14:15] op_sel_hi:[0,1,1]
	v_pk_fma_f32 v[16:17], v[150:151], v[60:61], v[16:17] op_sel_hi:[0,1,1]
	v_pk_fma_f32 v[10:11], v[150:151], v[76:77], v[10:11] op_sel_hi:[0,1,1]
	s_waitcnt vmcnt(11)
	v_pk_fma_f32 v[12:13], v[152:153], v[68:69], v[12:13] op_sel_hi:[0,1,1]
	v_pk_fma_f32 v[14:15], v[152:153], v[24:25], v[14:15] op_sel_hi:[0,1,1]
	v_pk_fma_f32 v[16:17], v[152:153], v[40:41], v[16:17] op_sel_hi:[0,1,1]
	v_pk_fma_f32 v[10:11], v[152:153], v[56:57], v[10:11] op_sel_hi:[0,1,1]
	s_waitcnt vmcnt(10)
	v_pk_fma_f32 v[12:13], v[154:155], v[30:31], v[12:13] op_sel_hi:[0,1,1]
	v_pk_fma_f32 v[14:15], v[154:155], v[46:47], v[14:15] op_sel_hi:[0,1,1]
	v_pk_fma_f32 v[16:17], v[154:155], v[62:63], v[16:17] op_sel_hi:[0,1,1]
	v_pk_fma_f32 v[10:11], v[154:155], v[78:79], v[10:11] op_sel_hi:[0,1,1]
	s_waitcnt vmcnt(9)
	v_pk_fma_f32 v[12:13], v[156:157], v[22:23], v[12:13] op_sel_hi:[0,1,1]
	v_pk_fma_f32 v[14:15], v[156:157], v[38:39], v[14:15] op_sel_hi:[0,1,1]
	v_pk_fma_f32 v[16:17], v[156:157], v[54:55], v[16:17] op_sel_hi:[0,1,1]
	v_pk_fma_f32 v[10:11], v[156:157], v[70:71], v[10:11] op_sel_hi:[0,1,1]
	v_mov_b32_e32 v101, v122
	v_mov_b32_e32 v122, v115
	v_mov_b32_e32 v114, v116
	v_mov_b32_e32 v115, v124
	v_mov_b32_e32 v124, v117
	v_mov_b32_e32 v116, v130
	v_mov_b32_e32 v117, v138
	s_waitcnt vmcnt(8)
	v_pk_fma_f32 v[12:13], v[158:159], v[32:33], v[12:13] op_sel_hi:[0,1,1]
	v_pk_fma_f32 v[14:15], v[158:159], v[48:49], v[14:15] op_sel_hi:[0,1,1]
	v_pk_fma_f32 v[16:17], v[158:159], v[64:65], v[16:17] op_sel_hi:[0,1,1]
	v_pk_fma_f32 v[10:11], v[158:159], v[80:81], v[10:11] op_sel_hi:[0,1,1]
	v_mov_b32_e32 v138, v131
	s_waitcnt vmcnt(7)
	v_pk_fma_f32 v[12:13], v[160:161], v[72:73], v[12:13] op_sel_hi:[0,1,1]
	v_pk_fma_f32 v[14:15], v[160:161], v[84:85], v[14:15] op_sel_hi:[0,1,1]
	v_pk_fma_f32 v[16:17], v[160:161], v[100:101], v[16:17] op_sel_hi:[0,1,1]
	v_pk_fma_f32 v[10:11], v[160:161], v[116:117], v[10:11] op_sel_hi:[0,1,1]
	v_mov_b32_e32 v130, v132
	v_mov_b32_e32 v131, v140
	s_waitcnt vmcnt(6)
	v_pk_fma_f32 v[12:13], v[162:163], v[90:91], v[12:13] op_sel_hi:[0,1,1]
	v_pk_fma_f32 v[14:15], v[162:163], v[106:107], v[14:15] op_sel_hi:[0,1,1]
	v_pk_fma_f32 v[16:17], v[162:163], v[122:123], v[16:17] op_sel_hi:[0,1,1]
	v_pk_fma_f32 v[10:11], v[162:163], v[138:139], v[10:11] op_sel_hi:[0,1,1]
	v_mov_b32_e32 v140, v133
	s_waitcnt vmcnt(5)
	v_pk_fma_f32 v[12:13], v[164:165], v[82:83], v[12:13] op_sel_hi:[0,1,1]
	v_pk_fma_f32 v[14:15], v[164:165], v[98:99], v[14:15] op_sel_hi:[0,1,1]
	v_pk_fma_f32 v[16:17], v[164:165], v[114:115], v[16:17] op_sel_hi:[0,1,1]
	v_pk_fma_f32 v[10:11], v[164:165], v[130:131], v[10:11] op_sel_hi:[0,1,1]
	v_mov_b32_e32 v132, v86
	v_mov_b32_e32 v133, v94
	v_mov_b32_e32 v94, v87
	v_mov_b32_e32 v86, v88
	v_mov_b32_e32 v87, v96
	v_mov_b32_e32 v96, v89
	v_mov_b32_e32 v88, v102
	v_mov_b32_e32 v89, v110
	v_mov_b32_e32 v110, v103
	v_mov_b32_e32 v102, v104
	v_mov_b32_e32 v103, v112
	v_mov_b32_e32 v112, v105
	v_mov_b32_e32 v104, v118
	v_mov_b32_e32 v105, v126
	v_mov_b32_e32 v126, v119
	v_mov_b32_e32 v118, v120
	v_mov_b32_e32 v119, v128
	v_mov_b32_e32 v128, v121
	v_mov_b32_e32 v120, v134
	v_mov_b32_e32 v121, v142
	s_waitcnt vmcnt(4)
	v_pk_fma_f32 v[12:13], v[166:167], v[92:93], v[12:13] op_sel_hi:[0,1,1]
	v_pk_fma_f32 v[14:15], v[166:167], v[108:109], v[14:15] op_sel_hi:[0,1,1]
	v_pk_fma_f32 v[16:17], v[166:167], v[124:125], v[16:17] op_sel_hi:[0,1,1]
	v_pk_fma_f32 v[10:11], v[166:167], v[140:141], v[10:11] op_sel_hi:[0,1,1]
	v_mov_b32_e32 v142, v135
	s_waitcnt vmcnt(3)
	v_pk_fma_f32 v[12:13], v[168:169], v[132:133], v[12:13] op_sel_hi:[0,1,1]
	v_pk_fma_f32 v[14:15], v[168:169], v[88:89], v[14:15] op_sel_hi:[0,1,1]
	v_pk_fma_f32 v[16:17], v[168:169], v[104:105], v[16:17] op_sel_hi:[0,1,1]
	v_pk_fma_f32 v[10:11], v[168:169], v[120:121], v[10:11] op_sel_hi:[0,1,1]
	v_mov_b32_e32 v134, v136
	v_mov_b32_e32 v135, v144
	s_waitcnt vmcnt(2)
	v_pk_fma_f32 v[12:13], v[170:171], v[94:95], v[12:13] op_sel_hi:[0,1,1]
	v_pk_fma_f32 v[14:15], v[170:171], v[110:111], v[14:15] op_sel_hi:[0,1,1]
	v_pk_fma_f32 v[16:17], v[170:171], v[126:127], v[16:17] op_sel_hi:[0,1,1]
	v_pk_fma_f32 v[10:11], v[170:171], v[142:143], v[10:11] op_sel_hi:[0,1,1]
	s_add_i32 s77, s77, 0x24000
	s_add_i32 s9, s9, 64
	v_mov_b32_e32 v144, v137
	s_waitcnt vmcnt(1)
	v_pk_fma_f32 v[12:13], v[172:173], v[86:87], v[12:13] op_sel_hi:[0,1,1]
	v_pk_fma_f32 v[14:15], v[172:173], v[102:103], v[14:15] op_sel_hi:[0,1,1]
	v_pk_fma_f32 v[16:17], v[172:173], v[118:119], v[16:17] op_sel_hi:[0,1,1]
	v_pk_fma_f32 v[10:11], v[172:173], v[134:135], v[10:11] op_sel_hi:[0,1,1]
	s_cmp_eq_u32 s77, 0x120000
	s_waitcnt vmcnt(0)
	v_pk_fma_f32 v[12:13], v[174:175], v[96:97], v[12:13] op_sel_hi:[0,1,1]
	v_pk_fma_f32 v[14:15], v[174:175], v[112:113], v[14:15] op_sel_hi:[0,1,1]
	v_pk_fma_f32 v[16:17], v[174:175], v[128:129], v[16:17] op_sel_hi:[0,1,1]
	v_pk_fma_f32 v[10:11], v[174:175], v[144:145], v[10:11] op_sel_hi:[0,1,1]
	s_cbranch_scc0 .LBB0_9
; #define LDS_BARRIER() do { asm volatile("s_waitcnt lgkmcnt(0)" ::: "memory"); __builtin_amdgcn_s_barrier(); asm volatile("" ::: "memory"); } while (0)
; __device__ __forceinline__ void phase_mod(const float* c, const float* ada_w, const float* ada_b, float* mod, unsigned char* ldsb) {
;     ...
; #pragma unroll
;         for (int b = 0; b < 8; ++b) red[(w * 8 + b) * 64 + lane] = acc[b];
;         LDS_BARRIER();
;         {
;             const int b = w;
;             float s = ada_b[l * 9216 + n0 + lane];
; #pragma unroll
;             for (int ww = 0; ww < 8; ++ww) s += red[(ww * 8 + b) * 64 + lane];
;             mod[(unsigned)(l * 8 + b) * 9216 + n0 + lane] = s;
;         }
;         LDS_BARRIER();
	s_mul_i32 s6, s76, 0x2400
	s_add_i32 s6, s6, s8
	v_add_u32_e32 v4, s72, v1
	v_or_b32_e32 v8, s6, v2
	v_readlane_b32 s56, v253, 16
	ds_write2st64_b32 v4, v12, v13 offset0:128 offset1:129
	ds_write2st64_b32 v4, v14, v15 offset0:130 offset1:131
	ds_write2st64_b32 v4, v16, v17 offset0:132 offset1:133
	ds_write2st64_b32 v4, v10, v11 offset0:134 offset1:135
	v_ashrrev_i32_e32 v9, 31, v8
	v_readlane_b32 s62, v253, 22
	v_readlane_b32 s63, v253, 23
	s_waitcnt lgkmcnt(0)
	s_barrier
	s_lshl_b32 s6, s76, 3
	v_lshl_add_u64 v[8:9], v[8:9], 2, s[62:63]
	global_load_dword v18, v[8:9], off
	s_add_i32 s6, s6, s33
	s_mulk_i32 s6, 0x2400
	ds_read2st64_b32 v[8:9], v3 offset0:128 offset1:136
	ds_read2st64_b32 v[10:11], v3 offset0:144 offset1:152
	ds_read2st64_b32 v[12:13], v3 offset0:160 offset1:168
	ds_read2st64_b32 v[14:15], v3 offset0:176 offset1:184
	s_add_i32 s6, s6, s8
	v_or_b32_e32 v4, s6, v2
	v_lshl_add_u64 v[16:17], v[4:5], 2, s[0:1]
	s_add_i32 s3, s3, s34
	v_readlane_b32 s57, v253, 17
	v_readlane_b32 s60, v253, 20
	v_readlane_b32 s61, v253, 21
	v_readlane_b32 s70, v253, 30
	v_readlane_b32 s71, v253, 31
	s_cmpk_gt_i32 s3, 0x11f
	v_readlane_b32 s58, v253, 18
	v_readlane_b32 s59, v253, 19
	v_readlane_b32 s64, v253, 24
	v_readlane_b32 s65, v253, 25
	v_readlane_b32 s66, v253, 26
	v_readlane_b32 s67, v253, 27
	v_readlane_b32 s68, v253, 28
	v_readlane_b32 s69, v253, 29
	s_waitcnt vmcnt(0) lgkmcnt(3)
	v_add_f32_e32 v4, v18, v8
	v_add_f32_e32 v4, v4, v9
	s_waitcnt lgkmcnt(2)
	v_add_f32_e32 v4, v4, v10
	v_add_f32_e32 v4, v4, v11
	s_waitcnt lgkmcnt(1)
	v_add_f32_e32 v4, v4, v12
	v_add_f32_e32 v4, v4, v13
	s_waitcnt lgkmcnt(0)
	v_add_f32_e32 v4, v4, v14
	v_add_f32_e32 v4, v4, v15
	global_store_dword v[16:17], v4, off
	s_waitcnt lgkmcnt(0)
	s_barrier
	s_cbranch_scc0 .LBB0_8

;     __device__ __forceinline__ void operator()(const f32x4 (&acc)[2][2][4][2], const Unit& u, int wr, int wc, int fr, int fq) const {
;     ...
;         } else if (wc == 0 && fq < 2) {
; #pragma unroll
;             for (int ai = 0; ai < 2; ++ai)
; #pragma unroll
;                 for (int m = 0; m < 4; ++m)
; #pragma unroll
;                     for (int n = 0; n < 2; ++n) *(f32x4*)(bd + (unsigned)(row0 + ai * HALF + m * 16) * 16 + 8 * fq + 4 * n) = acc[ai][0][m][n];
.LBB0_220:
	s_and_saveexec_b64 s[18:19], s[8:9]
	s_cbranch_execz .LBB0_222
	v_lshlrev_b32_e32 v32, 4, v148
	v_lshl_add_u64 v[150:151], v[32:33], 2, v[138:139]
	global_store_dwordx4 v[150:151], v[126:129], off
	global_store_dwordx4 v[150:151], v[122:125], off offset:16
	global_store_dwordx4 v[150:151], v[110:113], off offset:1024
	global_store_dwordx4 v[150:151], v[106:109], off offset:1040
	global_store_dwordx4 v[150:151], v[94:97], off offset:2048
	global_store_dwordx4 v[150:151], v[90:93], off offset:2064
	global_store_dwordx4 v[150:151], v[78:81], off offset:3072
	global_store_dwordx4 v[150:151], v[74:77], off offset:3088
	v_add_u32_e32 v150, 0x800, v32
	v_mov_b32_e32 v151, v33
	v_lshl_add_u64 v[150:151], v[150:151], 2, v[138:139]
	global_store_dwordx4 v[150:151], v[62:65], off
	global_store_dwordx4 v[150:151], v[58:61], off offset:16
	v_add_u32_e32 v150, 0x900, v32
	v_mov_b32_e32 v151, v33
	v_lshl_add_u64 v[150:151], v[150:151], 2, v[138:139]
	global_store_dwordx4 v[150:151], v[46:49], off
	global_store_dwordx4 v[150:151], v[42:45], off offset:16
	v_add_u32_e32 v150, 0xa00, v32
	v_mov_b32_e32 v151, v33
	v_lshl_add_u64 v[150:151], v[150:151], 2, v[138:139]
	v_add_u32_e32 v32, 0xb00, v32
	global_store_dwordx4 v[150:151], v[28:31], off
	global_store_dwordx4 v[150:151], v[24:27], off offset:16
	v_lshl_add_u64 v[150:151], v[32:33], 2, v[138:139]
	global_store_dwordx4 v[150:151], v[12:15], off
	global_store_dwordx4 v[150:151], v[8:11], off offset:16

; __device__ __forceinline__ float sigm_f(float x) { return __builtin_amdgcn_rcpf(1.0f + fexp(-x)); }
;     __device__ __forceinline__ void operator()(const f32x4 (&acc)[2][2][4][2], const Unit& u, int wr, int wc, int fr, int fq) const {
;     ...
;                         for (int n = 0; n < 2; ++n)
; #pragma unroll
;                             for (int j = 0; j < 4; ++j) { float v = acc[ai][bj][m][n][j]; if (act) v = sigm_f(v); o[4 * n + j] = (h16)v; }
.LBB0_223:
	v_mul_f32_e32 v32, 0xbfb8aa3b, v126
	v_mul_f32_e32 v126, 0xbfb8aa3b, v127
	v_mul_f32_e32 v127, 0xbfb8aa3b, v128
	v_mul_f32_e32 v124, 0xbfb8aa3b, v124
	v_mul_f32_e32 v125, 0xbfb8aa3b, v125
	v_exp_f32_e32 v32, v32
	v_exp_f32_e32 v126, v126
	v_exp_f32_e32 v127, v127
	v_mul_f32_e32 v128, 0xbfb8aa3b, v129
	v_exp_f32_e32 v124, v124
	v_exp_f32_e32 v125, v125
	v_mul_f32_e32 v110, 0xbfb8aa3b, v110
	v_mul_f32_e32 v111, 0xbfb8aa3b, v111
	v_mul_f32_e32 v106, 0xbfb8aa3b, v106
	v_mul_f32_e32 v107, 0xbfb8aa3b, v107
	v_mul_f32_e32 v108, 0xbfb8aa3b, v108
	v_mul_f32_e32 v109, 0xbfb8aa3b, v109
	v_mul_f32_e32 v94, 0xbfb8aa3b, v94
	v_mul_f32_e32 v95, 0xbfb8aa3b, v95
	v_mul_f32_e32 v90, 0xbfb8aa3b, v90
	v_mul_f32_e32 v91, 0xbfb8aa3b, v91
	v_mul_f32_e32 v92, 0xbfb8aa3b, v92
	v_mul_f32_e32 v93, 0xbfb8aa3b, v93
	v_mul_f32_e32 v78, 0xbfb8aa3b, v78
	v_mul_f32_e32 v79, 0xbfb8aa3b, v79
	v_mul_f32_e32 v74, 0xbfb8aa3b, v74
	v_mul_f32_e32 v75, 0xbfb8aa3b, v75
	v_mul_f32_e32 v76, 0xbfb8aa3b, v76
	v_mul_f32_e32 v77, 0xbfb8aa3b, v77
	v_mul_f32_e32 v62, 0xbfb8aa3b, v62
	v_mul_f32_e32 v63, 0xbfb8aa3b, v63
	v_mul_f32_e32 v58, 0xbfb8aa3b, v58
	v_mul_f32_e32 v59, 0xbfb8aa3b, v59
	v_mul_f32_e32 v60, 0xbfb8aa3b, v60
	v_mul_f32_e32 v61, 0xbfb8aa3b, v61
	v_mul_f32_e32 v46, 0xbfb8aa3b, v46
	v_mul_f32_e32 v47, 0xbfb8aa3b, v47
	v_mul_f32_e32 v42, 0xbfb8aa3b, v42
	v_mul_f32_e32 v43, 0xbfb8aa3b, v43
	v_mul_f32_e32 v44, 0xbfb8aa3b, v44
	v_mul_f32_e32 v45, 0xbfb8aa3b, v45
	v_mul_f32_e32 v28, 0xbfb8aa3b, v28
	v_mul_f32_e32 v29, 0xbfb8aa3b, v29
	v_mul_f32_e32 v24, 0xbfb8aa3b, v24
	v_mul_f32_e32 v25, 0xbfb8aa3b, v25
	v_mul_f32_e32 v26, 0xbfb8aa3b, v26
	v_mul_f32_e32 v27, 0xbfb8aa3b, v27
	v_exp_f32_e32 v128, v128
	v_mul_f32_e32 v122, 0xbfb8aa3b, v122
	v_mul_f32_e32 v123, 0xbfb8aa3b, v123
	v_exp_f32_e32 v110, v110
	v_exp_f32_e32 v111, v111
	v_exp_f32_e32 v106, v106
	v_exp_f32_e32 v107, v107
	v_exp_f32_e32 v108, v108
	v_exp_f32_e32 v109, v109
	v_exp_f32_e32 v94, v94
	v_exp_f32_e32 v95, v95
	v_exp_f32_e32 v90, v90
	v_exp_f32_e32 v91, v91
	v_exp_f32_e32 v92, v92
	v_exp_f32_e32 v93, v93
	v_exp_f32_e32 v78, v78
	v_exp_f32_e32 v79, v79
	v_exp_f32_e32 v74, v74
	v_exp_f32_e32 v75, v75
	v_exp_f32_e32 v76, v76
	v_exp_f32_e32 v77, v77
	v_exp_f32_e32 v62, v62
	v_exp_f32_e32 v63, v63
	v_exp_f32_e32 v58, v58
	v_exp_f32_e32 v59, v59
	v_exp_f32_e32 v60, v60
	v_exp_f32_e32 v61, v61
	v_exp_f32_e32 v46, v46
	v_exp_f32_e32 v47, v47
	v_exp_f32_e32 v42, v42
	v_exp_f32_e32 v43, v43
	v_exp_f32_e32 v44, v44
	v_exp_f32_e32 v45, v45
	v_exp_f32_e32 v28, v28
	v_exp_f32_e32 v29, v29
	v_exp_f32_e32 v24, v24
	v_exp_f32_e32 v25, v25
	v_exp_f32_e32 v26, v26
	v_exp_f32_e32 v27, v27
	v_mul_f32_e32 v12, 0xbfb8aa3b, v12
	v_mul_f32_e32 v13, 0xbfb8aa3b, v13
	v_mul_f32_e32 v8, 0xbfb8aa3b, v8
	v_mul_f32_e32 v9, 0xbfb8aa3b, v9
	v_mul_f32_e32 v10, 0xbfb8aa3b, v10
	v_mul_f32_e32 v11, 0xbfb8aa3b, v11
	v_exp_f32_e32 v122, v122
	v_exp_f32_e32 v123, v123
	v_mul_f32_e32 v118, 0xbfb8aa3b, v118
	v_mul_f32_e32 v119, 0xbfb8aa3b, v119
	v_mul_f32_e32 v120, 0xbfb8aa3b, v120
	v_mul_f32_e32 v121, 0xbfb8aa3b, v121
	v_mul_f32_e32 v114, 0xbfb8aa3b, v114
	v_mul_f32_e32 v115, 0xbfb8aa3b, v115
	v_mul_f32_e32 v116, 0xbfb8aa3b, v116
	v_mul_f32_e32 v117, 0xbfb8aa3b, v117
	v_mul_f32_e32 v112, 0xbfb8aa3b, v112
	v_mul_f32_e32 v113, 0xbfb8aa3b, v113
	v_mul_f32_e32 v102, 0xbfb8aa3b, v102
	v_mul_f32_e32 v103, 0xbfb8aa3b, v103
	v_mul_f32_e32 v104, 0xbfb8aa3b, v104
	v_mul_f32_e32 v105, 0xbfb8aa3b, v105
	v_mul_f32_e32 v98, 0xbfb8aa3b, v98
	v_mul_f32_e32 v99, 0xbfb8aa3b, v99
	v_mul_f32_e32 v100, 0xbfb8aa3b, v100
	v_mul_f32_e32 v101, 0xbfb8aa3b, v101
	v_mul_f32_e32 v96, 0xbfb8aa3b, v96
	v_mul_f32_e32 v97, 0xbfb8aa3b, v97
	v_mul_f32_e32 v86, 0xbfb8aa3b, v86
	v_mul_f32_e32 v87, 0xbfb8aa3b, v87
	v_mul_f32_e32 v88, 0xbfb8aa3b, v88
	v_mul_f32_e32 v89, 0xbfb8aa3b, v89
	v_mul_f32_e32 v82, 0xbfb8aa3b, v82
	v_mul_f32_e32 v83, 0xbfb8aa3b, v83
	v_mul_f32_e32 v84, 0xbfb8aa3b, v84
	v_mul_f32_e32 v85, 0xbfb8aa3b, v85
	v_mul_f32_e32 v80, 0xbfb8aa3b, v80
	v_mul_f32_e32 v81, 0xbfb8aa3b, v81
	v_mul_f32_e32 v70, 0xbfb8aa3b, v70
	v_mul_f32_e32 v71, 0xbfb8aa3b, v71
	v_mul_f32_e32 v72, 0xbfb8aa3b, v72
	v_mul_f32_e32 v73, 0xbfb8aa3b, v73
	v_mul_f32_e32 v66, 0xbfb8aa3b, v66
	v_mul_f32_e32 v67, 0xbfb8aa3b, v67
	v_mul_f32_e32 v68, 0xbfb8aa3b, v68
	v_mul_f32_e32 v69, 0xbfb8aa3b, v69
	v_mul_f32_e32 v64, 0xbfb8aa3b, v64
	v_mul_f32_e32 v65, 0xbfb8aa3b, v65
	v_mul_f32_e32 v54, 0xbfb8aa3b, v54
	v_mul_f32_e32 v55, 0xbfb8aa3b, v55
	v_mul_f32_e32 v56, 0xbfb8aa3b, v56
	v_mul_f32_e32 v57, 0xbfb8aa3b, v57
	v_mul_f32_e32 v50, 0xbfb8aa3b, v50
	v_mul_f32_e32 v51, 0xbfb8aa3b, v51
	v_mul_f32_e32 v52, 0xbfb8aa3b, v52
	v_mul_f32_e32 v53, 0xbfb8aa3b, v53
	v_mul_f32_e32 v48, 0xbfb8aa3b, v48
	v_mul_f32_e32 v49, 0xbfb8aa3b, v49
	v_mul_f32_e32 v38, 0xbfb8aa3b, v38
	v_mul_f32_e32 v39, 0xbfb8aa3b, v39
	v_mul_f32_e32 v40, 0xbfb8aa3b, v40
	v_mul_f32_e32 v41, 0xbfb8aa3b, v41
	v_mul_f32_e32 v34, 0xbfb8aa3b, v34
	v_mul_f32_e32 v35, 0xbfb8aa3b, v35
	v_mul_f32_e32 v36, 0xbfb8aa3b, v36
	v_mul_f32_e32 v37, 0xbfb8aa3b, v37
	v_mul_f32_e32 v30, 0xbfb8aa3b, v30
	v_mul_f32_e32 v31, 0xbfb8aa3b, v31
	v_mul_f32_e32 v20, 0xbfb8aa3b, v20
	v_mul_f32_e32 v21, 0xbfb8aa3b, v21
	v_mul_f32_e32 v22, 0xbfb8aa3b, v22
	v_mul_f32_e32 v23, 0xbfb8aa3b, v23
	v_mul_f32_e32 v16, 0xbfb8aa3b, v16
	v_mul_f32_e32 v17, 0xbfb8aa3b, v17
	v_mul_f32_e32 v18, 0xbfb8aa3b, v18
	v_mul_f32_e32 v19, 0xbfb8aa3b, v19
	v_exp_f32_e32 v12, v12
	v_exp_f32_e32 v13, v13
	v_mul_f32_e32 v14, 0xbfb8aa3b, v14
	v_mul_f32_e32 v15, 0xbfb8aa3b, v15
	v_exp_f32_e32 v8, v8
	v_exp_f32_e32 v9, v9
	v_exp_f32_e32 v10, v10
	v_exp_f32_e32 v11, v11
	v_mul_f32_e32 v4, 0xbfb8aa3b, v4
; __device__ __forceinline__ float sigm_f(float x) { return __builtin_amdgcn_rcpf(1.0f + fexp(-x)); }
;     __device__ __forceinline__ void operator()(const f32x4 (&acc)[2][2][4][2], const Unit& u, int wr, int wc, int fr, int fq) const {
;     ...
;                         for (int n = 0; n < 2; ++n)
; #pragma unroll
;                             for (int j = 0; j < 4; ++j) { float v = acc[ai][bj][m][n][j]; if (act) v = sigm_f(v); o[4 * n + j] = (h16)v; }
	v_mul_f32_e32 v5, 0xbfb8aa3b, v5
	v_mul_f32_e32 v6, 0xbfb8aa3b, v6
	v_mul_f32_e32 v7, 0xbfb8aa3b, v7
	v_mul_f32_e32 v0, 0xbfb8aa3b, v0
	v_mul_f32_e32 v1, 0xbfb8aa3b, v1
	v_mul_f32_e32 v2, 0xbfb8aa3b, v2
	v_mul_f32_e32 v3, 0xbfb8aa3b, v3
	v_exp_f32_e32 v118, v118
	v_exp_f32_e32 v119, v119
	v_exp_f32_e32 v120, v120
	v_exp_f32_e32 v121, v121
	v_exp_f32_e32 v114, v114
	v_exp_f32_e32 v115, v115
	v_exp_f32_e32 v116, v116
	v_exp_f32_e32 v117, v117
	v_exp_f32_e32 v112, v112
	v_exp_f32_e32 v113, v113
	v_exp_f32_e32 v102, v102
	v_exp_f32_e32 v103, v103
	v_exp_f32_e32 v104, v104
	v_exp_f32_e32 v105, v105
	v_exp_f32_e32 v98, v98
	v_exp_f32_e32 v99, v99
	v_exp_f32_e32 v100, v100
	v_exp_f32_e32 v101, v101
	v_exp_f32_e32 v96, v96
	v_exp_f32_e32 v97, v97
	v_exp_f32_e32 v86, v86
	v_exp_f32_e32 v87, v87
	v_exp_f32_e32 v88, v88
	v_exp_f32_e32 v89, v89
	v_exp_f32_e32 v82, v82
	v_exp_f32_e32 v83, v83
	v_exp_f32_e32 v84, v84
	v_exp_f32_e32 v85, v85
	v_exp_f32_e32 v80, v80
	v_exp_f32_e32 v81, v81
	v_exp_f32_e32 v70, v70
	v_exp_f32_e32 v71, v71
	v_exp_f32_e32 v72, v72
	v_exp_f32_e32 v73, v73
	v_exp_f32_e32 v66, v66
	v_exp_f32_e32 v67, v67
	v_exp_f32_e32 v68, v68
	v_exp_f32_e32 v69, v69
	v_exp_f32_e32 v64, v64
	v_exp_f32_e32 v65, v65
	v_exp_f32_e32 v54, v54
	v_exp_f32_e32 v55, v55
	v_exp_f32_e32 v56, v56
	v_exp_f32_e32 v57, v57
	v_exp_f32_e32 v50, v50
	v_exp_f32_e32 v51, v51
	v_exp_f32_e32 v52, v52
	v_exp_f32_e32 v53, v53
	v_exp_f32_e32 v48, v48
	v_exp_f32_e32 v49, v49
	v_exp_f32_e32 v38, v38
	v_exp_f32_e32 v39, v39
	v_exp_f32_e32 v40, v40
	v_exp_f32_e32 v41, v41
	v_exp_f32_e32 v34, v34
	v_exp_f32_e32 v35, v35
	v_exp_f32_e32 v36, v36
	v_exp_f32_e32 v37, v37
	v_exp_f32_e32 v30, v30
	v_exp_f32_e32 v31, v31
	v_exp_f32_e32 v20, v20
	v_exp_f32_e32 v21, v21
	v_exp_f32_e32 v22, v22
	v_exp_f32_e32 v23, v23
	v_exp_f32_e32 v16, v16
	v_exp_f32_e32 v17, v17
	v_exp_f32_e32 v18, v18
	v_exp_f32_e32 v19, v19
	v_exp_f32_e32 v14, v14
	v_exp_f32_e32 v15, v15
	v_exp_f32_e32 v4, v4
	v_exp_f32_e32 v5, v5
	v_exp_f32_e32 v6, v6
	v_exp_f32_e32 v7, v7
	v_exp_f32_e32 v0, v0
	v_exp_f32_e32 v1, v1
	v_exp_f32_e32 v2, v2
	v_exp_f32_e32 v3, v3
	v_add_f32_e32 v32, 1.0, v32
	v_add_f32_e32 v126, 1.0, v126
	v_add_f32_e32 v127, 1.0, v127
	v_add_f32_e32 v124, 1.0, v124
	v_add_f32_e32 v125, 1.0, v125
	v_rcp_f32_e32 v32, v32
	v_rcp_f32_e32 v129, v127
	v_add_f32_e32 v127, 1.0, v128
	v_rcp_f32_e32 v124, v124
	v_rcp_f32_e32 v125, v125
	v_rcp_f32_e32 v149, v126
	v_add_f32_e32 v110, 1.0, v110
	v_add_f32_e32 v111, 1.0, v111
	v_add_f32_e32 v106, 1.0, v106
	v_add_f32_e32 v107, 1.0, v107
	v_add_f32_e32 v108, 1.0, v108
	v_add_f32_e32 v109, 1.0, v109
	v_add_f32_e32 v94, 1.0, v94
	v_add_f32_e32 v95, 1.0, v95
	v_add_f32_e32 v90, 1.0, v90
	v_add_f32_e32 v91, 1.0, v91
	v_add_f32_e32 v92, 1.0, v92
	v_add_f32_e32 v93, 1.0, v93
	v_add_f32_e32 v78, 1.0, v78
	v_add_f32_e32 v79, 1.0, v79
	v_add_f32_e32 v74, 1.0, v74
	v_add_f32_e32 v75, 1.0, v75
	v_add_f32_e32 v76, 1.0, v76
	v_add_f32_e32 v77, 1.0, v77
	v_add_f32_e32 v62, 1.0, v62
	v_add_f32_e32 v63, 1.0, v63
	v_add_f32_e32 v58, 1.0, v58
	v_add_f32_e32 v59, 1.0, v59
	v_add_f32_e32 v60, 1.0, v60
	v_add_f32_e32 v61, 1.0, v61
	v_add_f32_e32 v46, 1.0, v46
	v_add_f32_e32 v47, 1.0, v47
	v_add_f32_e32 v42, 1.0, v42
	v_add_f32_e32 v43, 1.0, v43
	v_add_f32_e32 v44, 1.0, v44
	v_add_f32_e32 v45, 1.0, v45
	v_add_f32_e32 v28, 1.0, v28
	v_add_f32_e32 v29, 1.0, v29
	v_add_f32_e32 v24, 1.0, v24
	v_add_f32_e32 v25, 1.0, v25
	v_add_f32_e32 v26, 1.0, v26
	v_add_f32_e32 v27, 1.0, v27
	v_add_f32_e32 v122, 1.0, v122
	v_add_f32_e32 v123, 1.0, v123
	v_rcp_f32_e32 v128, v127
	v_rcp_f32_e32 v110, v110
	v_rcp_f32_e32 v106, v106
	v_rcp_f32_e32 v108, v108
	v_rcp_f32_e32 v109, v109
	v_rcp_f32_e32 v107, v107
	v_rcp_f32_e32 v111, v111
	v_rcp_f32_e32 v94, v94
	v_rcp_f32_e32 v90, v90
	v_rcp_f32_e32 v92, v92
	v_rcp_f32_e32 v93, v93
	v_rcp_f32_e32 v91, v91
	v_rcp_f32_e32 v95, v95
	v_rcp_f32_e32 v78, v78
	v_rcp_f32_e32 v74, v74
	v_rcp_f32_e32 v76, v76
	v_rcp_f32_e32 v77, v77
	v_rcp_f32_e32 v75, v75
	v_rcp_f32_e32 v79, v79
	v_rcp_f32_e32 v62, v62
	v_rcp_f32_e32 v58, v58
	v_rcp_f32_e32 v60, v60
	v_rcp_f32_e32 v61, v61
	v_rcp_f32_e32 v59, v59
	v_rcp_f32_e32 v63, v63
	v_rcp_f32_e32 v46, v46
	v_rcp_f32_e32 v42, v42
	v_rcp_f32_e32 v44, v44
	v_rcp_f32_e32 v45, v45
	v_rcp_f32_e32 v43, v43
	v_rcp_f32_e32 v47, v47
	v_rcp_f32_e32 v28, v28
	v_rcp_f32_e32 v24, v24
	v_rcp_f32_e32 v26, v26
	v_rcp_f32_e32 v27, v27
	v_rcp_f32_e32 v25, v25
	v_rcp_f32_e32 v29, v29
	v_add_f32_e32 v12, 1.0, v12
	v_add_f32_e32 v13, 1.0, v13
	v_add_f32_e32 v8, 1.0, v8
	v_add_f32_e32 v9, 1.0, v9
	v_add_f32_e32 v10, 1.0, v10
	v_add_f32_e32 v11, 1.0, v11
	v_rcp_f32_e32 v122, v122
	v_rcp_f32_e32 v123, v123
	v_add_f32_e32 v118, 1.0, v118
	v_add_f32_e32 v119, 1.0, v119
	v_add_f32_e32 v120, 1.0, v120
	v_add_f32_e32 v121, 1.0, v121
	v_add_f32_e32 v114, 1.0, v114
	v_add_f32_e32 v115, 1.0, v115
	v_add_f32_e32 v116, 1.0, v116
	v_add_f32_e32 v117, 1.0, v117
	v_add_f32_e32 v112, 1.0, v112
	v_add_f32_e32 v113, 1.0, v113
	v_add_f32_e32 v102, 1.0, v102
	v_add_f32_e32 v103, 1.0, v103
	v_add_f32_e32 v104, 1.0, v104
	v_add_f32_e32 v105, 1.0, v105
	v_add_f32_e32 v98, 1.0, v98
	v_add_f32_e32 v99, 1.0, v99
	v_add_f32_e32 v100, 1.0, v100
	v_add_f32_e32 v101, 1.0, v101
	v_add_f32_e32 v96, 1.0, v96
	v_add_f32_e32 v97, 1.0, v97
	v_add_f32_e32 v86, 1.0, v86
	v_add_f32_e32 v87, 1.0, v87
	v_add_f32_e32 v88, 1.0, v88
	v_add_f32_e32 v89, 1.0, v89
	v_add_f32_e32 v82, 1.0, v82
	v_add_f32_e32 v83, 1.0, v83
	v_add_f32_e32 v84, 1.0, v84
	v_add_f32_e32 v85, 1.0, v85
	v_add_f32_e32 v80, 1.0, v80
	v_add_f32_e32 v81, 1.0, v81
	v_add_f32_e32 v70, 1.0, v70
	v_add_f32_e32 v71, 1.0, v71
; __device__ __forceinline__ float sigm_f(float x) { return __builtin_amdgcn_rcpf(1.0f + fexp(-x)); }
;     __device__ __forceinline__ void operator()(const f32x4 (&acc)[2][2][4][2], const Unit& u, int wr, int wc, int fr, int fq) const {
;     ...
;                         for (int n = 0; n < 2; ++n)
; #pragma unroll
;                             for (int j = 0; j < 4; ++j) { float v = acc[ai][bj][m][n][j]; if (act) v = sigm_f(v); o[4 * n + j] = (h16)v; }
;                         *(h16x8*)(O + (unsigned)(row0 + ai * HALF + m * 16) * ldc + col0 + bj * HALF) = o;
	v_add_f32_e32 v72, 1.0, v72
	v_add_f32_e32 v73, 1.0, v73
	v_add_f32_e32 v66, 1.0, v66
	v_add_f32_e32 v67, 1.0, v67
	v_add_f32_e32 v68, 1.0, v68
	v_add_f32_e32 v69, 1.0, v69
	v_add_f32_e32 v64, 1.0, v64
	v_add_f32_e32 v65, 1.0, v65
	v_add_f32_e32 v54, 1.0, v54
	v_add_f32_e32 v55, 1.0, v55
	v_add_f32_e32 v56, 1.0, v56
	v_add_f32_e32 v57, 1.0, v57
	v_add_f32_e32 v50, 1.0, v50
	v_add_f32_e32 v51, 1.0, v51
	v_add_f32_e32 v52, 1.0, v52
	v_add_f32_e32 v53, 1.0, v53
	v_add_f32_e32 v48, 1.0, v48
	v_add_f32_e32 v49, 1.0, v49
	v_add_f32_e32 v38, 1.0, v38
	v_add_f32_e32 v39, 1.0, v39
	v_add_f32_e32 v40, 1.0, v40
	v_add_f32_e32 v41, 1.0, v41
	v_add_f32_e32 v34, 1.0, v34
	v_add_f32_e32 v35, 1.0, v35
	v_add_f32_e32 v36, 1.0, v36
	v_add_f32_e32 v37, 1.0, v37
	v_add_f32_e32 v30, 1.0, v30
	v_add_f32_e32 v31, 1.0, v31
	v_add_f32_e32 v20, 1.0, v20
	v_add_f32_e32 v21, 1.0, v21
	v_add_f32_e32 v22, 1.0, v22
	v_add_f32_e32 v23, 1.0, v23
	v_add_f32_e32 v16, 1.0, v16
	v_add_f32_e32 v17, 1.0, v17
	v_add_f32_e32 v18, 1.0, v18
	v_add_f32_e32 v19, 1.0, v19
	v_rcp_f32_e32 v12, v12
	v_add_f32_e32 v14, 1.0, v14
	v_add_f32_e32 v15, 1.0, v15
	v_rcp_f32_e32 v8, v8
	v_rcp_f32_e32 v10, v10
	v_rcp_f32_e32 v11, v11
	v_rcp_f32_e32 v9, v9
	v_rcp_f32_e32 v13, v13
	v_add_f32_e32 v4, 1.0, v4
	v_add_f32_e32 v5, 1.0, v5
	v_add_f32_e32 v6, 1.0, v6
	v_add_f32_e32 v7, 1.0, v7
	v_add_f32_e32 v0, 1.0, v0
	v_add_f32_e32 v1, 1.0, v1
	v_add_f32_e32 v2, 1.0, v2
	v_add_f32_e32 v3, 1.0, v3
	v_readlane_b32 s18, v255, 30
	v_rcp_f32_e32 v118, v118
	v_rcp_f32_e32 v120, v120
	v_rcp_f32_e32 v114, v114
	v_rcp_f32_e32 v116, v116
	v_rcp_f32_e32 v117, v117
	v_rcp_f32_e32 v115, v115
	v_rcp_f32_e32 v121, v121
	v_rcp_f32_e32 v119, v119
	v_rcp_f32_e32 v112, v112
	v_rcp_f32_e32 v113, v113
	v_rcp_f32_e32 v102, v102
	v_rcp_f32_e32 v104, v104
	v_rcp_f32_e32 v98, v98
	v_rcp_f32_e32 v100, v100
	v_rcp_f32_e32 v101, v101
	v_rcp_f32_e32 v99, v99
	v_rcp_f32_e32 v105, v105
	v_rcp_f32_e32 v103, v103
	v_rcp_f32_e32 v96, v96
	v_rcp_f32_e32 v97, v97
	v_rcp_f32_e32 v86, v86
	v_rcp_f32_e32 v88, v88
	v_rcp_f32_e32 v82, v82
	v_rcp_f32_e32 v84, v84
	v_rcp_f32_e32 v85, v85
	v_rcp_f32_e32 v83, v83
	v_rcp_f32_e32 v89, v89
	v_rcp_f32_e32 v87, v87
	v_rcp_f32_e32 v80, v80
	v_rcp_f32_e32 v81, v81
	v_rcp_f32_e32 v70, v70
	v_rcp_f32_e32 v72, v72
	v_rcp_f32_e32 v66, v66
	v_rcp_f32_e32 v68, v68
	v_rcp_f32_e32 v69, v69
	v_rcp_f32_e32 v67, v67
	v_rcp_f32_e32 v73, v73
	v_rcp_f32_e32 v71, v71
	v_rcp_f32_e32 v64, v64
	v_rcp_f32_e32 v65, v65
	v_rcp_f32_e32 v54, v54
	v_rcp_f32_e32 v56, v56
	v_rcp_f32_e32 v50, v50
	v_rcp_f32_e32 v52, v52
	v_rcp_f32_e32 v53, v53
	v_rcp_f32_e32 v51, v51
	v_rcp_f32_e32 v57, v57
	v_rcp_f32_e32 v55, v55
	v_rcp_f32_e32 v48, v48
	v_rcp_f32_e32 v49, v49
	v_rcp_f32_e32 v38, v38
	v_rcp_f32_e32 v40, v40
	v_rcp_f32_e32 v34, v34
	v_rcp_f32_e32 v36, v36
	v_rcp_f32_e32 v37, v37
	v_rcp_f32_e32 v35, v35
	v_rcp_f32_e32 v41, v41
	v_rcp_f32_e32 v39, v39
	v_rcp_f32_e32 v30, v30
	v_rcp_f32_e32 v31, v31
	v_rcp_f32_e32 v20, v20
	v_rcp_f32_e32 v22, v22
	v_rcp_f32_e32 v16, v16
	v_rcp_f32_e32 v18, v18
	v_rcp_f32_e32 v19, v19
	v_rcp_f32_e32 v17, v17
	v_rcp_f32_e32 v23, v23
	v_rcp_f32_e32 v21, v21
	v_rcp_f32_e32 v14, v14
	v_rcp_f32_e32 v15, v15
	v_rcp_f32_e32 v4, v4
	v_rcp_f32_e32 v6, v6
	v_rcp_f32_e32 v0, v0
	v_rcp_f32_e32 v2, v2
	v_rcp_f32_e32 v3, v3
	v_rcp_f32_e32 v1, v1
	v_rcp_f32_e32 v7, v7
	v_rcp_f32_e32 v5, v5
	v_lshl_or_b32 v150, s69, 8, v146
	v_cvt_pk_f16_f32 v127, v124, v125
	v_cvt_pk_f16_f32 v124, v32, v149
	v_lshlrev_b32_e32 v32, 10, v148
	v_readlane_b32 s19, v255, 31
	v_ashrrev_i32_e32 v151, 31, v150
	v_cvt_pk_f16_f32 v125, v129, v128
	v_lshl_add_u64 v[128:129], v[32:33], 1, s[18:19]
	v_cvt_pk_f16_f32 v109, v108, v109
	v_cvt_pk_f16_f32 v108, v106, v107
	v_cvt_pk_f16_f32 v106, v110, v111
	v_or_b32_e32 v110, 0x4000, v32
	v_mov_b32_e32 v111, v33
	v_cvt_pk_f16_f32 v93, v92, v93
; __device__ __forceinline__ float sigm_f(float x) { return __builtin_amdgcn_rcpf(1.0f + fexp(-x)); }
;     __device__ __forceinline__ void operator()(const f32x4 (&acc)[2][2][4][2], const Unit& u, int wr, int wc, int fr, int fq) const {
;     ...
;             const int col0 = u.pn * BM + wc * 32 + 8 * fq;
; #pragma unroll
;             for (int ai = 0; ai < 2; ++ai)
; #pragma unroll
;                 for (int m = 0; m < 4; ++m)
; #pragma unroll
;                     for (int bj = 0; bj < 2; ++bj) {
;                         h16x8 o;
; #pragma unroll
;                         for (int n = 0; n < 2; ++n)
; #pragma unroll
;                             for (int j = 0; j < 4; ++j) { float v = acc[ai][bj][m][n][j]; if (act) v = sigm_f(v); o[4 * n + j] = (h16)v; }
;                         *(h16x8*)(O + (unsigned)(row0 + ai * HALF + m * 16) * ldc + col0 + bj * HALF) = o;
	v_cvt_pk_f16_f32 v92, v90, v91
	v_cvt_pk_f16_f32 v90, v94, v95
	v_or_b32_e32 v94, 0x8000, v32
	v_mov_b32_e32 v95, v33
	v_cvt_pk_f16_f32 v77, v76, v77
	v_cvt_pk_f16_f32 v76, v74, v75
	v_cvt_pk_f16_f32 v74, v78, v79
	v_or_b32_e32 v78, 0xc000, v32
	v_mov_b32_e32 v79, v33
	v_cvt_pk_f16_f32 v61, v60, v61
	v_cvt_pk_f16_f32 v60, v58, v59
	v_cvt_pk_f16_f32 v58, v62, v63
	v_add_u32_e32 v62, 0x20000, v32
	v_mov_b32_e32 v63, v33
	v_cvt_pk_f16_f32 v45, v44, v45
	v_cvt_pk_f16_f32 v44, v42, v43
	v_cvt_pk_f16_f32 v42, v46, v47
	v_add_u32_e32 v46, 0x24000, v32
	v_mov_b32_e32 v47, v33
	v_cvt_pk_f16_f32 v27, v26, v27
	v_cvt_pk_f16_f32 v26, v24, v25
	v_cvt_pk_f16_f32 v24, v28, v29
	v_add_u32_e32 v28, 0x28000, v32
	v_mov_b32_e32 v29, v33
	v_add_u32_e32 v32, 0x2c000, v32
	v_cvt_pk_f16_f32 v126, v122, v123
	v_lshlrev_b64 v[122:123], 1, v[150:151]
	v_lshl_add_u64 v[110:111], v[110:111], 1, s[18:19]
	v_lshl_add_u64 v[94:95], v[94:95], 1, s[18:19]
	v_lshl_add_u64 v[78:79], v[78:79], 1, s[18:19]
	v_lshl_add_u64 v[62:63], v[62:63], 1, s[18:19]
	v_lshl_add_u64 v[46:47], v[46:47], 1, s[18:19]
	v_lshl_add_u64 v[28:29], v[28:29], 1, s[18:19]
	v_cvt_pk_f16_f32 v11, v10, v11
	v_cvt_pk_f16_f32 v10, v8, v9
	v_cvt_pk_f16_f32 v8, v12, v13
	v_lshl_add_u64 v[12:13], v[32:33], 1, s[18:19]
	v_lshl_add_u64 v[128:129], v[128:129], 0, v[122:123]
	v_cvt_pk_f16_f32 v117, v116, v117
	v_cvt_pk_f16_f32 v116, v114, v115
	v_cvt_pk_f16_f32 v115, v120, v121
	v_cvt_pk_f16_f32 v114, v118, v119
	v_cvt_pk_f16_f32 v107, v112, v113
	v_lshl_add_u64 v[110:111], v[110:111], 0, v[122:123]
	v_cvt_pk_f16_f32 v101, v100, v101
	v_cvt_pk_f16_f32 v100, v98, v99
	v_cvt_pk_f16_f32 v99, v104, v105
	v_cvt_pk_f16_f32 v98, v102, v103
	v_cvt_pk_f16_f32 v91, v96, v97
	v_lshl_add_u64 v[94:95], v[94:95], 0, v[122:123]
	v_cvt_pk_f16_f32 v85, v84, v85
	v_cvt_pk_f16_f32 v84, v82, v83
	v_cvt_pk_f16_f32 v83, v88, v89
	v_cvt_pk_f16_f32 v82, v86, v87
	v_cvt_pk_f16_f32 v75, v80, v81
	v_lshl_add_u64 v[78:79], v[78:79], 0, v[122:123]
	v_cvt_pk_f16_f32 v69, v68, v69
	v_cvt_pk_f16_f32 v68, v66, v67
	v_cvt_pk_f16_f32 v67, v72, v73
	v_cvt_pk_f16_f32 v66, v70, v71
	v_cvt_pk_f16_f32 v59, v64, v65
	v_lshl_add_u64 v[62:63], v[62:63], 0, v[122:123]
	v_cvt_pk_f16_f32 v53, v52, v53
	v_cvt_pk_f16_f32 v52, v50, v51
	v_cvt_pk_f16_f32 v51, v56, v57
	v_cvt_pk_f16_f32 v50, v54, v55
	v_cvt_pk_f16_f32 v43, v48, v49
	v_lshl_add_u64 v[46:47], v[46:47], 0, v[122:123]
	v_cvt_pk_f16_f32 v37, v36, v37
	v_cvt_pk_f16_f32 v36, v34, v35
	v_cvt_pk_f16_f32 v35, v40, v41
	v_cvt_pk_f16_f32 v34, v38, v39
	v_cvt_pk_f16_f32 v25, v30, v31
	v_lshl_add_u64 v[28:29], v[28:29], 0, v[122:123]
	v_cvt_pk_f16_f32 v19, v18, v19
	v_cvt_pk_f16_f32 v18, v16, v17
	v_cvt_pk_f16_f32 v17, v22, v23
	v_cvt_pk_f16_f32 v16, v20, v21
	v_cvt_pk_f16_f32 v9, v14, v15
	v_lshl_add_u64 v[12:13], v[12:13], 0, v[122:123]
	v_cvt_pk_f16_f32 v3, v2, v3
	v_cvt_pk_f16_f32 v2, v0, v1
	v_cvt_pk_f16_f32 v1, v6, v7
	v_cvt_pk_f16_f32 v0, v4, v5
	global_store_dwordx4 v[128:129], v[124:127], off
	global_store_dwordx4 v[128:129], v[114:117], off offset:256
	global_store_dwordx4 v[110:111], v[106:109], off
	global_store_dwordx4 v[110:111], v[98:101], off offset:256
	global_store_dwordx4 v[94:95], v[90:93], off
	global_store_dwordx4 v[94:95], v[82:85], off offset:256
	global_store_dwordx4 v[78:79], v[74:77], off
	global_store_dwordx4 v[78:79], v[66:69], off offset:256
	global_store_dwordx4 v[62:63], v[58:61], off
	global_store_dwordx4 v[62:63], v[50:53], off offset:256
	global_store_dwordx4 v[46:47], v[42:45], off
	global_store_dwordx4 v[46:47], v[34:37], off offset:256
	global_store_dwordx4 v[28:29], v[24:27], off
	global_store_dwordx4 v[28:29], v[16:19], off offset:256
	global_store_dwordx4 v[12:13], v[8:11], off
	global_store_dwordx4 v[12:13], v[0:3], off offset:256
	s_andn2_b64 vcc, exec, s[4:5]
	s_mov_b64 s[4:5], -1
	s_cbranch_vccnz .LBB0_206

; __device__ __forceinline__ float shx(float v, int m, int lane) { return __int_as_float(__builtin_amdgcn_ds_bpermute((lane ^ m) << 2, __float_as_int(v))); }
; __device__ __forceinline__ float silu_f(float x) { return x * __builtin_amdgcn_rcpf(1.0f + fexp(-x)); }
; __device__ __forceinline__ void phase_dnprep(h16* Pdn, const h16* halo, const float* bd, const float* convw, const float* a_log, const float* dt_bias,
;                              h16* Tg, h16* qkg, float* gcg, float* betag, float* s2g, LAS unsigned char* ldsl, unsigned char* ldsb) {
;     ...
;             const int rr = lane >> 3, cp = lane & 7, i = 8 * w + rr;
;             h16* gp = Pdn + (tok0 + i) * 4096 + h * 128 + 16 * cp;
;             const float bt_i = bts[i];
; #pragma unroll
;             for (int seg = 0; seg < 3; ++seg) {
;                 float y[16];
; #pragma unroll
;                 for (int e = 0; e < 16; ++e) y[e] = 0.f;
; #pragma unroll
;                 for (int j = 0; j < 4; ++j) {
;                     const h16x8 x0 = *(const h16x8*)(raw + (i + j) * RP + seg * 128 + 16 * cp), x1 = *(const h16x8*)(raw + (i + j) * RP + seg * 128 + 16 * cp + 8);
;                     const f32x4* cwp = (const f32x4*)(cw + j * 384 + seg * 128 + 16 * cp);
;                     const f32x4 c0 = cwp[0], c1 = cwp[1], c2 = cwp[2], c3 = cwp[3];
; #pragma unroll
;                     for (int e = 0; e < 4; ++e) {
;                         y[e] += c0[e] * (float)x0[e]; y[4 + e] += c1[e] * (float)x0[4 + e];
;                         y[8 + e] += c2[e] * (float)x1[e]; y[12 + e] += c3[e] * (float)x1[4 + e];
;                     }
;                 }
; #pragma unroll
;                 for (int e = 0; e < 16; ++e) y[e] = silu_f(y[e]);
;                 float scl = bt_i;
;                 if (seg < 2) {
;                     float ss = 0.f;
; #pragma unroll
;                     for (int e = 0; e < 16; ++e) ss += y[e] * y[e];
;                     ss += shx(ss, 1, lane); ss += shx(ss, 2, lane); ss += shx(ss, 4, lane);
;                     scl = rsqrtf(ss + 1e-6f) * (seg == 0 ? 0.08838834764831845f : 1.0f);
.LBB0_354:
	s_nop 0
	v_readlane_b32 s60, v254, 43
	v_readlane_b32 s69, v254, 52
	v_lshrrev_b32_e32 v0, 3, v99
	s_mov_b32 s45, s69
	v_or_b32_e32 v2, s37, v0
	v_readlane_b32 s61, v254, 44
	v_readlane_b32 s62, v254, 45
	v_readlane_b32 s63, v254, 46
	v_readlane_b32 s64, v254, 47
	v_readlane_b32 s65, v254, 48
	v_readlane_b32 s66, v254, 49
	v_readlane_b32 s67, v254, 50
	v_readlane_b32 s68, v254, 51
	v_readlane_b32 s70, v254, 53
	v_readlane_b32 s71, v254, 54
	v_readlane_b32 s72, v254, 55
	v_readlane_b32 s73, v254, 56
	v_readlane_b32 s74, v254, 57
	v_readlane_b32 s75, v254, 58
	v_writelane_b32 v254, s36, 43
	s_lshl_b32 s0, s20, 12
	s_or_b32 s0, s0, s21
	v_writelane_b32 v254, s37, 44
	v_writelane_b32 v254, s38, 45
	v_writelane_b32 v254, s39, 46
	v_writelane_b32 v254, s40, 47
	v_writelane_b32 v254, s41, 48
	v_writelane_b32 v254, s42, 49
	v_writelane_b32 v254, s43, 50
	v_writelane_b32 v254, s44, 51
	v_writelane_b32 v254, s45, 52
	v_add_lshl_u32 v32, s0, v2, 12
	v_writelane_b32 v254, s46, 53
	v_lshlrev_b32_e32 v3, 4, v82
	v_lshl_add_u64 v[0:1], v[32:33], 1, s[86:87]
	s_mov_b32 s21, s69
	s_lshl_b32 s20, s3, 8
	v_writelane_b32 v254, s47, 54
	v_and_b32_e32 v3, 0x70, v3
	v_writelane_b32 v254, s48, 55
	v_lshl_add_u64 v[0:1], v[0:1], 0, s[20:21]
	v_lshlrev_b32_e32 v32, 1, v3
	v_writelane_b32 v254, s49, 56
	v_lshl_add_u64 v[86:87], v[0:1], 0, v[32:33]
	v_lshl_add_u32 v0, v2, 2, 0
	v_writelane_b32 v254, s50, 57
	v_add_u32_e32 v0, 0x27700, v0
	v_writelane_b32 v254, s51, 58
	ds_read_b32 v88, v0
	v_lshl_add_u32 v0, v3, 2, 0
	s_movk_i32 s0, 0x110
	v_add_u32_e32 v83, 0x25e00, v0
	v_mul_lo_u32 v0, v2, s0
	v_readlane_b32 s1, v254, 39
	v_readlane_b32 s0, v254, 38
	v_xor_b32_e32 v104, 4, v4
	v_add3_u32 v105, s1, v32, v0
	s_movk_i32 s1, 0x300
	v_add3_u32 v101, s0, v32, v0
	v_mul_lo_u32 v0, v2, s1
	v_add3_u32 v32, s78, v32, v0
	v_xor_b32_e32 v103, 8, v4
	v_xor_b32_e32 v102, 16, v4
	ds_read_b128 v[0:3], v32
	ds_read_b128 v[50:53], v32 offset:16
	ds_read_b128 v[38:41], v83
	ds_read_b128 v[8:11], v83 offset:16
	ds_read_b128 v[106:109], v83 offset:32
	ds_read_b128 v[58:61], v83 offset:48
	ds_read_b128 v[4:7], v32 offset:768
	ds_read_b128 v[54:57], v32 offset:784
	ds_read_b128 v[42:45], v83 offset:1536
	ds_read_b128 v[20:23], v83 offset:1552
	ds_read_b128 v[110:113], v83 offset:1568
	ds_read_b128 v[70:73], v83 offset:1584
	ds_read_b128 v[16:19], v32 offset:1536
	ds_read_b128 v[66:69], v32 offset:1552
	ds_read_b128 v[46:49], v83 offset:3072
	ds_read_b128 v[28:31], v83 offset:3088
	ds_read_b128 v[114:117], v83 offset:3104
	ds_read_b128 v[78:81], v83 offset:3120
	ds_read_b128 v[24:27], v32 offset:2304
	ds_read_b128 v[74:77], v32 offset:2320
	ds_read_b128 v[34:37], v83 offset:4608
	ds_read_b128 v[12:15], v83 offset:4624
	ds_read_b128 v[118:121], v83 offset:4640
	ds_read_b128 v[62:65], v83 offset:4656
	s_waitcnt lgkmcnt(0)
	v_cvt_f32_f16_e32 v90, v50
	v_cvt_f32_f16_sdwa v91, v50 dst_sel:DWORD dst_unused:UNUSED_PAD src0_sel:WORD_1
	v_cvt_f32_f16_e32 v92, v54
	v_cvt_f32_f16_sdwa v93, v54 dst_sel:DWORD dst_unused:UNUSED_PAD src0_sel:WORD_1
	v_cvt_f32_f16_e32 v54, v55
	v_pk_fma_f32 v[90:91], v[106:107], v[90:91], 0 op_sel_hi:[1,1,0]
	v_cvt_f32_f16_sdwa v55, v55 dst_sel:DWORD dst_unused:UNUSED_PAD src0_sel:WORD_1
	v_pk_fma_f32 v[90:91], v[110:111], v[92:93], v[90:91]
	v_cvt_f32_f16_e32 v92, v66
	v_cvt_f32_f16_sdwa v93, v66 dst_sel:DWORD dst_unused:UNUSED_PAD src0_sel:WORD_1
	v_cvt_f32_f16_e32 v66, v52
	s_mov_b32 s1, 0x800000
	v_and_b32_e32 v100, 15, v82
	v_pk_fma_f32 v[90:91], v[114:115], v[92:93], v[90:91]
	v_cvt_f32_f16_e32 v92, v74
	v_cvt_f32_f16_sdwa v93, v74 dst_sel:DWORD dst_unused:UNUSED_PAD src0_sel:WORD_1
	v_lshrrev_b32_e32 v84, 4, v99
	v_pk_fma_f32 v[90:91], v[118:119], v[92:93], v[90:91]
	s_nop 0
	v_mul_f32_e32 v50, 0xbfb8aa3b, v90
	v_exp_f32_e32 v50, v50
	s_nop 0
	v_add_f32_e32 v50, 1.0, v50
	v_rcp_f32_e32 v92, v50
	v_mul_f32_e32 v50, 0xbfb8aa3b, v91
	v_exp_f32_e32 v50, v50
	s_nop 0
	v_add_f32_e32 v50, 1.0, v50
	v_rcp_f32_e32 v93, v50
	v_cvt_f32_f16_e32 v50, v51
	v_cvt_f32_f16_sdwa v51, v51 dst_sel:DWORD dst_unused:UNUSED_PAD src0_sel:WORD_1
	v_pk_mul_f32 v[90:91], v[90:91], v[92:93]
	s_nop 0
	v_pk_mul_f32 v[92:93], v[90:91], v[90:91]
	v_pk_fma_f32 v[50:51], v[108:109], v[50:51], 0 op_sel_hi:[1,1,0]
	s_nop 0
	v_pk_fma_f32 v[50:51], v[112:113], v[54:55], v[50:51]
	v_cvt_f32_f16_e32 v54, v67
	v_cvt_f32_f16_sdwa v55, v67 dst_sel:DWORD dst_unused:UNUSED_PAD src0_sel:WORD_1
	v_cvt_f32_f16_sdwa v67, v52 dst_sel:DWORD dst_unused:UNUSED_PAD src0_sel:WORD_1
	v_pk_fma_f32 v[50:51], v[116:117], v[54:55], v[50:51]
	v_pk_fma_f32 v[58:59], v[58:59], v[66:67], 0 op_sel_hi:[1,1,0]
	v_cvt_f32_f16_e32 v66, v56
	v_cvt_f32_f16_sdwa v67, v56 dst_sel:DWORD dst_unused:UNUSED_PAD src0_sel:WORD_1
	v_cvt_f32_f16_e32 v56, v57
	v_cvt_f32_f16_sdwa v57, v57 dst_sel:DWORD dst_unused:UNUSED_PAD src0_sel:WORD_1
	v_cvt_f32_f16_e32 v54, v75
	v_pk_fma_f32 v[58:59], v[70:71], v[66:67], v[58:59]
	v_cvt_f32_f16_e32 v66, v68
	v_cvt_f32_f16_sdwa v67, v68 dst_sel:DWORD dst_unused:UNUSED_PAD src0_sel:WORD_1
	v_cvt_f32_f16_sdwa v55, v75 dst_sel:DWORD dst_unused:UNUSED_PAD src0_sel:WORD_1
	v_pk_fma_f32 v[58:59], v[78:79], v[66:67], v[58:59]
	v_cvt_f32_f16_e32 v66, v76
	v_cvt_f32_f16_sdwa v67, v76 dst_sel:DWORD dst_unused:UNUSED_PAD src0_sel:WORD_1
	v_pk_fma_f32 v[50:51], v[120:121], v[54:55], v[50:51]
	v_pk_fma_f32 v[58:59], v[62:63], v[66:67], v[58:59]
	s_nop 0
	v_mul_f32_e32 v52, 0xbfb8aa3b, v58
	v_exp_f32_e32 v52, v52
	v_mul_f32_e32 v54, 0xbfb8aa3b, v50
	v_mul_f32_e32 v55, 0xbfb8aa3b, v51
	v_exp_f32_e32 v54, v54
	v_add_f32_e32 v52, 1.0, v52
	v_rcp_f32_e32 v62, v52
	v_mul_f32_e32 v52, 0xbfb8aa3b, v59
; __device__ __forceinline__ float shx(float v, int m, int lane) { return __int_as_float(__builtin_amdgcn_ds_bpermute((lane ^ m) << 2, __float_as_int(v))); }
; __device__ __forceinline__ float silu_f(float x) { return x * __builtin_amdgcn_rcpf(1.0f + fexp(-x)); }
; __device__ __forceinline__ void phase_dnprep(h16* Pdn, const h16* halo, const float* bd, const float* convw, const float* a_log, const float* dt_bias,
;                              h16* Tg, h16* qkg, float* gcg, float* betag, float* s2g, LAS unsigned char* ldsl, unsigned char* ldsb) {
;     ...
;                 for (int j = 0; j < 4; ++j) {
;                     const h16x8 x0 = *(const h16x8*)(raw + (i + j) * RP + seg * 128 + 16 * cp), x1 = *(const h16x8*)(raw + (i + j) * RP + seg * 128 + 16 * cp + 8);
;                     const f32x4* cwp = (const f32x4*)(cw + j * 384 + seg * 128 + 16 * cp);
;                     const f32x4 c0 = cwp[0], c1 = cwp[1], c2 = cwp[2], c3 = cwp[3];
; #pragma unroll
;                     for (int e = 0; e < 4; ++e) {
;                         y[e] += c0[e] * (float)x0[e]; y[4 + e] += c1[e] * (float)x0[4 + e];
;                         y[8 + e] += c2[e] * (float)x1[e]; y[12 + e] += c3[e] * (float)x1[4 + e];
;                     }
;                 }
; #pragma unroll
;                 for (int e = 0; e < 16; ++e) y[e] = silu_f(y[e]);
;                 float scl = bt_i;
;                 if (seg < 2) {
;                     float ss = 0.f;
; #pragma unroll
;                     for (int e = 0; e < 16; ++e) ss += y[e] * y[e];
;                     ss += shx(ss, 1, lane); ss += shx(ss, 2, lane); ss += shx(ss, 4, lane);
;                     scl = rsqrtf(ss + 1e-6f) * (seg == 0 ? 0.08838834764831845f : 1.0f);
	v_exp_f32_e32 v52, v52
	v_exp_f32_e32 v55, v55
	v_add_f32_e32 v54, 1.0, v54
	v_rcp_f32_e32 v54, v54
	v_add_f32_e32 v52, 1.0, v52
	v_rcp_f32_e32 v63, v52
	v_cvt_f32_f16_e32 v52, v53
	v_cvt_f32_f16_sdwa v53, v53 dst_sel:DWORD dst_unused:UNUSED_PAD src0_sel:WORD_1
	v_add_f32_e32 v55, 1.0, v55
	v_rcp_f32_e32 v55, v55
	v_pk_mul_f32 v[58:59], v[58:59], v[62:63]
	v_pk_fma_f32 v[52:53], v[60:61], v[52:53], 0 op_sel_hi:[1,1,0]
	v_cvt_f32_f16_e32 v60, v0
	v_cvt_f32_f16_sdwa v61, v0 dst_sel:DWORD dst_unused:UNUSED_PAD src0_sel:WORD_1
	v_pk_fma_f32 v[52:53], v[72:73], v[56:57], v[52:53]
	v_cvt_f32_f16_e32 v56, v69
	v_cvt_f32_f16_sdwa v57, v69 dst_sel:DWORD dst_unused:UNUSED_PAD src0_sel:WORD_1
	v_pk_fma_f32 v[38:39], v[38:39], v[60:61], 0 op_sel_hi:[1,1,0]
	v_cvt_f32_f16_e32 v60, v4
	v_cvt_f32_f16_sdwa v61, v4 dst_sel:DWORD dst_unused:UNUSED_PAD src0_sel:WORD_1
	v_cvt_f32_f16_e32 v4, v5
	v_cvt_f32_f16_sdwa v5, v5 dst_sel:DWORD dst_unused:UNUSED_PAD src0_sel:WORD_1
	v_pk_fma_f32 v[52:53], v[80:81], v[56:57], v[52:53]
	v_pk_fma_f32 v[38:39], v[42:43], v[60:61], v[38:39]
	v_cvt_f32_f16_e32 v42, v16
	v_cvt_f32_f16_sdwa v43, v16 dst_sel:DWORD dst_unused:UNUSED_PAD src0_sel:WORD_1
	v_cvt_f32_f16_e32 v16, v2
	v_cvt_f32_f16_e32 v56, v77
	v_cvt_f32_f16_sdwa v57, v77 dst_sel:DWORD dst_unused:UNUSED_PAD src0_sel:WORD_1
	v_pk_fma_f32 v[38:39], v[46:47], v[42:43], v[38:39]
	v_cvt_f32_f16_e32 v42, v24
	v_cvt_f32_f16_sdwa v43, v24 dst_sel:DWORD dst_unused:UNUSED_PAD src0_sel:WORD_1
	v_pk_fma_f32 v[52:53], v[64:65], v[56:57], v[52:53]
	v_pk_mul_f32 v[50:51], v[50:51], v[54:55]
	v_mul_f32_e32 v56, 0xbfb8aa3b, v52
	v_pk_fma_f32 v[34:35], v[34:35], v[42:43], v[38:39]
	v_mul_f32_e32 v57, 0xbfb8aa3b, v53
	v_mul_f32_e32 v0, 0xbfb8aa3b, v34
	v_exp_f32_e32 v0, v0
	v_exp_f32_e32 v56, v56
	v_exp_f32_e32 v57, v57
	v_pk_mul_f32 v[54:55], v[50:51], v[50:51]
	v_add_f32_e32 v0, 1.0, v0
	v_rcp_f32_e32 v38, v0
	v_mul_f32_e32 v0, 0xbfb8aa3b, v35
	v_exp_f32_e32 v0, v0
	v_add_f32_e32 v56, 1.0, v56
	v_add_f32_e32 v57, 1.0, v57
	v_rcp_f32_e32 v56, v56
	v_add_f32_e32 v0, 1.0, v0
	v_rcp_f32_e32 v39, v0
	v_cvt_f32_f16_e32 v0, v1
	v_cvt_f32_f16_sdwa v1, v1 dst_sel:DWORD dst_unused:UNUSED_PAD src0_sel:WORD_1
	v_rcp_f32_e32 v57, v57
	v_pk_mul_f32 v[34:35], v[34:35], v[38:39]
	v_pk_mul_f32 v[62:63], v[58:59], v[58:59]
	v_pk_fma_f32 v[0:1], v[40:41], v[0:1], 0 op_sel_hi:[1,1,0]
	v_pk_mul_f32 v[38:39], v[34:35], v[34:35]
	v_pk_fma_f32 v[0:1], v[44:45], v[4:5], v[0:1]
	v_cvt_f32_f16_e32 v4, v17
	v_cvt_f32_f16_sdwa v5, v17 dst_sel:DWORD dst_unused:UNUSED_PAD src0_sel:WORD_1
	v_cvt_f32_f16_sdwa v17, v2 dst_sel:DWORD dst_unused:UNUSED_PAD src0_sel:WORD_1
	v_pk_mul_f32 v[52:53], v[52:53], v[56:57]
	v_pk_fma_f32 v[0:1], v[48:49], v[4:5], v[0:1]
	v_pk_fma_f32 v[8:9], v[8:9], v[16:17], 0 op_sel_hi:[1,1,0]
	v_cvt_f32_f16_e32 v16, v6
	v_cvt_f32_f16_sdwa v17, v6 dst_sel:DWORD dst_unused:UNUSED_PAD src0_sel:WORD_1
	v_cvt_f32_f16_e32 v6, v7
	v_cvt_f32_f16_sdwa v7, v7 dst_sel:DWORD dst_unused:UNUSED_PAD src0_sel:WORD_1
	v_cvt_f32_f16_e32 v4, v25
	v_pk_fma_f32 v[8:9], v[20:21], v[16:17], v[8:9]
	v_cvt_f32_f16_e32 v16, v18
	v_cvt_f32_f16_sdwa v17, v18 dst_sel:DWORD dst_unused:UNUSED_PAD src0_sel:WORD_1
	v_cvt_f32_f16_sdwa v5, v25 dst_sel:DWORD dst_unused:UNUSED_PAD src0_sel:WORD_1
	v_pk_mul_f32 v[56:57], v[52:53], v[52:53]
	v_pk_fma_f32 v[8:9], v[28:29], v[16:17], v[8:9]
	v_cvt_f32_f16_e32 v16, v26
	v_cvt_f32_f16_sdwa v17, v26 dst_sel:DWORD dst_unused:UNUSED_PAD src0_sel:WORD_1
	v_pk_fma_f32 v[0:1], v[36:37], v[4:5], v[0:1]
	v_pk_fma_f32 v[8:9], v[12:13], v[16:17], v[8:9]
	s_nop 0
	v_mul_f32_e32 v2, 0xbfb8aa3b, v8
	v_exp_f32_e32 v2, v2
	v_mul_f32_e32 v4, 0xbfb8aa3b, v0
	v_mul_f32_e32 v5, 0xbfb8aa3b, v1
	v_exp_f32_e32 v4, v4
	v_add_f32_e32 v2, 1.0, v2
	v_rcp_f32_e32 v12, v2
	v_mul_f32_e32 v2, 0xbfb8aa3b, v9
	v_exp_f32_e32 v2, v2
	v_exp_f32_e32 v5, v5
	v_add_f32_e32 v4, 1.0, v4
	v_rcp_f32_e32 v4, v4
	v_add_f32_e32 v2, 1.0, v2
	v_rcp_f32_e32 v13, v2
	v_cvt_f32_f16_e32 v2, v3
	v_cvt_f32_f16_sdwa v3, v3 dst_sel:DWORD dst_unused:UNUSED_PAD src0_sel:WORD_1
	v_add_f32_e32 v5, 1.0, v5
	v_rcp_f32_e32 v5, v5
	v_pk_mul_f32 v[8:9], v[8:9], v[12:13]
	v_pk_fma_f32 v[2:3], v[10:11], v[2:3], 0 op_sel_hi:[1,1,0]
	v_pk_mul_f32 v[12:13], v[8:9], v[8:9]
	v_pk_fma_f32 v[2:3], v[22:23], v[6:7], v[2:3]
	v_cvt_f32_f16_e32 v6, v19
	v_cvt_f32_f16_sdwa v7, v19 dst_sel:DWORD dst_unused:UNUSED_PAD src0_sel:WORD_1
	v_pk_mul_f32 v[0:1], v[0:1], v[4:5]
	v_pk_fma_f32 v[2:3], v[30:31], v[6:7], v[2:3]
	v_cvt_f32_f16_e32 v6, v27
	v_cvt_f32_f16_sdwa v7, v27 dst_sel:DWORD dst_unused:UNUSED_PAD src0_sel:WORD_1
	v_pk_mul_f32 v[4:5], v[0:1], v[0:1]
	v_pk_fma_f32 v[2:3], v[14:15], v[6:7], v[2:3]
	s_nop 0
	v_mul_f32_e32 v6, 0xbfb8aa3b, v2
	v_mul_f32_e32 v7, 0xbfb8aa3b, v3
	v_exp_f32_e32 v6, v6
	v_exp_f32_e32 v7, v7
	v_add_f32_e32 v6, 1.0, v6
	v_add_f32_e32 v7, 1.0, v7
	v_rcp_f32_e32 v6, v6
	v_rcp_f32_e32 v7, v7
	s_nop 0
	v_pk_mul_f32 v[10:11], v[2:3], v[6:7]
	v_add_f32_e32 v6, v38, v39
	v_add_f32_e32 v4, v4, v6
	v_add_f32_e32 v4, v5, v4
	v_add_f32_e32 v4, v12, v4
	v_pk_mul_f32 v[2:3], v[10:11], v[10:11]
	v_add_f32_e32 v4, v13, v4
	v_add_f32_e32 v2, v2, v4
	v_add_f32_e32 v2, v3, v2
	v_add_f32_e32 v2, v92, v2
	v_add_f32_e32 v2, v93, v2
	v_add_f32_e32 v2, v54, v2
	v_add_f32_e32 v2, v55, v2
	v_add_f32_e32 v2, v62, v2
	v_add_f32_e32 v2, v63, v2
	v_add_f32_e32 v2, v56, v2
	v_add_f32_e32 v2, v57, v2
	ds_bpermute_b32 v3, v104, v2
	s_waitcnt lgkmcnt(0)
	v_add_f32_e32 v2, v2, v3
	ds_bpermute_b32 v3, v103, v2
	s_waitcnt lgkmcnt(0)
	v_add_f32_e32 v2, v2, v3
	ds_bpermute_b32 v3, v102, v2
	s_waitcnt lgkmcnt(0)
; __device__ __forceinline__ float shx(float v, int m, int lane) { return __int_as_float(__builtin_amdgcn_ds_bpermute((lane ^ m) << 2, __float_as_int(v))); }
; __device__ __forceinline__ float silu_f(float x) { return x * __builtin_amdgcn_rcpf(1.0f + fexp(-x)); }
; __device__ __forceinline__ void phase_dnprep(h16* Pdn, const h16* halo, const float* bd, const float* convw, const float* a_log, const float* dt_bias,
;                              h16* Tg, h16* qkg, float* gcg, float* betag, float* s2g, LAS unsigned char* ldsl, unsigned char* ldsb) {
;     ...
;                 for (int e = 0; e < 16; ++e) y[e] = silu_f(y[e]);
;                 float scl = bt_i;
;                 if (seg < 2) {
;                     float ss = 0.f;
; #pragma unroll
;                     for (int e = 0; e < 16; ++e) ss += y[e] * y[e];
;                     ss += shx(ss, 1, lane); ss += shx(ss, 2, lane); ss += shx(ss, 4, lane);
;                     scl = rsqrtf(ss + 1e-6f) * (seg == 0 ? 0.08838834764831845f : 1.0f);
;                 }
;                 h16x8 o0, o1;
; #pragma unroll
;                 for (int e = 0; e < 8; ++e) { o0[e] = (h16)(y[e] * scl); o1[e] = (h16)(y[8 + e] * scl); }
;                 if (seg == 0) { *(h16x8*)(qn + i * 136 + 16 * cp) = o0; *(h16x8*)(qn + i * 136 + 16 * cp + 8) = o1; }
;                 if (seg == 1) { *(h16x8*)(kn + i * 136 + 16 * cp) = o0; *(h16x8*)(kn + i * 136 + 16 * cp + 8) = o1; }
;                 gst((h16x8*)(gp + seg * 1024), o0); gst((h16x8*)(gp + seg * 1024 + 8), o1);
	v_add_f32_e32 v2, v2, v3
	v_add_f32_e32 v2, 0x358637bd, v2
	v_cmp_gt_f32_e32 vcc, s1, v2
	v_mul_f32_e32 v3, 0x4b800000, v2
	s_nop 0
	v_cndmask_b32_e32 v2, v2, v3, vcc
	v_rsq_f32_e32 v2, v2
	s_nop 0
	v_mul_f32_e32 v3, 0x45800000, v2
	v_cndmask_b32_e32 v2, v2, v3, vcc
	v_mul_f32_e32 v12, 0x3db504f3, v2
	v_pk_mul_f32 v[2:3], v[34:35], v[12:13] op_sel_hi:[1,0]
	v_pk_mul_f32 v[0:1], v[0:1], v[12:13] op_sel_hi:[1,0]
	v_cvt_pk_f16_f32 v2, v2, v3
	v_cvt_pk_f16_f32 v3, v0, v1
	v_pk_mul_f32 v[0:1], v[50:51], v[12:13] op_sel_hi:[1,0]
	v_pk_mul_f32 v[4:5], v[90:91], v[12:13] op_sel_hi:[1,0]
	v_cvt_pk_f16_f32 v7, v0, v1
	v_pk_mul_f32 v[0:1], v[8:9], v[12:13] op_sel_hi:[1,0]
	v_cvt_pk_f16_f32 v6, v4, v5
	v_cvt_pk_f16_f32 v4, v0, v1
	v_pk_mul_f32 v[0:1], v[58:59], v[12:13] op_sel_hi:[1,0]
	s_nop 0
	v_cvt_pk_f16_f32 v8, v0, v1
	v_pk_mul_f32 v[0:1], v[10:11], v[12:13] op_sel_hi:[1,0]
	s_nop 0
	v_cvt_pk_f16_f32 v5, v0, v1
	v_pk_mul_f32 v[0:1], v[52:53], v[12:13] op_sel_hi:[1,0]
	s_nop 0
	v_cvt_pk_f16_f32 v9, v0, v1
	ds_write_b128 v105, v[2:5]
	ds_write_b128 v105, v[6:9] offset:16
	global_store_dwordx4 v[86:87], v[2:5], off
	global_store_dwordx4 v[86:87], v[6:9], off offset:16
	ds_read_b128 v[24:27], v32 offset:256
	ds_read_b128 v[74:77], v32 offset:272
	ds_read_b128 v[46:49], v83 offset:512
	ds_read_b128 v[28:31], v83 offset:528
	ds_read_b128 v[106:109], v83 offset:544
	ds_read_b128 v[78:81], v83 offset:560
	ds_read_b128 v[16:19], v32 offset:1024
	ds_read_b128 v[62:65], v32 offset:1040
	ds_read_b128 v[42:45], v83 offset:2048
	ds_read_b128 v[20:23], v83 offset:2064
	ds_read_b128 v[110:113], v83 offset:2080
	ds_read_b128 v[66:69], v83 offset:2096
	ds_read_b128 v[4:7], v32 offset:1792
	ds_read_b128 v[54:57], v32 offset:1808
	ds_read_b128 v[38:41], v83 offset:3584
	ds_read_b128 v[12:15], v83 offset:3600
	ds_read_b128 v[114:117], v83 offset:3616
	ds_read_b128 v[70:73], v83 offset:3632
	ds_read_b128 v[8:11], v32 offset:2560
	ds_read_b128 v[58:61], v32 offset:2576
	ds_read_b128 v[34:37], v83 offset:5120
	ds_read_b128 v[0:3], v83 offset:5136
	ds_read_b128 v[118:121], v83 offset:5152
	ds_read_b128 v[50:53], v83 offset:5168
	s_waitcnt lgkmcnt(0)
	v_cvt_f32_f16_e32 v90, v74
	v_cvt_f32_f16_sdwa v91, v74 dst_sel:DWORD dst_unused:UNUSED_PAD src0_sel:WORD_1
	v_cvt_f32_f16_e32 v92, v62
	v_cvt_f32_f16_sdwa v93, v62 dst_sel:DWORD dst_unused:UNUSED_PAD src0_sel:WORD_1
	v_cvt_f32_f16_e32 v74, v75
	v_pk_fma_f32 v[90:91], v[106:107], v[90:91], 0 op_sel_hi:[1,1,0]
	v_cvt_f32_f16_sdwa v75, v75 dst_sel:DWORD dst_unused:UNUSED_PAD src0_sel:WORD_1
	v_pk_fma_f32 v[90:91], v[110:111], v[92:93], v[90:91]
	v_cvt_f32_f16_e32 v92, v54
	v_cvt_f32_f16_sdwa v93, v54 dst_sel:DWORD dst_unused:UNUSED_PAD src0_sel:WORD_1
	v_cvt_f32_f16_e32 v62, v63
	v_cvt_f32_f16_sdwa v63, v63 dst_sel:DWORD dst_unused:UNUSED_PAD src0_sel:WORD_1
	v_pk_fma_f32 v[74:75], v[108:109], v[74:75], 0 op_sel_hi:[1,1,0]
	v_pk_fma_f32 v[90:91], v[114:115], v[92:93], v[90:91]
	v_cvt_f32_f16_e32 v92, v58
	v_cvt_f32_f16_sdwa v93, v58 dst_sel:DWORD dst_unused:UNUSED_PAD src0_sel:WORD_1
	v_pk_fma_f32 v[62:63], v[112:113], v[62:63], v[74:75]
	v_cvt_f32_f16_e32 v74, v64
	v_cvt_f32_f16_sdwa v75, v64 dst_sel:DWORD dst_unused:UNUSED_PAD src0_sel:WORD_1
	v_pk_fma_f32 v[90:91], v[118:119], v[92:93], v[90:91]
	v_cvt_f32_f16_e32 v64, v65
	v_mul_f32_e32 v54, 0xbfb8aa3b, v90
	v_exp_f32_e32 v54, v54
	v_cvt_f32_f16_sdwa v65, v65 dst_sel:DWORD dst_unused:UNUSED_PAD src0_sel:WORD_1
	v_cvt_f32_f16_e32 v58, v59
	v_cvt_f32_f16_sdwa v59, v59 dst_sel:DWORD dst_unused:UNUSED_PAD src0_sel:WORD_1
	v_add_f32_e32 v54, 1.0, v54
	v_rcp_f32_e32 v92, v54
	v_mul_f32_e32 v54, 0xbfb8aa3b, v91
	v_exp_f32_e32 v54, v54
	s_nop 0
	v_add_f32_e32 v54, 1.0, v54
	v_rcp_f32_e32 v93, v54
	v_cvt_f32_f16_e32 v54, v55
	v_cvt_f32_f16_sdwa v55, v55 dst_sel:DWORD dst_unused:UNUSED_PAD src0_sel:WORD_1
	v_pk_mul_f32 v[90:91], v[90:91], v[92:93]
	s_nop 0
	v_pk_mul_f32 v[92:93], v[90:91], v[90:91]
	v_pk_fma_f32 v[54:55], v[116:117], v[54:55], v[62:63]
	v_cvt_f32_f16_e32 v62, v76
	v_cvt_f32_f16_sdwa v63, v76 dst_sel:DWORD dst_unused:UNUSED_PAD src0_sel:WORD_1
	v_pk_fma_f32 v[54:55], v[120:121], v[58:59], v[54:55]
	v_pk_fma_f32 v[62:63], v[78:79], v[62:63], 0 op_sel_hi:[1,1,0]
	s_nop 0
	v_pk_fma_f32 v[62:63], v[66:67], v[74:75], v[62:63]
	v_cvt_f32_f16_e32 v66, v56
	v_cvt_f32_f16_sdwa v67, v56 dst_sel:DWORD dst_unused:UNUSED_PAD src0_sel:WORD_1
	v_mul_f32_e32 v58, 0xbfb8aa3b, v54
	v_mul_f32_e32 v59, 0xbfb8aa3b, v55
	v_exp_f32_e32 v58, v58
	v_pk_fma_f32 v[62:63], v[70:71], v[66:67], v[62:63]
	v_cvt_f32_f16_e32 v66, v60
	v_cvt_f32_f16_sdwa v67, v60 dst_sel:DWORD dst_unused:UNUSED_PAD src0_sel:WORD_1
	v_cvt_f32_f16_e32 v60, v61
	v_cvt_f32_f16_sdwa v61, v61 dst_sel:DWORD dst_unused:UNUSED_PAD src0_sel:WORD_1
	v_exp_f32_e32 v59, v59
	v_pk_fma_f32 v[50:51], v[50:51], v[66:67], v[62:63]
	v_cvt_f32_f16_e32 v66, v77
	v_mul_f32_e32 v56, 0xbfb8aa3b, v50
	v_exp_f32_e32 v56, v56
	v_cvt_f32_f16_sdwa v67, v77 dst_sel:DWORD dst_unused:UNUSED_PAD src0_sel:WORD_1
	v_add_f32_e32 v58, 1.0, v58
	v_add_f32_e32 v59, 1.0, v59
	v_add_f32_e32 v56, 1.0, v56
	v_rcp_f32_e32 v62, v56
	v_mul_f32_e32 v56, 0xbfb8aa3b, v51
	v_exp_f32_e32 v56, v56
	v_pk_fma_f32 v[66:67], v[80:81], v[66:67], 0 op_sel_hi:[1,1,0]
	v_rcp_f32_e32 v58, v58
	v_pk_fma_f32 v[64:65], v[68:69], v[64:65], v[66:67]
	v_add_f32_e32 v56, 1.0, v56
	v_rcp_f32_e32 v63, v56
	v_cvt_f32_f16_e32 v56, v57
	v_cvt_f32_f16_sdwa v57, v57 dst_sel:DWORD dst_unused:UNUSED_PAD src0_sel:WORD_1
	v_rcp_f32_e32 v59, v59
	v_pk_mul_f32 v[50:51], v[50:51], v[62:63]
	v_pk_fma_f32 v[56:57], v[72:73], v[56:57], v[64:65]
	s_nop 0
	v_pk_fma_f32 v[52:53], v[52:53], v[60:61], v[56:57]
; __device__ __forceinline__ float shx(float v, int m, int lane) { return __int_as_float(__builtin_amdgcn_ds_bpermute((lane ^ m) << 2, __float_as_int(v))); }
; __device__ __forceinline__ void phase_dnprep(h16* Pdn, const h16* halo, const float* bd, const float* convw, const float* a_log, const float* dt_bias,
;                              h16* Tg, h16* qkg, float* gcg, float* betag, float* s2g, LAS unsigned char* ldsl, unsigned char* ldsb) {
;     ...
;             for (int seg = 0; seg < 3; ++seg) {
;                 float y[16];
; #pragma unroll
;                 for (int e = 0; e < 16; ++e) y[e] = 0.f;
; #pragma unroll
;                 for (int j = 0; j < 4; ++j) {
;                     const h16x8 x0 = *(const h16x8*)(raw + (i + j) * RP + seg * 128 + 16 * cp), x1 = *(const h16x8*)(raw + (i + j) * RP + seg * 128 + 16 * cp + 8);
;                     const f32x4* cwp = (const f32x4*)(cw + j * 384 + seg * 128 + 16 * cp);
;                     const f32x4 c0 = cwp[0], c1 = cwp[1], c2 = cwp[2], c3 = cwp[3];
; #pragma unroll
;                     for (int e = 0; e < 4; ++e) {
;                         y[e] += c0[e] * (float)x0[e]; y[4 + e] += c1[e] * (float)x0[4 + e];
;                         y[8 + e] += c2[e] * (float)x1[e]; y[12 + e] += c3[e] * (float)x1[4 + e];
;                     }
;                 }
; #pragma unroll
;                 for (int e = 0; e < 16; ++e) y[e] = silu_f(y[e]);
;                 float scl = bt_i;
;                 if (seg < 2) {
;                     float ss = 0.f;
; #pragma unroll
;                     for (int e = 0; e < 16; ++e) ss += y[e] * y[e];
;                     ss += shx(ss, 1, lane); ss += shx(ss, 2, lane); ss += shx(ss, 4, lane);
;                     scl = rsqrtf(ss + 1e-6f) * (seg == 0 ? 0.08838834764831845f : 1.0f);
;                 }
;                 h16x8 o0, o1;
; #pragma unroll
;                 for (int e = 0; e < 8; ++e) { o0[e] = (h16)(y[e] * scl); o1[e] = (h16)(y[8 + e] * scl); }
;                 if (seg == 0) { *(h16x8*)(qn + i * 136 + 16 * cp) = o0; *(h16x8*)(qn + i * 136 + 16 * cp + 8) = o1; }
;                 if (seg == 1) { *(h16x8*)(kn + i * 136 + 16 * cp) = o0; *(h16x8*)(kn + i * 136 + 16 * cp + 8) = o1; }
;                 gst((h16x8*)(gp + seg * 1024), o0); gst((h16x8*)(gp + seg * 1024 + 8), o1);
	v_cvt_f32_f16_e32 v60, v24
	v_cvt_f32_f16_sdwa v61, v24 dst_sel:DWORD dst_unused:UNUSED_PAD src0_sel:WORD_1
	v_cvt_f32_f16_e32 v24, v25
	v_cvt_f32_f16_sdwa v25, v25 dst_sel:DWORD dst_unused:UNUSED_PAD src0_sel:WORD_1
	v_mul_f32_e32 v56, 0xbfb8aa3b, v52
	v_pk_fma_f32 v[46:47], v[46:47], v[60:61], 0 op_sel_hi:[1,1,0]
	v_cvt_f32_f16_e32 v60, v16
	v_cvt_f32_f16_sdwa v61, v16 dst_sel:DWORD dst_unused:UNUSED_PAD src0_sel:WORD_1
	v_cvt_f32_f16_e32 v16, v17
	v_cvt_f32_f16_sdwa v17, v17 dst_sel:DWORD dst_unused:UNUSED_PAD src0_sel:WORD_1
	v_pk_fma_f32 v[24:25], v[48:49], v[24:25], 0 op_sel_hi:[1,1,0]
	v_pk_fma_f32 v[42:43], v[42:43], v[60:61], v[46:47]
	v_cvt_f32_f16_e32 v46, v4
	v_cvt_f32_f16_sdwa v47, v4 dst_sel:DWORD dst_unused:UNUSED_PAD src0_sel:WORD_1
	v_pk_fma_f32 v[16:17], v[44:45], v[16:17], v[24:25]
	v_cvt_f32_f16_e32 v24, v18
	v_cvt_f32_f16_sdwa v25, v18 dst_sel:DWORD dst_unused:UNUSED_PAD src0_sel:WORD_1
	v_pk_fma_f32 v[38:39], v[38:39], v[46:47], v[42:43]
	v_cvt_f32_f16_e32 v42, v8
	v_cvt_f32_f16_sdwa v43, v8 dst_sel:DWORD dst_unused:UNUSED_PAD src0_sel:WORD_1
	v_cvt_f32_f16_e32 v18, v19
	v_cvt_f32_f16_sdwa v19, v19 dst_sel:DWORD dst_unused:UNUSED_PAD src0_sel:WORD_1
	v_cvt_f32_f16_e32 v8, v9
	v_pk_fma_f32 v[34:35], v[34:35], v[42:43], v[38:39]
	v_cvt_f32_f16_sdwa v9, v9 dst_sel:DWORD dst_unused:UNUSED_PAD src0_sel:WORD_1
	v_mul_f32_e32 v4, 0xbfb8aa3b, v34
	v_exp_f32_e32 v4, v4
	v_mul_f32_e32 v57, 0xbfb8aa3b, v53
	v_exp_f32_e32 v56, v56
	v_exp_f32_e32 v57, v57
	v_add_f32_e32 v4, 1.0, v4
	v_rcp_f32_e32 v38, v4
	v_mul_f32_e32 v4, 0xbfb8aa3b, v35
	v_exp_f32_e32 v4, v4
	v_add_f32_e32 v56, 1.0, v56
	v_add_f32_e32 v57, 1.0, v57
	v_pk_mul_f32 v[54:55], v[54:55], v[58:59]
	v_add_f32_e32 v4, 1.0, v4
	v_rcp_f32_e32 v39, v4
	v_cvt_f32_f16_e32 v4, v5
	v_cvt_f32_f16_sdwa v5, v5 dst_sel:DWORD dst_unused:UNUSED_PAD src0_sel:WORD_1
	v_rcp_f32_e32 v56, v56
	v_pk_mul_f32 v[34:35], v[34:35], v[38:39]
	v_rcp_f32_e32 v57, v57
	v_pk_fma_f32 v[4:5], v[40:41], v[4:5], v[16:17]
	v_cvt_f32_f16_e32 v16, v26
	v_cvt_f32_f16_sdwa v17, v26 dst_sel:DWORD dst_unused:UNUSED_PAD src0_sel:WORD_1
	v_pk_fma_f32 v[4:5], v[36:37], v[8:9], v[4:5]
	v_pk_mul_f32 v[38:39], v[34:35], v[34:35]
	v_mul_f32_e32 v8, 0xbfb8aa3b, v4
	v_pk_fma_f32 v[16:17], v[28:29], v[16:17], 0 op_sel_hi:[1,1,0]
	v_mul_f32_e32 v9, 0xbfb8aa3b, v5
	v_pk_fma_f32 v[16:17], v[20:21], v[24:25], v[16:17]
	v_cvt_f32_f16_e32 v20, v6
	v_cvt_f32_f16_sdwa v21, v6 dst_sel:DWORD dst_unused:UNUSED_PAD src0_sel:WORD_1
	v_exp_f32_e32 v8, v8
	v_exp_f32_e32 v9, v9
	v_pk_mul_f32 v[58:59], v[54:55], v[54:55]
	v_pk_fma_f32 v[12:13], v[12:13], v[20:21], v[16:17]
	v_cvt_f32_f16_e32 v16, v10
	v_cvt_f32_f16_sdwa v17, v10 dst_sel:DWORD dst_unused:UNUSED_PAD src0_sel:WORD_1
	v_cvt_f32_f16_e32 v10, v11
	v_cvt_f32_f16_sdwa v11, v11 dst_sel:DWORD dst_unused:UNUSED_PAD src0_sel:WORD_1
	v_add_f32_e32 v8, 1.0, v8
	v_pk_fma_f32 v[0:1], v[0:1], v[16:17], v[12:13]
	v_cvt_f32_f16_e32 v16, v27
	v_mul_f32_e32 v6, 0xbfb8aa3b, v0
	v_exp_f32_e32 v6, v6
	v_cvt_f32_f16_sdwa v17, v27 dst_sel:DWORD dst_unused:UNUSED_PAD src0_sel:WORD_1
	v_add_f32_e32 v9, 1.0, v9
	v_rcp_f32_e32 v8, v8
	v_add_f32_e32 v6, 1.0, v6
	v_rcp_f32_e32 v12, v6
	v_mul_f32_e32 v6, 0xbfb8aa3b, v1
	v_exp_f32_e32 v6, v6
	v_pk_fma_f32 v[16:17], v[30:31], v[16:17], 0 op_sel_hi:[1,1,0]
	v_rcp_f32_e32 v9, v9
	v_pk_fma_f32 v[16:17], v[22:23], v[18:19], v[16:17]
	v_add_f32_e32 v6, 1.0, v6
	v_rcp_f32_e32 v13, v6
	v_cvt_f32_f16_e32 v6, v7
	v_cvt_f32_f16_sdwa v7, v7 dst_sel:DWORD dst_unused:UNUSED_PAD src0_sel:WORD_1
	v_pk_mul_f32 v[4:5], v[4:5], v[8:9]
	v_pk_mul_f32 v[12:13], v[0:1], v[12:13]
	v_pk_mul_f32 v[8:9], v[4:5], v[4:5]
	v_pk_fma_f32 v[6:7], v[14:15], v[6:7], v[16:17]
	v_pk_mul_f32 v[0:1], v[12:13], v[12:13]
	v_pk_fma_f32 v[2:3], v[2:3], v[10:11], v[6:7]
	v_pk_mul_f32 v[62:63], v[50:51], v[50:51]
	v_mul_f32_e32 v6, 0xbfb8aa3b, v2
	v_mul_f32_e32 v7, 0xbfb8aa3b, v3
	v_exp_f32_e32 v6, v6
	v_exp_f32_e32 v7, v7
	v_pk_mul_f32 v[52:53], v[52:53], v[56:57]
	v_add_f32_e32 v6, 1.0, v6
	v_add_f32_e32 v7, 1.0, v7
	v_rcp_f32_e32 v6, v6
	v_rcp_f32_e32 v7, v7
	v_pk_mul_f32 v[56:57], v[52:53], v[52:53]
	v_pk_mul_f32 v[10:11], v[2:3], v[6:7]
	v_add_f32_e32 v6, v38, v39
	v_add_f32_e32 v6, v8, v6
	v_add_f32_e32 v6, v9, v6
	v_add_f32_e32 v0, v0, v6
	v_pk_mul_f32 v[2:3], v[10:11], v[10:11]
	v_add_f32_e32 v0, v1, v0
	v_add_f32_e32 v0, v2, v0
	v_add_f32_e32 v0, v3, v0
	v_add_f32_e32 v0, v92, v0
	v_add_f32_e32 v0, v93, v0
	v_add_f32_e32 v0, v58, v0
	v_add_f32_e32 v0, v59, v0
	v_add_f32_e32 v0, v62, v0
	v_add_f32_e32 v0, v63, v0
	v_add_f32_e32 v0, v56, v0
	v_add_f32_e32 v0, v57, v0
	ds_bpermute_b32 v1, v104, v0
	s_waitcnt lgkmcnt(0)
	v_add_f32_e32 v0, v0, v1
	ds_bpermute_b32 v1, v103, v0
	s_waitcnt lgkmcnt(0)
	v_add_f32_e32 v0, v0, v1
	ds_bpermute_b32 v1, v102, v0
	s_waitcnt lgkmcnt(0)
	v_add_f32_e32 v0, v0, v1
	v_add_f32_e32 v0, 0x358637bd, v0
	v_cmp_gt_f32_e32 vcc, s1, v0
	v_mul_f32_e32 v1, 0x4b800000, v0
	s_movk_i32 s1, 0x1000
	v_cndmask_b32_e32 v0, v0, v1, vcc
	v_rsq_f32_e32 v0, v0
	s_nop 0
	v_mul_f32_e32 v1, 0x45800000, v0
	v_cndmask_b32_e32 v14, v0, v1, vcc
	v_pk_mul_f32 v[2:3], v[90:91], v[14:15] op_sel_hi:[1,0]
	v_pk_mul_f32 v[0:1], v[34:35], v[14:15] op_sel_hi:[1,0]
	v_cvt_pk_f16_f32 v6, v2, v3
	v_pk_mul_f32 v[2:3], v[4:5], v[14:15] op_sel_hi:[1,0]
	v_cvt_pk_f16_f32 v0, v0, v1
	v_cvt_pk_f16_f32 v1, v2, v3
	v_pk_mul_f32 v[2:3], v[54:55], v[14:15] op_sel_hi:[1,0]
	v_pk_mul_f32 v[4:5], v[50:51], v[14:15] op_sel_hi:[1,0]
	v_cvt_pk_f16_f32 v7, v2, v3
	v_pk_mul_f32 v[2:3], v[12:13], v[14:15] op_sel_hi:[1,0]
	v_cvt_pk_f16_f32 v8, v4, v5
	v_pk_mul_f32 v[4:5], v[10:11], v[14:15] op_sel_hi:[1,0]
	v_cvt_pk_f16_f32 v2, v2, v3
	v_cvt_pk_f16_f32 v3, v4, v5
	v_pk_mul_f32 v[4:5], v[52:53], v[14:15] op_sel_hi:[1,0]
	s_nop 0
	v_cvt_pk_f16_f32 v9, v4, v5
	ds_write_b128 v101, v[0:3]
	ds_write_b128 v101, v[6:9] offset:16
	global_store_dwordx4 v[86:87], v[0:3], off offset:2048
	global_store_dwordx4 v[86:87], v[6:9], off offset:2064
	ds_read_b128 v[0:3], v83 offset:5664
	ds_read_b128 v[12:15], v32 offset:2832
	ds_read_b128 v[16:19], v83 offset:4128
	ds_read_b128 v[24:27], v32 offset:2064
	ds_read_b128 v[28:31], v83 offset:2592
	ds_read_b128 v[34:37], v32 offset:1296
	ds_read_b128 v[20:23], v83 offset:1024
	ds_read_b128 v[4:7], v83 offset:1040
	ds_read_b128 v[38:41], v83 offset:1056
	ds_read_b128 v[42:45], v83 offset:1072
	ds_read_b128 v[8:11], v32 offset:512
	ds_read_b128 v[46:49], v32 offset:528
	s_waitcnt lgkmcnt(0)
; __device__ __forceinline__ float shx(float v, int m, int lane) { return __int_as_float(__builtin_amdgcn_ds_bpermute((lane ^ m) << 2, __float_as_int(v))); }
; __device__ __forceinline__ float silu_f(float x) { return x * __builtin_amdgcn_rcpf(1.0f + fexp(-x)); }
; __device__ __forceinline__ void phase_dnprep(h16* Pdn, const h16* halo, const float* bd, const float* convw, const float* a_log, const float* dt_bias,
;                              h16* Tg, h16* qkg, float* gcg, float* betag, float* s2g, LAS unsigned char* ldsl, unsigned char* ldsb) {
;     ...
;                 for (int j = 0; j < 4; ++j) {
;                     const h16x8 x0 = *(const h16x8*)(raw + (i + j) * RP + seg * 128 + 16 * cp), x1 = *(const h16x8*)(raw + (i + j) * RP + seg * 128 + 16 * cp + 8);
;                     const f32x4* cwp = (const f32x4*)(cw + j * 384 + seg * 128 + 16 * cp);
;                     const f32x4 c0 = cwp[0], c1 = cwp[1], c2 = cwp[2], c3 = cwp[3];
; #pragma unroll
;                     for (int e = 0; e < 4; ++e) {
;                         y[e] += c0[e] * (float)x0[e]; y[4 + e] += c1[e] * (float)x0[4 + e];
;                         y[8 + e] += c2[e] * (float)x1[e]; y[12 + e] += c3[e] * (float)x1[4 + e];
;                     }
;                 }
; #pragma unroll
;                 for (int e = 0; e < 16; ++e) y[e] = silu_f(y[e]);
;                 float scl = bt_i;
;                 if (seg < 2) {
;                     float ss = 0.f;
; #pragma unroll
;                     for (int e = 0; e < 16; ++e) ss += y[e] * y[e];
;                     ss += shx(ss, 1, lane); ss += shx(ss, 2, lane); ss += shx(ss, 4, lane);
;                     scl = rsqrtf(ss + 1e-6f) * (seg == 0 ? 0.08838834764831845f : 1.0f);
;                 }
;                 h16x8 o0, o1;
; #pragma unroll
;                 for (int e = 0; e < 8; ++e) { o0[e] = (h16)(y[e] * scl); o1[e] = (h16)(y[8 + e] * scl); }
;                 if (seg == 0) { *(h16x8*)(qn + i * 136 + 16 * cp) = o0; *(h16x8*)(qn + i * 136 + 16 * cp + 8) = o1; }
;                 if (seg == 1) { *(h16x8*)(kn + i * 136 + 16 * cp) = o0; *(h16x8*)(kn + i * 136 + 16 * cp + 8) = o1; }
;                 gst((h16x8*)(gp + seg * 1024), o0); gst((h16x8*)(gp + seg * 1024 + 8), o1);
	v_cvt_f32_f16_e32 v54, v34
	v_cvt_f32_f16_sdwa v55, v34 dst_sel:DWORD dst_unused:UNUSED_PAD src0_sel:WORD_1
	v_cvt_f32_f16_e32 v52, v24
	v_cvt_f32_f16_sdwa v53, v24 dst_sel:DWORD dst_unused:UNUSED_PAD src0_sel:WORD_1
	v_cvt_f32_f16_e32 v56, v46
	v_cvt_f32_f16_sdwa v57, v46 dst_sel:DWORD dst_unused:UNUSED_PAD src0_sel:WORD_1
	v_cvt_f32_f16_e32 v50, v12
	v_cvt_f32_f16_sdwa v51, v12 dst_sel:DWORD dst_unused:UNUSED_PAD src0_sel:WORD_1
	v_cvt_f32_f16_e32 v24, v35
	v_pk_fma_f32 v[38:39], v[38:39], v[56:57], 0 op_sel_hi:[1,1,0]
	v_cvt_f32_f16_e32 v34, v48
	v_pk_fma_f32 v[28:29], v[28:29], v[54:55], v[38:39]
	s_nop 0
	v_pk_fma_f32 v[16:17], v[16:17], v[52:53], v[28:29]
	v_cvt_f32_f16_e32 v28, v47
	v_pk_fma_f32 v[0:1], v[0:1], v[50:51], v[16:17]
	v_cvt_f32_f16_sdwa v29, v47 dst_sel:DWORD dst_unused:UNUSED_PAD src0_sel:WORD_1
	v_mul_f32_e32 v12, 0xbfb8aa3b, v0
	v_exp_f32_e32 v12, v12
	v_pk_fma_f32 v[28:29], v[40:41], v[28:29], 0 op_sel_hi:[1,1,0]
	v_add_f32_e32 v12, 1.0, v12
	v_rcp_f32_e32 v16, v12
	v_mul_f32_e32 v12, 0xbfb8aa3b, v1
	v_exp_f32_e32 v12, v12
	s_nop 0
	v_add_f32_e32 v12, 1.0, v12
	v_rcp_f32_e32 v17, v12
	v_cvt_f32_f16_e32 v12, v13
	v_cvt_f32_f16_sdwa v13, v13 dst_sel:DWORD dst_unused:UNUSED_PAD src0_sel:WORD_1
	v_pk_mul_f32 v[0:1], v[0:1], v[16:17]
	v_cvt_f32_f16_e32 v16, v25
	v_cvt_f32_f16_sdwa v17, v25 dst_sel:DWORD dst_unused:UNUSED_PAD src0_sel:WORD_1
	v_cvt_f32_f16_sdwa v25, v35 dst_sel:DWORD dst_unused:UNUSED_PAD src0_sel:WORD_1
	s_nop 0
	v_pk_mul_f32 v[0:1], v[88:89], v[0:1] op_sel_hi:[0,1]
	v_cvt_pk_f16_f32 v0, v0, v1
	v_cvt_f32_f16_sdwa v35, v48 dst_sel:DWORD dst_unused:UNUSED_PAD src0_sel:WORD_1
	v_pk_fma_f32 v[24:25], v[30:31], v[24:25], v[28:29]
	v_pk_fma_f32 v[34:35], v[42:43], v[34:35], 0 op_sel_hi:[1,1,0]
	v_pk_fma_f32 v[16:17], v[18:19], v[16:17], v[24:25]
	v_cvt_f32_f16_e32 v24, v36
	v_pk_fma_f32 v[2:3], v[2:3], v[12:13], v[16:17]
	ds_read_b128 v[16:19], v83 offset:5680
	ds_read_b128 v[28:31], v83 offset:4144
	ds_read_b128 v[38:41], v83 offset:2608
	v_mul_f32_e32 v1, 0xbfb8aa3b, v2
	v_exp_f32_e32 v1, v1
	v_cvt_f32_f16_sdwa v25, v36 dst_sel:DWORD dst_unused:UNUSED_PAD src0_sel:WORD_1
	v_cvt_f32_f16_e32 v42, v8
	v_cvt_f32_f16_sdwa v43, v8 dst_sel:DWORD dst_unused:UNUSED_PAD src0_sel:WORD_1
	v_add_f32_e32 v1, 1.0, v1
	v_rcp_f32_e32 v12, v1
	v_mul_f32_e32 v1, 0xbfb8aa3b, v3
	v_exp_f32_e32 v1, v1
	s_waitcnt lgkmcnt(0)
	v_pk_fma_f32 v[24:25], v[38:39], v[24:25], v[34:35]
	v_pk_fma_f32 v[20:21], v[20:21], v[42:43], 0 op_sel_hi:[1,1,0]
	v_add_f32_e32 v1, 1.0, v1
	v_rcp_f32_e32 v13, v1
	s_nop 0
	v_pk_mul_f32 v[2:3], v[2:3], v[12:13]
	s_nop 0
	v_pk_mul_f32 v[2:3], v[88:89], v[2:3] op_sel_hi:[0,1]
	v_cvt_f32_f16_e32 v12, v26
	v_cvt_f32_f16_sdwa v13, v26 dst_sel:DWORD dst_unused:UNUSED_PAD src0_sel:WORD_1
	v_cvt_pk_f16_f32 v1, v2, v3
	v_cvt_f32_f16_e32 v2, v14
	v_cvt_f32_f16_sdwa v3, v14 dst_sel:DWORD dst_unused:UNUSED_PAD src0_sel:WORD_1
	v_pk_fma_f32 v[12:13], v[28:29], v[12:13], v[24:25]
	v_cvt_f32_f16_e32 v24, v49
	v_cvt_f32_f16_sdwa v25, v49 dst_sel:DWORD dst_unused:UNUSED_PAD src0_sel:WORD_1
	v_pk_fma_f32 v[2:3], v[16:17], v[2:3], v[12:13]
	v_cvt_f32_f16_e32 v16, v37
	v_mul_f32_e32 v12, 0xbfb8aa3b, v2
	v_mul_f32_e32 v13, 0xbfb8aa3b, v3
	v_exp_f32_e32 v12, v12
	v_exp_f32_e32 v13, v13
	v_cvt_f32_f16_sdwa v17, v37 dst_sel:DWORD dst_unused:UNUSED_PAD src0_sel:WORD_1
	v_cvt_f32_f16_e32 v14, v27
	v_add_f32_e32 v12, 1.0, v12
	v_add_f32_e32 v13, 1.0, v13
	v_rcp_f32_e32 v12, v12
	v_rcp_f32_e32 v13, v13
	v_pk_fma_f32 v[24:25], v[44:45], v[24:25], 0 op_sel_hi:[1,1,0]
	v_pk_mul_f32 v[2:3], v[2:3], v[12:13]
	v_cvt_f32_f16_e32 v12, v15
	v_cvt_f32_f16_sdwa v13, v15 dst_sel:DWORD dst_unused:UNUSED_PAD src0_sel:WORD_1
	v_cvt_f32_f16_sdwa v15, v27 dst_sel:DWORD dst_unused:UNUSED_PAD src0_sel:WORD_1
	v_pk_fma_f32 v[16:17], v[40:41], v[16:17], v[24:25]
	v_pk_mul_f32 v[2:3], v[88:89], v[2:3] op_sel_hi:[0,1]
	v_cvt_pk_f16_f32 v2, v2, v3
	v_pk_fma_f32 v[14:15], v[30:31], v[14:15], v[16:17]
	s_nop 0
	v_pk_fma_f32 v[12:13], v[18:19], v[12:13], v[14:15]
	s_nop 0
	v_mul_f32_e32 v3, 0xbfb8aa3b, v12
	v_exp_f32_e32 v3, v3
	s_nop 0
	v_add_f32_e32 v3, 1.0, v3
	v_rcp_f32_e32 v14, v3
	v_mul_f32_e32 v3, 0xbfb8aa3b, v13
	v_exp_f32_e32 v3, v3
	s_nop 0
	v_add_f32_e32 v3, 1.0, v3
	v_rcp_f32_e32 v15, v3
	s_nop 0
	v_pk_mul_f32 v[12:13], v[12:13], v[14:15]
	s_nop 0
	v_pk_mul_f32 v[12:13], v[88:89], v[12:13] op_sel_hi:[0,1]
	v_cvt_pk_f16_f32 v3, v12, v13
	ds_read_b128 v[38:41], v83 offset:2560
	ds_read_b128 v[12:15], v32 offset:1280
	ds_read_b128 v[34:37], v83 offset:4096
	ds_read_b128 v[16:19], v32 offset:2048
	ds_read_b128 v[28:31], v83 offset:5632
	ds_read_b128 v[24:27], v32 offset:2816
	s_waitcnt lgkmcnt(4)
	v_cvt_f32_f16_e32 v42, v12
	v_cvt_f32_f16_sdwa v43, v12 dst_sel:DWORD dst_unused:UNUSED_PAD src0_sel:WORD_1
	v_cvt_f32_f16_e32 v12, v13
	v_cvt_f32_f16_sdwa v13, v13 dst_sel:DWORD dst_unused:UNUSED_PAD src0_sel:WORD_1
	v_pk_fma_f32 v[20:21], v[38:39], v[42:43], v[20:21]
	s_waitcnt lgkmcnt(2)
; #define LDS_BARRIER() do { asm volatile("s_waitcnt lgkmcnt(0)" ::: "memory"); __builtin_amdgcn_s_barrier(); asm volatile("" ::: "memory"); } while (0)
; #define MFMA16(a, b, c) __builtin_amdgcn_mfma_f32_16x16x32_f16((a), (b), (c), 0, 0, 0)
; __device__ __forceinline__ void phase_dnprep(h16* Pdn, const h16* halo, const float* bd, const float* convw, const float* a_log, const float* dt_bias,
;                              h16* Tg, h16* qkg, float* gcg, float* betag, float* s2g, LAS unsigned char* ldsl, unsigned char* ldsb) {
;     ...
;                 h16x8 o0, o1;
; #pragma unroll
;                 for (int e = 0; e < 8; ++e) { o0[e] = (h16)(y[e] * scl); o1[e] = (h16)(y[8 + e] * scl); }
;                 if (seg == 0) { *(h16x8*)(qn + i * 136 + 16 * cp) = o0; *(h16x8*)(qn + i * 136 + 16 * cp + 8) = o1; }
;                 if (seg == 1) { *(h16x8*)(kn + i * 136 + 16 * cp) = o0; *(h16x8*)(kn + i * 136 + 16 * cp + 8) = o1; }
;                 gst((h16x8*)(gp + seg * 1024), o0); gst((h16x8*)(gp + seg * 1024 + 8), o1);
;             }
;         }
;         LDS_BARRIER();
; #pragma unroll
;         for (int idx0 = 0; idx0 < 4; ++idx0) {
;             const int idx = w + 8 * idx0;
;             const int isqk = idx >> 4, ti = (idx >> 2) & 3, tj = idx & 3;
;             f32x4 acc = {0.f, 0.f, 0.f, 0.f};
;             if (tj <= ti) {
;                 const h16* As = isqk ? qn : kn;
; #pragma unroll
;                 for (int kk = 0; kk < 4; ++kk) {
;                     const h16x8 a = *(const h16x8*)(As + (16 * ti + fr) * 136 + 32 * kk + 8 * g);
;                     const h16x8 bb = *(const h16x8*)(kn + (16 * tj + fr) * 136 + 32 * kk + 8 * g);
;                     acc = MFMA16(a, bb, acc);
	v_cvt_f32_f16_e32 v38, v16
	v_cvt_f32_f16_sdwa v39, v16 dst_sel:DWORD dst_unused:UNUSED_PAD src0_sel:WORD_1
	v_cvt_f32_f16_e32 v16, v17
	v_cvt_f32_f16_sdwa v17, v17 dst_sel:DWORD dst_unused:UNUSED_PAD src0_sel:WORD_1
	v_pk_fma_f32 v[20:21], v[34:35], v[38:39], v[20:21]
	s_waitcnt lgkmcnt(0)
	v_cvt_f32_f16_e32 v34, v24
	v_cvt_f32_f16_sdwa v35, v24 dst_sel:DWORD dst_unused:UNUSED_PAD src0_sel:WORD_1
	v_cvt_f32_f16_e32 v38, v10
	v_cvt_f32_f16_sdwa v39, v10 dst_sel:DWORD dst_unused:UNUSED_PAD src0_sel:WORD_1
	v_cvt_f32_f16_e32 v24, v14
	v_pk_fma_f32 v[20:21], v[28:29], v[34:35], v[20:21]
	v_pk_fma_f32 v[4:5], v[4:5], v[38:39], 0 op_sel_hi:[1,1,0]
	v_mul_f32_e32 v8, 0xbfb8aa3b, v20
	v_exp_f32_e32 v8, v8
	s_nop 0
	v_add_f32_e32 v8, 1.0, v8
	v_rcp_f32_e32 v28, v8
	v_mul_f32_e32 v8, 0xbfb8aa3b, v21
	v_exp_f32_e32 v8, v8
	s_nop 0
	v_add_f32_e32 v8, 1.0, v8
	v_rcp_f32_e32 v29, v8
	s_nop 0
	v_pk_mul_f32 v[20:21], v[20:21], v[28:29]
	s_nop 0
	v_pk_mul_f32 v[20:21], v[88:89], v[20:21] op_sel_hi:[0,1]
	v_cvt_pk_f16_f32 v8, v20, v21
	v_cvt_f32_f16_e32 v20, v9
	v_cvt_f32_f16_sdwa v21, v9 dst_sel:DWORD dst_unused:UNUSED_PAD src0_sel:WORD_1
	v_pk_fma_f32 v[20:21], v[22:23], v[20:21], 0 op_sel_hi:[1,1,0]
	s_nop 0
	v_pk_fma_f32 v[12:13], v[40:41], v[12:13], v[20:21]
	s_nop 0
	v_pk_fma_f32 v[12:13], v[36:37], v[16:17], v[12:13]
	v_cvt_f32_f16_e32 v16, v25
	v_cvt_f32_f16_sdwa v17, v25 dst_sel:DWORD dst_unused:UNUSED_PAD src0_sel:WORD_1
	v_cvt_f32_f16_sdwa v25, v14 dst_sel:DWORD dst_unused:UNUSED_PAD src0_sel:WORD_1
	v_cvt_f32_f16_e32 v14, v15
	v_cvt_f32_f16_sdwa v15, v15 dst_sel:DWORD dst_unused:UNUSED_PAD src0_sel:WORD_1
	v_pk_fma_f32 v[12:13], v[30:31], v[16:17], v[12:13]
	ds_read_b128 v[20:23], v83 offset:5648
	ds_read_b128 v[28:31], v83 offset:4112
	ds_read_b128 v[34:37], v83 offset:2576
	v_mul_f32_e32 v9, 0xbfb8aa3b, v12
	v_exp_f32_e32 v9, v9
	s_waitcnt lgkmcnt(0)
	v_pk_fma_f32 v[4:5], v[34:35], v[24:25], v[4:5]
	v_add_f32_e32 v9, 1.0, v9
	v_rcp_f32_e32 v16, v9
	v_mul_f32_e32 v9, 0xbfb8aa3b, v13
	v_exp_f32_e32 v9, v9
	s_nop 0
	v_add_f32_e32 v9, 1.0, v9
	v_rcp_f32_e32 v17, v9
	s_nop 0
	v_pk_mul_f32 v[12:13], v[12:13], v[16:17]
	s_nop 0
	v_pk_mul_f32 v[12:13], v[88:89], v[12:13] op_sel_hi:[0,1]
	v_cvt_f32_f16_e32 v16, v18
	v_cvt_f32_f16_sdwa v17, v18 dst_sel:DWORD dst_unused:UNUSED_PAD src0_sel:WORD_1
	v_cvt_pk_f16_f32 v9, v12, v13
	v_cvt_f32_f16_e32 v12, v26
	v_cvt_f32_f16_sdwa v13, v26 dst_sel:DWORD dst_unused:UNUSED_PAD src0_sel:WORD_1
	v_pk_fma_f32 v[4:5], v[28:29], v[16:17], v[4:5]
	v_cvt_f32_f16_e32 v16, v11
	v_cvt_f32_f16_sdwa v17, v11 dst_sel:DWORD dst_unused:UNUSED_PAD src0_sel:WORD_1
	v_pk_fma_f32 v[4:5], v[20:21], v[12:13], v[4:5]
	v_pk_fma_f32 v[6:7], v[6:7], v[16:17], 0 op_sel_hi:[1,1,0]
	v_mul_f32_e32 v10, 0xbfb8aa3b, v4
	v_exp_f32_e32 v10, v10
	v_pk_fma_f32 v[6:7], v[36:37], v[14:15], v[6:7]
	v_add_f32_e32 v10, 1.0, v10
	v_rcp_f32_e32 v12, v10
	v_mul_f32_e32 v10, 0xbfb8aa3b, v5
	v_exp_f32_e32 v10, v10
	s_nop 0
	v_add_f32_e32 v10, 1.0, v10
	v_rcp_f32_e32 v13, v10
	s_nop 0
	v_pk_mul_f32 v[4:5], v[4:5], v[12:13]
	s_nop 0
	v_pk_mul_f32 v[4:5], v[88:89], v[4:5] op_sel_hi:[0,1]
	v_cvt_f32_f16_e32 v12, v19
	v_cvt_f32_f16_sdwa v13, v19 dst_sel:DWORD dst_unused:UNUSED_PAD src0_sel:WORD_1
	v_cvt_pk_f16_f32 v10, v4, v5
	v_cvt_f32_f16_e32 v4, v27
	v_cvt_f32_f16_sdwa v5, v27 dst_sel:DWORD dst_unused:UNUSED_PAD src0_sel:WORD_1
	v_pk_fma_f32 v[6:7], v[30:31], v[12:13], v[6:7]
	s_nop 0
	v_pk_fma_f32 v[4:5], v[22:23], v[4:5], v[6:7]
	s_nop 0
	v_mul_f32_e32 v6, 0xbfb8aa3b, v4
	v_mul_f32_e32 v7, 0xbfb8aa3b, v5
	v_exp_f32_e32 v6, v6
	v_exp_f32_e32 v7, v7
	v_or_b32_e32 v22, s76, v100
	v_add_f32_e32 v6, 1.0, v6
	v_add_f32_e32 v7, 1.0, v7
	v_rcp_f32_e32 v6, v6
	v_rcp_f32_e32 v7, v7
	s_nop 0
	v_pk_mul_f32 v[4:5], v[4:5], v[6:7]
	s_nop 0
	v_pk_mul_f32 v[4:5], v[88:89], v[4:5] op_sel_hi:[0,1]
	v_cvt_pk_f16_f32 v11, v4, v5
	v_add_co_u32_e32 v4, vcc, s1, v86
	s_nop 1
	v_addc_co_u32_e32 v5, vcc, 0, v87, vcc
	global_store_dwordx4 v[4:5], v[8:11], off
	global_store_dwordx4 v[4:5], v[0:3], off offset:16
	s_waitcnt lgkmcnt(0)
	s_barrier
	s_and_b64 vcc, exec, s[28:29]
	v_mul_u32_u24_e32 v0, 0x110, v22
	v_and_b32_e32 v2, 48, v99
	v_lshlrev_b32_e32 v1, 3, v84
	v_add3_u32 v23, s0, v0, v2
	v_or_b32_e32 v2, s95, v100
	v_mov_b32_e32 v0, 0
	v_lshlrev_b32_e32 v24, 1, v1
	v_mul_u32_u24_e32 v25, 0x110, v2
	v_mov_b32_e32 v1, 0
	v_mov_b32_e32 v2, 0
	v_mov_b32_e32 v3, 0
	s_cbranch_vccz .LBB0_356
	v_add3_u32 v12, s94, v25, v24
	ds_read_b128 v[0:3], v12
	ds_read_b128 v[4:7], v23
	s_waitcnt lgkmcnt(0)
	v_mfma_f32_16x16x32_f16 v[0:3], v[0:3], v[4:7], 0
	ds_read_b128 v[4:7], v12 offset:64
	ds_read_b128 v[8:11], v23 offset:64
	s_waitcnt lgkmcnt(0)
	v_mfma_f32_16x16x32_f16 v[0:3], v[4:7], v[8:11], v[0:3]
	ds_read_b128 v[4:7], v12 offset:128
	ds_read_b128 v[8:11], v23 offset:128
	s_waitcnt lgkmcnt(0)
	v_mfma_f32_16x16x32_f16 v[0:3], v[4:7], v[8:11], v[0:3]
	ds_read_b128 v[4:7], v12 offset:192
	ds_read_b128 v[8:11], v23 offset:192
	s_waitcnt lgkmcnt(0)
	v_mfma_f32_16x16x32_f16 v[0:3], v[4:7], v[8:11], v[0:3]

;     __device__ __forceinline__ void operator()(const f32x4 (&acc)[2][2][4][2], const Unit& u, int wr, int wc, int fr, int fq) const {
;     ...
;         asm volatile("s_waitcnt lgkmcnt(0)" ::: "memory"); __builtin_amdgcn_s_barrier(); asm volatile("" ::: "memory");
;         if (tid < 256) {
;             const float part = (red[tid * 4 + 0] + red[tid * 4 + 1]) + (red[tid * 4 + 2] + red[tid * 4 + 3]);
;             __hip_atomic_store(ss + (unsigned)(u.pm * 4 + u.pn) * 256 + tid, part, __ATOMIC_RELAXED, __HIP_MEMORY_SCOPE_AGENT);
;         }
.LBB0_583:
	s_or_b64 exec, exec, s[28:29]
	s_waitcnt lgkmcnt(0)
	s_barrier
	s_and_saveexec_b64 s[28:29], s[6:7]
	s_cbranch_execz .LBB0_585
	v_readlane_b32 s36, v254, 43
	v_readlane_b32 s37, v254, 44
	v_readlane_b32 s38, v254, 45
	v_readlane_b32 s39, v254, 46
	v_readlane_b32 s40, v254, 47
	v_readlane_b32 s41, v254, 48
	v_readlane_b32 s42, v254, 49
	v_readlane_b32 s43, v254, 50
	v_readlane_b32 s44, v254, 51
	v_readlane_b32 s45, v254, 52
	v_readlane_b32 s46, v254, 53
	v_readlane_b32 s47, v254, 54
	v_readlane_b32 s48, v254, 55
	v_readlane_b32 s49, v254, 56
	v_readlane_b32 s50, v254, 57
	v_readlane_b32 s51, v254, 58
	s_mov_b32 s25, s45
	v_writelane_b32 v254, s36, 43
	s_waitcnt lgkmcnt(0)
	ds_read_b128 v[0:3], v207
	s_lshl_b32 s30, s73, 10
	v_writelane_b32 v254, s37, 44
	v_writelane_b32 v254, s38, 45
	v_writelane_b32 v254, s39, 46
	v_writelane_b32 v254, s40, 47
	v_writelane_b32 v254, s41, 48
	v_writelane_b32 v254, s42, 49
	v_writelane_b32 v254, s43, 50
	v_writelane_b32 v254, s44, 51
	v_writelane_b32 v254, s45, 52
	v_writelane_b32 v254, s46, 53
	v_writelane_b32 v254, s47, 54
	v_writelane_b32 v254, s48, 55
	s_waitcnt lgkmcnt(0)
	v_mov_b32_e32 v4, v1
	v_mov_b32_e32 v5, v2
	v_mov_b32_e32 v1, v3
	v_writelane_b32 v254, s49, 56
	s_add_i32 s24, s30, s24
	v_pk_add_f32 v[0:1], v[4:5], v[0:1]
	v_writelane_b32 v254, s50, 57
	v_pk_add_f32 v[0:1], v[0:1], v[0:1] op_sel:[0,1] op_sel_hi:[1,0]
	v_writelane_b32 v254, s51, 58
	v_lshl_add_u64 v[2:3], s[24:25], 2, v[140:141]
	global_store_dword v[2:3], v0, off sc1

;     __device__ __forceinline__ void operator()(const f32x4 (&acc)[2][2][4][2], const Unit& u, int wr, int wc, int fr, int fq) const {
;     ...
;         if (tid < 256) {
;             float tot = 0.f;
; #pragma unroll
;             for (int q = 0; q < 4; ++q) tot += __hip_atomic_load(ss + (unsigned)(u.pm * 4 + q) * 256 + tid, __ATOMIC_RELAXED, __HIP_MEMORY_SCOPE_AGENT);
;             rs[tid] = rsqrtf(tot * (1.0f / 1024.0f) + 1e-6f);
;         }
;         asm volatile("s_waitcnt lgkmcnt(0)" ::: "memory"); __builtin_amdgcn_s_barrier(); asm volatile("" ::: "memory");
;         const float* sh = FINAL ? ln : shp + b * 9216; const float* sc = FINAL ? ln : scp + b * 9216;
; #pragma unroll
;         for (int bj = 0; bj < 2; ++bj) {
;             const int col = col0 + bj * HALF;
;             const f32x4 l0 = *(const f32x4*)(ln + col), l1 = *(const f32x4*)(ln + col + 4), s0 = *(const f32x4*)(sh + col), s1 = *(const f32x4*)(sh + col + 4),
;                         c0 = *(const f32x4*)(sc + col), c1 = *(const f32x4*)(sc + col + 4);
; #pragma unroll
;             for (int ai = 0; ai < 2; ++ai)
; #pragma unroll
;                 for (int m = 0; m < 4; ++m) {
;                     const float rstd = rs[ai * HALF + wr * 64 + m * 16 + fr];
;                     const h16x8 o = ov[ai][m][bj];
;                     if (FINAL) {
;                         f32x4 y0, y1;
; #pragma unroll
;                         for (int j = 0; j < 4; ++j) { y0[j] = (float)o[j] * rstd * l0[j]; y1[j] = (float)o[4 + j] * rstd * l1[j]; }
;                         float* yp = fout + (unsigned)(row0 + ai * HALF + m * 16) * DM + col;
;                         *(f32x4*)yp = y0; *(f32x4*)(yp + 4) = y1;
;                     } else {
;                         h16x8 y;
; #pragma unroll
;                         for (int j = 0; j < 4; ++j) { y[j] = (h16)((float)o[j] * rstd * l0[j] * (1.0f + c0[j]) + s0[j]); y[4 + j] = (h16)((float)o[4 + j] * rstd * l1[j] * (1.0f + c1[j]) + s1[j]); }
;                         *(h16x8*)(xn + (unsigned)(row0 + ai * HALF + m * 16) * DM + col) = y;
.LBB0_601:
	s_or_b64 exec, exec, s[28:29]
	s_barrier
	s_and_saveexec_b64 s[28:29], s[6:7]
	s_cbranch_execz .LBB0_603
	v_readlane_b32 s36, v254, 43
	v_readlane_b32 s45, v254, 52
	s_mov_b32 s25, s45
	s_lshl_b32 s24, s73, 10
	s_waitcnt lgkmcnt(0)
	v_lshl_add_u64 v[0:1], s[24:25], 2, v[140:141]
	global_load_dword v2, v[0:1], off sc1
	global_load_dword v3, v[0:1], off offset:1024 sc1
	v_readlane_b32 s37, v254, 44
	v_readlane_b32 s38, v254, 45
	v_readlane_b32 s39, v254, 46
	v_readlane_b32 s40, v254, 47
	v_readlane_b32 s41, v254, 48
	v_readlane_b32 s42, v254, 49
	v_readlane_b32 s43, v254, 50
	v_readlane_b32 s44, v254, 51
	v_readlane_b32 s46, v254, 53
	v_readlane_b32 s47, v254, 54
	v_readlane_b32 s48, v254, 55
	v_readlane_b32 s49, v254, 56
	v_readlane_b32 s50, v254, 57
	v_readlane_b32 s51, v254, 58
	v_writelane_b32 v254, s36, 43
	s_mov_b32 s24, 0x800000
	s_waitcnt vmcnt(0) lgkmcnt(0)
	v_add_f32_e32 v2, 0, v2
	v_add_f32_e32 v2, v2, v3
	global_load_dword v3, v[0:1], off offset:2048 sc1
	v_writelane_b32 v254, s37, 44
	global_load_dword v0, v[0:1], off offset:3072 sc1
	v_writelane_b32 v254, s38, 45
	v_writelane_b32 v254, s39, 46
	v_writelane_b32 v254, s40, 47
	v_writelane_b32 v254, s41, 48
	v_writelane_b32 v254, s42, 49
	v_writelane_b32 v254, s43, 50
	v_writelane_b32 v254, s44, 51
	v_writelane_b32 v254, s45, 52
	v_writelane_b32 v254, s46, 53
	v_writelane_b32 v254, s47, 54
	v_writelane_b32 v254, s48, 55
	v_writelane_b32 v254, s49, 56
	v_writelane_b32 v254, s50, 57
	v_writelane_b32 v254, s51, 58
	s_waitcnt vmcnt(0) lgkmcnt(0)
	v_add_f32_e32 v2, v2, v3
	v_add_f32_e32 v0, v2, v0
	v_fmamk_f32 v0, v0, 0x3a800000, v193
	v_cmp_gt_f32_e32 vcc, s24, v0
	v_mul_f32_e32 v1, 0x4b800000, v0
	s_nop 0
	v_cndmask_b32_e32 v0, v0, v1, vcc
	v_rsq_f32_e32 v0, v0
	s_nop 0
	v_mul_f32_e32 v1, 0x45800000, v0
	v_cndmask_b32_e32 v0, v0, v1, vcc
	ds_write_b32 v204, v0
.LBB0_603:
	s_or_b64 exec, exec, s[28:29]
	s_add_u32 s28, s96, s26
	s_addc_u32 s29, s97, s27
	s_add_u32 s26, s54, s26
	v_lshlrev_b64 v[8:9], 2, v[150:151]
	s_addc_u32 s27, s55, s27
	s_waitcnt lgkmcnt(0)
	s_barrier
	v_lshl_add_u64 v[168:169], s[12:13], 0, v[8:9]
	v_lshl_add_u64 v[170:171], s[26:27], 0, v[8:9]
	s_waitcnt lgkmcnt(0)
	global_load_dwordx4 v[0:3], v[168:169], off offset:16
	global_load_dwordx4 v[4:7], v[168:169], off
	global_load_dwordx4 v[208:211], v[170:171], off
	global_load_dwordx4 v[212:215], v[170:171], off offset:16
	v_lshl_add_u64 v[172:173], s[28:29], 0, v[8:9]
	global_load_dwordx4 v[12:15], v[172:173], off
	global_load_dwordx4 v[8:11], v[172:173], off offset:16
	ds_read_b32 v32, v205
	v_mov_b32_e32 v149, v33
	v_lshlrev_b64 v[174:175], 1, v[150:151]
	v_lshl_add_u64 v[150:151], v[148:149], 1, s[84:85]
	v_lshl_add_u64 v[150:151], v[150:151], 0, v[174:175]
	s_waitcnt lgkmcnt(0)
	v_pk_mul_f32 v[124:125], v[32:33], v[124:125] op_sel_hi:[0,1]
	v_pk_mul_f32 v[128:129], v[32:33], v[128:129] op_sel_hi:[0,1]
	v_pk_mul_f32 v[122:123], v[32:33], v[122:123] op_sel_hi:[0,1]
	v_pk_mul_f32 v[126:127], v[32:33], v[126:127] op_sel_hi:[0,1]
	v_or_b32_e32 v32, 0x4000, v148
	s_and_b64 vcc, exec, s[10:11]
	s_mov_b64 s[10:11], -1
	s_waitcnt vmcnt(0)
	v_pk_mul_f32 v[198:199], v[0:1], v[128:129]
	v_pk_mul_f32 v[196:197], v[4:5], v[124:125]
	v_pk_mul_f32 v[122:123], v[6:7], v[122:123]
	v_pk_mul_f32 v[216:217], v[2:3], v[126:127]
	v_pk_add_f32 v[176:177], v[208:209], 1.0 op_sel_hi:[1,0]
	v_pk_add_f32 v[128:129], v[212:213], 1.0 op_sel_hi:[1,0]
	v_pk_add_f32 v[126:127], v[210:211], 1.0 op_sel_hi:[1,0]
	v_pk_add_f32 v[124:125], v[214:215], 1.0 op_sel_hi:[1,0]
	v_pk_fma_f32 v[196:197], v[176:177], v[196:197], v[12:13]
	v_pk_fma_f32 v[198:199], v[128:129], v[198:199], v[8:9]
	v_pk_fma_f32 v[122:123], v[126:127], v[122:123], v[14:15]
	v_pk_fma_f32 v[212:213], v[124:125], v[216:217], v[10:11]
	v_cvt_pk_f16_f32 v208, v196, v197
	v_cvt_pk_f16_f32 v210, v198, v199
	v_cvt_pk_f16_f32 v209, v122, v123
	v_cvt_pk_f16_f32 v211, v212, v213
	global_store_dwordx4 v[150:151], v[208:211], off
	ds_read_b32 v196, v205 offset:64
	v_lshl_add_u64 v[122:123], v[32:33], 1, s[84:85]
	v_lshl_add_u64 v[122:123], v[122:123], 0, v[174:175]
	v_or_b32_e32 v32, 0x8000, v148
	s_waitcnt lgkmcnt(0)
	v_pk_mul_f32 v[108:109], v[196:197], v[108:109] op_sel_hi:[0,1]
	v_pk_mul_f32 v[112:113], v[196:197], v[112:113] op_sel_hi:[0,1]
	v_pk_mul_f32 v[106:107], v[196:197], v[106:107] op_sel_hi:[0,1]
	v_pk_mul_f32 v[110:111], v[196:197], v[110:111] op_sel_hi:[0,1]
	v_pk_mul_f32 v[108:109], v[4:5], v[108:109]
	v_pk_mul_f32 v[112:113], v[0:1], v[112:113]
	v_pk_mul_f32 v[106:107], v[6:7], v[106:107]
	v_pk_mul_f32 v[110:111], v[2:3], v[110:111]
	v_pk_fma_f32 v[108:109], v[176:177], v[108:109], v[12:13]
	v_pk_fma_f32 v[112:113], v[128:129], v[112:113], v[8:9]
	v_pk_fma_f32 v[196:197], v[126:127], v[106:107], v[14:15]
	v_pk_fma_f32 v[110:111], v[124:125], v[110:111], v[10:11]
	v_cvt_pk_f16_f32 v106, v108, v109
	v_cvt_pk_f16_f32 v108, v112, v113
	v_cvt_pk_f16_f32 v107, v196, v197
	v_cvt_pk_f16_f32 v109, v110, v111
	global_store_dwordx4 v[122:123], v[106:109], off
	ds_read_b32 v108, v205 offset:128
	s_waitcnt lgkmcnt(0)
;     __device__ __forceinline__ void operator()(const f32x4 (&acc)[2][2][4][2], const Unit& u, int wr, int wc, int fr, int fq) const {
;     ...
;         for (int bj = 0; bj < 2; ++bj) {
;             const int col = col0 + bj * HALF;
;             const f32x4 l0 = *(const f32x4*)(ln + col), l1 = *(const f32x4*)(ln + col + 4), s0 = *(const f32x4*)(sh + col), s1 = *(const f32x4*)(sh + col + 4),
;                         c0 = *(const f32x4*)(sc + col), c1 = *(const f32x4*)(sc + col + 4);
; #pragma unroll
;             for (int ai = 0; ai < 2; ++ai)
; #pragma unroll
;                 for (int m = 0; m < 4; ++m) {
;                     const float rstd = rs[ai * HALF + wr * 64 + m * 16 + fr];
;                     const h16x8 o = ov[ai][m][bj];
;                     if (FINAL) {
;                         f32x4 y0, y1;
; #pragma unroll
;                         for (int j = 0; j < 4; ++j) { y0[j] = (float)o[j] * rstd * l0[j]; y1[j] = (float)o[4 + j] * rstd * l1[j]; }
;                         float* yp = fout + (unsigned)(row0 + ai * HALF + m * 16) * DM + col;
;                         *(f32x4*)yp = y0; *(f32x4*)(yp + 4) = y1;
;                     } else {
;                         h16x8 y;
; #pragma unroll
;                         for (int j = 0; j < 4; ++j) { y[j] = (h16)((float)o[j] * rstd * l0[j] * (1.0f + c0[j]) + s0[j]); y[4 + j] = (h16)((float)o[4 + j] * rstd * l1[j] * (1.0f + c1[j]) + s1[j]); }
;                         *(h16x8*)(xn + (unsigned)(row0 + ai * HALF + m * 16) * DM + col) = y;
	v_pk_mul_f32 v[92:93], v[108:109], v[92:93] op_sel_hi:[0,1]
	v_pk_mul_f32 v[96:97], v[108:109], v[96:97] op_sel_hi:[0,1]
	v_pk_mul_f32 v[90:91], v[108:109], v[90:91] op_sel_hi:[0,1]
	v_pk_mul_f32 v[94:95], v[108:109], v[94:95] op_sel_hi:[0,1]
	v_pk_mul_f32 v[92:93], v[4:5], v[92:93]
	v_pk_mul_f32 v[96:97], v[0:1], v[96:97]
	v_pk_mul_f32 v[90:91], v[6:7], v[90:91]
	v_pk_mul_f32 v[94:95], v[2:3], v[94:95]
	v_lshl_add_u64 v[106:107], v[32:33], 1, s[84:85]
	v_pk_fma_f32 v[92:93], v[176:177], v[92:93], v[12:13]
	v_pk_fma_f32 v[96:97], v[128:129], v[96:97], v[8:9]
	v_pk_fma_f32 v[108:109], v[126:127], v[90:91], v[14:15]
	v_pk_fma_f32 v[94:95], v[124:125], v[94:95], v[10:11]
	v_lshl_add_u64 v[106:107], v[106:107], 0, v[174:175]
	v_cvt_pk_f16_f32 v90, v92, v93
	v_cvt_pk_f16_f32 v92, v96, v97
	v_cvt_pk_f16_f32 v91, v108, v109
	v_cvt_pk_f16_f32 v93, v94, v95
	global_store_dwordx4 v[106:107], v[90:93], off
	ds_read_b32 v92, v205 offset:192
	v_or_b32_e32 v32, 0xc000, v148
	v_lshl_add_u64 v[90:91], v[32:33], 1, s[84:85]
	v_lshl_add_u64 v[90:91], v[90:91], 0, v[174:175]
	v_add_u32_e32 v32, 0x20000, v148
	s_waitcnt lgkmcnt(0)
	v_pk_mul_f32 v[76:77], v[92:93], v[76:77] op_sel_hi:[0,1]
	v_pk_mul_f32 v[80:81], v[92:93], v[80:81] op_sel_hi:[0,1]
	v_pk_mul_f32 v[74:75], v[92:93], v[74:75] op_sel_hi:[0,1]
	v_pk_mul_f32 v[78:79], v[92:93], v[78:79] op_sel_hi:[0,1]
	v_pk_mul_f32 v[76:77], v[4:5], v[76:77]
	v_pk_mul_f32 v[80:81], v[0:1], v[80:81]
	v_pk_mul_f32 v[74:75], v[6:7], v[74:75]
	v_pk_mul_f32 v[78:79], v[2:3], v[78:79]
	v_pk_fma_f32 v[76:77], v[176:177], v[76:77], v[12:13]
	v_pk_fma_f32 v[80:81], v[128:129], v[80:81], v[8:9]
	v_pk_fma_f32 v[92:93], v[126:127], v[74:75], v[14:15]
	v_pk_fma_f32 v[78:79], v[124:125], v[78:79], v[10:11]
	v_cvt_pk_f16_f32 v74, v76, v77
	v_cvt_pk_f16_f32 v76, v80, v81
	v_cvt_pk_f16_f32 v75, v92, v93
	v_cvt_pk_f16_f32 v77, v78, v79
	global_store_dwordx4 v[90:91], v[74:77], off
	ds_read_b32 v76, v205 offset:512
	s_waitcnt lgkmcnt(0)
	v_pk_mul_f32 v[60:61], v[76:77], v[60:61] op_sel_hi:[0,1]
	v_pk_mul_f32 v[64:65], v[76:77], v[64:65] op_sel_hi:[0,1]
	v_pk_mul_f32 v[58:59], v[76:77], v[58:59] op_sel_hi:[0,1]
	v_pk_mul_f32 v[62:63], v[76:77], v[62:63] op_sel_hi:[0,1]
	v_pk_mul_f32 v[60:61], v[4:5], v[60:61]
	v_pk_mul_f32 v[64:65], v[0:1], v[64:65]
	v_pk_mul_f32 v[58:59], v[6:7], v[58:59]
	v_pk_mul_f32 v[62:63], v[2:3], v[62:63]
	v_lshl_add_u64 v[74:75], v[32:33], 1, s[84:85]
	v_pk_fma_f32 v[60:61], v[176:177], v[60:61], v[12:13]
	v_pk_fma_f32 v[64:65], v[128:129], v[64:65], v[8:9]
	v_pk_fma_f32 v[76:77], v[126:127], v[58:59], v[14:15]
	v_pk_fma_f32 v[62:63], v[124:125], v[62:63], v[10:11]
	v_lshl_add_u64 v[74:75], v[74:75], 0, v[174:175]
	v_cvt_pk_f16_f32 v58, v60, v61
	v_cvt_pk_f16_f32 v60, v64, v65
	v_cvt_pk_f16_f32 v59, v76, v77
	v_cvt_pk_f16_f32 v61, v62, v63
	global_store_dwordx4 v[74:75], v[58:61], off
	ds_read_b32 v32, v205 offset:576
	s_waitcnt lgkmcnt(0)
	v_pk_mul_f32 v[46:47], v[32:33], v[46:47] op_sel_hi:[0,1]
	v_pk_mul_f32 v[42:43], v[32:33], v[42:43] op_sel_hi:[0,1]
	v_pk_mul_f32 v[48:49], v[32:33], v[48:49] op_sel_hi:[0,1]
	v_pk_mul_f32 v[44:45], v[32:33], v[44:45] op_sel_hi:[0,1]
	v_pk_mul_f32 v[46:47], v[0:1], v[46:47]
	v_pk_mul_f32 v[42:43], v[2:3], v[42:43]
	v_pk_mul_f32 v[48:49], v[4:5], v[48:49]
	v_pk_mul_f32 v[58:59], v[6:7], v[44:45]
	v_pk_fma_f32 v[46:47], v[128:129], v[46:47], v[8:9]
	v_pk_fma_f32 v[42:43], v[124:125], v[42:43], v[10:11]
	v_add_u32_e32 v32, 0x24000, v148
	v_pk_fma_f32 v[44:45], v[176:177], v[48:49], v[12:13]
	v_cvt_pk_f16_f32 v46, v46, v47
	v_pk_fma_f32 v[48:49], v[126:127], v[58:59], v[14:15]
	v_cvt_pk_f16_f32 v47, v42, v43
	v_lshl_add_u64 v[42:43], v[32:33], 1, s[84:85]
	v_cvt_pk_f16_f32 v44, v44, v45
	v_cvt_pk_f16_f32 v45, v48, v49
	v_lshl_add_u64 v[42:43], v[42:43], 0, v[174:175]
	global_store_dwordx4 v[42:43], v[44:47], off
	ds_read_b32 v32, v205 offset:640
	s_waitcnt lgkmcnt(0)
	v_pk_mul_f32 v[24:25], v[32:33], v[24:25] op_sel_hi:[0,1]
	v_pk_mul_f32 v[30:31], v[32:33], v[30:31] op_sel_hi:[0,1]
	v_pk_mul_f32 v[28:29], v[32:33], v[28:29] op_sel_hi:[0,1]
	v_pk_mul_f32 v[26:27], v[32:33], v[26:27] op_sel_hi:[0,1]
	v_pk_mul_f32 v[24:25], v[2:3], v[24:25]
	v_pk_mul_f32 v[30:31], v[4:5], v[30:31]
	v_pk_mul_f32 v[28:29], v[0:1], v[28:29]
	v_pk_mul_f32 v[26:27], v[6:7], v[26:27]
	v_pk_fma_f32 v[24:25], v[124:125], v[24:25], v[10:11]
	v_add_u32_e32 v32, 0x28000, v148
	v_pk_fma_f32 v[30:31], v[176:177], v[30:31], v[12:13]
	v_pk_fma_f32 v[28:29], v[128:129], v[28:29], v[8:9]
	v_pk_fma_f32 v[26:27], v[126:127], v[26:27], v[14:15]
	v_cvt_pk_f16_f32 v47, v24, v25
	v_lshl_add_u64 v[24:25], v[32:33], 1, s[84:85]
	v_cvt_pk_f16_f32 v44, v30, v31
	v_cvt_pk_f16_f32 v46, v28, v29
	v_cvt_pk_f16_f32 v45, v26, v27
	v_lshl_add_u64 v[24:25], v[24:25], 0, v[174:175]
	global_store_dwordx4 v[24:25], v[44:47], off
	ds_read_b32 v30, v205 offset:704
	v_add_u32_e32 v32, 0x2c000, v148
	s_waitcnt lgkmcnt(0)
	v_pk_mul_f32 v[26:27], v[30:31], v[166:167] op_sel_hi:[0,1]
	v_pk_mul_f32 v[4:5], v[4:5], v[26:27]
	s_nop 0
	v_pk_fma_f32 v[4:5], v[176:177], v[4:5], v[12:13]
	s_nop 0
	v_cvt_pk_f16_f32 v26, v4, v5
	v_pk_mul_f32 v[4:5], v[30:31], v[162:163] op_sel_hi:[0,1]
	v_pk_mul_f32 v[0:1], v[0:1], v[4:5]
	s_nop 0
	v_pk_fma_f32 v[0:1], v[128:129], v[0:1], v[8:9]
	s_nop 0
	v_cvt_pk_f16_f32 v28, v0, v1
	v_pk_mul_f32 v[0:1], v[30:31], v[164:165] op_sel_hi:[0,1]
	v_pk_mul_f32 v[0:1], v[6:7], v[0:1]
	s_nop 0
	v_pk_fma_f32 v[0:1], v[126:127], v[0:1], v[14:15]
	s_nop 0
	v_cvt_pk_f16_f32 v27, v0, v1
	v_pk_mul_f32 v[0:1], v[30:31], v[160:161] op_sel_hi:[0,1]
	v_pk_mul_f32 v[0:1], v[2:3], v[0:1]
	s_nop 0
	v_pk_fma_f32 v[0:1], v[124:125], v[0:1], v[10:11]
	s_nop 0
	v_cvt_pk_f16_f32 v29, v0, v1
	v_lshl_add_u64 v[0:1], v[32:33], 1, s[84:85]
	v_lshl_add_u64 v[0:1], v[0:1], 0, v[174:175]
	global_store_dwordx4 v[0:1], v[26:29], off
	global_load_dwordx4 v[2:5], v[168:169], off offset:512
	global_load_dwordx4 v[6:9], v[170:171], off offset:512
	global_load_dwordx4 v[10:13], v[168:169], off offset:528
	s_nop 0
	global_load_dwordx4 v[26:29], v[170:171], off offset:528
	global_load_dwordx4 v[44:47], v[172:173], off offset:512
	global_load_dwordx4 v[58:61], v[172:173], off offset:528
	ds_read_b32 v14, v205
	s_waitcnt lgkmcnt(0)
;     __device__ __forceinline__ void operator()(const f32x4 (&acc)[2][2][4][2], const Unit& u, int wr, int wc, int fr, int fq) const {
;     ...
;         for (int bj = 0; bj < 2; ++bj) {
;             const int col = col0 + bj * HALF;
;             const f32x4 l0 = *(const f32x4*)(ln + col), l1 = *(const f32x4*)(ln + col + 4), s0 = *(const f32x4*)(sh + col), s1 = *(const f32x4*)(sh + col + 4),
;                         c0 = *(const f32x4*)(sc + col), c1 = *(const f32x4*)(sc + col + 4);
; #pragma unroll
;             for (int ai = 0; ai < 2; ++ai)
; #pragma unroll
;                 for (int m = 0; m < 4; ++m) {
;                     const float rstd = rs[ai * HALF + wr * 64 + m * 16 + fr];
;                     const h16x8 o = ov[ai][m][bj];
;                     if (FINAL) {
;                         f32x4 y0, y1;
; #pragma unroll
;                         for (int j = 0; j < 4; ++j) { y0[j] = (float)o[j] * rstd * l0[j]; y1[j] = (float)o[4 + j] * rstd * l1[j]; }
;                         float* yp = fout + (unsigned)(row0 + ai * HALF + m * 16) * DM + col;
;                         *(f32x4*)yp = y0; *(f32x4*)(yp + 4) = y1;
;                     } else {
;                         h16x8 y;
; #pragma unroll
;                         for (int j = 0; j < 4; ++j) { y[j] = (h16)((float)o[j] * rstd * l0[j] * (1.0f + c0[j]) + s0[j]); y[4 + j] = (h16)((float)o[4 + j] * rstd * l1[j] * (1.0f + c1[j]) + s1[j]); }
;                         *(h16x8*)(xn + (unsigned)(row0 + ai * HALF + m * 16) * DM + col) = y;
	v_pk_mul_f32 v[30:31], v[14:15], v[120:121] op_sel_hi:[0,1]
	v_pk_mul_f32 v[48:49], v[14:15], v[118:119] op_sel_hi:[0,1]
	v_pk_mul_f32 v[62:63], v[14:15], v[116:117] op_sel_hi:[0,1]
	v_pk_mul_f32 v[14:15], v[14:15], v[114:115] op_sel_hi:[0,1]
	s_waitcnt vmcnt(0)
	v_pk_mul_f32 v[30:31], v[2:3], v[30:31]
	v_pk_add_f32 v[64:65], v[6:7], 1.0 op_sel_hi:[1,0]
	v_pk_mul_f32 v[6:7], v[10:11], v[48:49]
	v_pk_add_f32 v[26:27], v[26:27], 1.0 op_sel_hi:[1,0]
	v_pk_mul_f32 v[48:49], v[4:5], v[62:63]
	v_pk_add_f32 v[62:63], v[8:9], 1.0 op_sel_hi:[1,0]
	v_pk_mul_f32 v[8:9], v[12:13], v[14:15]
	v_pk_add_f32 v[14:15], v[28:29], 1.0 op_sel_hi:[1,0]
	v_pk_fma_f32 v[28:29], v[64:65], v[30:31], v[44:45]
	v_pk_fma_f32 v[30:31], v[26:27], v[6:7], v[58:59]
	v_pk_fma_f32 v[48:49], v[62:63], v[48:49], v[46:47]
	v_pk_fma_f32 v[76:77], v[14:15], v[8:9], v[60:61]
	v_cvt_pk_f16_f32 v6, v28, v29
	v_cvt_pk_f16_f32 v8, v30, v31
	v_cvt_pk_f16_f32 v7, v48, v49
	v_cvt_pk_f16_f32 v9, v76, v77
	global_store_dwordx4 v[150:151], v[6:9], off offset:256
	ds_read_b32 v6, v205 offset:64
	s_waitcnt lgkmcnt(0)
	v_pk_mul_f32 v[28:29], v[6:7], v[102:103] op_sel_hi:[0,1]
	v_pk_mul_f32 v[8:9], v[6:7], v[104:105] op_sel_hi:[0,1]
	v_pk_mul_f32 v[30:31], v[6:7], v[100:101] op_sel_hi:[0,1]
	v_pk_mul_f32 v[6:7], v[6:7], v[98:99] op_sel_hi:[0,1]
	v_pk_mul_f32 v[8:9], v[2:3], v[8:9]
	v_pk_mul_f32 v[28:29], v[10:11], v[28:29]
	v_pk_mul_f32 v[30:31], v[4:5], v[30:31]
	v_pk_mul_f32 v[6:7], v[12:13], v[6:7]
	v_pk_fma_f32 v[8:9], v[64:65], v[8:9], v[44:45]
	v_pk_fma_f32 v[28:29], v[26:27], v[28:29], v[58:59]
	v_pk_fma_f32 v[30:31], v[62:63], v[30:31], v[46:47]
	v_pk_fma_f32 v[48:49], v[14:15], v[6:7], v[60:61]
	v_cvt_pk_f16_f32 v6, v8, v9
	v_cvt_pk_f16_f32 v8, v28, v29
	v_cvt_pk_f16_f32 v7, v30, v31
	v_cvt_pk_f16_f32 v9, v48, v49
	global_store_dwordx4 v[122:123], v[6:9], off offset:256
	ds_read_b32 v6, v205 offset:128
	s_waitcnt lgkmcnt(0)
	v_pk_mul_f32 v[28:29], v[6:7], v[86:87] op_sel_hi:[0,1]
	v_pk_mul_f32 v[8:9], v[6:7], v[88:89] op_sel_hi:[0,1]
	v_pk_mul_f32 v[30:31], v[6:7], v[84:85] op_sel_hi:[0,1]
	v_pk_mul_f32 v[6:7], v[6:7], v[82:83] op_sel_hi:[0,1]
	v_pk_mul_f32 v[8:9], v[2:3], v[8:9]
	v_pk_mul_f32 v[28:29], v[10:11], v[28:29]
	v_pk_mul_f32 v[30:31], v[4:5], v[30:31]
	v_pk_mul_f32 v[6:7], v[12:13], v[6:7]
	v_pk_fma_f32 v[8:9], v[64:65], v[8:9], v[44:45]
	v_pk_fma_f32 v[28:29], v[26:27], v[28:29], v[58:59]
	v_pk_fma_f32 v[30:31], v[62:63], v[30:31], v[46:47]
	v_pk_fma_f32 v[48:49], v[14:15], v[6:7], v[60:61]
	v_cvt_pk_f16_f32 v6, v8, v9
	v_cvt_pk_f16_f32 v8, v28, v29
	v_cvt_pk_f16_f32 v7, v30, v31
	v_cvt_pk_f16_f32 v9, v48, v49
	global_store_dwordx4 v[106:107], v[6:9], off offset:256
	ds_read_b32 v6, v205 offset:192
	s_waitcnt lgkmcnt(0)
	v_pk_mul_f32 v[28:29], v[6:7], v[70:71] op_sel_hi:[0,1]
	v_pk_mul_f32 v[8:9], v[6:7], v[72:73] op_sel_hi:[0,1]
	v_pk_mul_f32 v[30:31], v[6:7], v[68:69] op_sel_hi:[0,1]
	v_pk_mul_f32 v[6:7], v[6:7], v[66:67] op_sel_hi:[0,1]
	v_pk_mul_f32 v[8:9], v[2:3], v[8:9]
	v_pk_mul_f32 v[28:29], v[10:11], v[28:29]
	v_pk_mul_f32 v[30:31], v[4:5], v[30:31]
	v_pk_mul_f32 v[6:7], v[12:13], v[6:7]
	v_pk_fma_f32 v[8:9], v[64:65], v[8:9], v[44:45]
	v_pk_fma_f32 v[28:29], v[26:27], v[28:29], v[58:59]
	v_pk_fma_f32 v[30:31], v[62:63], v[30:31], v[46:47]
	v_pk_fma_f32 v[48:49], v[14:15], v[6:7], v[60:61]
	v_cvt_pk_f16_f32 v6, v8, v9
	v_cvt_pk_f16_f32 v8, v28, v29
	v_cvt_pk_f16_f32 v7, v30, v31
	v_cvt_pk_f16_f32 v9, v48, v49
	global_store_dwordx4 v[90:91], v[6:9], off offset:256
	ds_read_b32 v28, v205 offset:512
	s_waitcnt lgkmcnt(0)
	v_pk_mul_f32 v[30:31], v[28:29], v[52:53] op_sel_hi:[0,1]
	v_pk_mul_f32 v[6:7], v[28:29], v[56:57] op_sel_hi:[0,1]
	v_pk_mul_f32 v[8:9], v[28:29], v[54:55] op_sel_hi:[0,1]
	v_pk_mul_f32 v[28:29], v[28:29], v[50:51] op_sel_hi:[0,1]
	v_pk_mul_f32 v[6:7], v[2:3], v[6:7]
	v_pk_mul_f32 v[8:9], v[10:11], v[8:9]
	v_pk_mul_f32 v[30:31], v[4:5], v[30:31]
	v_pk_mul_f32 v[28:29], v[12:13], v[28:29]
	v_pk_fma_f32 v[6:7], v[64:65], v[6:7], v[44:45]
	v_pk_fma_f32 v[8:9], v[26:27], v[8:9], v[58:59]
	v_pk_fma_f32 v[30:31], v[62:63], v[30:31], v[46:47]
	v_pk_fma_f32 v[28:29], v[14:15], v[28:29], v[60:61]
	v_cvt_pk_f16_f32 v6, v6, v7
	v_cvt_pk_f16_f32 v8, v8, v9
	v_cvt_pk_f16_f32 v7, v30, v31
	v_cvt_pk_f16_f32 v9, v28, v29
	global_store_dwordx4 v[74:75], v[6:9], off offset:256
	ds_read_b32 v28, v205 offset:576
	s_waitcnt lgkmcnt(0)
	v_pk_mul_f32 v[30:31], v[28:29], v[36:37] op_sel_hi:[0,1]
	v_pk_mul_f32 v[6:7], v[28:29], v[40:41] op_sel_hi:[0,1]
	v_pk_mul_f32 v[8:9], v[28:29], v[38:39] op_sel_hi:[0,1]
	v_pk_mul_f32 v[28:29], v[28:29], v[34:35] op_sel_hi:[0,1]
	v_pk_mul_f32 v[6:7], v[2:3], v[6:7]
	v_pk_mul_f32 v[8:9], v[10:11], v[8:9]
	v_pk_mul_f32 v[30:31], v[4:5], v[30:31]
	v_pk_mul_f32 v[28:29], v[12:13], v[28:29]
	v_pk_fma_f32 v[6:7], v[64:65], v[6:7], v[44:45]
	v_pk_fma_f32 v[8:9], v[26:27], v[8:9], v[58:59]
	v_pk_fma_f32 v[30:31], v[62:63], v[30:31], v[46:47]
	v_pk_fma_f32 v[28:29], v[14:15], v[28:29], v[60:61]
	v_cvt_pk_f16_f32 v6, v6, v7
	v_cvt_pk_f16_f32 v8, v8, v9
	v_cvt_pk_f16_f32 v7, v30, v31
	v_cvt_pk_f16_f32 v9, v28, v29
	global_store_dwordx4 v[42:43], v[6:9], off offset:256
	ds_read_b32 v28, v205 offset:640
	s_waitcnt lgkmcnt(0)
	v_pk_mul_f32 v[18:19], v[28:29], v[18:19] op_sel_hi:[0,1]
	v_pk_mul_f32 v[6:7], v[28:29], v[22:23] op_sel_hi:[0,1]
	v_pk_mul_f32 v[8:9], v[28:29], v[20:21] op_sel_hi:[0,1]
	v_pk_mul_f32 v[16:17], v[28:29], v[16:17] op_sel_hi:[0,1]
	v_pk_mul_f32 v[6:7], v[2:3], v[6:7]
	v_pk_mul_f32 v[8:9], v[10:11], v[8:9]
	v_pk_mul_f32 v[18:19], v[4:5], v[18:19]
	v_pk_mul_f32 v[16:17], v[12:13], v[16:17]
	v_pk_fma_f32 v[6:7], v[64:65], v[6:7], v[44:45]
	v_pk_fma_f32 v[8:9], v[26:27], v[8:9], v[58:59]
	v_pk_fma_f32 v[18:19], v[62:63], v[18:19], v[46:47]
	v_pk_fma_f32 v[16:17], v[14:15], v[16:17], v[60:61]
	v_cvt_pk_f16_f32 v6, v6, v7
	v_cvt_pk_f16_f32 v8, v8, v9
	v_cvt_pk_f16_f32 v7, v18, v19
	v_cvt_pk_f16_f32 v9, v16, v17
	global_store_dwordx4 v[24:25], v[6:9], off offset:256
	ds_read_b32 v16, v205 offset:704
	s_waitcnt lgkmcnt(0)
	v_pk_mul_f32 v[6:7], v[16:17], v[158:159] op_sel_hi:[0,1]
	v_pk_mul_f32 v[2:3], v[2:3], v[6:7]
	s_nop 0
	v_pk_fma_f32 v[2:3], v[64:65], v[2:3], v[44:45]
	s_nop 0
	v_cvt_pk_f16_f32 v6, v2, v3
	v_pk_mul_f32 v[2:3], v[16:17], v[154:155] op_sel_hi:[0,1]
	v_pk_mul_f32 v[2:3], v[10:11], v[2:3]
	s_nop 0
	v_pk_fma_f32 v[2:3], v[26:27], v[2:3], v[58:59]
	s_nop 0
	v_cvt_pk_f16_f32 v8, v2, v3
	v_pk_mul_f32 v[2:3], v[16:17], v[156:157] op_sel_hi:[0,1]
	v_pk_mul_f32 v[2:3], v[4:5], v[2:3]
	s_nop 0
	v_pk_fma_f32 v[2:3], v[62:63], v[2:3], v[46:47]
	s_nop 0
	v_cvt_pk_f16_f32 v7, v2, v3
	v_pk_mul_f32 v[2:3], v[16:17], v[152:153] op_sel_hi:[0,1]
	v_pk_mul_f32 v[2:3], v[12:13], v[2:3]
	s_nop 0
	v_pk_fma_f32 v[2:3], v[14:15], v[2:3], v[60:61]
	s_nop 0
	v_cvt_pk_f16_f32 v9, v2, v3
	global_store_dwordx4 v[0:1], v[6:9], off offset:256
	s_cbranch_vccnz .LBB0_552
	s_andn2_b64 vcc, exec, s[62:63]
	s_cbranch_vccnz .LBB0_551
	s_barrier
	s_branch .LBB0_551

;     __device__ __forceinline__ void operator()(const f32x4 (&acc)[2][2][4][2], const Unit& u, int wr, int wc, int fr, int fq) const {
;     ...
;         f32x4 gv[2][2];
; #pragma unroll
;         for (int bj = 0; bj < 2; ++bj)
; #pragma unroll
;             for (int n = 0; n < 2; ++n) gv[bj][n] = *(const f32x4*)(gate + b * 9216 + col0 + bj * HALF + 4 * n) * coef;
;         h16x8 ov[2][4][2];
; #pragma unroll
;         for (int ai = 0; ai < 2; ++ai)
; #pragma unroll
;             for (int m = 0; m < 4; ++m) {
;                 float sq = 0.f;
; #pragma unroll
;                 for (int bj = 0; bj < 2; ++bj) {
;                     const unsigned off = (unsigned)(row0 + ai * HALF + m * 16) * DM + col0 + bj * HALF;
;                     f32x4 xa, xb;
;                     if (F32IN) { xa = *(const f32x4*)(in32 + off); xb = *(const f32x4*)(in32 + off + 4); }
;                     else { const h16x8 xv = *(const h16x8*)(in16 + off); xa = (f32x4){(float)xv[0], (float)xv[1], (float)xv[2], (float)xv[3]}; xb = (f32x4){(float)xv[4], (float)xv[5], (float)xv[6], (float)xv[7]}; }
;                     h16x8 o;
; #pragma unroll
;                     for (int j = 0; j < 4; ++j) { o[j] = (h16)(xa[j] + gv[bj][0][j] * acc[ai][bj][m][0][j]); o[4 + j] = (h16)(xb[j] + gv[bj][1][j] * acc[ai][bj][m][1][j]); }
;                     if (!FINAL) *(h16x8*)(out + off) = o;
;                     ov[ai][m][bj] = o;
; #pragma unroll
;                     for (int j = 0; j < 8; ++j) sq += (float)o[j] * (float)o[j];
;                 }
.LBB0_634:
	s_lshr_b32 s22, s97, 4
	s_mulk_i32 s22, 0x2400
	s_ashr_i32 s23, s22, 31
	s_lshl_b32 s24, s24, 8
	s_lshl_b64 s[22:23], s[22:23], 2
	v_or_b32_e32 v146, s24, v175
	s_add_u32 s26, s72, s22
	s_addc_u32 s27, s73, s23
	v_ashrrev_i32_e32 v147, 31, v146
	v_lshl_add_u64 v[156:157], v[146:147], 2, s[26:27]
	global_load_dwordx4 v[148:151], v[156:157], off
	global_load_dwordx4 v[152:155], v[156:157], off offset:16
	v_lshl_add_u32 v144, s97, 18, v179
	v_readlane_b32 s36, v253, 16
	v_add_u32_e32 v32, v144, v146
	v_readlane_b32 s37, v253, 17
	v_readlane_b32 s38, v253, 18
	v_readlane_b32 s39, v253, 19
	v_lshl_add_u64 v[172:173], v[32:33], 2, s[36:37]
	global_load_dwordx4 v[204:207], v[156:157], off offset:512
	global_load_dwordx4 v[208:211], v[156:157], off offset:528
	v_readlane_b32 s30, v253, 16
	v_readlane_b32 s31, v253, 17
	v_lshlrev_b32_e32 v249, 2, v32
	s_nop 4
	v_add_u32_e32 v248, 0x0, v249
	global_load_dwordx4 v[216:219], v248, s[30:31]
	global_load_dwordx4 v[220:223], v248, s[30:31] offset:16
	global_load_dwordx4 v[224:227], v248, s[30:31] offset:512
	global_load_dwordx4 v[228:231], v248, s[30:31] offset:528
	v_add_u32_e32 v248, 0x10000, v249
	global_load_dwordx4 v[232:235], v248, s[30:31]
	global_load_dwordx4 v[236:239], v248, s[30:31] offset:16
	global_load_dwordx4 v[240:243], v248, s[30:31] offset:512
	global_load_dwordx4 v[244:247], v248, s[30:31] offset:528
	v_readlane_b32 s40, v253, 20
	v_readlane_b32 s41, v253, 21
	v_readlane_b32 s42, v253, 22
	v_readlane_b32 s43, v253, 23
	v_readlane_b32 s44, v253, 24
	v_readlane_b32 s45, v253, 25
	v_readlane_b32 s46, v253, 26
	v_readlane_b32 s47, v253, 27
	v_readlane_b32 s48, v253, 28
	v_readlane_b32 s49, v253, 29
	v_readlane_b32 s50, v253, 30
	v_readlane_b32 s51, v253, 31
	v_readlane_b32 s36, v253, 0
	v_readlane_b32 s48, v253, 12
	v_readlane_b32 s49, v253, 13
	v_readlane_b32 s37, v253, 1
	v_readlane_b32 s38, v253, 2
	v_lshl_add_u64 v[196:197], v[32:33], 1, s[48:49]
	v_readlane_b32 s39, v253, 3
	v_readlane_b32 s40, v253, 4
	v_readlane_b32 s41, v253, 5
	v_readlane_b32 s42, v253, 6
	v_readlane_b32 s43, v253, 7
	v_readlane_b32 s44, v253, 8
	v_readlane_b32 s45, v253, 9
	v_readlane_b32 s46, v253, 10
	v_readlane_b32 s47, v253, 11
	v_readlane_b32 s50, v253, 14
	v_readlane_b32 s51, v253, 15
	s_waitcnt vmcnt(6) lgkmcnt(0)
	v_pk_mul_f32 v[160:161], v[150:151], 0.5 op_sel_hi:[1,0]
	v_pk_mul_f32 v[162:163], v[148:149], 0.5 op_sel_hi:[1,0]
	v_pk_mul_f32 v[156:157], v[154:155], 0.5 op_sel_hi:[1,0]
	v_pk_mul_f32 v[158:159], v[152:153], 0.5 op_sel_hi:[1,0]
	v_pk_fma_f32 v[128:129], v[128:129], v[160:161], v[218:219]
	v_pk_fma_f32 v[126:127], v[126:127], v[162:163], v[216:217]
	v_pk_fma_f32 v[124:125], v[124:125], v[156:157], v[222:223]
	v_pk_fma_f32 v[122:123], v[122:123], v[158:159], v[220:221]
	v_cvt_pk_f16_f32 v164, v126, v127
	v_cvt_pk_f16_f32 v165, v128, v129
	v_cvt_pk_f16_f32 v166, v122, v123
	v_cvt_pk_f16_f32 v167, v124, v125
	global_store_dwordx4 v[196:197], v[164:167], off
	v_cvt_f32_f16_e32 v124, v164
	v_cvt_f32_f16_sdwa v125, v164 dst_sel:DWORD dst_unused:UNUSED_PAD src0_sel:WORD_1
	v_cvt_f32_f16_e32 v122, v165
	v_cvt_f32_f16_sdwa v123, v165 dst_sel:DWORD dst_unused:UNUSED_PAD src0_sel:WORD_1
	v_cvt_f32_f16_e32 v128, v166
	v_cvt_f32_f16_sdwa v129, v166 dst_sel:DWORD dst_unused:UNUSED_PAD src0_sel:WORD_1
	v_pk_mul_f32 v[154:155], v[204:205], 0.5 op_sel_hi:[1,0]
	v_pk_mul_f32 v[164:165], v[124:125], v[124:125]
	v_pk_mul_f32 v[152:153], v[206:207], 0.5 op_sel_hi:[1,0]
	v_cvt_f32_f16_e32 v126, v167
	v_cvt_f32_f16_sdwa v127, v167 dst_sel:DWORD dst_unused:UNUSED_PAD src0_sel:WORD_1
	v_pk_mul_f32 v[166:167], v[122:123], v[122:123]
	v_add_f32_e32 v145, v164, v165
	v_add_f32_e32 v145, v166, v145
	v_pk_mul_f32 v[148:149], v[210:211], 0.5 op_sel_hi:[1,0]
	v_pk_mul_f32 v[172:173], v[128:129], v[128:129]
	v_add_f32_e32 v145, v167, v145
	v_pk_mul_f32 v[150:151], v[208:209], 0.5 op_sel_hi:[1,0]
	v_add_f32_e32 v145, v172, v145
	v_pk_mul_f32 v[198:199], v[126:127], v[126:127]
	v_add_f32_e32 v145, v173, v145
	v_add_f32_e32 v145, v198, v145
	v_add_f32_e32 v145, v199, v145
	s_waitcnt vmcnt(6)
	v_pk_fma_f32 v[118:119], v[118:119], v[154:155], v[224:225]
	v_pk_fma_f32 v[120:121], v[120:121], v[152:153], v[226:227]
	v_cvt_pk_f16_f32 v166, v118, v119
	v_cvt_pk_f16_f32 v167, v120, v121
	v_cvt_f32_f16_e32 v120, v166
	v_cvt_f32_f16_sdwa v121, v166 dst_sel:DWORD dst_unused:UNUSED_PAD src0_sel:WORD_1
	s_waitcnt vmcnt(5)
	v_pk_fma_f32 v[116:117], v[116:117], v[148:149], v[230:231]
	v_pk_fma_f32 v[114:115], v[114:115], v[150:151], v[228:229]
	v_add_u32_e32 v248, 0x20000, v249
	global_load_dwordx4 v[216:219], v248, s[30:31]
	global_load_dwordx4 v[220:223], v248, s[30:31] offset:16
	global_load_dwordx4 v[224:227], v248, s[30:31] offset:512
	global_load_dwordx4 v[228:231], v248, s[30:31] offset:528
	v_cvt_pk_f16_f32 v169, v116, v117
	v_cvt_f32_f16_e32 v116, v167
	v_cvt_f32_f16_sdwa v117, v167 dst_sel:DWORD dst_unused:UNUSED_PAD src0_sel:WORD_1
	v_cvt_pk_f16_f32 v168, v114, v115
	v_cvt_f32_f16_e32 v118, v168
	v_cvt_f32_f16_sdwa v119, v168 dst_sel:DWORD dst_unused:UNUSED_PAD src0_sel:WORD_1
	v_pk_mul_f32 v[164:165], v[120:121], v[120:121]
	v_cvt_f32_f16_e32 v114, v169
	v_add_f32_e32 v145, v164, v145
	v_cvt_f32_f16_sdwa v115, v169 dst_sel:DWORD dst_unused:UNUSED_PAD src0_sel:WORD_1
	v_pk_mul_f32 v[170:171], v[116:117], v[116:117]
	v_add_f32_e32 v145, v165, v145
	v_add_f32_e32 v145, v170, v145
	v_pk_mul_f32 v[172:173], v[118:119], v[118:119]
	v_add_f32_e32 v145, v171, v145
	v_add_f32_e32 v145, v172, v145
	v_pk_mul_f32 v[204:205], v[114:115], v[114:115]
	v_add_f32_e32 v145, v173, v145
	v_add_f32_e32 v145, v204, v145
	v_add_f32_e32 v145, v205, v145
	ds_bpermute_b32 v164, v176, v145
	global_store_dwordx4 v[196:197], v[166:169], off offset:256
	s_waitcnt lgkmcnt(0)
	v_add_f32_e32 v145, v145, v164
	ds_bpermute_b32 v164, v177, v145
	s_and_saveexec_b64 s[26:27], s[4:5]
	s_cbranch_execz .LBB0_636
	s_waitcnt lgkmcnt(0)
	v_add_f32_e32 v145, v145, v164
	v_add_u32_e32 v164, s95, v178
	ds_write_b32 v164, v145
; __device__ __forceinline__ float shx(float v, int m, int lane) { return __int_as_float(__builtin_amdgcn_ds_bpermute((lane ^ m) << 2, __float_as_int(v))); }
;     __device__ __forceinline__ void operator()(const f32x4 (&acc)[2][2][4][2], const Unit& u, int wr, int wc, int fr, int fq) const {
;     ...
;             for (int m = 0; m < 4; ++m) {
;                 float sq = 0.f;
; #pragma unroll
;                 for (int bj = 0; bj < 2; ++bj) {
;                     const unsigned off = (unsigned)(row0 + ai * HALF + m * 16) * DM + col0 + bj * HALF;
;                     f32x4 xa, xb;
;                     if (F32IN) { xa = *(const f32x4*)(in32 + off); xb = *(const f32x4*)(in32 + off + 4); }
;                     else { const h16x8 xv = *(const h16x8*)(in16 + off); xa = (f32x4){(float)xv[0], (float)xv[1], (float)xv[2], (float)xv[3]}; xb = (f32x4){(float)xv[4], (float)xv[5], (float)xv[6], (float)xv[7]}; }
;                     h16x8 o;
; #pragma unroll
;                     for (int j = 0; j < 4; ++j) { o[j] = (h16)(xa[j] + gv[bj][0][j] * acc[ai][bj][m][0][j]); o[4 + j] = (h16)(xb[j] + gv[bj][1][j] * acc[ai][bj][m][1][j]); }
;                     if (!FINAL) *(h16x8*)(out + off) = o;
;                     ov[ai][m][bj] = o;
; #pragma unroll
;                     for (int j = 0; j < 8; ++j) sq += (float)o[j] * (float)o[j];
;                 }
;                 sq += shx(sq, 16, lane); sq += shx(sq, 32, lane);
;                 if (fq == 0) red[(ai * HALF + wr * 64 + m * 16 + fr) * 4 + wc] = sq;
.LBB0_636:
	s_or_b64 exec, exec, s[26:27]
	v_readlane_b32 s36, v253, 16
	v_add_u32_e32 v172, 0x4000, v32
	v_mov_b32_e32 v173, v33
	v_readlane_b32 s37, v253, 17
	v_readlane_b32 s56, v253, 0
	v_readlane_b32 s68, v253, 12
	v_lshl_add_u64 v[168:169], v[172:173], 2, s[36:37]
	s_waitcnt lgkmcnt(0)
	s_nop 0
	v_readlane_b32 s69, v253, 13
	v_add_u32_e32 v196, 0x4080, v32
	v_mov_b32_e32 v197, v33
	v_lshl_add_u64 v[172:173], v[172:173], 1, s[68:69]
	v_lshl_add_u64 v[198:199], v[196:197], 2, s[36:37]
	v_readlane_b32 s38, v253, 18
	v_readlane_b32 s39, v253, 19
	v_readlane_b32 s40, v253, 20
	v_readlane_b32 s41, v253, 21
	v_readlane_b32 s42, v253, 22
	v_readlane_b32 s43, v253, 23
	v_readlane_b32 s44, v253, 24
	v_readlane_b32 s45, v253, 25
	v_readlane_b32 s46, v253, 26
	v_readlane_b32 s47, v253, 27
	v_readlane_b32 s48, v253, 28
	v_readlane_b32 s49, v253, 29
	v_readlane_b32 s50, v253, 30
	v_readlane_b32 s51, v253, 31
	v_readlane_b32 s57, v253, 1
	v_readlane_b32 s58, v253, 2
	v_readlane_b32 s59, v253, 3
	v_readlane_b32 s60, v253, 4
	v_readlane_b32 s61, v253, 5
	v_readlane_b32 s62, v253, 6
	v_readlane_b32 s63, v253, 7
	v_readlane_b32 s64, v253, 8
	v_readlane_b32 s65, v253, 9
	v_readlane_b32 s66, v253, 10
	v_readlane_b32 s67, v253, 11
	v_readlane_b32 s70, v253, 14
	v_readlane_b32 s71, v253, 15
	s_waitcnt vmcnt(9)
	v_pk_fma_f32 v[112:113], v[112:113], v[160:161], v[234:235]
	v_pk_fma_f32 v[110:111], v[110:111], v[162:163], v[232:233]
	s_waitcnt vmcnt(8)
	v_pk_fma_f32 v[108:109], v[108:109], v[156:157], v[238:239]
	v_pk_fma_f32 v[106:107], v[106:107], v[158:159], v[236:237]
	v_cvt_pk_f16_f32 v164, v110, v111
	v_cvt_pk_f16_f32 v165, v112, v113
	v_cvt_pk_f16_f32 v166, v106, v107
	v_cvt_pk_f16_f32 v167, v108, v109
	global_store_dwordx4 v[172:173], v[164:167], off
	v_cvt_f32_f16_e32 v108, v164
	v_cvt_f32_f16_sdwa v109, v164 dst_sel:DWORD dst_unused:UNUSED_PAD src0_sel:WORD_1
	v_cvt_f32_f16_e32 v106, v165
	v_cvt_f32_f16_sdwa v107, v165 dst_sel:DWORD dst_unused:UNUSED_PAD src0_sel:WORD_1
	v_cvt_f32_f16_e32 v112, v166
	v_cvt_f32_f16_sdwa v113, v166 dst_sel:DWORD dst_unused:UNUSED_PAD src0_sel:WORD_1
	v_pk_mul_f32 v[164:165], v[108:109], v[108:109]
	v_cvt_f32_f16_e32 v110, v167
	v_cvt_f32_f16_sdwa v111, v167 dst_sel:DWORD dst_unused:UNUSED_PAD src0_sel:WORD_1
	v_pk_mul_f32 v[166:167], v[106:107], v[106:107]
	v_add_f32_e32 v145, v164, v165
	v_add_f32_e32 v145, v166, v145
	v_pk_mul_f32 v[172:173], v[112:113], v[112:113]
	v_add_f32_e32 v145, v167, v145
	v_add_f32_e32 v145, v172, v145
	v_pk_mul_f32 v[198:199], v[110:111], v[110:111]
	v_add_f32_e32 v145, v173, v145
	v_add_f32_e32 v145, v198, v145
	v_add_f32_e32 v145, v199, v145
	s_waitcnt vmcnt(8)
	v_pk_fma_f32 v[102:103], v[102:103], v[154:155], v[240:241]
	v_pk_fma_f32 v[104:105], v[104:105], v[152:153], v[242:243]
	v_cvt_pk_f16_f32 v166, v102, v103
	v_cvt_pk_f16_f32 v167, v104, v105
	v_cvt_f32_f16_e32 v104, v166
	v_cvt_f32_f16_sdwa v105, v166 dst_sel:DWORD dst_unused:UNUSED_PAD src0_sel:WORD_1
	s_waitcnt vmcnt(7)
	v_pk_fma_f32 v[100:101], v[100:101], v[148:149], v[246:247]
	v_pk_fma_f32 v[98:99], v[98:99], v[150:151], v[244:245]
	v_add_u32_e32 v248, 0x30000, v249
	global_load_dwordx4 v[232:235], v248, s[30:31]
	global_load_dwordx4 v[236:239], v248, s[30:31] offset:16
	global_load_dwordx4 v[240:243], v248, s[30:31] offset:512
	global_load_dwordx4 v[244:247], v248, s[30:31] offset:528
	v_cvt_pk_f16_f32 v169, v100, v101
	v_cvt_f32_f16_e32 v100, v167
	v_cvt_f32_f16_sdwa v101, v167 dst_sel:DWORD dst_unused:UNUSED_PAD src0_sel:WORD_1
	v_cvt_pk_f16_f32 v168, v98, v99
	v_cvt_f32_f16_e32 v102, v168
	v_cvt_f32_f16_sdwa v103, v168 dst_sel:DWORD dst_unused:UNUSED_PAD src0_sel:WORD_1
	v_pk_mul_f32 v[164:165], v[104:105], v[104:105]
	v_cvt_f32_f16_e32 v98, v169
	v_add_f32_e32 v145, v164, v145
	v_cvt_f32_f16_sdwa v99, v169 dst_sel:DWORD dst_unused:UNUSED_PAD src0_sel:WORD_1
	v_pk_mul_f32 v[170:171], v[100:101], v[100:101]
	v_add_f32_e32 v145, v165, v145
	v_add_f32_e32 v145, v170, v145
	v_pk_mul_f32 v[172:173], v[102:103], v[102:103]
	v_add_f32_e32 v145, v171, v145
	v_add_f32_e32 v145, v172, v145
	v_pk_mul_f32 v[204:205], v[98:99], v[98:99]
	v_add_f32_e32 v145, v173, v145
	v_add_f32_e32 v145, v204, v145
	v_add_f32_e32 v145, v205, v145
	ds_bpermute_b32 v164, v176, v145
	v_lshl_add_u64 v[170:171], v[196:197], 1, s[68:69]
	global_store_dwordx4 v[170:171], v[166:169], off
	s_waitcnt lgkmcnt(0)
	v_add_f32_e32 v145, v145, v164
	ds_bpermute_b32 v164, v177, v145
	s_and_saveexec_b64 s[26:27], s[4:5]
	s_cbranch_execz .LBB0_638
	s_waitcnt lgkmcnt(0)
	v_add_f32_e32 v145, v145, v164
	v_add_u32_e32 v164, s95, v178
	ds_write_b32 v164, v145 offset:256
; __device__ __forceinline__ float shx(float v, int m, int lane) { return __int_as_float(__builtin_amdgcn_ds_bpermute((lane ^ m) << 2, __float_as_int(v))); }
;     __device__ __forceinline__ void operator()(const f32x4 (&acc)[2][2][4][2], const Unit& u, int wr, int wc, int fr, int fq) const {
;     ...
;             for (int m = 0; m < 4; ++m) {
;                 float sq = 0.f;
; #pragma unroll
;                 for (int bj = 0; bj < 2; ++bj) {
;                     const unsigned off = (unsigned)(row0 + ai * HALF + m * 16) * DM + col0 + bj * HALF;
;                     f32x4 xa, xb;
;                     if (F32IN) { xa = *(const f32x4*)(in32 + off); xb = *(const f32x4*)(in32 + off + 4); }
;                     else { const h16x8 xv = *(const h16x8*)(in16 + off); xa = (f32x4){(float)xv[0], (float)xv[1], (float)xv[2], (float)xv[3]}; xb = (f32x4){(float)xv[4], (float)xv[5], (float)xv[6], (float)xv[7]}; }
;                     h16x8 o;
; #pragma unroll
;                     for (int j = 0; j < 4; ++j) { o[j] = (h16)(xa[j] + gv[bj][0][j] * acc[ai][bj][m][0][j]); o[4 + j] = (h16)(xb[j] + gv[bj][1][j] * acc[ai][bj][m][1][j]); }
;                     if (!FINAL) *(h16x8*)(out + off) = o;
;                     ov[ai][m][bj] = o;
; #pragma unroll
;                     for (int j = 0; j < 8; ++j) sq += (float)o[j] * (float)o[j];
;                 }
;                 sq += shx(sq, 16, lane); sq += shx(sq, 32, lane);
;                 if (fq == 0) red[(ai * HALF + wr * 64 + m * 16 + fr) * 4 + wc] = sq;
.LBB0_638:
	s_or_b64 exec, exec, s[26:27]
	v_readlane_b32 s36, v253, 16
	v_add_u32_e32 v172, 0x8000, v32
	v_mov_b32_e32 v173, v33
	v_readlane_b32 s37, v253, 17
	v_readlane_b32 s56, v253, 0
	v_readlane_b32 s68, v253, 12
	v_lshl_add_u64 v[168:169], v[172:173], 2, s[36:37]
	s_waitcnt lgkmcnt(0)
	s_nop 0
	v_readlane_b32 s69, v253, 13
	v_add_u32_e32 v196, 0x8080, v32
	v_mov_b32_e32 v197, v33
	v_lshl_add_u64 v[172:173], v[172:173], 1, s[68:69]
	v_lshl_add_u64 v[198:199], v[196:197], 2, s[36:37]
	v_readlane_b32 s38, v253, 18
	v_readlane_b32 s39, v253, 19
	v_readlane_b32 s40, v253, 20
	v_readlane_b32 s41, v253, 21
	v_readlane_b32 s42, v253, 22
	v_readlane_b32 s43, v253, 23
	v_readlane_b32 s44, v253, 24
	v_readlane_b32 s45, v253, 25
	v_readlane_b32 s46, v253, 26
	v_readlane_b32 s47, v253, 27
	v_readlane_b32 s48, v253, 28
	v_readlane_b32 s49, v253, 29
	v_readlane_b32 s50, v253, 30
	v_readlane_b32 s51, v253, 31
	v_readlane_b32 s57, v253, 1
	v_readlane_b32 s58, v253, 2
	v_readlane_b32 s59, v253, 3
	v_readlane_b32 s60, v253, 4
	v_readlane_b32 s61, v253, 5
	v_readlane_b32 s62, v253, 6
	v_readlane_b32 s63, v253, 7
	v_readlane_b32 s64, v253, 8
	v_readlane_b32 s65, v253, 9
	v_readlane_b32 s66, v253, 10
	v_readlane_b32 s67, v253, 11
	v_readlane_b32 s70, v253, 14
	v_readlane_b32 s71, v253, 15
	s_waitcnt vmcnt(10)
	v_pk_fma_f32 v[96:97], v[96:97], v[160:161], v[218:219]
	v_pk_fma_f32 v[94:95], v[94:95], v[162:163], v[216:217]
	s_waitcnt vmcnt(9)
	v_pk_fma_f32 v[92:93], v[92:93], v[156:157], v[222:223]
	v_pk_fma_f32 v[90:91], v[90:91], v[158:159], v[220:221]
	v_cvt_pk_f16_f32 v164, v94, v95
	v_cvt_pk_f16_f32 v165, v96, v97
	v_cvt_pk_f16_f32 v166, v90, v91
	v_cvt_pk_f16_f32 v167, v92, v93
	global_store_dwordx4 v[172:173], v[164:167], off
	v_cvt_f32_f16_e32 v92, v164
	v_cvt_f32_f16_sdwa v93, v164 dst_sel:DWORD dst_unused:UNUSED_PAD src0_sel:WORD_1
	v_cvt_f32_f16_e32 v90, v165
	v_cvt_f32_f16_sdwa v91, v165 dst_sel:DWORD dst_unused:UNUSED_PAD src0_sel:WORD_1
	v_cvt_f32_f16_e32 v96, v166
	v_cvt_f32_f16_sdwa v97, v166 dst_sel:DWORD dst_unused:UNUSED_PAD src0_sel:WORD_1
	v_pk_mul_f32 v[164:165], v[92:93], v[92:93]
	v_cvt_f32_f16_e32 v94, v167
	v_cvt_f32_f16_sdwa v95, v167 dst_sel:DWORD dst_unused:UNUSED_PAD src0_sel:WORD_1
	v_pk_mul_f32 v[166:167], v[90:91], v[90:91]
	v_add_f32_e32 v145, v164, v165
	v_add_f32_e32 v145, v166, v145
	v_pk_mul_f32 v[172:173], v[96:97], v[96:97]
	v_add_f32_e32 v145, v167, v145
	v_add_f32_e32 v145, v172, v145
	v_pk_mul_f32 v[198:199], v[94:95], v[94:95]
	v_add_f32_e32 v145, v173, v145
	v_add_f32_e32 v145, v198, v145
	v_add_f32_e32 v145, v199, v145
	s_waitcnt vmcnt(9)
	v_pk_fma_f32 v[86:87], v[86:87], v[154:155], v[224:225]
	v_pk_fma_f32 v[88:89], v[88:89], v[152:153], v[226:227]
	v_cvt_pk_f16_f32 v166, v86, v87
	v_cvt_pk_f16_f32 v167, v88, v89
	v_cvt_f32_f16_e32 v88, v166
	v_cvt_f32_f16_sdwa v89, v166 dst_sel:DWORD dst_unused:UNUSED_PAD src0_sel:WORD_1
	s_waitcnt vmcnt(8)
	v_pk_fma_f32 v[84:85], v[84:85], v[148:149], v[230:231]
	v_pk_fma_f32 v[82:83], v[82:83], v[150:151], v[228:229]
	v_add_u32_e32 v248, 0x80000, v249
	global_load_dwordx4 v[216:219], v248, s[30:31]
	global_load_dwordx4 v[220:223], v248, s[30:31] offset:16
	global_load_dwordx4 v[224:227], v248, s[30:31] offset:512
	global_load_dwordx4 v[228:231], v248, s[30:31] offset:528
	v_cvt_pk_f16_f32 v169, v84, v85
	v_cvt_f32_f16_e32 v84, v167
	v_cvt_f32_f16_sdwa v85, v167 dst_sel:DWORD dst_unused:UNUSED_PAD src0_sel:WORD_1
	v_cvt_pk_f16_f32 v168, v82, v83
	v_cvt_f32_f16_e32 v86, v168
	v_cvt_f32_f16_sdwa v87, v168 dst_sel:DWORD dst_unused:UNUSED_PAD src0_sel:WORD_1
	v_pk_mul_f32 v[164:165], v[88:89], v[88:89]
	v_cvt_f32_f16_e32 v82, v169
	v_add_f32_e32 v145, v164, v145
	v_cvt_f32_f16_sdwa v83, v169 dst_sel:DWORD dst_unused:UNUSED_PAD src0_sel:WORD_1
	v_pk_mul_f32 v[170:171], v[84:85], v[84:85]
	v_add_f32_e32 v145, v165, v145
	v_add_f32_e32 v145, v170, v145
	v_pk_mul_f32 v[172:173], v[86:87], v[86:87]
	v_add_f32_e32 v145, v171, v145
	v_add_f32_e32 v145, v172, v145
	v_pk_mul_f32 v[204:205], v[82:83], v[82:83]
	v_add_f32_e32 v145, v173, v145
	v_add_f32_e32 v145, v204, v145
	v_add_f32_e32 v145, v205, v145
	ds_bpermute_b32 v164, v176, v145
	v_lshl_add_u64 v[170:171], v[196:197], 1, s[68:69]
	global_store_dwordx4 v[170:171], v[166:169], off
	s_waitcnt lgkmcnt(0)
	v_add_f32_e32 v145, v145, v164
	ds_bpermute_b32 v164, v177, v145
	s_and_saveexec_b64 s[26:27], s[4:5]
	s_cbranch_execz .LBB0_640
	s_waitcnt lgkmcnt(0)
	v_add_f32_e32 v145, v145, v164
	v_add_u32_e32 v164, s95, v178
	ds_write_b32 v164, v145 offset:512
; __device__ __forceinline__ float shx(float v, int m, int lane) { return __int_as_float(__builtin_amdgcn_ds_bpermute((lane ^ m) << 2, __float_as_int(v))); }
;     __device__ __forceinline__ void operator()(const f32x4 (&acc)[2][2][4][2], const Unit& u, int wr, int wc, int fr, int fq) const {
;     ...
;             for (int m = 0; m < 4; ++m) {
;                 float sq = 0.f;
; #pragma unroll
;                 for (int bj = 0; bj < 2; ++bj) {
;                     const unsigned off = (unsigned)(row0 + ai * HALF + m * 16) * DM + col0 + bj * HALF;
;                     f32x4 xa, xb;
;                     if (F32IN) { xa = *(const f32x4*)(in32 + off); xb = *(const f32x4*)(in32 + off + 4); }
;                     else { const h16x8 xv = *(const h16x8*)(in16 + off); xa = (f32x4){(float)xv[0], (float)xv[1], (float)xv[2], (float)xv[3]}; xb = (f32x4){(float)xv[4], (float)xv[5], (float)xv[6], (float)xv[7]}; }
;                     h16x8 o;
; #pragma unroll
;                     for (int j = 0; j < 4; ++j) { o[j] = (h16)(xa[j] + gv[bj][0][j] * acc[ai][bj][m][0][j]); o[4 + j] = (h16)(xb[j] + gv[bj][1][j] * acc[ai][bj][m][1][j]); }
;                     if (!FINAL) *(h16x8*)(out + off) = o;
;                     ov[ai][m][bj] = o;
; #pragma unroll
;                     for (int j = 0; j < 8; ++j) sq += (float)o[j] * (float)o[j];
;                 }
;                 sq += shx(sq, 16, lane); sq += shx(sq, 32, lane);
;                 if (fq == 0) red[(ai * HALF + wr * 64 + m * 16 + fr) * 4 + wc] = sq;
.LBB0_640:
	s_or_b64 exec, exec, s[26:27]
	v_readlane_b32 s36, v253, 16
	v_add_u32_e32 v172, 0xc000, v32
	v_mov_b32_e32 v173, v33
	v_readlane_b32 s37, v253, 17
	v_readlane_b32 s56, v253, 0
	v_readlane_b32 s68, v253, 12
	v_lshl_add_u64 v[168:169], v[172:173], 2, s[36:37]
	s_waitcnt lgkmcnt(0)
	s_nop 0
	v_readlane_b32 s69, v253, 13
	v_add_u32_e32 v196, 0xc080, v32
	v_mov_b32_e32 v197, v33
	v_lshl_add_u64 v[172:173], v[172:173], 1, s[68:69]
	v_lshl_add_u64 v[198:199], v[196:197], 2, s[36:37]
	v_readlane_b32 s38, v253, 18
	v_readlane_b32 s39, v253, 19
	v_readlane_b32 s40, v253, 20
	v_readlane_b32 s41, v253, 21
	v_readlane_b32 s42, v253, 22
	v_readlane_b32 s43, v253, 23
	v_readlane_b32 s44, v253, 24
	v_readlane_b32 s45, v253, 25
	v_readlane_b32 s46, v253, 26
	v_readlane_b32 s47, v253, 27
	v_readlane_b32 s48, v253, 28
	v_readlane_b32 s49, v253, 29
	v_readlane_b32 s50, v253, 30
	v_readlane_b32 s51, v253, 31
	v_readlane_b32 s57, v253, 1
	v_readlane_b32 s58, v253, 2
	v_readlane_b32 s59, v253, 3
	v_readlane_b32 s60, v253, 4
	v_readlane_b32 s61, v253, 5
	v_readlane_b32 s62, v253, 6
	v_readlane_b32 s63, v253, 7
	v_readlane_b32 s64, v253, 8
	v_readlane_b32 s65, v253, 9
	v_readlane_b32 s66, v253, 10
	v_readlane_b32 s67, v253, 11
	v_readlane_b32 s70, v253, 14
	v_readlane_b32 s71, v253, 15
	s_waitcnt vmcnt(10)
	v_pk_fma_f32 v[80:81], v[80:81], v[160:161], v[234:235]
	v_pk_fma_f32 v[78:79], v[78:79], v[162:163], v[232:233]
	s_waitcnt vmcnt(9)
	v_pk_fma_f32 v[76:77], v[76:77], v[156:157], v[238:239]
	v_pk_fma_f32 v[74:75], v[74:75], v[158:159], v[236:237]
	v_cvt_pk_f16_f32 v164, v78, v79
	v_cvt_pk_f16_f32 v165, v80, v81
	v_cvt_pk_f16_f32 v166, v74, v75
	v_cvt_pk_f16_f32 v167, v76, v77
	global_store_dwordx4 v[172:173], v[164:167], off
	v_cvt_f32_f16_e32 v76, v164
	v_cvt_f32_f16_sdwa v77, v164 dst_sel:DWORD dst_unused:UNUSED_PAD src0_sel:WORD_1
	v_cvt_f32_f16_e32 v74, v165
	v_cvt_f32_f16_sdwa v75, v165 dst_sel:DWORD dst_unused:UNUSED_PAD src0_sel:WORD_1
	v_cvt_f32_f16_e32 v80, v166
	v_cvt_f32_f16_sdwa v81, v166 dst_sel:DWORD dst_unused:UNUSED_PAD src0_sel:WORD_1
	v_pk_mul_f32 v[164:165], v[76:77], v[76:77]
	v_cvt_f32_f16_e32 v78, v167
	v_cvt_f32_f16_sdwa v79, v167 dst_sel:DWORD dst_unused:UNUSED_PAD src0_sel:WORD_1
	v_pk_mul_f32 v[166:167], v[74:75], v[74:75]
	v_add_f32_e32 v145, v164, v165
	v_add_f32_e32 v145, v166, v145
	v_pk_mul_f32 v[172:173], v[80:81], v[80:81]
	v_add_f32_e32 v145, v167, v145
	v_add_f32_e32 v145, v172, v145
	v_pk_mul_f32 v[198:199], v[78:79], v[78:79]
	v_add_f32_e32 v145, v173, v145
	v_add_f32_e32 v145, v198, v145
	v_add_f32_e32 v145, v199, v145
	s_waitcnt vmcnt(9)
	v_pk_fma_f32 v[70:71], v[70:71], v[154:155], v[240:241]
	v_pk_fma_f32 v[72:73], v[72:73], v[152:153], v[242:243]
	v_cvt_pk_f16_f32 v166, v70, v71
	v_cvt_pk_f16_f32 v167, v72, v73
	v_cvt_f32_f16_e32 v72, v166
	v_cvt_f32_f16_sdwa v73, v166 dst_sel:DWORD dst_unused:UNUSED_PAD src0_sel:WORD_1
	s_waitcnt vmcnt(8)
	v_pk_fma_f32 v[68:69], v[68:69], v[148:149], v[246:247]
	v_pk_fma_f32 v[66:67], v[66:67], v[150:151], v[244:245]
	v_add_u32_e32 v248, 0x90000, v249
	global_load_dwordx4 v[232:235], v248, s[30:31]
	global_load_dwordx4 v[236:239], v248, s[30:31] offset:16
	global_load_dwordx4 v[240:243], v248, s[30:31] offset:512
	global_load_dwordx4 v[244:247], v248, s[30:31] offset:528
	v_cvt_pk_f16_f32 v169, v68, v69
	v_cvt_f32_f16_e32 v68, v167
	v_cvt_f32_f16_sdwa v69, v167 dst_sel:DWORD dst_unused:UNUSED_PAD src0_sel:WORD_1
	v_cvt_pk_f16_f32 v168, v66, v67
	v_cvt_f32_f16_e32 v70, v168
	v_cvt_f32_f16_sdwa v71, v168 dst_sel:DWORD dst_unused:UNUSED_PAD src0_sel:WORD_1
	v_pk_mul_f32 v[164:165], v[72:73], v[72:73]
	v_cvt_f32_f16_e32 v66, v169
	v_add_f32_e32 v145, v164, v145
	v_cvt_f32_f16_sdwa v67, v169 dst_sel:DWORD dst_unused:UNUSED_PAD src0_sel:WORD_1
	v_pk_mul_f32 v[170:171], v[68:69], v[68:69]
	v_add_f32_e32 v145, v165, v145
	v_add_f32_e32 v145, v170, v145
	v_pk_mul_f32 v[172:173], v[70:71], v[70:71]
	v_add_f32_e32 v145, v171, v145
	v_add_f32_e32 v145, v172, v145
	v_pk_mul_f32 v[204:205], v[66:67], v[66:67]
	v_add_f32_e32 v145, v173, v145
	v_add_f32_e32 v145, v204, v145
	v_add_f32_e32 v145, v205, v145
	ds_bpermute_b32 v164, v176, v145
	v_lshl_add_u64 v[170:171], v[196:197], 1, s[68:69]
	global_store_dwordx4 v[170:171], v[166:169], off
	s_waitcnt lgkmcnt(0)
	v_add_f32_e32 v145, v145, v164
	ds_bpermute_b32 v164, v177, v145
	s_and_saveexec_b64 s[26:27], s[4:5]
	s_cbranch_execz .LBB0_642
	s_waitcnt lgkmcnt(0)
	v_add_f32_e32 v145, v145, v164
	v_add_u32_e32 v164, s95, v178
	ds_write_b32 v164, v145 offset:768
; __device__ __forceinline__ float shx(float v, int m, int lane) { return __int_as_float(__builtin_amdgcn_ds_bpermute((lane ^ m) << 2, __float_as_int(v))); }
;     __device__ __forceinline__ void operator()(const f32x4 (&acc)[2][2][4][2], const Unit& u, int wr, int wc, int fr, int fq) const {
;     ...
;             for (int m = 0; m < 4; ++m) {
;                 float sq = 0.f;
; #pragma unroll
;                 for (int bj = 0; bj < 2; ++bj) {
;                     const unsigned off = (unsigned)(row0 + ai * HALF + m * 16) * DM + col0 + bj * HALF;
;                     f32x4 xa, xb;
;                     if (F32IN) { xa = *(const f32x4*)(in32 + off); xb = *(const f32x4*)(in32 + off + 4); }
;                     else { const h16x8 xv = *(const h16x8*)(in16 + off); xa = (f32x4){(float)xv[0], (float)xv[1], (float)xv[2], (float)xv[3]}; xb = (f32x4){(float)xv[4], (float)xv[5], (float)xv[6], (float)xv[7]}; }
;                     h16x8 o;
; #pragma unroll
;                     for (int j = 0; j < 4; ++j) { o[j] = (h16)(xa[j] + gv[bj][0][j] * acc[ai][bj][m][0][j]); o[4 + j] = (h16)(xb[j] + gv[bj][1][j] * acc[ai][bj][m][1][j]); }
;                     if (!FINAL) *(h16x8*)(out + off) = o;
;                     ov[ai][m][bj] = o;
; #pragma unroll
;                     for (int j = 0; j < 8; ++j) sq += (float)o[j] * (float)o[j];
;                 }
;                 sq += shx(sq, 16, lane); sq += shx(sq, 32, lane);
;                 if (fq == 0) red[(ai * HALF + wr * 64 + m * 16 + fr) * 4 + wc] = sq;
.LBB0_642:
	s_or_b64 exec, exec, s[26:27]
	v_readlane_b32 s36, v253, 16
	v_add_u32_e32 v172, 0x20000, v32
	v_mov_b32_e32 v173, v33
	v_readlane_b32 s37, v253, 17
	v_readlane_b32 s56, v253, 0
	v_readlane_b32 s68, v253, 12
	v_lshl_add_u64 v[168:169], v[172:173], 2, s[36:37]
	s_waitcnt lgkmcnt(0)
	s_nop 0
	v_readlane_b32 s69, v253, 13
	v_add_u32_e32 v196, 0x20080, v32
	v_mov_b32_e32 v197, v33
	v_lshl_add_u64 v[172:173], v[172:173], 1, s[68:69]
	v_lshl_add_u64 v[198:199], v[196:197], 2, s[36:37]
	v_readlane_b32 s38, v253, 18
	v_readlane_b32 s39, v253, 19
	v_readlane_b32 s40, v253, 20
	v_readlane_b32 s41, v253, 21
	v_readlane_b32 s42, v253, 22
	v_readlane_b32 s43, v253, 23
	v_readlane_b32 s44, v253, 24
	v_readlane_b32 s45, v253, 25
	v_readlane_b32 s46, v253, 26
	v_readlane_b32 s47, v253, 27
	v_readlane_b32 s48, v253, 28
	v_readlane_b32 s49, v253, 29
	v_readlane_b32 s50, v253, 30
	v_readlane_b32 s51, v253, 31
	v_readlane_b32 s57, v253, 1
	v_readlane_b32 s58, v253, 2
	v_readlane_b32 s59, v253, 3
	v_readlane_b32 s60, v253, 4
	v_readlane_b32 s61, v253, 5
	v_readlane_b32 s62, v253, 6
	v_readlane_b32 s63, v253, 7
	v_readlane_b32 s64, v253, 8
	v_readlane_b32 s65, v253, 9
	v_readlane_b32 s66, v253, 10
	v_readlane_b32 s67, v253, 11
	v_readlane_b32 s70, v253, 14
	v_readlane_b32 s71, v253, 15
	s_waitcnt vmcnt(10)
	v_pk_fma_f32 v[64:65], v[64:65], v[160:161], v[218:219]
	v_pk_fma_f32 v[62:63], v[62:63], v[162:163], v[216:217]
	s_waitcnt vmcnt(9)
	v_pk_fma_f32 v[60:61], v[60:61], v[156:157], v[222:223]
	v_pk_fma_f32 v[58:59], v[58:59], v[158:159], v[220:221]
	v_cvt_pk_f16_f32 v164, v62, v63
	v_cvt_pk_f16_f32 v165, v64, v65
	v_cvt_pk_f16_f32 v166, v58, v59
	v_cvt_pk_f16_f32 v167, v60, v61
	global_store_dwordx4 v[172:173], v[164:167], off
	v_cvt_f32_f16_e32 v60, v164
	v_cvt_f32_f16_sdwa v61, v164 dst_sel:DWORD dst_unused:UNUSED_PAD src0_sel:WORD_1
	v_cvt_f32_f16_e32 v58, v165
	v_cvt_f32_f16_sdwa v59, v165 dst_sel:DWORD dst_unused:UNUSED_PAD src0_sel:WORD_1
	v_cvt_f32_f16_e32 v64, v166
	v_cvt_f32_f16_sdwa v65, v166 dst_sel:DWORD dst_unused:UNUSED_PAD src0_sel:WORD_1
	v_pk_mul_f32 v[164:165], v[60:61], v[60:61]
	v_cvt_f32_f16_e32 v62, v167
	v_cvt_f32_f16_sdwa v63, v167 dst_sel:DWORD dst_unused:UNUSED_PAD src0_sel:WORD_1
	v_pk_mul_f32 v[166:167], v[58:59], v[58:59]
	v_add_f32_e32 v145, v164, v165
	v_add_f32_e32 v145, v166, v145
	v_pk_mul_f32 v[172:173], v[64:65], v[64:65]
	v_add_f32_e32 v145, v167, v145
	v_add_f32_e32 v145, v172, v145
	v_pk_mul_f32 v[198:199], v[62:63], v[62:63]
	v_add_f32_e32 v145, v173, v145
	v_add_f32_e32 v145, v198, v145
	v_add_f32_e32 v145, v199, v145
	s_waitcnt vmcnt(9)
	v_pk_fma_f32 v[54:55], v[54:55], v[154:155], v[224:225]
	v_pk_fma_f32 v[56:57], v[56:57], v[152:153], v[226:227]
	v_cvt_pk_f16_f32 v166, v54, v55
	v_cvt_pk_f16_f32 v167, v56, v57
	v_cvt_f32_f16_e32 v56, v166
	v_cvt_f32_f16_sdwa v57, v166 dst_sel:DWORD dst_unused:UNUSED_PAD src0_sel:WORD_1
	s_waitcnt vmcnt(8)
	v_pk_fma_f32 v[52:53], v[52:53], v[148:149], v[230:231]
	v_pk_fma_f32 v[50:51], v[50:51], v[150:151], v[228:229]
	v_add_u32_e32 v248, 0xa0000, v249
	global_load_dwordx4 v[216:219], v248, s[30:31]
	global_load_dwordx4 v[220:223], v248, s[30:31] offset:16
	global_load_dwordx4 v[224:227], v248, s[30:31] offset:512
	global_load_dwordx4 v[228:231], v248, s[30:31] offset:528
	v_cvt_pk_f16_f32 v169, v52, v53
	v_cvt_f32_f16_e32 v52, v167
	v_cvt_f32_f16_sdwa v53, v167 dst_sel:DWORD dst_unused:UNUSED_PAD src0_sel:WORD_1
	v_cvt_pk_f16_f32 v168, v50, v51
	v_cvt_f32_f16_e32 v54, v168
	v_cvt_f32_f16_sdwa v55, v168 dst_sel:DWORD dst_unused:UNUSED_PAD src0_sel:WORD_1
	v_pk_mul_f32 v[164:165], v[56:57], v[56:57]
	v_cvt_f32_f16_e32 v50, v169
	v_add_f32_e32 v145, v164, v145
	v_cvt_f32_f16_sdwa v51, v169 dst_sel:DWORD dst_unused:UNUSED_PAD src0_sel:WORD_1
	v_pk_mul_f32 v[170:171], v[52:53], v[52:53]
	v_add_f32_e32 v145, v165, v145
	v_add_f32_e32 v145, v170, v145
	v_pk_mul_f32 v[172:173], v[54:55], v[54:55]
	v_add_f32_e32 v145, v171, v145
	v_add_f32_e32 v145, v172, v145
	v_pk_mul_f32 v[204:205], v[50:51], v[50:51]
	v_add_f32_e32 v145, v173, v145
	v_add_f32_e32 v145, v204, v145
	v_add_f32_e32 v145, v205, v145
	ds_bpermute_b32 v164, v176, v145
	v_lshl_add_u64 v[170:171], v[196:197], 1, s[68:69]
	global_store_dwordx4 v[170:171], v[166:169], off
	s_waitcnt lgkmcnt(0)
	v_add_f32_e32 v145, v145, v164
	ds_bpermute_b32 v164, v177, v145
	s_and_saveexec_b64 s[26:27], s[4:5]
	s_cbranch_execz .LBB0_644
	s_waitcnt lgkmcnt(0)
	v_add_f32_e32 v145, v145, v164
	v_add_u32_e32 v164, s95, v178
	ds_write_b32 v164, v145 offset:2048
; __device__ __forceinline__ float shx(float v, int m, int lane) { return __int_as_float(__builtin_amdgcn_ds_bpermute((lane ^ m) << 2, __float_as_int(v))); }
;     __device__ __forceinline__ void operator()(const f32x4 (&acc)[2][2][4][2], const Unit& u, int wr, int wc, int fr, int fq) const {
;     ...
;             for (int m = 0; m < 4; ++m) {
;                 float sq = 0.f;
; #pragma unroll
;                 for (int bj = 0; bj < 2; ++bj) {
;                     const unsigned off = (unsigned)(row0 + ai * HALF + m * 16) * DM + col0 + bj * HALF;
;                     f32x4 xa, xb;
;                     if (F32IN) { xa = *(const f32x4*)(in32 + off); xb = *(const f32x4*)(in32 + off + 4); }
;                     else { const h16x8 xv = *(const h16x8*)(in16 + off); xa = (f32x4){(float)xv[0], (float)xv[1], (float)xv[2], (float)xv[3]}; xb = (f32x4){(float)xv[4], (float)xv[5], (float)xv[6], (float)xv[7]}; }
;                     h16x8 o;
; #pragma unroll
;                     for (int j = 0; j < 4; ++j) { o[j] = (h16)(xa[j] + gv[bj][0][j] * acc[ai][bj][m][0][j]); o[4 + j] = (h16)(xb[j] + gv[bj][1][j] * acc[ai][bj][m][1][j]); }
;                     if (!FINAL) *(h16x8*)(out + off) = o;
;                     ov[ai][m][bj] = o;
; #pragma unroll
;                     for (int j = 0; j < 8; ++j) sq += (float)o[j] * (float)o[j];
;                 }
;                 sq += shx(sq, 16, lane); sq += shx(sq, 32, lane);
;                 if (fq == 0) red[(ai * HALF + wr * 64 + m * 16 + fr) * 4 + wc] = sq;
.LBB0_644:
	s_or_b64 exec, exec, s[26:27]
	v_readlane_b32 s36, v253, 16
	v_add_u32_e32 v172, 0x24000, v32
	v_mov_b32_e32 v173, v33
	v_readlane_b32 s37, v253, 17
	v_readlane_b32 s56, v253, 0
	v_readlane_b32 s68, v253, 12
	v_lshl_add_u64 v[168:169], v[172:173], 2, s[36:37]
	s_waitcnt lgkmcnt(0)
	s_nop 0
	v_readlane_b32 s69, v253, 13
	v_add_u32_e32 v196, 0x24080, v32
	v_mov_b32_e32 v197, v33
	v_lshl_add_u64 v[172:173], v[172:173], 1, s[68:69]
	v_lshl_add_u64 v[198:199], v[196:197], 2, s[36:37]
	v_readlane_b32 s38, v253, 18
	v_readlane_b32 s39, v253, 19
	v_readlane_b32 s40, v253, 20
	v_readlane_b32 s41, v253, 21
	v_readlane_b32 s42, v253, 22
	v_readlane_b32 s43, v253, 23
	v_readlane_b32 s44, v253, 24
	v_readlane_b32 s45, v253, 25
	v_readlane_b32 s46, v253, 26
	v_readlane_b32 s47, v253, 27
	v_readlane_b32 s48, v253, 28
	v_readlane_b32 s49, v253, 29
	v_readlane_b32 s50, v253, 30
	v_readlane_b32 s51, v253, 31
	v_readlane_b32 s57, v253, 1
	v_readlane_b32 s58, v253, 2
	v_readlane_b32 s59, v253, 3
	v_readlane_b32 s60, v253, 4
	v_readlane_b32 s61, v253, 5
	v_readlane_b32 s62, v253, 6
	v_readlane_b32 s63, v253, 7
	v_readlane_b32 s64, v253, 8
	v_readlane_b32 s65, v253, 9
	v_readlane_b32 s66, v253, 10
	v_readlane_b32 s67, v253, 11
	v_readlane_b32 s70, v253, 14
	v_readlane_b32 s71, v253, 15
	s_waitcnt vmcnt(10)
	v_pk_fma_f32 v[48:49], v[48:49], v[160:161], v[234:235]
	v_pk_fma_f32 v[46:47], v[46:47], v[162:163], v[232:233]
	s_waitcnt vmcnt(9)
	v_pk_fma_f32 v[44:45], v[44:45], v[156:157], v[238:239]
	v_pk_fma_f32 v[42:43], v[42:43], v[158:159], v[236:237]
	v_cvt_pk_f16_f32 v164, v46, v47
	v_cvt_pk_f16_f32 v165, v48, v49
	v_cvt_pk_f16_f32 v166, v42, v43
	v_cvt_pk_f16_f32 v167, v44, v45
	global_store_dwordx4 v[172:173], v[164:167], off
	v_cvt_f32_f16_e32 v48, v164
	v_cvt_f32_f16_sdwa v49, v164 dst_sel:DWORD dst_unused:UNUSED_PAD src0_sel:WORD_1
	v_cvt_f32_f16_e32 v44, v165
	v_cvt_f32_f16_sdwa v45, v165 dst_sel:DWORD dst_unused:UNUSED_PAD src0_sel:WORD_1
	v_cvt_f32_f16_e32 v46, v166
	v_cvt_f32_f16_sdwa v47, v166 dst_sel:DWORD dst_unused:UNUSED_PAD src0_sel:WORD_1
	v_pk_mul_f32 v[164:165], v[48:49], v[48:49]
	v_cvt_f32_f16_e32 v42, v167
	v_cvt_f32_f16_sdwa v43, v167 dst_sel:DWORD dst_unused:UNUSED_PAD src0_sel:WORD_1
	v_pk_mul_f32 v[166:167], v[44:45], v[44:45]
	v_add_f32_e32 v145, v164, v165
	v_add_f32_e32 v145, v166, v145
	v_pk_mul_f32 v[172:173], v[46:47], v[46:47]
	v_add_f32_e32 v145, v167, v145
	v_add_f32_e32 v145, v172, v145
	v_pk_mul_f32 v[198:199], v[42:43], v[42:43]
	v_add_f32_e32 v145, v173, v145
	v_add_f32_e32 v145, v198, v145
	v_add_f32_e32 v145, v199, v145
	s_waitcnt vmcnt(9)
	v_pk_fma_f32 v[38:39], v[38:39], v[154:155], v[240:241]
	v_pk_fma_f32 v[40:41], v[40:41], v[152:153], v[242:243]
	v_cvt_pk_f16_f32 v166, v38, v39
	v_cvt_pk_f16_f32 v167, v40, v41
	v_cvt_f32_f16_e32 v40, v166
	v_cvt_f32_f16_sdwa v41, v166 dst_sel:DWORD dst_unused:UNUSED_PAD src0_sel:WORD_1
	s_waitcnt vmcnt(8)
	v_pk_fma_f32 v[36:37], v[36:37], v[148:149], v[246:247]
	v_pk_fma_f32 v[34:35], v[34:35], v[150:151], v[244:245]
	v_add_u32_e32 v248, 0xb0000, v249
	global_load_dwordx4 v[232:235], v248, s[30:31]
	global_load_dwordx4 v[236:239], v248, s[30:31] offset:16
	global_load_dwordx4 v[240:243], v248, s[30:31] offset:512
	global_load_dwordx4 v[244:247], v248, s[30:31] offset:528
	v_cvt_pk_f16_f32 v169, v36, v37
	v_cvt_f32_f16_e32 v36, v167
	v_cvt_f32_f16_sdwa v37, v167 dst_sel:DWORD dst_unused:UNUSED_PAD src0_sel:WORD_1
	v_cvt_pk_f16_f32 v168, v34, v35
	v_cvt_f32_f16_e32 v38, v168
	v_cvt_f32_f16_sdwa v39, v168 dst_sel:DWORD dst_unused:UNUSED_PAD src0_sel:WORD_1
	v_pk_mul_f32 v[164:165], v[40:41], v[40:41]
	v_cvt_f32_f16_e32 v34, v169
	v_add_f32_e32 v145, v164, v145
	v_cvt_f32_f16_sdwa v35, v169 dst_sel:DWORD dst_unused:UNUSED_PAD src0_sel:WORD_1
	v_pk_mul_f32 v[170:171], v[36:37], v[36:37]
	v_add_f32_e32 v145, v165, v145
	v_add_f32_e32 v145, v170, v145
	v_pk_mul_f32 v[172:173], v[38:39], v[38:39]
	v_add_f32_e32 v145, v171, v145
	v_add_f32_e32 v145, v172, v145
	v_pk_mul_f32 v[204:205], v[34:35], v[34:35]
	v_add_f32_e32 v145, v173, v145
	v_add_f32_e32 v145, v204, v145
	v_add_f32_e32 v145, v205, v145
	ds_bpermute_b32 v164, v176, v145
	v_lshl_add_u64 v[170:171], v[196:197], 1, s[68:69]
	global_store_dwordx4 v[170:171], v[166:169], off
	s_waitcnt lgkmcnt(0)
	v_add_f32_e32 v145, v145, v164
	ds_bpermute_b32 v164, v177, v145
	s_and_saveexec_b64 s[26:27], s[4:5]
	s_cbranch_execz .LBB0_646
	s_waitcnt lgkmcnt(0)
	v_add_f32_e32 v145, v145, v164
	v_add_u32_e32 v164, s95, v178
	ds_write_b32 v164, v145 offset:2304
; __device__ __forceinline__ float shx(float v, int m, int lane) { return __int_as_float(__builtin_amdgcn_ds_bpermute((lane ^ m) << 2, __float_as_int(v))); }
;     __device__ __forceinline__ void operator()(const f32x4 (&acc)[2][2][4][2], const Unit& u, int wr, int wc, int fr, int fq) const {
;     ...
;             for (int m = 0; m < 4; ++m) {
;                 float sq = 0.f;
; #pragma unroll
;                 for (int bj = 0; bj < 2; ++bj) {
;                     const unsigned off = (unsigned)(row0 + ai * HALF + m * 16) * DM + col0 + bj * HALF;
;                     f32x4 xa, xb;
;                     if (F32IN) { xa = *(const f32x4*)(in32 + off); xb = *(const f32x4*)(in32 + off + 4); }
;                     else { const h16x8 xv = *(const h16x8*)(in16 + off); xa = (f32x4){(float)xv[0], (float)xv[1], (float)xv[2], (float)xv[3]}; xb = (f32x4){(float)xv[4], (float)xv[5], (float)xv[6], (float)xv[7]}; }
;                     h16x8 o;
; #pragma unroll
;                     for (int j = 0; j < 4; ++j) { o[j] = (h16)(xa[j] + gv[bj][0][j] * acc[ai][bj][m][0][j]); o[4 + j] = (h16)(xb[j] + gv[bj][1][j] * acc[ai][bj][m][1][j]); }
;                     if (!FINAL) *(h16x8*)(out + off) = o;
;                     ov[ai][m][bj] = o;
; #pragma unroll
;                     for (int j = 0; j < 8; ++j) sq += (float)o[j] * (float)o[j];
;                 }
;                 sq += shx(sq, 16, lane); sq += shx(sq, 32, lane);
;                 if (fq == 0) red[(ai * HALF + wr * 64 + m * 16 + fr) * 4 + wc] = sq;
.LBB0_646:
	s_or_b64 exec, exec, s[26:27]
	v_readlane_b32 s36, v253, 16
	v_add_u32_e32 v172, 0x28000, v32
	v_mov_b32_e32 v173, v33
	v_readlane_b32 s37, v253, 17
	v_readlane_b32 s56, v253, 0
	v_readlane_b32 s68, v253, 12
	v_lshl_add_u64 v[168:169], v[172:173], 2, s[36:37]
	s_waitcnt lgkmcnt(0)
	s_nop 0
	v_readlane_b32 s69, v253, 13
	v_add_u32_e32 v196, 0x28080, v32
	v_mov_b32_e32 v197, v33
	v_lshl_add_u64 v[172:173], v[172:173], 1, s[68:69]
	v_lshl_add_u64 v[198:199], v[196:197], 2, s[36:37]
	v_readlane_b32 s38, v253, 18
	v_readlane_b32 s39, v253, 19
	v_readlane_b32 s40, v253, 20
	v_readlane_b32 s41, v253, 21
	v_readlane_b32 s42, v253, 22
	v_readlane_b32 s43, v253, 23
	v_readlane_b32 s44, v253, 24
	v_readlane_b32 s45, v253, 25
	v_readlane_b32 s46, v253, 26
	v_readlane_b32 s47, v253, 27
	v_readlane_b32 s48, v253, 28
	v_readlane_b32 s49, v253, 29
	v_readlane_b32 s50, v253, 30
	v_readlane_b32 s51, v253, 31
	v_readlane_b32 s57, v253, 1
	v_readlane_b32 s58, v253, 2
	v_readlane_b32 s59, v253, 3
	v_readlane_b32 s60, v253, 4
	v_readlane_b32 s61, v253, 5
	v_readlane_b32 s62, v253, 6
	v_readlane_b32 s63, v253, 7
	v_readlane_b32 s64, v253, 8
	v_readlane_b32 s65, v253, 9
	v_readlane_b32 s66, v253, 10
	v_readlane_b32 s67, v253, 11
	v_readlane_b32 s70, v253, 14
	v_readlane_b32 s71, v253, 15
	s_waitcnt vmcnt(10)
	v_pk_fma_f32 v[30:31], v[30:31], v[160:161], v[218:219]
	v_pk_fma_f32 v[28:29], v[28:29], v[162:163], v[216:217]
	s_waitcnt vmcnt(9)
	v_pk_fma_f32 v[26:27], v[26:27], v[156:157], v[222:223]
	v_pk_fma_f32 v[24:25], v[24:25], v[158:159], v[220:221]
	v_cvt_pk_f16_f32 v164, v28, v29
	v_cvt_pk_f16_f32 v165, v30, v31
	v_cvt_pk_f16_f32 v166, v24, v25
	v_cvt_pk_f16_f32 v167, v26, v27
	global_store_dwordx4 v[172:173], v[164:167], off
	v_cvt_f32_f16_e32 v30, v164
	v_cvt_f32_f16_sdwa v31, v164 dst_sel:DWORD dst_unused:UNUSED_PAD src0_sel:WORD_1
	v_cvt_f32_f16_e32 v26, v165
	v_cvt_f32_f16_sdwa v27, v165 dst_sel:DWORD dst_unused:UNUSED_PAD src0_sel:WORD_1
	v_cvt_f32_f16_e32 v28, v166
	v_cvt_f32_f16_sdwa v29, v166 dst_sel:DWORD dst_unused:UNUSED_PAD src0_sel:WORD_1
	v_pk_mul_f32 v[164:165], v[30:31], v[30:31]
	v_cvt_f32_f16_e32 v24, v167
	v_cvt_f32_f16_sdwa v25, v167 dst_sel:DWORD dst_unused:UNUSED_PAD src0_sel:WORD_1
	v_pk_mul_f32 v[166:167], v[26:27], v[26:27]
	v_add_f32_e32 v145, v164, v165
	v_add_f32_e32 v145, v166, v145
	v_pk_mul_f32 v[172:173], v[28:29], v[28:29]
	v_add_f32_e32 v145, v167, v145
	v_add_f32_e32 v145, v172, v145
	v_pk_mul_f32 v[198:199], v[24:25], v[24:25]
	v_add_f32_e32 v145, v173, v145
	v_add_f32_e32 v145, v198, v145
	v_add_f32_e32 v145, v199, v145
	s_waitcnt vmcnt(9)
	v_pk_fma_f32 v[20:21], v[20:21], v[154:155], v[224:225]
	v_pk_fma_f32 v[22:23], v[22:23], v[152:153], v[226:227]
	v_cvt_pk_f16_f32 v166, v20, v21
	v_cvt_pk_f16_f32 v167, v22, v23
	v_cvt_f32_f16_e32 v22, v166
	v_cvt_f32_f16_sdwa v23, v166 dst_sel:DWORD dst_unused:UNUSED_PAD src0_sel:WORD_1
	s_waitcnt vmcnt(8)
	v_pk_fma_f32 v[18:19], v[18:19], v[148:149], v[230:231]
	v_pk_fma_f32 v[16:17], v[16:17], v[150:151], v[228:229]
	v_cvt_pk_f16_f32 v169, v18, v19
	v_cvt_f32_f16_e32 v18, v167
	v_cvt_f32_f16_sdwa v19, v167 dst_sel:DWORD dst_unused:UNUSED_PAD src0_sel:WORD_1
	v_cvt_pk_f16_f32 v168, v16, v17
	v_cvt_f32_f16_e32 v20, v168
	v_cvt_f32_f16_sdwa v21, v168 dst_sel:DWORD dst_unused:UNUSED_PAD src0_sel:WORD_1
	v_pk_mul_f32 v[164:165], v[22:23], v[22:23]
	v_cvt_f32_f16_e32 v16, v169
	v_add_f32_e32 v145, v164, v145
	v_cvt_f32_f16_sdwa v17, v169 dst_sel:DWORD dst_unused:UNUSED_PAD src0_sel:WORD_1
	v_pk_mul_f32 v[170:171], v[18:19], v[18:19]
	v_add_f32_e32 v145, v165, v145
	v_add_f32_e32 v145, v170, v145
	v_pk_mul_f32 v[172:173], v[20:21], v[20:21]
	v_add_f32_e32 v145, v171, v145
	v_add_f32_e32 v145, v172, v145
	v_pk_mul_f32 v[204:205], v[16:17], v[16:17]
	v_add_f32_e32 v145, v173, v145
	v_add_f32_e32 v145, v204, v145
	v_add_f32_e32 v145, v205, v145
	ds_bpermute_b32 v164, v176, v145
	v_lshl_add_u64 v[170:171], v[196:197], 1, s[68:69]
	global_store_dwordx4 v[170:171], v[166:169], off
	s_waitcnt lgkmcnt(0)
	v_add_f32_e32 v145, v145, v164
	ds_bpermute_b32 v164, v177, v145
	s_and_saveexec_b64 s[26:27], s[4:5]
	s_cbranch_execz .LBB0_648
	s_waitcnt lgkmcnt(0)
	v_add_f32_e32 v145, v145, v164
	v_add_u32_e32 v164, s95, v178
	ds_write_b32 v164, v145 offset:2560
; __device__ __forceinline__ float shx(float v, int m, int lane) { return __int_as_float(__builtin_amdgcn_ds_bpermute((lane ^ m) << 2, __float_as_int(v))); }
;     __device__ __forceinline__ void operator()(const f32x4 (&acc)[2][2][4][2], const Unit& u, int wr, int wc, int fr, int fq) const {
;     ...
;             for (int m = 0; m < 4; ++m) {
;                 float sq = 0.f;
; #pragma unroll
;                 for (int bj = 0; bj < 2; ++bj) {
;                     const unsigned off = (unsigned)(row0 + ai * HALF + m * 16) * DM + col0 + bj * HALF;
;                     f32x4 xa, xb;
;                     if (F32IN) { xa = *(const f32x4*)(in32 + off); xb = *(const f32x4*)(in32 + off + 4); }
;                     else { const h16x8 xv = *(const h16x8*)(in16 + off); xa = (f32x4){(float)xv[0], (float)xv[1], (float)xv[2], (float)xv[3]}; xb = (f32x4){(float)xv[4], (float)xv[5], (float)xv[6], (float)xv[7]}; }
;                     h16x8 o;
; #pragma unroll
;                     for (int j = 0; j < 4; ++j) { o[j] = (h16)(xa[j] + gv[bj][0][j] * acc[ai][bj][m][0][j]); o[4 + j] = (h16)(xb[j] + gv[bj][1][j] * acc[ai][bj][m][1][j]); }
;                     if (!FINAL) *(h16x8*)(out + off) = o;
;                     ov[ai][m][bj] = o;
; #pragma unroll
;                     for (int j = 0; j < 8; ++j) sq += (float)o[j] * (float)o[j];
;                 }
;                 sq += shx(sq, 16, lane); sq += shx(sq, 32, lane);
;                 if (fq == 0) red[(ai * HALF + wr * 64 + m * 16 + fr) * 4 + wc] = sq;
;             }
;         asm volatile("s_waitcnt lgkmcnt(0)" ::: "memory"); __builtin_amdgcn_s_barrier(); asm volatile("" ::: "memory");
;         if (tid < 256) {
;             const float part = (red[tid * 4 + 0] + red[tid * 4 + 1]) + (red[tid * 4 + 2] + red[tid * 4 + 3]);
;             __hip_atomic_store(ss + (unsigned)(u.pm * 4 + u.pn) * 256 + tid, part, __ATOMIC_RELAXED, __HIP_MEMORY_SCOPE_AGENT);
.LBB0_648:
	s_or_b64 exec, exec, s[26:27]
	v_readlane_b32 s36, v253, 16
	v_add_u32_e32 v172, 0x2c000, v32
	v_mov_b32_e32 v173, v33
	v_readlane_b32 s37, v253, 17
	v_readlane_b32 s56, v253, 0
	v_readlane_b32 s68, v253, 12
	v_lshl_add_u64 v[168:169], v[172:173], 2, s[36:37]
	s_waitcnt lgkmcnt(0)
	s_nop 0
	v_readlane_b32 s69, v253, 13
	v_add_u32_e32 v32, 0x2c080, v32
	v_readlane_b32 s38, v253, 18
	v_lshl_add_u64 v[172:173], v[172:173], 1, s[68:69]
	v_readlane_b32 s39, v253, 19
	v_readlane_b32 s40, v253, 20
	v_readlane_b32 s41, v253, 21
	v_readlane_b32 s42, v253, 22
	v_readlane_b32 s43, v253, 23
	v_readlane_b32 s44, v253, 24
	v_readlane_b32 s45, v253, 25
	v_readlane_b32 s46, v253, 26
	v_readlane_b32 s47, v253, 27
	v_readlane_b32 s48, v253, 28
	v_readlane_b32 s49, v253, 29
	v_readlane_b32 s50, v253, 30
	v_readlane_b32 s51, v253, 31
	v_readlane_b32 s57, v253, 1
	v_readlane_b32 s58, v253, 2
	v_readlane_b32 s59, v253, 3
	v_readlane_b32 s60, v253, 4
	v_readlane_b32 s61, v253, 5
	v_readlane_b32 s62, v253, 6
	v_readlane_b32 s63, v253, 7
	v_readlane_b32 s64, v253, 8
	v_readlane_b32 s65, v253, 9
	v_readlane_b32 s66, v253, 10
	v_readlane_b32 s67, v253, 11
	v_readlane_b32 s70, v253, 14
	v_readlane_b32 s71, v253, 15
	s_waitcnt vmcnt(5)
	v_pk_fma_f32 v[156:157], v[10:11], v[156:157], v[238:239]
	s_waitcnt vmcnt(6)
	v_pk_fma_f32 v[14:15], v[14:15], v[160:161], v[234:235]
	v_pk_fma_f32 v[12:13], v[12:13], v[162:163], v[232:233]
	v_pk_fma_f32 v[8:9], v[8:9], v[158:159], v[236:237]
	v_cvt_pk_f16_f32 v168, v12, v13
	v_cvt_pk_f16_f32 v169, v14, v15
	v_cvt_pk_f16_f32 v170, v8, v9
	v_cvt_pk_f16_f32 v171, v156, v157
	v_cvt_f32_f16_e32 v162, v168
	v_cvt_f32_f16_sdwa v163, v168 dst_sel:DWORD dst_unused:UNUSED_PAD src0_sel:WORD_1
	v_cvt_f32_f16_e32 v160, v169
	v_cvt_f32_f16_sdwa v161, v169 dst_sel:DWORD dst_unused:UNUSED_PAD src0_sel:WORD_1
	global_store_dwordx4 v[172:173], v[168:171], off
	v_cvt_f32_f16_e32 v158, v170
	v_cvt_f32_f16_sdwa v159, v170 dst_sel:DWORD dst_unused:UNUSED_PAD src0_sel:WORD_1
	v_lshl_add_u64 v[168:169], v[32:33], 2, s[36:37]
	v_cvt_f32_f16_e32 v156, v171
	v_cvt_f32_f16_sdwa v157, v171 dst_sel:DWORD dst_unused:UNUSED_PAD src0_sel:WORD_1
	s_nop 0
	v_pk_mul_f32 v[12:13], v[162:163], v[162:163]
	v_pk_mul_f32 v[14:15], v[160:161], v[160:161]
	v_add_f32_e32 v12, v12, v13
	v_add_f32_e32 v12, v14, v12
	v_pk_mul_f32 v[10:11], v[158:159], v[158:159]
	v_add_f32_e32 v12, v15, v12
	v_add_f32_e32 v10, v10, v12
	v_pk_mul_f32 v[8:9], v[156:157], v[156:157]
	v_add_f32_e32 v10, v11, v10
	v_add_f32_e32 v8, v8, v10
	v_add_f32_e32 v8, v9, v8
	v_lshl_add_u64 v[172:173], v[32:33], 1, s[68:69]
	s_waitcnt vmcnt(4)
	v_pk_fma_f32 v[0:1], v[0:1], v[150:151], v[244:245]
	s_waitcnt vmcnt(5)
	v_pk_fma_f32 v[4:5], v[4:5], v[154:155], v[240:241]
	v_pk_fma_f32 v[6:7], v[6:7], v[152:153], v[242:243]
	v_cvt_pk_f16_f32 v168, v4, v5
	v_cvt_f32_f16_e32 v154, v168
	v_cvt_f32_f16_sdwa v155, v168 dst_sel:DWORD dst_unused:UNUSED_PAD src0_sel:WORD_1
	v_cvt_pk_f16_f32 v169, v6, v7
	v_cvt_f32_f16_e32 v152, v169
	v_cvt_f32_f16_sdwa v153, v169 dst_sel:DWORD dst_unused:UNUSED_PAD src0_sel:WORD_1
	v_cvt_pk_f16_f32 v170, v0, v1
	v_pk_mul_f32 v[4:5], v[154:155], v[154:155]
	v_pk_fma_f32 v[2:3], v[2:3], v[148:149], v[246:247]
	v_cvt_f32_f16_e32 v150, v170
	v_cvt_f32_f16_sdwa v151, v170 dst_sel:DWORD dst_unused:UNUSED_PAD src0_sel:WORD_1
	v_cvt_pk_f16_f32 v171, v2, v3
	v_add_f32_e32 v4, v4, v8
	v_pk_mul_f32 v[6:7], v[152:153], v[152:153]
	v_cvt_f32_f16_e32 v148, v171
	v_cvt_f32_f16_sdwa v149, v171 dst_sel:DWORD dst_unused:UNUSED_PAD src0_sel:WORD_1
	v_add_f32_e32 v4, v5, v4
	v_add_f32_e32 v4, v6, v4
	v_pk_mul_f32 v[0:1], v[150:151], v[150:151]
	v_add_f32_e32 v4, v7, v4
	v_add_f32_e32 v0, v0, v4
	v_pk_mul_f32 v[2:3], v[148:149], v[148:149]
	v_add_f32_e32 v0, v1, v0
	v_add_f32_e32 v0, v2, v0
	v_add_f32_e32 v0, v3, v0
	ds_bpermute_b32 v1, v176, v0
	global_store_dwordx4 v[172:173], v[168:171], off
	s_waitcnt lgkmcnt(0)
	v_add_f32_e32 v0, v0, v1
	ds_bpermute_b32 v1, v177, v0
	s_and_saveexec_b64 s[26:27], s[4:5]
	s_cbranch_execz .LBB0_650
	s_waitcnt lgkmcnt(0)
	v_add_f32_e32 v0, v0, v1
	v_add_u32_e32 v1, s95, v178
	ds_write_b32 v1, v0 offset:2816
.LBB0_650:
	s_or_b64 exec, exec, s[26:27]
	s_waitcnt lgkmcnt(0)
	s_barrier
	s_and_saveexec_b64 s[26:27], s[6:7]
	s_cbranch_execz .LBB0_652
	v_readlane_b32 s36, v254, 43
	s_lshl_b32 s28, s97, 10
	v_readlane_b32 s44, v254, 51
	v_readlane_b32 s45, v254, 52
	v_readlane_b32 s49, v254, 56
	v_readlane_b32 s40, v254, 47
	v_readlane_b32 s41, v254, 48
	v_readlane_b32 s42, v254, 49
	v_readlane_b32 s43, v254, 50
	v_readlane_b32 s46, v254, 53
	v_readlane_b32 s47, v254, 54
	v_readlane_b32 s48, v254, 55
	v_readlane_b32 s50, v254, 57
	v_readlane_b32 s51, v254, 58
	s_add_i32 s44, s28, s24
	s_mov_b32 s49, s45
	v_readlane_b32 s37, v254, 44
	v_readlane_b32 s38, v254, 45
	v_readlane_b32 s39, v254, 46
	v_writelane_b32 v254, s40, 43
	s_waitcnt lgkmcnt(0)
	ds_read_b128 v[0:3], v191
	s_waitcnt lgkmcnt(0)
	v_mov_b32_e32 v4, v1
	v_writelane_b32 v254, s41, 44
	v_writelane_b32 v254, s42, 45
	v_writelane_b32 v254, s43, 46
	v_writelane_b32 v254, s44, 47
	v_writelane_b32 v254, s45, 48
	v_writelane_b32 v254, s46, 49
	v_writelane_b32 v254, s47, 50
	v_writelane_b32 v254, s48, 51
	v_writelane_b32 v254, s49, 52
	v_writelane_b32 v254, s50, 53
	v_writelane_b32 v254, s51, 54
	v_writelane_b32 v254, s52, 55
	v_mov_b32_e32 v5, v2
	v_mov_b32_e32 v1, v3
	v_writelane_b32 v254, s53, 56
	v_pk_add_f32 v[0:1], v[4:5], v[0:1]
	v_writelane_b32 v254, s54, 57
	v_pk_add_f32 v[0:1], v[0:1], v[0:1] op_sel:[0,1] op_sel_hi:[1,0]
	v_writelane_b32 v254, s55, 58
	v_lshl_add_u64 v[2:3], s[44:45], 2, v[138:139]
	global_store_dword v[2:3], v0, off sc1

;     __device__ __forceinline__ void operator()(const f32x4 (&acc)[2][2][4][2], const Unit& u, int wr, int wc, int fr, int fq) const {
;     ...
;         if (tid < 256) {
;             float tot = 0.f;
; #pragma unroll
;             for (int q = 0; q < 4; ++q) tot += __hip_atomic_load(ss + (unsigned)(u.pm * 4 + q) * 256 + tid, __ATOMIC_RELAXED, __HIP_MEMORY_SCOPE_AGENT);
;             rs[tid] = rsqrtf(tot * (1.0f / 1024.0f) + 1e-6f);
;         }
;         asm volatile("s_waitcnt lgkmcnt(0)" ::: "memory"); __builtin_amdgcn_s_barrier(); asm volatile("" ::: "memory");
;         const float* sh = FINAL ? ln : shp + b * 9216; const float* sc = FINAL ? ln : scp + b * 9216;
; #pragma unroll
;         for (int bj = 0; bj < 2; ++bj) {
;             const int col = col0 + bj * HALF;
;             const f32x4 l0 = *(const f32x4*)(ln + col), l1 = *(const f32x4*)(ln + col + 4), s0 = *(const f32x4*)(sh + col), s1 = *(const f32x4*)(sh + col + 4),
;                         c0 = *(const f32x4*)(sc + col), c1 = *(const f32x4*)(sc + col + 4);
; #pragma unroll
;             for (int ai = 0; ai < 2; ++ai)
; #pragma unroll
;                 for (int m = 0; m < 4; ++m) {
;                     const float rstd = rs[ai * HALF + wr * 64 + m * 16 + fr];
;                     const h16x8 o = ov[ai][m][bj];
;                     if (FINAL) {
;                         f32x4 y0, y1;
; #pragma unroll
;                         for (int j = 0; j < 4; ++j) { y0[j] = (float)o[j] * rstd * l0[j]; y1[j] = (float)o[4 + j] * rstd * l1[j]; }
;                         float* yp = fout + (unsigned)(row0 + ai * HALF + m * 16) * DM + col;
;                         *(f32x4*)yp = y0; *(f32x4*)(yp + 4) = y1;
;                     } else {
;                         h16x8 y;
; #pragma unroll
;                         for (int j = 0; j < 4; ++j) { y[j] = (h16)((float)o[j] * rstd * l0[j] * (1.0f + c0[j]) + s0[j]); y[4 + j] = (h16)((float)o[4 + j] * rstd * l1[j] * (1.0f + c1[j]) + s1[j]); }
;                         *(h16x8*)(xn + (unsigned)(row0 + ai * HALF + m * 16) * DM + col) = y;
.LBB0_668:
	s_or_b64 exec, exec, s[26:27]
	s_barrier
	s_and_saveexec_b64 s[26:27], s[6:7]
	s_cbranch_execz .LBB0_670
	v_readlane_b32 s36, v254, 43
	v_readlane_b32 s44, v254, 51
	v_readlane_b32 s45, v254, 52
	v_readlane_b32 s49, v254, 56
	v_readlane_b32 s40, v254, 47
	v_readlane_b32 s41, v254, 48
	v_readlane_b32 s42, v254, 49
	v_readlane_b32 s43, v254, 50
	v_readlane_b32 s46, v254, 53
	v_readlane_b32 s47, v254, 54
	v_readlane_b32 s48, v254, 55
	v_readlane_b32 s50, v254, 57
	v_readlane_b32 s51, v254, 58
	s_lshl_b32 s44, s97, 10
	s_mov_b32 s49, s45
	v_readlane_b32 s37, v254, 44
	v_readlane_b32 s38, v254, 45
	v_readlane_b32 s39, v254, 46
	v_writelane_b32 v254, s40, 43
	s_waitcnt lgkmcnt(0)
	s_nop 0
	v_lshl_add_u64 v[0:1], s[44:45], 2, v[138:139]
	global_load_dword v2, v[0:1], off sc1
	global_load_dword v3, v[0:1], off offset:1024 sc1
	v_writelane_b32 v254, s41, 44
	v_writelane_b32 v254, s42, 45
	v_writelane_b32 v254, s43, 46
	v_writelane_b32 v254, s44, 47
	v_writelane_b32 v254, s45, 48
	v_writelane_b32 v254, s46, 49
	v_writelane_b32 v254, s47, 50
	v_writelane_b32 v254, s48, 51
	v_writelane_b32 v254, s49, 52
	v_writelane_b32 v254, s50, 53
	v_writelane_b32 v254, s51, 54
	v_writelane_b32 v254, s52, 55
	v_writelane_b32 v254, s53, 56
	v_writelane_b32 v254, s54, 57
	v_writelane_b32 v254, s55, 58
	s_waitcnt vmcnt(0) lgkmcnt(0)
	v_add_f32_e32 v2, 0, v2
	v_add_f32_e32 v2, v2, v3
	global_load_dword v3, v[0:1], off offset:2048 sc1
	s_waitcnt vmcnt(0) lgkmcnt(0)
	v_add_f32_e32 v2, v2, v3
	global_load_dword v0, v[0:1], off offset:3072 sc1
	s_waitcnt vmcnt(0) lgkmcnt(0)
	v_add_f32_e32 v0, v2, v0
	v_fmamk_f32 v0, v0, 0x3a800000, v193
	v_cmp_gt_f32_e32 vcc, s25, v0
	v_mul_f32_e32 v1, 0x4b800000, v0
	s_nop 0
	v_cndmask_b32_e32 v0, v0, v1, vcc
	v_rsq_f32_e32 v0, v0
	s_nop 0
	v_mul_f32_e32 v1, 0x45800000, v0
	v_cndmask_b32_e32 v0, v0, v1, vcc
	ds_write_b32 v180, v0
.LBB0_670:
	s_or_b64 exec, exec, s[26:27]
	s_add_u32 s26, s75, s22
	s_addc_u32 s27, s78, s23
	s_add_u32 s22, s79, s22
	v_lshlrev_b64 v[8:9], 2, v[146:147]
	s_addc_u32 s23, s80, s23
	s_waitcnt lgkmcnt(0)
	s_barrier
	v_lshl_add_u64 v[164:165], s[12:13], 0, v[8:9]
	v_lshl_add_u64 v[166:167], s[22:23], 0, v[8:9]
	s_waitcnt lgkmcnt(0)
	global_load_dwordx4 v[0:3], v[164:165], off offset:16
	global_load_dwordx4 v[4:7], v[164:165], off
	global_load_dwordx4 v[204:207], v[166:167], off
	global_load_dwordx4 v[208:211], v[166:167], off offset:16
	v_lshl_add_u64 v[168:169], s[26:27], 0, v[8:9]
	global_load_dwordx4 v[12:15], v[168:169], off
	global_load_dwordx4 v[8:11], v[168:169], off offset:16
	ds_read_b32 v32, v181
	v_mov_b32_e32 v145, v33
	v_lshlrev_b64 v[170:171], 1, v[146:147]
	v_lshl_add_u64 v[146:147], v[144:145], 1, s[84:85]
	v_lshl_add_u64 v[146:147], v[146:147], 0, v[170:171]
	s_waitcnt lgkmcnt(0)
	v_pk_mul_f32 v[124:125], v[32:33], v[124:125] op_sel_hi:[0,1]
	v_pk_mul_f32 v[128:129], v[32:33], v[128:129] op_sel_hi:[0,1]
	v_pk_mul_f32 v[122:123], v[32:33], v[122:123] op_sel_hi:[0,1]
	v_pk_mul_f32 v[126:127], v[32:33], v[126:127] op_sel_hi:[0,1]
	v_or_b32_e32 v32, 0x4000, v144
	s_and_b64 vcc, exec, s[10:11]
	s_mov_b64 s[10:11], -1
	s_waitcnt vmcnt(0)
	v_pk_mul_f32 v[198:199], v[0:1], v[128:129]
	v_pk_mul_f32 v[196:197], v[4:5], v[124:125]
	v_pk_mul_f32 v[122:123], v[6:7], v[122:123]
	v_pk_mul_f32 v[212:213], v[2:3], v[126:127]
	v_pk_add_f32 v[172:173], v[204:205], 1.0 op_sel_hi:[1,0]
	v_pk_add_f32 v[128:129], v[208:209], 1.0 op_sel_hi:[1,0]
	v_pk_add_f32 v[126:127], v[206:207], 1.0 op_sel_hi:[1,0]
	v_pk_add_f32 v[124:125], v[210:211], 1.0 op_sel_hi:[1,0]
	v_pk_fma_f32 v[196:197], v[172:173], v[196:197], v[12:13]
	v_pk_fma_f32 v[198:199], v[128:129], v[198:199], v[8:9]
	v_pk_fma_f32 v[122:123], v[126:127], v[122:123], v[14:15]
	v_pk_fma_f32 v[208:209], v[124:125], v[212:213], v[10:11]
	v_cvt_pk_f16_f32 v204, v196, v197
	v_cvt_pk_f16_f32 v206, v198, v199
	v_cvt_pk_f16_f32 v205, v122, v123
	v_cvt_pk_f16_f32 v207, v208, v209
	global_store_dwordx4 v[146:147], v[204:207], off
	ds_read_b32 v196, v181 offset:64
	v_lshl_add_u64 v[122:123], v[32:33], 1, s[84:85]
	v_lshl_add_u64 v[122:123], v[122:123], 0, v[170:171]
	v_or_b32_e32 v32, 0x8000, v144
	s_waitcnt lgkmcnt(0)
	v_pk_mul_f32 v[108:109], v[196:197], v[108:109] op_sel_hi:[0,1]
	v_pk_mul_f32 v[112:113], v[196:197], v[112:113] op_sel_hi:[0,1]
	v_pk_mul_f32 v[106:107], v[196:197], v[106:107] op_sel_hi:[0,1]
	v_pk_mul_f32 v[110:111], v[196:197], v[110:111] op_sel_hi:[0,1]
	v_pk_mul_f32 v[108:109], v[4:5], v[108:109]
	v_pk_mul_f32 v[112:113], v[0:1], v[112:113]
	v_pk_mul_f32 v[106:107], v[6:7], v[106:107]
	v_pk_mul_f32 v[110:111], v[2:3], v[110:111]
	v_pk_fma_f32 v[108:109], v[172:173], v[108:109], v[12:13]
	v_pk_fma_f32 v[112:113], v[128:129], v[112:113], v[8:9]
	v_pk_fma_f32 v[196:197], v[126:127], v[106:107], v[14:15]
	v_pk_fma_f32 v[110:111], v[124:125], v[110:111], v[10:11]
	v_cvt_pk_f16_f32 v106, v108, v109
	v_cvt_pk_f16_f32 v108, v112, v113
	v_cvt_pk_f16_f32 v107, v196, v197
	v_cvt_pk_f16_f32 v109, v110, v111
	global_store_dwordx4 v[122:123], v[106:109], off
	ds_read_b32 v108, v181 offset:128
	s_waitcnt lgkmcnt(0)
;     __device__ __forceinline__ void operator()(const f32x4 (&acc)[2][2][4][2], const Unit& u, int wr, int wc, int fr, int fq) const {
;     ...
;         for (int bj = 0; bj < 2; ++bj) {
;             const int col = col0 + bj * HALF;
;             const f32x4 l0 = *(const f32x4*)(ln + col), l1 = *(const f32x4*)(ln + col + 4), s0 = *(const f32x4*)(sh + col), s1 = *(const f32x4*)(sh + col + 4),
;                         c0 = *(const f32x4*)(sc + col), c1 = *(const f32x4*)(sc + col + 4);
; #pragma unroll
;             for (int ai = 0; ai < 2; ++ai)
; #pragma unroll
;                 for (int m = 0; m < 4; ++m) {
;                     const float rstd = rs[ai * HALF + wr * 64 + m * 16 + fr];
;                     const h16x8 o = ov[ai][m][bj];
;                     if (FINAL) {
;                         f32x4 y0, y1;
; #pragma unroll
;                         for (int j = 0; j < 4; ++j) { y0[j] = (float)o[j] * rstd * l0[j]; y1[j] = (float)o[4 + j] * rstd * l1[j]; }
;                         float* yp = fout + (unsigned)(row0 + ai * HALF + m * 16) * DM + col;
;                         *(f32x4*)yp = y0; *(f32x4*)(yp + 4) = y1;
;                     } else {
;                         h16x8 y;
; #pragma unroll
;                         for (int j = 0; j < 4; ++j) { y[j] = (h16)((float)o[j] * rstd * l0[j] * (1.0f + c0[j]) + s0[j]); y[4 + j] = (h16)((float)o[4 + j] * rstd * l1[j] * (1.0f + c1[j]) + s1[j]); }
;                         *(h16x8*)(xn + (unsigned)(row0 + ai * HALF + m * 16) * DM + col) = y;
	v_pk_mul_f32 v[92:93], v[108:109], v[92:93] op_sel_hi:[0,1]
	v_pk_mul_f32 v[96:97], v[108:109], v[96:97] op_sel_hi:[0,1]
	v_pk_mul_f32 v[90:91], v[108:109], v[90:91] op_sel_hi:[0,1]
	v_pk_mul_f32 v[94:95], v[108:109], v[94:95] op_sel_hi:[0,1]
	v_pk_mul_f32 v[92:93], v[4:5], v[92:93]
	v_pk_mul_f32 v[96:97], v[0:1], v[96:97]
	v_pk_mul_f32 v[90:91], v[6:7], v[90:91]
	v_pk_mul_f32 v[94:95], v[2:3], v[94:95]
	v_lshl_add_u64 v[106:107], v[32:33], 1, s[84:85]
	v_pk_fma_f32 v[92:93], v[172:173], v[92:93], v[12:13]
	v_pk_fma_f32 v[96:97], v[128:129], v[96:97], v[8:9]
	v_pk_fma_f32 v[108:109], v[126:127], v[90:91], v[14:15]
	v_pk_fma_f32 v[94:95], v[124:125], v[94:95], v[10:11]
	v_lshl_add_u64 v[106:107], v[106:107], 0, v[170:171]
	v_cvt_pk_f16_f32 v90, v92, v93
	v_cvt_pk_f16_f32 v92, v96, v97
	v_cvt_pk_f16_f32 v91, v108, v109
	v_cvt_pk_f16_f32 v93, v94, v95
	global_store_dwordx4 v[106:107], v[90:93], off
	ds_read_b32 v92, v181 offset:192
	v_or_b32_e32 v32, 0xc000, v144
	v_lshl_add_u64 v[90:91], v[32:33], 1, s[84:85]
	v_lshl_add_u64 v[90:91], v[90:91], 0, v[170:171]
	v_add_u32_e32 v32, 0x20000, v144
	s_waitcnt lgkmcnt(0)
	v_pk_mul_f32 v[76:77], v[92:93], v[76:77] op_sel_hi:[0,1]
	v_pk_mul_f32 v[80:81], v[92:93], v[80:81] op_sel_hi:[0,1]
	v_pk_mul_f32 v[74:75], v[92:93], v[74:75] op_sel_hi:[0,1]
	v_pk_mul_f32 v[78:79], v[92:93], v[78:79] op_sel_hi:[0,1]
	v_pk_mul_f32 v[76:77], v[4:5], v[76:77]
	v_pk_mul_f32 v[80:81], v[0:1], v[80:81]
	v_pk_mul_f32 v[74:75], v[6:7], v[74:75]
	v_pk_mul_f32 v[78:79], v[2:3], v[78:79]
	v_pk_fma_f32 v[76:77], v[172:173], v[76:77], v[12:13]
	v_pk_fma_f32 v[80:81], v[128:129], v[80:81], v[8:9]
	v_pk_fma_f32 v[92:93], v[126:127], v[74:75], v[14:15]
	v_pk_fma_f32 v[78:79], v[124:125], v[78:79], v[10:11]
	v_cvt_pk_f16_f32 v74, v76, v77
	v_cvt_pk_f16_f32 v76, v80, v81
	v_cvt_pk_f16_f32 v75, v92, v93
	v_cvt_pk_f16_f32 v77, v78, v79
	global_store_dwordx4 v[90:91], v[74:77], off
	ds_read_b32 v76, v181 offset:512
	s_waitcnt lgkmcnt(0)
	v_pk_mul_f32 v[60:61], v[76:77], v[60:61] op_sel_hi:[0,1]
	v_pk_mul_f32 v[64:65], v[76:77], v[64:65] op_sel_hi:[0,1]
	v_pk_mul_f32 v[58:59], v[76:77], v[58:59] op_sel_hi:[0,1]
	v_pk_mul_f32 v[62:63], v[76:77], v[62:63] op_sel_hi:[0,1]
	v_pk_mul_f32 v[60:61], v[4:5], v[60:61]
	v_pk_mul_f32 v[64:65], v[0:1], v[64:65]
	v_pk_mul_f32 v[58:59], v[6:7], v[58:59]
	v_pk_mul_f32 v[62:63], v[2:3], v[62:63]
	v_lshl_add_u64 v[74:75], v[32:33], 1, s[84:85]
	v_pk_fma_f32 v[60:61], v[172:173], v[60:61], v[12:13]
	v_pk_fma_f32 v[64:65], v[128:129], v[64:65], v[8:9]
	v_pk_fma_f32 v[76:77], v[126:127], v[58:59], v[14:15]
	v_pk_fma_f32 v[62:63], v[124:125], v[62:63], v[10:11]
	v_lshl_add_u64 v[74:75], v[74:75], 0, v[170:171]
	v_cvt_pk_f16_f32 v58, v60, v61
	v_cvt_pk_f16_f32 v60, v64, v65
	v_cvt_pk_f16_f32 v59, v76, v77
	v_cvt_pk_f16_f32 v61, v62, v63
	global_store_dwordx4 v[74:75], v[58:61], off
	ds_read_b32 v32, v181 offset:576
	s_waitcnt lgkmcnt(0)
	v_pk_mul_f32 v[46:47], v[32:33], v[46:47] op_sel_hi:[0,1]
	v_pk_mul_f32 v[42:43], v[32:33], v[42:43] op_sel_hi:[0,1]
	v_pk_mul_f32 v[48:49], v[32:33], v[48:49] op_sel_hi:[0,1]
	v_pk_mul_f32 v[44:45], v[32:33], v[44:45] op_sel_hi:[0,1]
	v_pk_mul_f32 v[46:47], v[0:1], v[46:47]
	v_pk_mul_f32 v[42:43], v[2:3], v[42:43]
	v_pk_mul_f32 v[48:49], v[4:5], v[48:49]
	v_pk_mul_f32 v[58:59], v[6:7], v[44:45]
	v_pk_fma_f32 v[46:47], v[128:129], v[46:47], v[8:9]
	v_pk_fma_f32 v[42:43], v[124:125], v[42:43], v[10:11]
	v_add_u32_e32 v32, 0x24000, v144
	v_pk_fma_f32 v[44:45], v[172:173], v[48:49], v[12:13]
	v_cvt_pk_f16_f32 v46, v46, v47
	v_pk_fma_f32 v[48:49], v[126:127], v[58:59], v[14:15]
	v_cvt_pk_f16_f32 v47, v42, v43
	v_lshl_add_u64 v[42:43], v[32:33], 1, s[84:85]
	v_cvt_pk_f16_f32 v44, v44, v45
	v_cvt_pk_f16_f32 v45, v48, v49
	v_lshl_add_u64 v[42:43], v[42:43], 0, v[170:171]
	global_store_dwordx4 v[42:43], v[44:47], off
	ds_read_b32 v32, v181 offset:640
	s_waitcnt lgkmcnt(0)
	v_pk_mul_f32 v[24:25], v[32:33], v[24:25] op_sel_hi:[0,1]
	v_pk_mul_f32 v[30:31], v[32:33], v[30:31] op_sel_hi:[0,1]
	v_pk_mul_f32 v[28:29], v[32:33], v[28:29] op_sel_hi:[0,1]
	v_pk_mul_f32 v[26:27], v[32:33], v[26:27] op_sel_hi:[0,1]
	v_pk_mul_f32 v[24:25], v[2:3], v[24:25]
	v_pk_mul_f32 v[30:31], v[4:5], v[30:31]
	v_pk_mul_f32 v[28:29], v[0:1], v[28:29]
	v_pk_mul_f32 v[26:27], v[6:7], v[26:27]
	v_pk_fma_f32 v[24:25], v[124:125], v[24:25], v[10:11]
	v_add_u32_e32 v32, 0x28000, v144
	v_pk_fma_f32 v[30:31], v[172:173], v[30:31], v[12:13]
	v_pk_fma_f32 v[28:29], v[128:129], v[28:29], v[8:9]
	v_pk_fma_f32 v[26:27], v[126:127], v[26:27], v[14:15]
	v_cvt_pk_f16_f32 v47, v24, v25
	v_lshl_add_u64 v[24:25], v[32:33], 1, s[84:85]
	v_cvt_pk_f16_f32 v44, v30, v31
	v_cvt_pk_f16_f32 v46, v28, v29
	v_cvt_pk_f16_f32 v45, v26, v27
	v_lshl_add_u64 v[24:25], v[24:25], 0, v[170:171]
	global_store_dwordx4 v[24:25], v[44:47], off
	ds_read_b32 v30, v181 offset:704
	v_add_u32_e32 v32, 0x2c000, v144
	s_waitcnt lgkmcnt(0)
	v_pk_mul_f32 v[26:27], v[30:31], v[162:163] op_sel_hi:[0,1]
	v_pk_mul_f32 v[4:5], v[4:5], v[26:27]
	s_nop 0
	v_pk_fma_f32 v[4:5], v[172:173], v[4:5], v[12:13]
	s_nop 0
	v_cvt_pk_f16_f32 v26, v4, v5
	v_pk_mul_f32 v[4:5], v[30:31], v[158:159] op_sel_hi:[0,1]
	v_pk_mul_f32 v[0:1], v[0:1], v[4:5]
	s_nop 0
	v_pk_fma_f32 v[0:1], v[128:129], v[0:1], v[8:9]
	s_nop 0
	v_cvt_pk_f16_f32 v28, v0, v1
	v_pk_mul_f32 v[0:1], v[30:31], v[160:161] op_sel_hi:[0,1]
	v_pk_mul_f32 v[0:1], v[6:7], v[0:1]
	s_nop 0
	v_pk_fma_f32 v[0:1], v[126:127], v[0:1], v[14:15]
	s_nop 0
	v_cvt_pk_f16_f32 v27, v0, v1
	v_pk_mul_f32 v[0:1], v[30:31], v[156:157] op_sel_hi:[0,1]
	v_pk_mul_f32 v[0:1], v[2:3], v[0:1]
	s_nop 0
	v_pk_fma_f32 v[0:1], v[124:125], v[0:1], v[10:11]
	s_nop 0
	v_cvt_pk_f16_f32 v29, v0, v1
	v_lshl_add_u64 v[0:1], v[32:33], 1, s[84:85]
	v_lshl_add_u64 v[0:1], v[0:1], 0, v[170:171]
	global_store_dwordx4 v[0:1], v[26:29], off
	global_load_dwordx4 v[2:5], v[164:165], off offset:512
	global_load_dwordx4 v[6:9], v[166:167], off offset:512
	global_load_dwordx4 v[10:13], v[164:165], off offset:528
	s_nop 0
	global_load_dwordx4 v[26:29], v[166:167], off offset:528
	global_load_dwordx4 v[44:47], v[168:169], off offset:512
	global_load_dwordx4 v[58:61], v[168:169], off offset:528
	ds_read_b32 v14, v181
	s_waitcnt lgkmcnt(0)
;     __device__ __forceinline__ void operator()(const f32x4 (&acc)[2][2][4][2], const Unit& u, int wr, int wc, int fr, int fq) const {
;     ...
;         for (int bj = 0; bj < 2; ++bj) {
;             const int col = col0 + bj * HALF;
;             const f32x4 l0 = *(const f32x4*)(ln + col), l1 = *(const f32x4*)(ln + col + 4), s0 = *(const f32x4*)(sh + col), s1 = *(const f32x4*)(sh + col + 4),
;                         c0 = *(const f32x4*)(sc + col), c1 = *(const f32x4*)(sc + col + 4);
; #pragma unroll
;             for (int ai = 0; ai < 2; ++ai)
; #pragma unroll
;                 for (int m = 0; m < 4; ++m) {
;                     const float rstd = rs[ai * HALF + wr * 64 + m * 16 + fr];
;                     const h16x8 o = ov[ai][m][bj];
;                     if (FINAL) {
;                         f32x4 y0, y1;
; #pragma unroll
;                         for (int j = 0; j < 4; ++j) { y0[j] = (float)o[j] * rstd * l0[j]; y1[j] = (float)o[4 + j] * rstd * l1[j]; }
;                         float* yp = fout + (unsigned)(row0 + ai * HALF + m * 16) * DM + col;
;                         *(f32x4*)yp = y0; *(f32x4*)(yp + 4) = y1;
;                     } else {
;                         h16x8 y;
; #pragma unroll
;                         for (int j = 0; j < 4; ++j) { y[j] = (h16)((float)o[j] * rstd * l0[j] * (1.0f + c0[j]) + s0[j]); y[4 + j] = (h16)((float)o[4 + j] * rstd * l1[j] * (1.0f + c1[j]) + s1[j]); }
;                         *(h16x8*)(xn + (unsigned)(row0 + ai * HALF + m * 16) * DM + col) = y;
	v_pk_mul_f32 v[30:31], v[14:15], v[120:121] op_sel_hi:[0,1]
	v_pk_mul_f32 v[48:49], v[14:15], v[118:119] op_sel_hi:[0,1]
	v_pk_mul_f32 v[62:63], v[14:15], v[116:117] op_sel_hi:[0,1]
	v_pk_mul_f32 v[14:15], v[14:15], v[114:115] op_sel_hi:[0,1]
	s_waitcnt vmcnt(0)
	v_pk_mul_f32 v[30:31], v[2:3], v[30:31]
	v_pk_add_f32 v[64:65], v[6:7], 1.0 op_sel_hi:[1,0]
	v_pk_mul_f32 v[6:7], v[10:11], v[48:49]
	v_pk_add_f32 v[26:27], v[26:27], 1.0 op_sel_hi:[1,0]
	v_pk_mul_f32 v[48:49], v[4:5], v[62:63]
	v_pk_add_f32 v[62:63], v[8:9], 1.0 op_sel_hi:[1,0]
	v_pk_mul_f32 v[8:9], v[12:13], v[14:15]
	v_pk_add_f32 v[14:15], v[28:29], 1.0 op_sel_hi:[1,0]
	v_pk_fma_f32 v[28:29], v[64:65], v[30:31], v[44:45]
	v_pk_fma_f32 v[30:31], v[26:27], v[6:7], v[58:59]
	v_pk_fma_f32 v[48:49], v[62:63], v[48:49], v[46:47]
	v_pk_fma_f32 v[76:77], v[14:15], v[8:9], v[60:61]
	v_cvt_pk_f16_f32 v6, v28, v29
	v_cvt_pk_f16_f32 v8, v30, v31
	v_cvt_pk_f16_f32 v7, v48, v49
	v_cvt_pk_f16_f32 v9, v76, v77
	global_store_dwordx4 v[146:147], v[6:9], off offset:256
	ds_read_b32 v6, v181 offset:64
	s_waitcnt lgkmcnt(0)
	v_pk_mul_f32 v[28:29], v[6:7], v[102:103] op_sel_hi:[0,1]
	v_pk_mul_f32 v[8:9], v[6:7], v[104:105] op_sel_hi:[0,1]
	v_pk_mul_f32 v[30:31], v[6:7], v[100:101] op_sel_hi:[0,1]
	v_pk_mul_f32 v[6:7], v[6:7], v[98:99] op_sel_hi:[0,1]
	v_pk_mul_f32 v[8:9], v[2:3], v[8:9]
	v_pk_mul_f32 v[28:29], v[10:11], v[28:29]
	v_pk_mul_f32 v[30:31], v[4:5], v[30:31]
	v_pk_mul_f32 v[6:7], v[12:13], v[6:7]
	v_pk_fma_f32 v[8:9], v[64:65], v[8:9], v[44:45]
	v_pk_fma_f32 v[28:29], v[26:27], v[28:29], v[58:59]
	v_pk_fma_f32 v[30:31], v[62:63], v[30:31], v[46:47]
	v_pk_fma_f32 v[48:49], v[14:15], v[6:7], v[60:61]
	v_cvt_pk_f16_f32 v6, v8, v9
	v_cvt_pk_f16_f32 v8, v28, v29
	v_cvt_pk_f16_f32 v7, v30, v31
	v_cvt_pk_f16_f32 v9, v48, v49
	global_store_dwordx4 v[122:123], v[6:9], off offset:256
	ds_read_b32 v6, v181 offset:128
	s_waitcnt lgkmcnt(0)
	v_pk_mul_f32 v[28:29], v[6:7], v[86:87] op_sel_hi:[0,1]
	v_pk_mul_f32 v[8:9], v[6:7], v[88:89] op_sel_hi:[0,1]
	v_pk_mul_f32 v[30:31], v[6:7], v[84:85] op_sel_hi:[0,1]
	v_pk_mul_f32 v[6:7], v[6:7], v[82:83] op_sel_hi:[0,1]
	v_pk_mul_f32 v[8:9], v[2:3], v[8:9]
	v_pk_mul_f32 v[28:29], v[10:11], v[28:29]
	v_pk_mul_f32 v[30:31], v[4:5], v[30:31]
	v_pk_mul_f32 v[6:7], v[12:13], v[6:7]
	v_pk_fma_f32 v[8:9], v[64:65], v[8:9], v[44:45]
	v_pk_fma_f32 v[28:29], v[26:27], v[28:29], v[58:59]
	v_pk_fma_f32 v[30:31], v[62:63], v[30:31], v[46:47]
	v_pk_fma_f32 v[48:49], v[14:15], v[6:7], v[60:61]
	v_cvt_pk_f16_f32 v6, v8, v9
	v_cvt_pk_f16_f32 v8, v28, v29
	v_cvt_pk_f16_f32 v7, v30, v31
	v_cvt_pk_f16_f32 v9, v48, v49
	global_store_dwordx4 v[106:107], v[6:9], off offset:256
	ds_read_b32 v6, v181 offset:192
	s_waitcnt lgkmcnt(0)
	v_pk_mul_f32 v[28:29], v[6:7], v[70:71] op_sel_hi:[0,1]
	v_pk_mul_f32 v[8:9], v[6:7], v[72:73] op_sel_hi:[0,1]
	v_pk_mul_f32 v[30:31], v[6:7], v[68:69] op_sel_hi:[0,1]
	v_pk_mul_f32 v[6:7], v[6:7], v[66:67] op_sel_hi:[0,1]
	v_pk_mul_f32 v[8:9], v[2:3], v[8:9]
	v_pk_mul_f32 v[28:29], v[10:11], v[28:29]
	v_pk_mul_f32 v[30:31], v[4:5], v[30:31]
	v_pk_mul_f32 v[6:7], v[12:13], v[6:7]
	v_pk_fma_f32 v[8:9], v[64:65], v[8:9], v[44:45]
	v_pk_fma_f32 v[28:29], v[26:27], v[28:29], v[58:59]
	v_pk_fma_f32 v[30:31], v[62:63], v[30:31], v[46:47]
	v_pk_fma_f32 v[48:49], v[14:15], v[6:7], v[60:61]
	v_cvt_pk_f16_f32 v6, v8, v9
	v_cvt_pk_f16_f32 v8, v28, v29
	v_cvt_pk_f16_f32 v7, v30, v31
	v_cvt_pk_f16_f32 v9, v48, v49
	global_store_dwordx4 v[90:91], v[6:9], off offset:256
	ds_read_b32 v28, v181 offset:512
	s_waitcnt lgkmcnt(0)
	v_pk_mul_f32 v[30:31], v[28:29], v[52:53] op_sel_hi:[0,1]
	v_pk_mul_f32 v[6:7], v[28:29], v[56:57] op_sel_hi:[0,1]
	v_pk_mul_f32 v[8:9], v[28:29], v[54:55] op_sel_hi:[0,1]
	v_pk_mul_f32 v[28:29], v[28:29], v[50:51] op_sel_hi:[0,1]
	v_pk_mul_f32 v[6:7], v[2:3], v[6:7]
	v_pk_mul_f32 v[8:9], v[10:11], v[8:9]
	v_pk_mul_f32 v[30:31], v[4:5], v[30:31]
	v_pk_mul_f32 v[28:29], v[12:13], v[28:29]
	v_pk_fma_f32 v[6:7], v[64:65], v[6:7], v[44:45]
	v_pk_fma_f32 v[8:9], v[26:27], v[8:9], v[58:59]
	v_pk_fma_f32 v[30:31], v[62:63], v[30:31], v[46:47]
	v_pk_fma_f32 v[28:29], v[14:15], v[28:29], v[60:61]
	v_cvt_pk_f16_f32 v6, v6, v7
	v_cvt_pk_f16_f32 v8, v8, v9
	v_cvt_pk_f16_f32 v7, v30, v31
	v_cvt_pk_f16_f32 v9, v28, v29
	global_store_dwordx4 v[74:75], v[6:9], off offset:256
	ds_read_b32 v28, v181 offset:576
	s_waitcnt lgkmcnt(0)
	v_pk_mul_f32 v[30:31], v[28:29], v[36:37] op_sel_hi:[0,1]
	v_pk_mul_f32 v[6:7], v[28:29], v[40:41] op_sel_hi:[0,1]
	v_pk_mul_f32 v[8:9], v[28:29], v[38:39] op_sel_hi:[0,1]
	v_pk_mul_f32 v[28:29], v[28:29], v[34:35] op_sel_hi:[0,1]
	v_pk_mul_f32 v[6:7], v[2:3], v[6:7]
	v_pk_mul_f32 v[8:9], v[10:11], v[8:9]
	v_pk_mul_f32 v[30:31], v[4:5], v[30:31]
	v_pk_mul_f32 v[28:29], v[12:13], v[28:29]
	v_pk_fma_f32 v[6:7], v[64:65], v[6:7], v[44:45]
	v_pk_fma_f32 v[8:9], v[26:27], v[8:9], v[58:59]
	v_pk_fma_f32 v[30:31], v[62:63], v[30:31], v[46:47]
	v_pk_fma_f32 v[28:29], v[14:15], v[28:29], v[60:61]
	v_cvt_pk_f16_f32 v6, v6, v7
	v_cvt_pk_f16_f32 v8, v8, v9
	v_cvt_pk_f16_f32 v7, v30, v31
	v_cvt_pk_f16_f32 v9, v28, v29
	global_store_dwordx4 v[42:43], v[6:9], off offset:256
	ds_read_b32 v28, v181 offset:640
	s_waitcnt lgkmcnt(0)
	v_pk_mul_f32 v[18:19], v[28:29], v[18:19] op_sel_hi:[0,1]
	v_pk_mul_f32 v[6:7], v[28:29], v[22:23] op_sel_hi:[0,1]
	v_pk_mul_f32 v[8:9], v[28:29], v[20:21] op_sel_hi:[0,1]
	v_pk_mul_f32 v[16:17], v[28:29], v[16:17] op_sel_hi:[0,1]
	v_pk_mul_f32 v[6:7], v[2:3], v[6:7]
	v_pk_mul_f32 v[8:9], v[10:11], v[8:9]
	v_pk_mul_f32 v[18:19], v[4:5], v[18:19]
	v_pk_mul_f32 v[16:17], v[12:13], v[16:17]
	v_pk_fma_f32 v[6:7], v[64:65], v[6:7], v[44:45]
	v_pk_fma_f32 v[8:9], v[26:27], v[8:9], v[58:59]
	v_pk_fma_f32 v[18:19], v[62:63], v[18:19], v[46:47]
	v_pk_fma_f32 v[16:17], v[14:15], v[16:17], v[60:61]
	v_cvt_pk_f16_f32 v6, v6, v7
	v_cvt_pk_f16_f32 v8, v8, v9
	v_cvt_pk_f16_f32 v7, v18, v19
	v_cvt_pk_f16_f32 v9, v16, v17
	global_store_dwordx4 v[24:25], v[6:9], off offset:256
	ds_read_b32 v16, v181 offset:704
	s_waitcnt lgkmcnt(0)
	v_pk_mul_f32 v[6:7], v[16:17], v[154:155] op_sel_hi:[0,1]
	v_pk_mul_f32 v[2:3], v[2:3], v[6:7]
	s_nop 0
	v_pk_fma_f32 v[2:3], v[64:65], v[2:3], v[44:45]
	s_nop 0
	v_cvt_pk_f16_f32 v6, v2, v3
	v_pk_mul_f32 v[2:3], v[16:17], v[150:151] op_sel_hi:[0,1]
	v_pk_mul_f32 v[2:3], v[10:11], v[2:3]
	s_nop 0
	v_pk_fma_f32 v[2:3], v[26:27], v[2:3], v[58:59]
	s_nop 0
	v_cvt_pk_f16_f32 v8, v2, v3
	v_pk_mul_f32 v[2:3], v[16:17], v[152:153] op_sel_hi:[0,1]
	v_pk_mul_f32 v[2:3], v[4:5], v[2:3]
	s_nop 0
	v_pk_fma_f32 v[2:3], v[62:63], v[2:3], v[46:47]
	s_nop 0
	v_cvt_pk_f16_f32 v7, v2, v3
	v_pk_mul_f32 v[2:3], v[16:17], v[148:149] op_sel_hi:[0,1]
	v_pk_mul_f32 v[2:3], v[12:13], v[2:3]
	s_nop 0
	v_pk_fma_f32 v[2:3], v[14:15], v[2:3], v[60:61]
	s_nop 0
	v_cvt_pk_f16_f32 v9, v2, v3
	global_store_dwordx4 v[0:1], v[6:9], off offset:256
	s_cbranch_vccnz .LBB0_619
	s_andn2_b64 vcc, exec, s[16:17]
	s_cbranch_vccnz .LBB0_618
	s_barrier
	s_branch .LBB0_618

; __device__ __forceinline__ float shx(float v, int m, int lane) { return __int_as_float(__builtin_amdgcn_ds_bpermute((lane ^ m) << 2, __float_as_int(v))); }
;     __device__ __forceinline__ void operator()(const f32x4 (&acc)[2][2][4][2], const Unit& u, int wr, int wc, int fr, int fq) const {
;     ...
;         f32x4 gv[2][2];
; #pragma unroll
;         for (int bj = 0; bj < 2; ++bj)
; #pragma unroll
;             for (int n = 0; n < 2; ++n) gv[bj][n] = *(const f32x4*)(gate + b * 9216 + col0 + bj * HALF + 4 * n) * coef;
;         h16x8 ov[2][4][2];
; #pragma unroll
;         for (int ai = 0; ai < 2; ++ai)
; #pragma unroll
;             for (int m = 0; m < 4; ++m) {
;                 float sq = 0.f;
; #pragma unroll
;                 for (int bj = 0; bj < 2; ++bj) {
;                     const unsigned off = (unsigned)(row0 + ai * HALF + m * 16) * DM + col0 + bj * HALF;
;                     f32x4 xa, xb;
;                     if (F32IN) { xa = *(const f32x4*)(in32 + off); xb = *(const f32x4*)(in32 + off + 4); }
;                     else { const h16x8 xv = *(const h16x8*)(in16 + off); xa = (f32x4){(float)xv[0], (float)xv[1], (float)xv[2], (float)xv[3]}; xb = (f32x4){(float)xv[4], (float)xv[5], (float)xv[6], (float)xv[7]}; }
;                     h16x8 o;
; #pragma unroll
;                     for (int j = 0; j < 4; ++j) { o[j] = (h16)(xa[j] + gv[bj][0][j] * acc[ai][bj][m][0][j]); o[4 + j] = (h16)(xb[j] + gv[bj][1][j] * acc[ai][bj][m][1][j]); }
;                     if (!FINAL) *(h16x8*)(out + off) = o;
;                     ov[ai][m][bj] = o;
; #pragma unroll
;                     for (int j = 0; j < 8; ++j) sq += (float)o[j] * (float)o[j];
;                 }
;                 sq += shx(sq, 16, lane); sq += shx(sq, 32, lane);
;                 if (fq == 0) red[(ai * HALF + wr * 64 + m * 16 + fr) * 4 + wc] = sq;
.LBB0_702:
	s_lshl_b32 s20, s24, 8
	v_or_b32_e32 v146, s20, v173
	v_lshl_add_u32 v144, s73, 18, v176
	v_readlane_b32 s22, v255, 27
	v_add_u32_e32 v32, v144, v146
	v_readlane_b32 s23, v255, 28
	s_lshr_b32 s18, s73, 4
	s_mulk_i32 s18, 0x2400
	v_lshl_add_u64 v[148:149], v[32:33], 1, s[22:23]
	global_load_dwordx4 v[148:151], v[148:149], off
	s_ashr_i32 s19, s18, 31
	s_lshl_b64 s[18:19], s[18:19], 2
	v_mov_b32_e32 v153, v33
	v_or_b32_e32 v152, 0x80, v32
	s_add_u32 s18, s35, s18
	v_lshl_add_u64 v[152:153], v[152:153], 1, s[22:23]
	v_ashrrev_i32_e32 v147, 31, v146
	s_addc_u32 s19, s54, s19
	global_load_dwordx4 v[152:155], v[152:153], off
	v_lshl_add_u64 v[160:161], v[146:147], 2, s[18:19]
	global_load_dwordx4 v[156:159], v[160:161], off
	global_load_dwordx4 v[164:167], v[160:161], off offset:16
	global_load_dwordx4 v[168:171], v[160:161], off offset:512
	global_load_dwordx4 v[204:207], v[160:161], off offset:528
	s_waitcnt vmcnt(0) lgkmcnt(0)
	v_cvt_f32_f16_e32 v190, v148
	v_cvt_f32_f16_sdwa v191, v148 dst_sel:DWORD dst_unused:UNUSED_PAD src0_sel:WORD_1
	v_cvt_f32_f16_e32 v196, v149
	v_cvt_f32_f16_sdwa v197, v149 dst_sel:DWORD dst_unused:UNUSED_PAD src0_sel:WORD_1
	v_cvt_f32_f16_e32 v198, v150
	v_cvt_f32_f16_sdwa v199, v150 dst_sel:DWORD dst_unused:UNUSED_PAD src0_sel:WORD_1
	v_cvt_f32_f16_e32 v208, v151
	v_cvt_f32_f16_sdwa v209, v151 dst_sel:DWORD dst_unused:UNUSED_PAD src0_sel:WORD_1
	v_pk_mul_f32 v[162:163], v[156:157], 0.5 op_sel_hi:[1,0]
	v_pk_mul_f32 v[160:161], v[158:159], 0.5 op_sel_hi:[1,0]
	v_pk_mul_f32 v[158:159], v[164:165], 0.5 op_sel_hi:[1,0]
	v_pk_fma_f32 v[126:127], v[126:127], v[162:163], v[190:191]
	v_cvt_f32_f16_e32 v210, v152
	v_cvt_f32_f16_sdwa v211, v152 dst_sel:DWORD dst_unused:UNUSED_PAD src0_sel:WORD_1
	v_cvt_f32_f16_e32 v212, v153
	v_cvt_f32_f16_sdwa v213, v153 dst_sel:DWORD dst_unused:UNUSED_PAD src0_sel:WORD_1
	v_cvt_f32_f16_e32 v216, v155
	v_cvt_f32_f16_sdwa v217, v155 dst_sel:DWORD dst_unused:UNUSED_PAD src0_sel:WORD_1
	v_pk_mul_f32 v[156:157], v[166:167], 0.5 op_sel_hi:[1,0]
	v_pk_fma_f32 v[128:129], v[128:129], v[160:161], v[196:197]
	v_pk_fma_f32 v[122:123], v[122:123], v[158:159], v[198:199]
	v_cvt_pk_f16_f32 v126, v126, v127
	v_pk_fma_f32 v[124:125], v[124:125], v[156:157], v[208:209]
	v_cvt_pk_f16_f32 v127, v128, v129
	v_cvt_pk_f16_f32 v128, v122, v123
	v_cvt_f32_f16_e32 v122, v126
	v_cvt_f32_f16_sdwa v123, v126 dst_sel:DWORD dst_unused:UNUSED_PAD src0_sel:WORD_1
	v_cvt_pk_f16_f32 v129, v124, v125
	v_cvt_f32_f16_e32 v124, v127
	v_cvt_f32_f16_sdwa v125, v127 dst_sel:DWORD dst_unused:UNUSED_PAD src0_sel:WORD_1
	v_cvt_f32_f16_e32 v214, v154
	v_cvt_f32_f16_sdwa v215, v154 dst_sel:DWORD dst_unused:UNUSED_PAD src0_sel:WORD_1
	v_pk_mul_f32 v[152:153], v[170:171], 0.5 op_sel_hi:[1,0]
	v_pk_mul_f32 v[154:155], v[168:169], 0.5 op_sel_hi:[1,0]
	v_pk_mul_f32 v[148:149], v[206:207], 0.5 op_sel_hi:[1,0]
	v_pk_fma_f32 v[118:119], v[118:119], v[154:155], v[210:211]
	v_pk_fma_f32 v[120:121], v[120:121], v[152:153], v[212:213]
	v_pk_fma_f32 v[116:117], v[116:117], v[148:149], v[216:217]
	v_cvt_f32_f16_e32 v126, v128
	v_cvt_f32_f16_sdwa v127, v128 dst_sel:DWORD dst_unused:UNUSED_PAD src0_sel:WORD_1
	v_cvt_pk_f16_f32 v118, v118, v119
	v_cvt_pk_f16_f32 v119, v120, v121
	v_cvt_pk_f16_f32 v145, v116, v117
	v_pk_mul_f32 v[164:165], v[122:123], v[122:123]
	v_cvt_f32_f16_e32 v128, v129
	v_cvt_f32_f16_sdwa v129, v129 dst_sel:DWORD dst_unused:UNUSED_PAD src0_sel:WORD_1
	v_cvt_f32_f16_e32 v116, v118
	v_cvt_f32_f16_sdwa v117, v118 dst_sel:DWORD dst_unused:UNUSED_PAD src0_sel:WORD_1
	v_cvt_f32_f16_e32 v120, v119
	v_cvt_f32_f16_sdwa v121, v119 dst_sel:DWORD dst_unused:UNUSED_PAD src0_sel:WORD_1
	v_cvt_f32_f16_e32 v118, v145
	v_cvt_f32_f16_sdwa v119, v145 dst_sel:DWORD dst_unused:UNUSED_PAD src0_sel:WORD_1
	v_pk_mul_f32 v[166:167], v[124:125], v[124:125]
	v_add_f32_e32 v145, v164, v165
	v_add_f32_e32 v145, v166, v145
	v_pk_mul_f32 v[168:169], v[126:127], v[126:127]
	v_add_f32_e32 v145, v167, v145
	v_pk_mul_f32 v[150:151], v[204:205], 0.5 op_sel_hi:[1,0]
	v_add_f32_e32 v145, v168, v145
	v_pk_fma_f32 v[114:115], v[114:115], v[150:151], v[214:215]
	v_pk_mul_f32 v[170:171], v[128:129], v[128:129]
	v_add_f32_e32 v145, v169, v145
	v_cvt_pk_f16_f32 v115, v114, v115
	v_add_f32_e32 v145, v170, v145
	v_cvt_f32_f16_e32 v114, v115
	v_cvt_f32_f16_sdwa v115, v115 dst_sel:DWORD dst_unused:UNUSED_PAD src0_sel:WORD_1
	v_pk_mul_f32 v[190:191], v[116:117], v[116:117]
	v_add_f32_e32 v145, v171, v145
	v_add_f32_e32 v145, v190, v145
	v_pk_mul_f32 v[196:197], v[120:121], v[120:121]
	v_add_f32_e32 v145, v191, v145
	v_add_f32_e32 v145, v196, v145
	v_pk_mul_f32 v[198:199], v[114:115], v[114:115]
	v_add_f32_e32 v145, v197, v145
	v_add_f32_e32 v145, v198, v145
	v_pk_mul_f32 v[204:205], v[118:119], v[118:119]
	v_add_f32_e32 v145, v199, v145
	v_add_f32_e32 v145, v204, v145
	v_add_f32_e32 v145, v205, v145
	ds_bpermute_b32 v164, v174, v145
	s_waitcnt lgkmcnt(0)
	v_add_f32_e32 v145, v145, v164
	ds_bpermute_b32 v164, v175, v145
	s_and_saveexec_b64 s[18:19], s[4:5]
	s_cbranch_execz .LBB0_704
	s_waitcnt lgkmcnt(0)
	v_add_f32_e32 v145, v145, v164
	ds_write_b32 v181, v145
; __device__ __forceinline__ float shx(float v, int m, int lane) { return __int_as_float(__builtin_amdgcn_ds_bpermute((lane ^ m) << 2, __float_as_int(v))); }
;     __device__ __forceinline__ void operator()(const f32x4 (&acc)[2][2][4][2], const Unit& u, int wr, int wc, int fr, int fq) const {
;     ...
;             for (int m = 0; m < 4; ++m) {
;                 float sq = 0.f;
; #pragma unroll
;                 for (int bj = 0; bj < 2; ++bj) {
;                     const unsigned off = (unsigned)(row0 + ai * HALF + m * 16) * DM + col0 + bj * HALF;
;                     f32x4 xa, xb;
;                     if (F32IN) { xa = *(const f32x4*)(in32 + off); xb = *(const f32x4*)(in32 + off + 4); }
;                     else { const h16x8 xv = *(const h16x8*)(in16 + off); xa = (f32x4){(float)xv[0], (float)xv[1], (float)xv[2], (float)xv[3]}; xb = (f32x4){(float)xv[4], (float)xv[5], (float)xv[6], (float)xv[7]}; }
;                     h16x8 o;
; #pragma unroll
;                     for (int j = 0; j < 4; ++j) { o[j] = (h16)(xa[j] + gv[bj][0][j] * acc[ai][bj][m][0][j]); o[4 + j] = (h16)(xb[j] + gv[bj][1][j] * acc[ai][bj][m][1][j]); }
;                     if (!FINAL) *(h16x8*)(out + off) = o;
;                     ov[ai][m][bj] = o;
; #pragma unroll
;                     for (int j = 0; j < 8; ++j) sq += (float)o[j] * (float)o[j];
;                 }
;                 sq += shx(sq, 16, lane); sq += shx(sq, 32, lane);
;                 if (fq == 0) red[(ai * HALF + wr * 64 + m * 16 + fr) * 4 + wc] = sq;
.LBB0_704:
	s_or_b64 exec, exec, s[18:19]
	v_readlane_b32 s18, v255, 27
	s_waitcnt lgkmcnt(0)
	v_add_u32_e32 v164, 0x4000, v32
	v_mov_b32_e32 v165, v33
	v_readlane_b32 s19, v255, 28
	v_add_u32_e32 v168, 0x4080, v32
	v_mov_b32_e32 v169, v33
	v_lshl_add_u64 v[164:165], v[164:165], 1, s[18:19]
	global_load_dwordx4 v[164:167], v[164:165], off
	v_lshl_add_u64 v[168:169], v[168:169], 1, s[18:19]
	global_load_dwordx4 v[168:171], v[168:169], off
	s_waitcnt vmcnt(0) lgkmcnt(0)
	v_cvt_f32_f16_e32 v190, v164
	v_cvt_f32_f16_sdwa v191, v164 dst_sel:DWORD dst_unused:UNUSED_PAD src0_sel:WORD_1
	v_cvt_f32_f16_e32 v164, v165
	v_cvt_f32_f16_sdwa v165, v165 dst_sel:DWORD dst_unused:UNUSED_PAD src0_sel:WORD_1
	v_cvt_f32_f16_e32 v196, v166
	v_cvt_f32_f16_sdwa v197, v166 dst_sel:DWORD dst_unused:UNUSED_PAD src0_sel:WORD_1
	v_cvt_f32_f16_e32 v166, v167
	v_cvt_f32_f16_sdwa v167, v167 dst_sel:DWORD dst_unused:UNUSED_PAD src0_sel:WORD_1
	v_pk_fma_f32 v[110:111], v[110:111], v[162:163], v[190:191]
	v_pk_fma_f32 v[112:113], v[112:113], v[160:161], v[164:165]
	v_pk_fma_f32 v[106:107], v[106:107], v[158:159], v[196:197]
	v_cvt_pk_f16_f32 v110, v110, v111
	v_pk_fma_f32 v[108:109], v[108:109], v[156:157], v[166:167]
	v_cvt_pk_f16_f32 v111, v112, v113
	v_cvt_pk_f16_f32 v112, v106, v107
	v_cvt_f32_f16_e32 v106, v110
	v_cvt_f32_f16_sdwa v107, v110 dst_sel:DWORD dst_unused:UNUSED_PAD src0_sel:WORD_1
	v_cvt_f32_f16_e32 v198, v168
	v_cvt_f32_f16_sdwa v199, v168 dst_sel:DWORD dst_unused:UNUSED_PAD src0_sel:WORD_1
	v_cvt_pk_f16_f32 v113, v108, v109
	v_cvt_f32_f16_e32 v108, v111
	v_cvt_f32_f16_sdwa v109, v111 dst_sel:DWORD dst_unused:UNUSED_PAD src0_sel:WORD_1
	v_cvt_f32_f16_e32 v168, v169
	v_cvt_f32_f16_sdwa v169, v169 dst_sel:DWORD dst_unused:UNUSED_PAD src0_sel:WORD_1
	v_cvt_f32_f16_e32 v204, v170
	v_cvt_f32_f16_sdwa v205, v170 dst_sel:DWORD dst_unused:UNUSED_PAD src0_sel:WORD_1
	v_cvt_f32_f16_e32 v110, v112
	v_cvt_f32_f16_sdwa v111, v112 dst_sel:DWORD dst_unused:UNUSED_PAD src0_sel:WORD_1
	v_pk_mul_f32 v[164:165], v[106:107], v[106:107]
	v_cvt_f32_f16_e32 v170, v171
	v_cvt_f32_f16_sdwa v171, v171 dst_sel:DWORD dst_unused:UNUSED_PAD src0_sel:WORD_1
	v_pk_fma_f32 v[102:103], v[102:103], v[154:155], v[198:199]
	v_cvt_f32_f16_e32 v112, v113
	v_cvt_f32_f16_sdwa v113, v113 dst_sel:DWORD dst_unused:UNUSED_PAD src0_sel:WORD_1
	v_pk_mul_f32 v[166:167], v[108:109], v[108:109]
	v_add_f32_e32 v145, v164, v165
	v_pk_fma_f32 v[104:105], v[104:105], v[152:153], v[168:169]
	v_pk_fma_f32 v[98:99], v[98:99], v[150:151], v[204:205]
	v_cvt_pk_f16_f32 v102, v102, v103
	v_add_f32_e32 v145, v166, v145
	v_cvt_pk_f16_f32 v103, v104, v105
	v_cvt_pk_f16_f32 v104, v98, v99
	v_cvt_f32_f16_e32 v98, v102
	v_cvt_f32_f16_sdwa v99, v102 dst_sel:DWORD dst_unused:UNUSED_PAD src0_sel:WORD_1
	v_pk_mul_f32 v[168:169], v[110:111], v[110:111]
	v_add_f32_e32 v145, v167, v145
	v_add_f32_e32 v145, v168, v145
	v_pk_fma_f32 v[100:101], v[100:101], v[148:149], v[170:171]
	v_cvt_f32_f16_e32 v102, v103
	v_cvt_f32_f16_sdwa v103, v103 dst_sel:DWORD dst_unused:UNUSED_PAD src0_sel:WORD_1
	v_pk_mul_f32 v[170:171], v[112:113], v[112:113]
	v_add_f32_e32 v145, v169, v145
	v_add_f32_e32 v145, v170, v145
	v_cvt_pk_f16_f32 v105, v100, v101
	v_cvt_f32_f16_e32 v100, v104
	v_cvt_f32_f16_sdwa v101, v104 dst_sel:DWORD dst_unused:UNUSED_PAD src0_sel:WORD_1
	v_pk_mul_f32 v[190:191], v[98:99], v[98:99]
	v_add_f32_e32 v145, v171, v145
	v_add_f32_e32 v145, v190, v145
	v_cvt_f32_f16_e32 v104, v105
	v_cvt_f32_f16_sdwa v105, v105 dst_sel:DWORD dst_unused:UNUSED_PAD src0_sel:WORD_1
	v_pk_mul_f32 v[196:197], v[102:103], v[102:103]
	v_add_f32_e32 v145, v191, v145
	v_add_f32_e32 v145, v196, v145
	v_pk_mul_f32 v[198:199], v[100:101], v[100:101]
	v_add_f32_e32 v145, v197, v145
	v_add_f32_e32 v145, v198, v145
	v_pk_mul_f32 v[204:205], v[104:105], v[104:105]
	v_add_f32_e32 v145, v199, v145
	v_add_f32_e32 v145, v204, v145
	v_add_f32_e32 v145, v205, v145
	ds_bpermute_b32 v164, v174, v145
	s_waitcnt lgkmcnt(0)
	v_add_f32_e32 v145, v145, v164
	ds_bpermute_b32 v164, v175, v145
	s_and_saveexec_b64 s[18:19], s[4:5]
	s_cbranch_execz .LBB0_706
	s_waitcnt lgkmcnt(0)
	v_add_f32_e32 v145, v145, v164
	ds_write_b32 v181, v145 offset:256
.LBB0_706:
	s_or_b64 exec, exec, s[18:19]
	v_readlane_b32 s18, v255, 27
	s_waitcnt lgkmcnt(0)
	v_add_u32_e32 v164, 0x8000, v32
	v_mov_b32_e32 v165, v33
	v_readlane_b32 s19, v255, 28
	v_add_u32_e32 v168, 0x8080, v32
	v_mov_b32_e32 v169, v33
	v_lshl_add_u64 v[164:165], v[164:165], 1, s[18:19]
	global_load_dwordx4 v[164:167], v[164:165], off
	v_lshl_add_u64 v[168:169], v[168:169], 1, s[18:19]
	global_load_dwordx4 v[168:171], v[168:169], off
	s_waitcnt vmcnt(0) lgkmcnt(0)
; __device__ __forceinline__ float shx(float v, int m, int lane) { return __int_as_float(__builtin_amdgcn_ds_bpermute((lane ^ m) << 2, __float_as_int(v))); }
;     __device__ __forceinline__ void operator()(const f32x4 (&acc)[2][2][4][2], const Unit& u, int wr, int wc, int fr, int fq) const {
;     ...
;             for (int m = 0; m < 4; ++m) {
;                 float sq = 0.f;
; #pragma unroll
;                 for (int bj = 0; bj < 2; ++bj) {
;                     const unsigned off = (unsigned)(row0 + ai * HALF + m * 16) * DM + col0 + bj * HALF;
;                     f32x4 xa, xb;
;                     if (F32IN) { xa = *(const f32x4*)(in32 + off); xb = *(const f32x4*)(in32 + off + 4); }
;                     else { const h16x8 xv = *(const h16x8*)(in16 + off); xa = (f32x4){(float)xv[0], (float)xv[1], (float)xv[2], (float)xv[3]}; xb = (f32x4){(float)xv[4], (float)xv[5], (float)xv[6], (float)xv[7]}; }
;                     h16x8 o;
; #pragma unroll
;                     for (int j = 0; j < 4; ++j) { o[j] = (h16)(xa[j] + gv[bj][0][j] * acc[ai][bj][m][0][j]); o[4 + j] = (h16)(xb[j] + gv[bj][1][j] * acc[ai][bj][m][1][j]); }
;                     if (!FINAL) *(h16x8*)(out + off) = o;
;                     ov[ai][m][bj] = o;
; #pragma unroll
;                     for (int j = 0; j < 8; ++j) sq += (float)o[j] * (float)o[j];
;                 }
;                 sq += shx(sq, 16, lane); sq += shx(sq, 32, lane);
;                 if (fq == 0) red[(ai * HALF + wr * 64 + m * 16 + fr) * 4 + wc] = sq;
	v_cvt_f32_f16_e32 v190, v164
	v_cvt_f32_f16_sdwa v191, v164 dst_sel:DWORD dst_unused:UNUSED_PAD src0_sel:WORD_1
	v_cvt_f32_f16_e32 v164, v165
	v_cvt_f32_f16_sdwa v165, v165 dst_sel:DWORD dst_unused:UNUSED_PAD src0_sel:WORD_1
	v_cvt_f32_f16_e32 v196, v166
	v_cvt_f32_f16_sdwa v197, v166 dst_sel:DWORD dst_unused:UNUSED_PAD src0_sel:WORD_1
	v_cvt_f32_f16_e32 v166, v167
	v_cvt_f32_f16_sdwa v167, v167 dst_sel:DWORD dst_unused:UNUSED_PAD src0_sel:WORD_1
	v_pk_fma_f32 v[94:95], v[94:95], v[162:163], v[190:191]
	v_cvt_f32_f16_e32 v198, v168
	v_cvt_f32_f16_sdwa v199, v168 dst_sel:DWORD dst_unused:UNUSED_PAD src0_sel:WORD_1
	v_cvt_f32_f16_e32 v168, v169
	v_cvt_f32_f16_sdwa v169, v169 dst_sel:DWORD dst_unused:UNUSED_PAD src0_sel:WORD_1
	v_cvt_f32_f16_e32 v204, v170
	v_cvt_f32_f16_sdwa v205, v170 dst_sel:DWORD dst_unused:UNUSED_PAD src0_sel:WORD_1
	v_cvt_f32_f16_e32 v170, v171
	v_cvt_f32_f16_sdwa v171, v171 dst_sel:DWORD dst_unused:UNUSED_PAD src0_sel:WORD_1
	v_pk_fma_f32 v[96:97], v[96:97], v[160:161], v[164:165]
	v_pk_fma_f32 v[90:91], v[90:91], v[158:159], v[196:197]
	v_cvt_pk_f16_f32 v94, v94, v95
	v_pk_fma_f32 v[92:93], v[92:93], v[156:157], v[166:167]
	v_cvt_pk_f16_f32 v95, v96, v97
	v_cvt_pk_f16_f32 v96, v90, v91
	v_cvt_f32_f16_e32 v90, v94
	v_cvt_f32_f16_sdwa v91, v94 dst_sel:DWORD dst_unused:UNUSED_PAD src0_sel:WORD_1
	v_cvt_pk_f16_f32 v97, v92, v93
	v_cvt_f32_f16_e32 v92, v95
	v_cvt_f32_f16_sdwa v93, v95 dst_sel:DWORD dst_unused:UNUSED_PAD src0_sel:WORD_1
	v_pk_fma_f32 v[86:87], v[86:87], v[154:155], v[198:199]
	v_pk_fma_f32 v[88:89], v[88:89], v[152:153], v[168:169]
	v_pk_fma_f32 v[84:85], v[84:85], v[148:149], v[170:171]
	v_cvt_f32_f16_e32 v94, v96
	v_cvt_f32_f16_sdwa v95, v96 dst_sel:DWORD dst_unused:UNUSED_PAD src0_sel:WORD_1
	v_cvt_pk_f16_f32 v86, v86, v87
	v_cvt_pk_f16_f32 v87, v88, v89
	v_cvt_pk_f16_f32 v145, v84, v85
	v_pk_mul_f32 v[164:165], v[90:91], v[90:91]
	v_cvt_f32_f16_e32 v96, v97
	v_cvt_f32_f16_sdwa v97, v97 dst_sel:DWORD dst_unused:UNUSED_PAD src0_sel:WORD_1
	v_cvt_f32_f16_e32 v84, v86
	v_cvt_f32_f16_sdwa v85, v86 dst_sel:DWORD dst_unused:UNUSED_PAD src0_sel:WORD_1
	v_cvt_f32_f16_e32 v88, v87
	v_cvt_f32_f16_sdwa v89, v87 dst_sel:DWORD dst_unused:UNUSED_PAD src0_sel:WORD_1
	v_cvt_f32_f16_e32 v86, v145
	v_cvt_f32_f16_sdwa v87, v145 dst_sel:DWORD dst_unused:UNUSED_PAD src0_sel:WORD_1
	v_pk_mul_f32 v[166:167], v[92:93], v[92:93]
	v_add_f32_e32 v145, v164, v165
	v_add_f32_e32 v145, v166, v145
	v_pk_mul_f32 v[168:169], v[94:95], v[94:95]
	v_add_f32_e32 v145, v167, v145
	v_add_f32_e32 v145, v168, v145
	v_pk_fma_f32 v[82:83], v[82:83], v[150:151], v[204:205]
	v_pk_mul_f32 v[170:171], v[96:97], v[96:97]
	v_add_f32_e32 v145, v169, v145
	v_cvt_pk_f16_f32 v83, v82, v83
	v_add_f32_e32 v145, v170, v145
	v_cvt_f32_f16_e32 v82, v83
	v_cvt_f32_f16_sdwa v83, v83 dst_sel:DWORD dst_unused:UNUSED_PAD src0_sel:WORD_1
	v_pk_mul_f32 v[190:191], v[84:85], v[84:85]
	v_add_f32_e32 v145, v171, v145
	v_add_f32_e32 v145, v190, v145
	v_pk_mul_f32 v[196:197], v[88:89], v[88:89]
	v_add_f32_e32 v145, v191, v145
	v_add_f32_e32 v145, v196, v145
	v_pk_mul_f32 v[198:199], v[82:83], v[82:83]
	v_add_f32_e32 v145, v197, v145
	v_add_f32_e32 v145, v198, v145
	v_pk_mul_f32 v[204:205], v[86:87], v[86:87]
	v_add_f32_e32 v145, v199, v145
	v_add_f32_e32 v145, v204, v145
	v_add_f32_e32 v145, v205, v145
	ds_bpermute_b32 v164, v174, v145
	s_waitcnt lgkmcnt(0)
	v_add_f32_e32 v145, v145, v164
	ds_bpermute_b32 v164, v175, v145
	s_and_saveexec_b64 s[18:19], s[4:5]
	s_cbranch_execz .LBB0_708
	s_waitcnt lgkmcnt(0)
	v_add_f32_e32 v145, v145, v164
	ds_write_b32 v181, v145 offset:512
.LBB0_708:
	s_or_b64 exec, exec, s[18:19]
	v_readlane_b32 s18, v255, 27
	s_waitcnt lgkmcnt(0)
	v_add_u32_e32 v164, 0xc000, v32
	v_mov_b32_e32 v165, v33
	v_readlane_b32 s19, v255, 28
	v_add_u32_e32 v168, 0xc080, v32
	v_mov_b32_e32 v169, v33
	v_lshl_add_u64 v[164:165], v[164:165], 1, s[18:19]
	global_load_dwordx4 v[164:167], v[164:165], off
	v_lshl_add_u64 v[168:169], v[168:169], 1, s[18:19]
	global_load_dwordx4 v[168:171], v[168:169], off
	s_waitcnt vmcnt(0) lgkmcnt(0)
	v_cvt_f32_f16_e32 v190, v164
	v_cvt_f32_f16_sdwa v191, v164 dst_sel:DWORD dst_unused:UNUSED_PAD src0_sel:WORD_1
	v_cvt_f32_f16_e32 v164, v165
	v_cvt_f32_f16_sdwa v165, v165 dst_sel:DWORD dst_unused:UNUSED_PAD src0_sel:WORD_1
	v_cvt_f32_f16_e32 v196, v166
	v_cvt_f32_f16_sdwa v197, v166 dst_sel:DWORD dst_unused:UNUSED_PAD src0_sel:WORD_1
	v_cvt_f32_f16_e32 v166, v167
	v_cvt_f32_f16_sdwa v167, v167 dst_sel:DWORD dst_unused:UNUSED_PAD src0_sel:WORD_1
	v_pk_fma_f32 v[78:79], v[78:79], v[162:163], v[190:191]
	v_pk_fma_f32 v[80:81], v[80:81], v[160:161], v[164:165]
	v_pk_fma_f32 v[74:75], v[74:75], v[158:159], v[196:197]
	v_cvt_pk_f16_f32 v78, v78, v79
	v_pk_fma_f32 v[76:77], v[76:77], v[156:157], v[166:167]
	v_cvt_pk_f16_f32 v79, v80, v81
	v_cvt_pk_f16_f32 v80, v74, v75
	v_cvt_f32_f16_e32 v74, v78
	v_cvt_f32_f16_sdwa v75, v78 dst_sel:DWORD dst_unused:UNUSED_PAD src0_sel:WORD_1
	v_cvt_f32_f16_e32 v198, v168
	v_cvt_f32_f16_sdwa v199, v168 dst_sel:DWORD dst_unused:UNUSED_PAD src0_sel:WORD_1
	v_cvt_pk_f16_f32 v81, v76, v77
	v_cvt_f32_f16_e32 v76, v79
	v_cvt_f32_f16_sdwa v77, v79 dst_sel:DWORD dst_unused:UNUSED_PAD src0_sel:WORD_1
	v_cvt_f32_f16_e32 v168, v169
	v_cvt_f32_f16_sdwa v169, v169 dst_sel:DWORD dst_unused:UNUSED_PAD src0_sel:WORD_1
	v_cvt_f32_f16_e32 v204, v170
	v_cvt_f32_f16_sdwa v205, v170 dst_sel:DWORD dst_unused:UNUSED_PAD src0_sel:WORD_1
	v_cvt_f32_f16_e32 v78, v80
	v_cvt_f32_f16_sdwa v79, v80 dst_sel:DWORD dst_unused:UNUSED_PAD src0_sel:WORD_1
	v_pk_mul_f32 v[164:165], v[74:75], v[74:75]
	v_cvt_f32_f16_e32 v170, v171
; __device__ __forceinline__ float shx(float v, int m, int lane) { return __int_as_float(__builtin_amdgcn_ds_bpermute((lane ^ m) << 2, __float_as_int(v))); }
;     __device__ __forceinline__ void operator()(const f32x4 (&acc)[2][2][4][2], const Unit& u, int wr, int wc, int fr, int fq) const {
;     ...
;             for (int m = 0; m < 4; ++m) {
;                 float sq = 0.f;
; #pragma unroll
;                 for (int bj = 0; bj < 2; ++bj) {
;                     const unsigned off = (unsigned)(row0 + ai * HALF + m * 16) * DM + col0 + bj * HALF;
;                     f32x4 xa, xb;
;                     if (F32IN) { xa = *(const f32x4*)(in32 + off); xb = *(const f32x4*)(in32 + off + 4); }
;                     else { const h16x8 xv = *(const h16x8*)(in16 + off); xa = (f32x4){(float)xv[0], (float)xv[1], (float)xv[2], (float)xv[3]}; xb = (f32x4){(float)xv[4], (float)xv[5], (float)xv[6], (float)xv[7]}; }
;                     h16x8 o;
; #pragma unroll
;                     for (int j = 0; j < 4; ++j) { o[j] = (h16)(xa[j] + gv[bj][0][j] * acc[ai][bj][m][0][j]); o[4 + j] = (h16)(xb[j] + gv[bj][1][j] * acc[ai][bj][m][1][j]); }
;                     if (!FINAL) *(h16x8*)(out + off) = o;
;                     ov[ai][m][bj] = o;
; #pragma unroll
;                     for (int j = 0; j < 8; ++j) sq += (float)o[j] * (float)o[j];
;                 }
;                 sq += shx(sq, 16, lane); sq += shx(sq, 32, lane);
;                 if (fq == 0) red[(ai * HALF + wr * 64 + m * 16 + fr) * 4 + wc] = sq;
	v_cvt_f32_f16_sdwa v171, v171 dst_sel:DWORD dst_unused:UNUSED_PAD src0_sel:WORD_1
	v_pk_fma_f32 v[70:71], v[70:71], v[154:155], v[198:199]
	v_cvt_f32_f16_e32 v80, v81
	v_cvt_f32_f16_sdwa v81, v81 dst_sel:DWORD dst_unused:UNUSED_PAD src0_sel:WORD_1
	v_pk_mul_f32 v[166:167], v[76:77], v[76:77]
	v_add_f32_e32 v145, v164, v165
	v_pk_fma_f32 v[72:73], v[72:73], v[152:153], v[168:169]
	v_pk_fma_f32 v[66:67], v[66:67], v[150:151], v[204:205]
	v_cvt_pk_f16_f32 v70, v70, v71
	v_add_f32_e32 v145, v166, v145
	v_cvt_pk_f16_f32 v71, v72, v73
	v_cvt_pk_f16_f32 v72, v66, v67
	v_cvt_f32_f16_e32 v66, v70
	v_cvt_f32_f16_sdwa v67, v70 dst_sel:DWORD dst_unused:UNUSED_PAD src0_sel:WORD_1
	v_pk_mul_f32 v[168:169], v[78:79], v[78:79]
	v_add_f32_e32 v145, v167, v145
	v_add_f32_e32 v145, v168, v145
	v_pk_fma_f32 v[68:69], v[68:69], v[148:149], v[170:171]
	v_cvt_f32_f16_e32 v70, v71
	v_cvt_f32_f16_sdwa v71, v71 dst_sel:DWORD dst_unused:UNUSED_PAD src0_sel:WORD_1
	v_pk_mul_f32 v[170:171], v[80:81], v[80:81]
	v_add_f32_e32 v145, v169, v145
	v_add_f32_e32 v145, v170, v145
	v_cvt_pk_f16_f32 v73, v68, v69
	v_cvt_f32_f16_e32 v68, v72
	v_cvt_f32_f16_sdwa v69, v72 dst_sel:DWORD dst_unused:UNUSED_PAD src0_sel:WORD_1
	v_pk_mul_f32 v[190:191], v[66:67], v[66:67]
	v_add_f32_e32 v145, v171, v145
	v_add_f32_e32 v145, v190, v145
	v_cvt_f32_f16_e32 v72, v73
	v_cvt_f32_f16_sdwa v73, v73 dst_sel:DWORD dst_unused:UNUSED_PAD src0_sel:WORD_1
	v_pk_mul_f32 v[196:197], v[70:71], v[70:71]
	v_add_f32_e32 v145, v191, v145
	v_add_f32_e32 v145, v196, v145
	v_pk_mul_f32 v[198:199], v[68:69], v[68:69]
	v_add_f32_e32 v145, v197, v145
	v_add_f32_e32 v145, v198, v145
	v_pk_mul_f32 v[204:205], v[72:73], v[72:73]
	v_add_f32_e32 v145, v199, v145
	v_add_f32_e32 v145, v204, v145
	v_add_f32_e32 v145, v205, v145
	ds_bpermute_b32 v164, v174, v145
	s_waitcnt lgkmcnt(0)
	v_add_f32_e32 v145, v145, v164
	ds_bpermute_b32 v164, v175, v145
	s_and_saveexec_b64 s[18:19], s[4:5]
	s_cbranch_execz .LBB0_710
	s_waitcnt lgkmcnt(0)
	v_add_f32_e32 v145, v145, v164
	ds_write_b32 v181, v145 offset:768
.LBB0_710:
	s_or_b64 exec, exec, s[18:19]
	v_readlane_b32 s18, v255, 27
	s_waitcnt lgkmcnt(0)
	v_add_u32_e32 v164, 0x20000, v32
	v_mov_b32_e32 v165, v33
	v_readlane_b32 s19, v255, 28
	v_add_u32_e32 v168, 0x20080, v32
	v_mov_b32_e32 v169, v33
	v_lshl_add_u64 v[164:165], v[164:165], 1, s[18:19]
	global_load_dwordx4 v[164:167], v[164:165], off
	v_lshl_add_u64 v[168:169], v[168:169], 1, s[18:19]
	global_load_dwordx4 v[168:171], v[168:169], off
	s_waitcnt vmcnt(0) lgkmcnt(0)
	v_cvt_f32_f16_e32 v190, v164
	v_cvt_f32_f16_sdwa v191, v164 dst_sel:DWORD dst_unused:UNUSED_PAD src0_sel:WORD_1
	v_cvt_f32_f16_e32 v164, v165
	v_cvt_f32_f16_sdwa v165, v165 dst_sel:DWORD dst_unused:UNUSED_PAD src0_sel:WORD_1
	v_cvt_f32_f16_e32 v196, v166
	v_cvt_f32_f16_sdwa v197, v166 dst_sel:DWORD dst_unused:UNUSED_PAD src0_sel:WORD_1
	v_cvt_f32_f16_e32 v166, v167
	v_cvt_f32_f16_sdwa v167, v167 dst_sel:DWORD dst_unused:UNUSED_PAD src0_sel:WORD_1
	v_pk_fma_f32 v[62:63], v[62:63], v[162:163], v[190:191]
	v_cvt_f32_f16_e32 v198, v168
	v_cvt_f32_f16_sdwa v199, v168 dst_sel:DWORD dst_unused:UNUSED_PAD src0_sel:WORD_1
	v_cvt_f32_f16_e32 v168, v169
	v_cvt_f32_f16_sdwa v169, v169 dst_sel:DWORD dst_unused:UNUSED_PAD src0_sel:WORD_1
	v_cvt_f32_f16_e32 v204, v170
	v_cvt_f32_f16_sdwa v205, v170 dst_sel:DWORD dst_unused:UNUSED_PAD src0_sel:WORD_1
	v_cvt_f32_f16_e32 v170, v171
	v_cvt_f32_f16_sdwa v171, v171 dst_sel:DWORD dst_unused:UNUSED_PAD src0_sel:WORD_1
	v_pk_fma_f32 v[64:65], v[64:65], v[160:161], v[164:165]
	v_pk_fma_f32 v[58:59], v[58:59], v[158:159], v[196:197]
	v_cvt_pk_f16_f32 v62, v62, v63
	v_pk_fma_f32 v[60:61], v[60:61], v[156:157], v[166:167]
	v_cvt_pk_f16_f32 v63, v64, v65
	v_cvt_pk_f16_f32 v64, v58, v59
	v_cvt_f32_f16_e32 v58, v62
	v_cvt_f32_f16_sdwa v59, v62 dst_sel:DWORD dst_unused:UNUSED_PAD src0_sel:WORD_1
	v_cvt_pk_f16_f32 v65, v60, v61
	v_cvt_f32_f16_e32 v60, v63
	v_cvt_f32_f16_sdwa v61, v63 dst_sel:DWORD dst_unused:UNUSED_PAD src0_sel:WORD_1
	v_pk_fma_f32 v[54:55], v[54:55], v[154:155], v[198:199]
	v_pk_fma_f32 v[56:57], v[56:57], v[152:153], v[168:169]
	v_pk_fma_f32 v[52:53], v[52:53], v[148:149], v[170:171]
	v_cvt_f32_f16_e32 v62, v64
	v_cvt_f32_f16_sdwa v63, v64 dst_sel:DWORD dst_unused:UNUSED_PAD src0_sel:WORD_1
	v_cvt_pk_f16_f32 v54, v54, v55
	v_cvt_pk_f16_f32 v55, v56, v57
	v_cvt_pk_f16_f32 v145, v52, v53
	v_pk_mul_f32 v[164:165], v[58:59], v[58:59]
	v_cvt_f32_f16_e32 v64, v65
	v_cvt_f32_f16_sdwa v65, v65 dst_sel:DWORD dst_unused:UNUSED_PAD src0_sel:WORD_1
	v_cvt_f32_f16_e32 v52, v54
	v_cvt_f32_f16_sdwa v53, v54 dst_sel:DWORD dst_unused:UNUSED_PAD src0_sel:WORD_1
	v_cvt_f32_f16_e32 v56, v55
	v_cvt_f32_f16_sdwa v57, v55 dst_sel:DWORD dst_unused:UNUSED_PAD src0_sel:WORD_1
	v_cvt_f32_f16_e32 v54, v145
	v_cvt_f32_f16_sdwa v55, v145 dst_sel:DWORD dst_unused:UNUSED_PAD src0_sel:WORD_1
	v_pk_mul_f32 v[166:167], v[60:61], v[60:61]
	v_add_f32_e32 v145, v164, v165
	v_add_f32_e32 v145, v166, v145
	v_pk_mul_f32 v[168:169], v[62:63], v[62:63]
	v_add_f32_e32 v145, v167, v145
	v_add_f32_e32 v145, v168, v145
	v_pk_fma_f32 v[50:51], v[50:51], v[150:151], v[204:205]
	v_pk_mul_f32 v[170:171], v[64:65], v[64:65]
	v_add_f32_e32 v145, v169, v145
	v_cvt_pk_f16_f32 v51, v50, v51
	v_add_f32_e32 v145, v170, v145
	v_cvt_f32_f16_e32 v50, v51
	v_cvt_f32_f16_sdwa v51, v51 dst_sel:DWORD dst_unused:UNUSED_PAD src0_sel:WORD_1
	v_pk_mul_f32 v[190:191], v[52:53], v[52:53]
	v_add_f32_e32 v145, v171, v145
	v_add_f32_e32 v145, v190, v145
	v_pk_mul_f32 v[196:197], v[56:57], v[56:57]
	v_add_f32_e32 v145, v191, v145
	v_add_f32_e32 v145, v196, v145
	v_pk_mul_f32 v[198:199], v[50:51], v[50:51]
	v_add_f32_e32 v145, v197, v145
	v_add_f32_e32 v145, v198, v145
	v_pk_mul_f32 v[204:205], v[54:55], v[54:55]
	v_add_f32_e32 v145, v199, v145
	v_add_f32_e32 v145, v204, v145
	v_add_f32_e32 v145, v205, v145
	ds_bpermute_b32 v164, v174, v145
	s_waitcnt lgkmcnt(0)
	v_add_f32_e32 v145, v145, v164
	ds_bpermute_b32 v164, v175, v145
	s_and_saveexec_b64 s[18:19], s[4:5]
	s_cbranch_execz .LBB0_712
	s_waitcnt lgkmcnt(0)
	v_add_f32_e32 v145, v145, v164
	ds_write_b32 v181, v145 offset:2048
; __device__ __forceinline__ float shx(float v, int m, int lane) { return __int_as_float(__builtin_amdgcn_ds_bpermute((lane ^ m) << 2, __float_as_int(v))); }
;     __device__ __forceinline__ void operator()(const f32x4 (&acc)[2][2][4][2], const Unit& u, int wr, int wc, int fr, int fq) const {
;     ...
;             for (int m = 0; m < 4; ++m) {
;                 float sq = 0.f;
; #pragma unroll
;                 for (int bj = 0; bj < 2; ++bj) {
;                     const unsigned off = (unsigned)(row0 + ai * HALF + m * 16) * DM + col0 + bj * HALF;
;                     f32x4 xa, xb;
;                     if (F32IN) { xa = *(const f32x4*)(in32 + off); xb = *(const f32x4*)(in32 + off + 4); }
;                     else { const h16x8 xv = *(const h16x8*)(in16 + off); xa = (f32x4){(float)xv[0], (float)xv[1], (float)xv[2], (float)xv[3]}; xb = (f32x4){(float)xv[4], (float)xv[5], (float)xv[6], (float)xv[7]}; }
;                     h16x8 o;
; #pragma unroll
;                     for (int j = 0; j < 4; ++j) { o[j] = (h16)(xa[j] + gv[bj][0][j] * acc[ai][bj][m][0][j]); o[4 + j] = (h16)(xb[j] + gv[bj][1][j] * acc[ai][bj][m][1][j]); }
;                     if (!FINAL) *(h16x8*)(out + off) = o;
;                     ov[ai][m][bj] = o;
; #pragma unroll
;                     for (int j = 0; j < 8; ++j) sq += (float)o[j] * (float)o[j];
;                 }
;                 sq += shx(sq, 16, lane); sq += shx(sq, 32, lane);
;                 if (fq == 0) red[(ai * HALF + wr * 64 + m * 16 + fr) * 4 + wc] = sq;
.LBB0_712:
	s_or_b64 exec, exec, s[18:19]
	v_readlane_b32 s18, v255, 27
	s_waitcnt lgkmcnt(0)
	v_add_u32_e32 v164, 0x24000, v32
	v_mov_b32_e32 v165, v33
	v_readlane_b32 s19, v255, 28
	v_add_u32_e32 v168, 0x24080, v32
	v_mov_b32_e32 v169, v33
	v_lshl_add_u64 v[164:165], v[164:165], 1, s[18:19]
	global_load_dwordx4 v[164:167], v[164:165], off
	v_lshl_add_u64 v[168:169], v[168:169], 1, s[18:19]
	global_load_dwordx4 v[168:171], v[168:169], off
	s_waitcnt vmcnt(0) lgkmcnt(0)
	v_cvt_f32_f16_e32 v190, v164
	v_cvt_f32_f16_sdwa v191, v164 dst_sel:DWORD dst_unused:UNUSED_PAD src0_sel:WORD_1
	v_cvt_f32_f16_e32 v164, v165
	v_cvt_f32_f16_sdwa v165, v165 dst_sel:DWORD dst_unused:UNUSED_PAD src0_sel:WORD_1
	v_cvt_f32_f16_e32 v196, v166
	v_cvt_f32_f16_sdwa v197, v166 dst_sel:DWORD dst_unused:UNUSED_PAD src0_sel:WORD_1
	v_cvt_f32_f16_e32 v166, v167
	v_cvt_f32_f16_sdwa v167, v167 dst_sel:DWORD dst_unused:UNUSED_PAD src0_sel:WORD_1
	v_cvt_f32_f16_e32 v198, v168
	v_cvt_f32_f16_sdwa v199, v168 dst_sel:DWORD dst_unused:UNUSED_PAD src0_sel:WORD_1
	v_cvt_f32_f16_e32 v168, v169
	v_cvt_f32_f16_sdwa v169, v169 dst_sel:DWORD dst_unused:UNUSED_PAD src0_sel:WORD_1
	v_cvt_f32_f16_e32 v204, v170
	v_cvt_f32_f16_sdwa v205, v170 dst_sel:DWORD dst_unused:UNUSED_PAD src0_sel:WORD_1
	v_cvt_f32_f16_e32 v170, v171
	v_cvt_f32_f16_sdwa v171, v171 dst_sel:DWORD dst_unused:UNUSED_PAD src0_sel:WORD_1
	v_pk_fma_f32 v[46:47], v[46:47], v[162:163], v[190:191]
	v_pk_fma_f32 v[48:49], v[48:49], v[160:161], v[164:165]
	v_pk_fma_f32 v[44:45], v[44:45], v[156:157], v[166:167]
	v_cvt_pk_f16_f32 v46, v46, v47
	v_cvt_pk_f16_f32 v47, v48, v49
	v_cvt_pk_f16_f32 v145, v44, v45
	v_cvt_f32_f16_e32 v44, v46
	v_cvt_f32_f16_sdwa v45, v46 dst_sel:DWORD dst_unused:UNUSED_PAD src0_sel:WORD_1
	v_pk_fma_f32 v[42:43], v[42:43], v[158:159], v[196:197]
	v_cvt_f32_f16_e32 v48, v47
	v_cvt_f32_f16_sdwa v49, v47 dst_sel:DWORD dst_unused:UNUSED_PAD src0_sel:WORD_1
	v_pk_fma_f32 v[38:39], v[38:39], v[154:155], v[198:199]
	v_pk_fma_f32 v[40:41], v[40:41], v[152:153], v[168:169]
	v_pk_fma_f32 v[36:37], v[36:37], v[148:149], v[170:171]
	v_cvt_pk_f16_f32 v43, v42, v43
	v_cvt_pk_f16_f32 v38, v38, v39
	v_cvt_pk_f16_f32 v39, v40, v41
	v_cvt_pk_f16_f32 v164, v36, v37
	v_cvt_f32_f16_e32 v42, v43
	v_cvt_f32_f16_sdwa v43, v43 dst_sel:DWORD dst_unused:UNUSED_PAD src0_sel:WORD_1
	v_cvt_f32_f16_e32 v36, v38
	v_cvt_f32_f16_sdwa v37, v38 dst_sel:DWORD dst_unused:UNUSED_PAD src0_sel:WORD_1
	v_cvt_f32_f16_e32 v40, v39
	v_cvt_f32_f16_sdwa v41, v39 dst_sel:DWORD dst_unused:UNUSED_PAD src0_sel:WORD_1
	v_cvt_f32_f16_e32 v38, v164
	v_cvt_f32_f16_sdwa v39, v164 dst_sel:DWORD dst_unused:UNUSED_PAD src0_sel:WORD_1
	v_pk_mul_f32 v[164:165], v[44:45], v[44:45]
	v_cvt_f32_f16_e32 v46, v145
	v_cvt_f32_f16_sdwa v47, v145 dst_sel:DWORD dst_unused:UNUSED_PAD src0_sel:WORD_1
	v_pk_mul_f32 v[166:167], v[48:49], v[48:49]
	v_add_f32_e32 v145, v164, v165
	v_add_f32_e32 v145, v166, v145
	v_pk_mul_f32 v[168:169], v[42:43], v[42:43]
	v_add_f32_e32 v145, v167, v145
	v_add_f32_e32 v145, v168, v145
	v_pk_fma_f32 v[34:35], v[34:35], v[150:151], v[204:205]
	v_pk_mul_f32 v[170:171], v[46:47], v[46:47]
	v_add_f32_e32 v145, v169, v145
	v_cvt_pk_f16_f32 v35, v34, v35
	v_add_f32_e32 v145, v170, v145
	v_cvt_f32_f16_e32 v34, v35
	v_cvt_f32_f16_sdwa v35, v35 dst_sel:DWORD dst_unused:UNUSED_PAD src0_sel:WORD_1
	v_pk_mul_f32 v[190:191], v[36:37], v[36:37]
	v_add_f32_e32 v145, v171, v145
	v_add_f32_e32 v145, v190, v145
	v_pk_mul_f32 v[196:197], v[40:41], v[40:41]
	v_add_f32_e32 v145, v191, v145
	v_add_f32_e32 v145, v196, v145
	v_pk_mul_f32 v[198:199], v[34:35], v[34:35]
	v_add_f32_e32 v145, v197, v145
	v_add_f32_e32 v145, v198, v145
	v_pk_mul_f32 v[204:205], v[38:39], v[38:39]
	v_add_f32_e32 v145, v199, v145
	v_add_f32_e32 v145, v204, v145
	v_add_f32_e32 v145, v205, v145
	ds_bpermute_b32 v164, v174, v145
	s_waitcnt lgkmcnt(0)
	v_add_f32_e32 v145, v145, v164
	ds_bpermute_b32 v164, v175, v145
	s_and_saveexec_b64 s[18:19], s[4:5]
	s_cbranch_execz .LBB0_714
	s_waitcnt lgkmcnt(0)
	v_add_f32_e32 v145, v145, v164
	ds_write_b32 v181, v145 offset:2304
.LBB0_714:
	s_or_b64 exec, exec, s[18:19]
	v_readlane_b32 s18, v255, 27
	s_waitcnt lgkmcnt(0)
	v_add_u32_e32 v164, 0x28000, v32
	v_mov_b32_e32 v165, v33
	v_readlane_b32 s19, v255, 28
	v_add_u32_e32 v168, 0x28080, v32
	v_mov_b32_e32 v169, v33
	v_lshl_add_u64 v[164:165], v[164:165], 1, s[18:19]
	global_load_dwordx4 v[164:167], v[164:165], off
	v_lshl_add_u64 v[168:169], v[168:169], 1, s[18:19]
	global_load_dwordx4 v[168:171], v[168:169], off
	s_waitcnt vmcnt(0) lgkmcnt(0)
; __device__ __forceinline__ float shx(float v, int m, int lane) { return __int_as_float(__builtin_amdgcn_ds_bpermute((lane ^ m) << 2, __float_as_int(v))); }
;     __device__ __forceinline__ void operator()(const f32x4 (&acc)[2][2][4][2], const Unit& u, int wr, int wc, int fr, int fq) const {
;     ...
;             for (int m = 0; m < 4; ++m) {
;                 float sq = 0.f;
; #pragma unroll
;                 for (int bj = 0; bj < 2; ++bj) {
;                     const unsigned off = (unsigned)(row0 + ai * HALF + m * 16) * DM + col0 + bj * HALF;
;                     f32x4 xa, xb;
;                     if (F32IN) { xa = *(const f32x4*)(in32 + off); xb = *(const f32x4*)(in32 + off + 4); }
;                     else { const h16x8 xv = *(const h16x8*)(in16 + off); xa = (f32x4){(float)xv[0], (float)xv[1], (float)xv[2], (float)xv[3]}; xb = (f32x4){(float)xv[4], (float)xv[5], (float)xv[6], (float)xv[7]}; }
;                     h16x8 o;
; #pragma unroll
;                     for (int j = 0; j < 4; ++j) { o[j] = (h16)(xa[j] + gv[bj][0][j] * acc[ai][bj][m][0][j]); o[4 + j] = (h16)(xb[j] + gv[bj][1][j] * acc[ai][bj][m][1][j]); }
;                     if (!FINAL) *(h16x8*)(out + off) = o;
;                     ov[ai][m][bj] = o;
; #pragma unroll
;                     for (int j = 0; j < 8; ++j) sq += (float)o[j] * (float)o[j];
;                 }
;                 sq += shx(sq, 16, lane); sq += shx(sq, 32, lane);
;                 if (fq == 0) red[(ai * HALF + wr * 64 + m * 16 + fr) * 4 + wc] = sq;
	v_cvt_f32_f16_e32 v190, v164
	v_cvt_f32_f16_sdwa v191, v164 dst_sel:DWORD dst_unused:UNUSED_PAD src0_sel:WORD_1
	v_cvt_f32_f16_e32 v164, v165
	v_cvt_f32_f16_sdwa v165, v165 dst_sel:DWORD dst_unused:UNUSED_PAD src0_sel:WORD_1
	v_cvt_f32_f16_e32 v196, v166
	v_cvt_f32_f16_sdwa v197, v166 dst_sel:DWORD dst_unused:UNUSED_PAD src0_sel:WORD_1
	v_cvt_f32_f16_e32 v166, v167
	v_cvt_f32_f16_sdwa v167, v167 dst_sel:DWORD dst_unused:UNUSED_PAD src0_sel:WORD_1
	v_cvt_f32_f16_e32 v198, v168
	v_cvt_f32_f16_sdwa v199, v168 dst_sel:DWORD dst_unused:UNUSED_PAD src0_sel:WORD_1
	v_cvt_f32_f16_e32 v168, v169
	v_cvt_f32_f16_sdwa v169, v169 dst_sel:DWORD dst_unused:UNUSED_PAD src0_sel:WORD_1
	v_cvt_f32_f16_e32 v204, v170
	v_cvt_f32_f16_sdwa v205, v170 dst_sel:DWORD dst_unused:UNUSED_PAD src0_sel:WORD_1
	v_cvt_f32_f16_e32 v170, v171
	v_cvt_f32_f16_sdwa v171, v171 dst_sel:DWORD dst_unused:UNUSED_PAD src0_sel:WORD_1
	v_pk_fma_f32 v[28:29], v[28:29], v[162:163], v[190:191]
	v_pk_fma_f32 v[30:31], v[30:31], v[160:161], v[164:165]
	v_pk_fma_f32 v[26:27], v[26:27], v[156:157], v[166:167]
	v_cvt_pk_f16_f32 v28, v28, v29
	v_cvt_pk_f16_f32 v29, v30, v31
	v_cvt_pk_f16_f32 v145, v26, v27
	v_cvt_f32_f16_e32 v26, v28
	v_cvt_f32_f16_sdwa v27, v28 dst_sel:DWORD dst_unused:UNUSED_PAD src0_sel:WORD_1
	v_pk_fma_f32 v[24:25], v[24:25], v[158:159], v[196:197]
	v_cvt_f32_f16_e32 v30, v29
	v_cvt_f32_f16_sdwa v31, v29 dst_sel:DWORD dst_unused:UNUSED_PAD src0_sel:WORD_1
	v_pk_fma_f32 v[20:21], v[20:21], v[154:155], v[198:199]
	v_pk_fma_f32 v[22:23], v[22:23], v[152:153], v[168:169]
	v_pk_fma_f32 v[18:19], v[18:19], v[148:149], v[170:171]
	v_cvt_pk_f16_f32 v25, v24, v25
	v_cvt_pk_f16_f32 v20, v20, v21
	v_cvt_pk_f16_f32 v21, v22, v23
	v_cvt_pk_f16_f32 v164, v18, v19
	v_cvt_f32_f16_e32 v24, v25
	v_cvt_f32_f16_sdwa v25, v25 dst_sel:DWORD dst_unused:UNUSED_PAD src0_sel:WORD_1
	v_cvt_f32_f16_e32 v18, v20
	v_cvt_f32_f16_sdwa v19, v20 dst_sel:DWORD dst_unused:UNUSED_PAD src0_sel:WORD_1
	v_cvt_f32_f16_e32 v22, v21
	v_cvt_f32_f16_sdwa v23, v21 dst_sel:DWORD dst_unused:UNUSED_PAD src0_sel:WORD_1
	v_cvt_f32_f16_e32 v20, v164
	v_cvt_f32_f16_sdwa v21, v164 dst_sel:DWORD dst_unused:UNUSED_PAD src0_sel:WORD_1
	v_pk_mul_f32 v[164:165], v[26:27], v[26:27]
	v_cvt_f32_f16_e32 v28, v145
	v_cvt_f32_f16_sdwa v29, v145 dst_sel:DWORD dst_unused:UNUSED_PAD src0_sel:WORD_1
	v_pk_mul_f32 v[166:167], v[30:31], v[30:31]
	v_add_f32_e32 v145, v164, v165
	v_add_f32_e32 v145, v166, v145
	v_pk_mul_f32 v[168:169], v[24:25], v[24:25]
	v_add_f32_e32 v145, v167, v145
	v_add_f32_e32 v145, v168, v145
	v_pk_fma_f32 v[16:17], v[16:17], v[150:151], v[204:205]
	v_pk_mul_f32 v[170:171], v[28:29], v[28:29]
	v_add_f32_e32 v145, v169, v145
	v_cvt_pk_f16_f32 v17, v16, v17
	v_add_f32_e32 v145, v170, v145
	v_cvt_f32_f16_e32 v16, v17
	v_cvt_f32_f16_sdwa v17, v17 dst_sel:DWORD dst_unused:UNUSED_PAD src0_sel:WORD_1
	v_pk_mul_f32 v[190:191], v[18:19], v[18:19]
	v_add_f32_e32 v145, v171, v145
	v_add_f32_e32 v145, v190, v145
	v_pk_mul_f32 v[196:197], v[22:23], v[22:23]
	v_add_f32_e32 v145, v191, v145
	v_add_f32_e32 v145, v196, v145
	v_pk_mul_f32 v[198:199], v[16:17], v[16:17]
	v_add_f32_e32 v145, v197, v145
	v_add_f32_e32 v145, v198, v145
	v_pk_mul_f32 v[204:205], v[20:21], v[20:21]
	v_add_f32_e32 v145, v199, v145
	v_add_f32_e32 v145, v204, v145
	v_add_f32_e32 v145, v205, v145
	ds_bpermute_b32 v164, v174, v145
	s_waitcnt lgkmcnt(0)
	v_add_f32_e32 v145, v145, v164
	ds_bpermute_b32 v164, v175, v145
	s_and_saveexec_b64 s[18:19], s[4:5]
	s_cbranch_execz .LBB0_716
	s_waitcnt lgkmcnt(0)
	v_add_f32_e32 v145, v145, v164
	ds_write_b32 v181, v145 offset:2560
; __device__ __forceinline__ float shx(float v, int m, int lane) { return __int_as_float(__builtin_amdgcn_ds_bpermute((lane ^ m) << 2, __float_as_int(v))); }
;     __device__ __forceinline__ void operator()(const f32x4 (&acc)[2][2][4][2], const Unit& u, int wr, int wc, int fr, int fq) const {
;     ...
;             for (int m = 0; m < 4; ++m) {
;                 float sq = 0.f;
; #pragma unroll
;                 for (int bj = 0; bj < 2; ++bj) {
;                     const unsigned off = (unsigned)(row0 + ai * HALF + m * 16) * DM + col0 + bj * HALF;
;                     f32x4 xa, xb;
;                     if (F32IN) { xa = *(const f32x4*)(in32 + off); xb = *(const f32x4*)(in32 + off + 4); }
;                     else { const h16x8 xv = *(const h16x8*)(in16 + off); xa = (f32x4){(float)xv[0], (float)xv[1], (float)xv[2], (float)xv[3]}; xb = (f32x4){(float)xv[4], (float)xv[5], (float)xv[6], (float)xv[7]}; }
;                     h16x8 o;
; #pragma unroll
;                     for (int j = 0; j < 4; ++j) { o[j] = (h16)(xa[j] + gv[bj][0][j] * acc[ai][bj][m][0][j]); o[4 + j] = (h16)(xb[j] + gv[bj][1][j] * acc[ai][bj][m][1][j]); }
;                     if (!FINAL) *(h16x8*)(out + off) = o;
;                     ov[ai][m][bj] = o;
; #pragma unroll
;                     for (int j = 0; j < 8; ++j) sq += (float)o[j] * (float)o[j];
;                 }
;                 sq += shx(sq, 16, lane); sq += shx(sq, 32, lane);
;                 if (fq == 0) red[(ai * HALF + wr * 64 + m * 16 + fr) * 4 + wc] = sq;
;             }
;         asm volatile("s_waitcnt lgkmcnt(0)" ::: "memory"); __builtin_amdgcn_s_barrier(); asm volatile("" ::: "memory");
;         if (tid < 256) {
;             const float part = (red[tid * 4 + 0] + red[tid * 4 + 1]) + (red[tid * 4 + 2] + red[tid * 4 + 3]);
;             __hip_atomic_store(ss + (unsigned)(u.pm * 4 + u.pn) * 256 + tid, part, __ATOMIC_RELAXED, __HIP_MEMORY_SCOPE_AGENT);
.LBB0_716:
	s_or_b64 exec, exec, s[18:19]
	v_readlane_b32 s18, v255, 27
	s_waitcnt lgkmcnt(0)
	v_add_u32_e32 v164, 0x2c000, v32
	v_mov_b32_e32 v165, v33
	v_readlane_b32 s19, v255, 28
	v_add_u32_e32 v32, 0x2c080, v32
	s_nop 0
	v_lshl_add_u64 v[164:165], v[164:165], 1, s[18:19]
	global_load_dwordx4 v[164:167], v[164:165], off
	s_waitcnt vmcnt(0) lgkmcnt(0)
	v_cvt_f32_f16_e32 v168, v164
	v_cvt_f32_f16_sdwa v169, v164 dst_sel:DWORD dst_unused:UNUSED_PAD src0_sel:WORD_1
	v_cvt_f32_f16_e32 v164, v165
	v_cvt_f32_f16_sdwa v165, v165 dst_sel:DWORD dst_unused:UNUSED_PAD src0_sel:WORD_1
	v_pk_fma_f32 v[12:13], v[12:13], v[162:163], v[168:169]
	s_nop 0
	v_cvt_pk_f16_f32 v13, v12, v13
	v_pk_fma_f32 v[14:15], v[14:15], v[160:161], v[164:165]
	v_cvt_f32_f16_e32 v164, v166
	v_cvt_f32_f16_sdwa v165, v166 dst_sel:DWORD dst_unused:UNUSED_PAD src0_sel:WORD_1
	v_cvt_f32_f16_e32 v12, v13
	v_cvt_f32_f16_sdwa v13, v13 dst_sel:DWORD dst_unused:UNUSED_PAD src0_sel:WORD_1
	v_cvt_pk_f16_f32 v15, v14, v15
	v_pk_fma_f32 v[8:9], v[8:9], v[158:159], v[164:165]
	v_cvt_f32_f16_e32 v14, v15
	v_cvt_pk_f16_f32 v8, v8, v9
	v_cvt_f32_f16_e32 v158, v8
	v_cvt_f32_f16_sdwa v159, v8 dst_sel:DWORD dst_unused:UNUSED_PAD src0_sel:WORD_1
	v_cvt_f32_f16_e32 v8, v167
	v_cvt_f32_f16_sdwa v9, v167 dst_sel:DWORD dst_unused:UNUSED_PAD src0_sel:WORD_1
	v_cvt_f32_f16_sdwa v15, v15 dst_sel:DWORD dst_unused:UNUSED_PAD src0_sel:WORD_1
	v_pk_mul_f32 v[162:163], v[12:13], v[12:13]
	v_pk_mul_f32 v[164:165], v[158:159], v[158:159]
	v_pk_fma_f32 v[8:9], v[10:11], v[156:157], v[8:9]
	v_pk_mul_f32 v[160:161], v[14:15], v[14:15]
	v_cvt_pk_f16_f32 v8, v8, v9
	v_cvt_f32_f16_e32 v10, v8
	v_cvt_f32_f16_sdwa v11, v8 dst_sel:DWORD dst_unused:UNUSED_PAD src0_sel:WORD_1
	v_lshl_add_u64 v[8:9], v[32:33], 1, s[18:19]
	global_load_dwordx4 v[166:169], v[8:9], off
	v_add_f32_e32 v32, v162, v163
	v_add_f32_e32 v32, v160, v32
	v_add_f32_e32 v32, v161, v32
	v_add_f32_e32 v32, v164, v32
	v_pk_mul_f32 v[156:157], v[10:11], v[10:11]
	v_add_f32_e32 v32, v165, v32
	v_add_f32_e32 v32, v156, v32
	v_add_f32_e32 v32, v157, v32
	s_waitcnt vmcnt(0) lgkmcnt(0)
	v_cvt_f32_f16_e32 v8, v166
	v_cvt_f32_f16_sdwa v9, v166 dst_sel:DWORD dst_unused:UNUSED_PAD src0_sel:WORD_1
	v_pk_fma_f32 v[4:5], v[4:5], v[154:155], v[8:9]
	v_cvt_f32_f16_e32 v154, v167
	v_cvt_f32_f16_sdwa v155, v167 dst_sel:DWORD dst_unused:UNUSED_PAD src0_sel:WORD_1
	v_cvt_pk_f16_f32 v4, v4, v5
	v_cvt_f32_f16_e32 v8, v4
	v_cvt_f32_f16_sdwa v9, v4 dst_sel:DWORD dst_unused:UNUSED_PAD src0_sel:WORD_1
	v_pk_fma_f32 v[6:7], v[6:7], v[152:153], v[154:155]
	v_cvt_f32_f16_e32 v154, v168
	v_cvt_f32_f16_sdwa v155, v168 dst_sel:DWORD dst_unused:UNUSED_PAD src0_sel:WORD_1
	v_cvt_pk_f16_f32 v6, v6, v7
	v_cvt_f32_f16_e32 v152, v6
	v_cvt_f32_f16_sdwa v153, v6 dst_sel:DWORD dst_unused:UNUSED_PAD src0_sel:WORD_1
	v_pk_fma_f32 v[0:1], v[0:1], v[150:151], v[154:155]
	v_cvt_f32_f16_e32 v154, v169
	v_cvt_f32_f16_sdwa v155, v169 dst_sel:DWORD dst_unused:UNUSED_PAD src0_sel:WORD_1
	v_cvt_pk_f16_f32 v0, v0, v1
	v_pk_mul_f32 v[4:5], v[8:9], v[8:9]
	v_cvt_f32_f16_e32 v150, v0
	v_cvt_f32_f16_sdwa v151, v0 dst_sel:DWORD dst_unused:UNUSED_PAD src0_sel:WORD_1
	v_pk_fma_f32 v[2:3], v[2:3], v[148:149], v[154:155]
	v_add_f32_e32 v4, v4, v32
	v_cvt_pk_f16_f32 v2, v2, v3
	v_pk_mul_f32 v[6:7], v[152:153], v[152:153]
	v_cvt_f32_f16_e32 v148, v2
	v_cvt_f32_f16_sdwa v149, v2 dst_sel:DWORD dst_unused:UNUSED_PAD src0_sel:WORD_1
	v_add_f32_e32 v4, v5, v4
	v_add_f32_e32 v4, v6, v4
	v_pk_mul_f32 v[0:1], v[150:151], v[150:151]
	v_add_f32_e32 v4, v7, v4
	v_add_f32_e32 v0, v0, v4
	v_pk_mul_f32 v[2:3], v[148:149], v[148:149]
	v_add_f32_e32 v0, v1, v0
	v_add_f32_e32 v0, v2, v0
	v_add_f32_e32 v0, v3, v0
	ds_bpermute_b32 v1, v174, v0
	s_waitcnt lgkmcnt(0)
	v_add_f32_e32 v0, v0, v1
	ds_bpermute_b32 v1, v175, v0
	s_and_saveexec_b64 s[18:19], s[4:5]
	s_cbranch_execz .LBB0_718
	s_waitcnt lgkmcnt(0)
	v_add_f32_e32 v0, v0, v1
	ds_write_b32 v181, v0 offset:2816
.LBB0_718:
	s_or_b64 exec, exec, s[18:19]
	s_waitcnt lgkmcnt(0)
	s_barrier
	s_and_saveexec_b64 s[18:19], s[6:7]
	s_cbranch_execz .LBB0_720
	v_readlane_b32 s36, v254, 43
	s_lshl_b32 s21, s73, 10
	v_readlane_b32 s45, v254, 52
	s_mov_b32 s25, s45
	s_add_i32 s24, s21, s20
	s_mov_b32 s21, s45
	v_readlane_b32 s37, v254, 44
	v_readlane_b32 s38, v254, 45
	v_readlane_b32 s39, v254, 46
	v_readlane_b32 s40, v254, 47
	v_readlane_b32 s41, v254, 48
	v_readlane_b32 s42, v254, 49
	v_readlane_b32 s43, v254, 50
	v_readlane_b32 s44, v254, 51
	v_readlane_b32 s46, v254, 53
	v_readlane_b32 s47, v254, 54
	v_readlane_b32 s48, v254, 55
	v_readlane_b32 s49, v254, 56
	v_readlane_b32 s50, v254, 57
	v_readlane_b32 s51, v254, 58
	v_writelane_b32 v254, s12, 43
	s_waitcnt lgkmcnt(0)
	ds_read_b128 v[0:3], v180
	s_waitcnt lgkmcnt(0)
	v_mov_b32_e32 v4, v1
	v_writelane_b32 v254, s13, 44
	v_writelane_b32 v254, s14, 45
	v_writelane_b32 v254, s15, 46
	v_writelane_b32 v254, s16, 47
	v_writelane_b32 v254, s17, 48
	v_writelane_b32 v254, s18, 49
	v_writelane_b32 v254, s19, 50
	v_writelane_b32 v254, s20, 51
	v_writelane_b32 v254, s21, 52
	v_writelane_b32 v254, s22, 53
	v_writelane_b32 v254, s23, 54
	v_writelane_b32 v254, s24, 55
	v_mov_b32_e32 v5, v2
	v_mov_b32_e32 v1, v3
	v_writelane_b32 v254, s25, 56
	v_pk_add_f32 v[0:1], v[4:5], v[0:1]
	v_writelane_b32 v254, s26, 57
	v_pk_add_f32 v[0:1], v[0:1], v[0:1] op_sel:[0,1] op_sel_hi:[1,0]
	v_writelane_b32 v254, s27, 58
	v_lshl_add_u64 v[2:3], s[24:25], 2, v[138:139]
	global_store_dword v[2:3], v0, off sc1

;     __device__ __forceinline__ void operator()(const f32x4 (&acc)[2][2][4][2], const Unit& u, int wr, int wc, int fr, int fq) const {
;     ...
;         if (tid < 256) {
;             float tot = 0.f;
; #pragma unroll
;             for (int q = 0; q < 4; ++q) tot += __hip_atomic_load(ss + (unsigned)(u.pm * 4 + q) * 256 + tid, __ATOMIC_RELAXED, __HIP_MEMORY_SCOPE_AGENT);
;             rs[tid] = rsqrtf(tot * (1.0f / 1024.0f) + 1e-6f);
;         }
.LBB0_736:
	s_or_b64 exec, exec, s[18:19]
	s_barrier
	s_and_saveexec_b64 s[18:19], s[6:7]
	s_cbranch_execz .LBB0_738
	v_readlane_b32 s36, v254, 43
	v_readlane_b32 s45, v254, 52
	s_mov_b32 s21, s45
	s_lshl_b32 s20, s73, 10
	s_mov_b32 s25, s45
	v_readlane_b32 s37, v254, 44
	v_readlane_b32 s38, v254, 45
	v_readlane_b32 s39, v254, 46
	v_readlane_b32 s40, v254, 47
	v_readlane_b32 s41, v254, 48
	v_readlane_b32 s42, v254, 49
	v_readlane_b32 s43, v254, 50
	v_readlane_b32 s44, v254, 51
	v_readlane_b32 s46, v254, 53
	v_readlane_b32 s47, v254, 54
	v_readlane_b32 s48, v254, 55
	v_readlane_b32 s49, v254, 56
	v_readlane_b32 s50, v254, 57
	v_readlane_b32 s51, v254, 58
	v_writelane_b32 v254, s16, 43
	s_waitcnt lgkmcnt(0)
	s_nop 0
	v_lshl_add_u64 v[0:1], s[20:21], 2, v[138:139]
	global_load_dword v2, v[0:1], off sc1
	global_load_dword v3, v[0:1], off offset:1024 sc1
	v_writelane_b32 v254, s17, 44
	v_writelane_b32 v254, s18, 45
	v_writelane_b32 v254, s19, 46
	v_writelane_b32 v254, s20, 47
	v_writelane_b32 v254, s21, 48
	v_writelane_b32 v254, s22, 49
	v_writelane_b32 v254, s23, 50
	v_writelane_b32 v254, s24, 51
	v_writelane_b32 v254, s25, 52
	v_writelane_b32 v254, s26, 53
	v_writelane_b32 v254, s27, 54
	v_writelane_b32 v254, s28, 55
	v_writelane_b32 v254, s29, 56
	v_writelane_b32 v254, s30, 57
	v_writelane_b32 v254, s31, 58
	s_mov_b32 s20, 0x800000
	s_waitcnt vmcnt(0) lgkmcnt(0)
	v_add_f32_e32 v2, 0, v2
	v_add_f32_e32 v2, v2, v3
	global_load_dword v3, v[0:1], off offset:2048 sc1
	s_waitcnt vmcnt(0) lgkmcnt(0)
	v_add_f32_e32 v2, v2, v3
	global_load_dword v0, v[0:1], off offset:3072 sc1
	s_waitcnt vmcnt(0) lgkmcnt(0)
	v_add_f32_e32 v0, v2, v0
	v_fmamk_f32 v0, v0, 0x3a800000, v193
	v_cmp_gt_f32_e32 vcc, s20, v0
	v_mul_f32_e32 v1, 0x4b800000, v0
	s_nop 0
	v_cndmask_b32_e32 v0, v0, v1, vcc
	v_rsq_f32_e32 v0, v0
	s_nop 0
	v_mul_f32_e32 v1, 0x45800000, v0
	v_cndmask_b32_e32 v0, v0, v1, vcc
	ds_write_b32 v177, v0

; __device__ __forceinline__ float silu_f(float x) { return x * __builtin_amdgcn_rcpf(1.0f + fexp(-x)); }
;     __device__ __forceinline__ void operator()(const f32x4 (&acc)[2][2][4][2], const Unit& u, int wr, int wc, int fr, int fq) const {
;         const int row0 = u.pm * BM + wr * 64 + fr, col0 = u.pn * 128 + wc * 32 + 8 * fq;
; #pragma unroll
;         for (int ai = 0; ai < 2; ++ai)
; #pragma unroll
;             for (int m = 0; m < 4; ++m) {
;                 h16x8 o;
; #pragma unroll
;                 for (int n = 0; n < 2; ++n)
; #pragma unroll
;                     for (int j = 0; j < 4; ++j) o[4 * n + j] = (h16)(silu_f(acc[ai][0][m][n][j]) * acc[ai][1][m][n][j]);
;                 *(h16x8*)(O + (unsigned)(row0 + ai * HALF + m * 16) * FF + col0) = o;
.LBB0_756:
	v_mul_f32_e32 v148, 0xbfb8aa3b, v126
	v_mul_f32_e32 v149, 0xbfb8aa3b, v127
	v_exp_f32_e32 v148, v148
	v_exp_f32_e32 v149, v149
	v_lshl_add_u32 v32, s16, 8, v142
	v_lshl_or_b32 v146, s17, 7, v144
	v_add_f32_e32 v148, 1.0, v148
	v_add_f32_e32 v149, 1.0, v149
	v_rcp_f32_e32 v148, v148
	v_rcp_f32_e32 v149, v149
	s_movk_i32 s9, 0xb00
	v_ashrrev_i32_e32 v147, 31, v146
	v_mul_lo_u32 v32, v32, s9
	v_pk_mul_f32 v[126:127], v[126:127], v[148:149]
	s_mov_b64 s[16:17], -1
	v_pk_mul_f32 v[122:123], v[126:127], v[122:123]
	s_andn2_b64 vcc, exec, s[4:5]
	v_cvt_pk_f16_f32 v122, v122, v123
	v_mul_f32_e32 v123, 0xbfb8aa3b, v128
	v_exp_f32_e32 v123, v123
	s_nop 0
	v_add_f32_e32 v123, 1.0, v123
	v_rcp_f32_e32 v126, v123
	v_mul_f32_e32 v123, 0xbfb8aa3b, v129
	v_exp_f32_e32 v123, v123
	s_nop 0
	v_add_f32_e32 v123, 1.0, v123
	v_rcp_f32_e32 v127, v123
	s_nop 0
	v_pk_mul_f32 v[126:127], v[128:129], v[126:127]
	s_nop 0
	v_pk_mul_f32 v[124:125], v[126:127], v[124:125]
	s_nop 0
	v_cvt_pk_f16_f32 v123, v124, v125
	v_mul_f32_e32 v124, 0xbfb8aa3b, v118
	v_mul_f32_e32 v125, 0xbfb8aa3b, v119
	v_exp_f32_e32 v124, v124
	v_exp_f32_e32 v125, v125
	v_add_f32_e32 v124, 1.0, v124
	v_add_f32_e32 v125, 1.0, v125
	v_rcp_f32_e32 v124, v124
	v_rcp_f32_e32 v125, v125
	s_nop 0
	v_pk_mul_f32 v[118:119], v[118:119], v[124:125]
	s_nop 0
	v_pk_mul_f32 v[114:115], v[118:119], v[114:115]
	s_nop 0
	v_cvt_pk_f16_f32 v124, v114, v115
	v_mul_f32_e32 v114, 0xbfb8aa3b, v120
	v_mul_f32_e32 v115, 0xbfb8aa3b, v121
	v_exp_f32_e32 v114, v114
	v_exp_f32_e32 v115, v115
	v_add_f32_e32 v114, 1.0, v114
	v_add_f32_e32 v115, 1.0, v115
	v_rcp_f32_e32 v114, v114
	v_rcp_f32_e32 v115, v115
	s_nop 0
	v_pk_mul_f32 v[114:115], v[120:121], v[114:115]
	s_nop 0
	v_pk_mul_f32 v[114:115], v[114:115], v[116:117]
	v_lshl_add_u64 v[116:117], v[32:33], 1, s[86:87]
	v_cvt_pk_f16_f32 v125, v114, v115
	v_lshlrev_b64 v[114:115], 1, v[146:147]
	v_lshl_add_u64 v[116:117], v[116:117], 0, v[114:115]
	global_store_dwordx4 v[116:117], v[122:125], off
	v_mul_f32_e32 v116, 0xbfb8aa3b, v110
	v_mul_f32_e32 v117, 0xbfb8aa3b, v111
	v_exp_f32_e32 v116, v116
	v_exp_f32_e32 v117, v117
	v_add_f32_e32 v116, 1.0, v116
	v_add_f32_e32 v117, 1.0, v117
	v_rcp_f32_e32 v116, v116
	v_rcp_f32_e32 v117, v117
	s_nop 0
	v_pk_mul_f32 v[110:111], v[110:111], v[116:117]
	s_nop 0
	v_pk_mul_f32 v[106:107], v[110:111], v[106:107]
	s_nop 0
	v_cvt_pk_f16_f32 v106, v106, v107
	v_mul_f32_e32 v107, 0xbfb8aa3b, v112
	v_exp_f32_e32 v107, v107
	s_nop 0
	v_add_f32_e32 v107, 1.0, v107
	v_rcp_f32_e32 v110, v107
	v_mul_f32_e32 v107, 0xbfb8aa3b, v113
	v_exp_f32_e32 v107, v107
	s_nop 0
	v_add_f32_e32 v107, 1.0, v107
	v_rcp_f32_e32 v111, v107
	s_nop 0
	v_pk_mul_f32 v[110:111], v[112:113], v[110:111]
	s_nop 0
	v_pk_mul_f32 v[108:109], v[110:111], v[108:109]
	s_nop 0
	v_cvt_pk_f16_f32 v107, v108, v109
	v_mul_f32_e32 v108, 0xbfb8aa3b, v102
	v_mul_f32_e32 v109, 0xbfb8aa3b, v103
	v_exp_f32_e32 v108, v108
	v_exp_f32_e32 v109, v109
	v_add_f32_e32 v108, 1.0, v108
	v_add_f32_e32 v109, 1.0, v109
	v_rcp_f32_e32 v108, v108
	v_rcp_f32_e32 v109, v109
	s_nop 0
	v_pk_mul_f32 v[102:103], v[102:103], v[108:109]
	s_nop 0
	v_pk_mul_f32 v[98:99], v[102:103], v[98:99]
	s_nop 0
	v_cvt_pk_f16_f32 v108, v98, v99
	v_mul_f32_e32 v98, 0xbfb8aa3b, v104
	v_mul_f32_e32 v99, 0xbfb8aa3b, v105
	v_exp_f32_e32 v98, v98
	v_exp_f32_e32 v99, v99
	v_add_f32_e32 v98, 1.0, v98
	v_add_f32_e32 v99, 1.0, v99
	v_rcp_f32_e32 v98, v98
	v_rcp_f32_e32 v99, v99
	s_nop 0
	v_pk_mul_f32 v[98:99], v[104:105], v[98:99]
	s_nop 0
	v_pk_mul_f32 v[98:99], v[98:99], v[100:101]
	s_nop 0
	v_cvt_pk_f16_f32 v109, v98, v99
	v_add_u32_e32 v98, 0xb000, v32
	v_mov_b32_e32 v99, v33
	v_lshl_add_u64 v[98:99], v[98:99], 1, s[86:87]
	v_lshl_add_u64 v[98:99], v[98:99], 0, v[114:115]
	global_store_dwordx4 v[98:99], v[106:109], off
	v_mul_f32_e32 v98, 0xbfb8aa3b, v94
	v_mul_f32_e32 v99, 0xbfb8aa3b, v95
	v_exp_f32_e32 v98, v98
	v_exp_f32_e32 v99, v99
	v_add_f32_e32 v98, 1.0, v98
	v_add_f32_e32 v99, 1.0, v99
	v_rcp_f32_e32 v98, v98
	v_rcp_f32_e32 v99, v99
	s_nop 0
	v_pk_mul_f32 v[94:95], v[94:95], v[98:99]
	s_nop 0
	v_pk_mul_f32 v[90:91], v[94:95], v[90:91]
	s_nop 0
	v_cvt_pk_f16_f32 v90, v90, v91
	v_mul_f32_e32 v91, 0xbfb8aa3b, v96
	v_exp_f32_e32 v91, v91
	s_nop 0
	v_add_f32_e32 v91, 1.0, v91
	v_rcp_f32_e32 v94, v91
	v_mul_f32_e32 v91, 0xbfb8aa3b, v97
	v_exp_f32_e32 v91, v91
	s_nop 0
	v_add_f32_e32 v91, 1.0, v91
	v_rcp_f32_e32 v95, v91
	s_nop 0
	v_pk_mul_f32 v[94:95], v[96:97], v[94:95]
	s_nop 0
	v_pk_mul_f32 v[92:93], v[94:95], v[92:93]
	s_nop 0
	v_cvt_pk_f16_f32 v91, v92, v93
	v_mul_f32_e32 v92, 0xbfb8aa3b, v86
	v_mul_f32_e32 v93, 0xbfb8aa3b, v87
	v_exp_f32_e32 v92, v92
	v_exp_f32_e32 v93, v93
	v_add_f32_e32 v92, 1.0, v92
	v_add_f32_e32 v93, 1.0, v93
	v_rcp_f32_e32 v92, v92
	v_rcp_f32_e32 v93, v93
	s_nop 0
	v_pk_mul_f32 v[86:87], v[86:87], v[92:93]
	s_nop 0
	v_pk_mul_f32 v[82:83], v[86:87], v[82:83]
	s_nop 0
	v_cvt_pk_f16_f32 v92, v82, v83
	v_mul_f32_e32 v82, 0xbfb8aa3b, v88
	v_mul_f32_e32 v83, 0xbfb8aa3b, v89
	v_exp_f32_e32 v82, v82
	v_exp_f32_e32 v83, v83
	v_add_f32_e32 v82, 1.0, v82
	v_add_f32_e32 v83, 1.0, v83
	v_rcp_f32_e32 v82, v82
	v_rcp_f32_e32 v83, v83
	s_nop 0
	v_pk_mul_f32 v[82:83], v[88:89], v[82:83]
	s_nop 0
	v_pk_mul_f32 v[82:83], v[82:83], v[84:85]
	s_nop 0
	v_cvt_pk_f16_f32 v93, v82, v83
	v_add_u32_e32 v82, 0x16000, v32
	v_mov_b32_e32 v83, v33
	v_lshl_add_u64 v[82:83], v[82:83], 1, s[86:87]
	v_lshl_add_u64 v[82:83], v[82:83], 0, v[114:115]
	global_store_dwordx4 v[82:83], v[90:93], off
	v_mul_f32_e32 v82, 0xbfb8aa3b, v78
	v_mul_f32_e32 v83, 0xbfb8aa3b, v79
	v_exp_f32_e32 v82, v82
	v_exp_f32_e32 v83, v83
	v_add_f32_e32 v82, 1.0, v82
; __device__ __forceinline__ float silu_f(float x) { return x * __builtin_amdgcn_rcpf(1.0f + fexp(-x)); }
;     __device__ __forceinline__ void operator()(const f32x4 (&acc)[2][2][4][2], const Unit& u, int wr, int wc, int fr, int fq) const {
;         const int row0 = u.pm * BM + wr * 64 + fr, col0 = u.pn * 128 + wc * 32 + 8 * fq;
; #pragma unroll
;         for (int ai = 0; ai < 2; ++ai)
; #pragma unroll
;             for (int m = 0; m < 4; ++m) {
;                 h16x8 o;
; #pragma unroll
;                 for (int n = 0; n < 2; ++n)
; #pragma unroll
;                     for (int j = 0; j < 4; ++j) o[4 * n + j] = (h16)(silu_f(acc[ai][0][m][n][j]) * acc[ai][1][m][n][j]);
;                 *(h16x8*)(O + (unsigned)(row0 + ai * HALF + m * 16) * FF + col0) = o;
	v_add_f32_e32 v83, 1.0, v83
	v_rcp_f32_e32 v82, v82
	v_rcp_f32_e32 v83, v83
	s_nop 0
	v_pk_mul_f32 v[78:79], v[78:79], v[82:83]
	s_nop 0
	v_pk_mul_f32 v[74:75], v[78:79], v[74:75]
	s_nop 0
	v_cvt_pk_f16_f32 v74, v74, v75
	v_mul_f32_e32 v75, 0xbfb8aa3b, v80
	v_exp_f32_e32 v75, v75
	s_nop 0
	v_add_f32_e32 v75, 1.0, v75
	v_rcp_f32_e32 v78, v75
	v_mul_f32_e32 v75, 0xbfb8aa3b, v81
	v_exp_f32_e32 v75, v75
	s_nop 0
	v_add_f32_e32 v75, 1.0, v75
	v_rcp_f32_e32 v79, v75
	s_nop 0
	v_pk_mul_f32 v[78:79], v[80:81], v[78:79]
	s_nop 0
	v_pk_mul_f32 v[76:77], v[78:79], v[76:77]
	s_nop 0
	v_cvt_pk_f16_f32 v75, v76, v77
	v_mul_f32_e32 v76, 0xbfb8aa3b, v70
	v_mul_f32_e32 v77, 0xbfb8aa3b, v71
	v_exp_f32_e32 v76, v76
	v_exp_f32_e32 v77, v77
	v_add_f32_e32 v76, 1.0, v76
	v_add_f32_e32 v77, 1.0, v77
	v_rcp_f32_e32 v76, v76
	v_rcp_f32_e32 v77, v77
	s_nop 0
	v_pk_mul_f32 v[70:71], v[70:71], v[76:77]
	s_nop 0
	v_pk_mul_f32 v[66:67], v[70:71], v[66:67]
	s_nop 0
	v_cvt_pk_f16_f32 v76, v66, v67
	v_mul_f32_e32 v66, 0xbfb8aa3b, v72
	v_mul_f32_e32 v67, 0xbfb8aa3b, v73
	v_exp_f32_e32 v66, v66
	v_exp_f32_e32 v67, v67
	v_add_f32_e32 v66, 1.0, v66
	v_add_f32_e32 v67, 1.0, v67
	v_rcp_f32_e32 v66, v66
	v_rcp_f32_e32 v67, v67
	s_nop 0
	v_pk_mul_f32 v[66:67], v[72:73], v[66:67]
	s_nop 0
	v_pk_mul_f32 v[66:67], v[66:67], v[68:69]
	s_nop 0
	v_cvt_pk_f16_f32 v77, v66, v67
	v_add_u32_e32 v66, 0x21000, v32
	v_mov_b32_e32 v67, v33
	v_lshl_add_u64 v[66:67], v[66:67], 1, s[86:87]
	v_lshl_add_u64 v[66:67], v[66:67], 0, v[114:115]
	global_store_dwordx4 v[66:67], v[74:77], off
	v_mul_f32_e32 v66, 0xbfb8aa3b, v62
	v_mul_f32_e32 v67, 0xbfb8aa3b, v63
	v_exp_f32_e32 v66, v66
	v_exp_f32_e32 v67, v67
	v_add_f32_e32 v66, 1.0, v66
	v_add_f32_e32 v67, 1.0, v67
	v_rcp_f32_e32 v66, v66
	v_rcp_f32_e32 v67, v67
	s_nop 0
	v_pk_mul_f32 v[62:63], v[62:63], v[66:67]
	s_nop 0
	v_pk_mul_f32 v[58:59], v[62:63], v[58:59]
	s_nop 0
	v_cvt_pk_f16_f32 v58, v58, v59
	v_mul_f32_e32 v59, 0xbfb8aa3b, v64
	v_exp_f32_e32 v59, v59
	s_nop 0
	v_add_f32_e32 v59, 1.0, v59
	v_rcp_f32_e32 v62, v59
	v_mul_f32_e32 v59, 0xbfb8aa3b, v65
	v_exp_f32_e32 v59, v59
	s_nop 0
	v_add_f32_e32 v59, 1.0, v59
	v_rcp_f32_e32 v63, v59
	s_nop 0
	v_pk_mul_f32 v[62:63], v[64:65], v[62:63]
	s_nop 0
	v_pk_mul_f32 v[60:61], v[62:63], v[60:61]
	s_nop 0
	v_cvt_pk_f16_f32 v59, v60, v61
	v_mul_f32_e32 v60, 0xbfb8aa3b, v54
	v_mul_f32_e32 v61, 0xbfb8aa3b, v55
	v_exp_f32_e32 v60, v60
	v_exp_f32_e32 v61, v61
	v_add_f32_e32 v60, 1.0, v60
	v_add_f32_e32 v61, 1.0, v61
	v_rcp_f32_e32 v60, v60
	v_rcp_f32_e32 v61, v61
	s_nop 0
	v_pk_mul_f32 v[54:55], v[54:55], v[60:61]
	s_nop 0
	v_pk_mul_f32 v[50:51], v[54:55], v[50:51]
	s_nop 0
	v_cvt_pk_f16_f32 v60, v50, v51
	v_mul_f32_e32 v50, 0xbfb8aa3b, v56
	v_mul_f32_e32 v51, 0xbfb8aa3b, v57
	v_exp_f32_e32 v50, v50
	v_exp_f32_e32 v51, v51
	v_add_f32_e32 v50, 1.0, v50
	v_add_f32_e32 v51, 1.0, v51
	v_rcp_f32_e32 v50, v50
	v_rcp_f32_e32 v51, v51
	s_nop 0
	v_pk_mul_f32 v[50:51], v[56:57], v[50:51]
	s_nop 0
	v_pk_mul_f32 v[50:51], v[50:51], v[52:53]
	s_nop 0
	v_cvt_pk_f16_f32 v61, v50, v51
	v_add_u32_e32 v50, 0x58000, v32
	v_mov_b32_e32 v51, v33
	v_lshl_add_u64 v[50:51], v[50:51], 1, s[86:87]
	v_lshl_add_u64 v[50:51], v[50:51], 0, v[114:115]
	global_store_dwordx4 v[50:51], v[58:61], off
	v_mul_f32_e32 v50, 0xbfb8aa3b, v46
	v_mul_f32_e32 v51, 0xbfb8aa3b, v47
	v_exp_f32_e32 v50, v50
	v_exp_f32_e32 v51, v51
	v_add_f32_e32 v50, 1.0, v50
	v_add_f32_e32 v51, 1.0, v51
	v_rcp_f32_e32 v50, v50
	v_rcp_f32_e32 v51, v51
	s_nop 0
	v_pk_mul_f32 v[46:47], v[46:47], v[50:51]
	s_nop 0
	v_pk_mul_f32 v[42:43], v[46:47], v[42:43]
	s_nop 0
	v_cvt_pk_f16_f32 v42, v42, v43
	v_mul_f32_e32 v43, 0xbfb8aa3b, v48
	v_exp_f32_e32 v43, v43
	s_nop 0
	v_add_f32_e32 v43, 1.0, v43
	v_rcp_f32_e32 v46, v43
	v_mul_f32_e32 v43, 0xbfb8aa3b, v49
	v_exp_f32_e32 v43, v43
	s_nop 0
	v_add_f32_e32 v43, 1.0, v43
	v_rcp_f32_e32 v47, v43
	s_nop 0
	v_pk_mul_f32 v[46:47], v[48:49], v[46:47]
	s_nop 0
	v_pk_mul_f32 v[44:45], v[46:47], v[44:45]
	s_nop 0
	v_cvt_pk_f16_f32 v43, v44, v45
	v_mul_f32_e32 v44, 0xbfb8aa3b, v38
	v_mul_f32_e32 v45, 0xbfb8aa3b, v39
	v_exp_f32_e32 v44, v44
	v_exp_f32_e32 v45, v45
	v_add_f32_e32 v44, 1.0, v44
	v_add_f32_e32 v45, 1.0, v45
; __device__ __forceinline__ float silu_f(float x) { return x * __builtin_amdgcn_rcpf(1.0f + fexp(-x)); }
; #define PG8_BAR __builtin_amdgcn_s_barrier()
;     __device__ __forceinline__ void operator()(const f32x4 (&acc)[2][2][4][2], const Unit& u, int wr, int wc, int fr, int fq) const {
;         const int row0 = u.pm * BM + wr * 64 + fr, col0 = u.pn * 128 + wc * 32 + 8 * fq;
; #pragma unroll
;         for (int ai = 0; ai < 2; ++ai)
; #pragma unroll
;             for (int m = 0; m < 4; ++m) {
;                 h16x8 o;
; #pragma unroll
;                 for (int n = 0; n < 2; ++n)
; #pragma unroll
;                     for (int j = 0; j < 4; ++j) o[4 * n + j] = (h16)(silu_f(acc[ai][0][m][n][j]) * acc[ai][1][m][n][j]);
;                 *(h16x8*)(O + (unsigned)(row0 + ai * HALF + m * 16) * FF + col0) = o;
; template <class Epi>
; __device__ __forceinline__ void gemm_phase(LAS unsigned char* lds, const Gemm g, const StaticOrder& S, const Epi& E) {
;     ...
;         cur = nxt; cA = nA; cB = nB; ++ui;
;         if (wr == 1) PG8_BAR;
	v_rcp_f32_e32 v44, v44
	v_rcp_f32_e32 v45, v45
	s_nop 0
	v_pk_mul_f32 v[38:39], v[38:39], v[44:45]
	s_nop 0
	v_pk_mul_f32 v[34:35], v[38:39], v[34:35]
	s_nop 0
	v_cvt_pk_f16_f32 v44, v34, v35
	v_mul_f32_e32 v34, 0xbfb8aa3b, v40
	v_mul_f32_e32 v35, 0xbfb8aa3b, v41
	v_exp_f32_e32 v34, v34
	v_exp_f32_e32 v35, v35
	v_add_f32_e32 v34, 1.0, v34
	v_add_f32_e32 v35, 1.0, v35
	v_rcp_f32_e32 v34, v34
	v_rcp_f32_e32 v35, v35
	s_nop 0
	v_pk_mul_f32 v[34:35], v[40:41], v[34:35]
	s_nop 0
	v_pk_mul_f32 v[34:35], v[34:35], v[36:37]
	s_nop 0
	v_cvt_pk_f16_f32 v45, v34, v35
	v_add_u32_e32 v34, 0x63000, v32
	v_mov_b32_e32 v35, v33
	v_lshl_add_u64 v[34:35], v[34:35], 1, s[86:87]
	v_lshl_add_u64 v[34:35], v[34:35], 0, v[114:115]
	global_store_dwordx4 v[34:35], v[42:45], off
	v_mul_f32_e32 v34, 0xbfb8aa3b, v28
	v_mul_f32_e32 v35, 0xbfb8aa3b, v29
	v_exp_f32_e32 v34, v34
	v_exp_f32_e32 v35, v35
	v_add_f32_e32 v34, 1.0, v34
	v_add_f32_e32 v35, 1.0, v35
	v_rcp_f32_e32 v34, v34
	v_rcp_f32_e32 v35, v35
	s_nop 0
	v_pk_mul_f32 v[28:29], v[28:29], v[34:35]
	s_nop 0
	v_pk_mul_f32 v[24:25], v[28:29], v[24:25]
	s_nop 0
	v_cvt_pk_f16_f32 v24, v24, v25
	v_mul_f32_e32 v25, 0xbfb8aa3b, v30
	v_exp_f32_e32 v25, v25
	s_nop 0
	v_add_f32_e32 v25, 1.0, v25
	v_rcp_f32_e32 v28, v25
	v_mul_f32_e32 v25, 0xbfb8aa3b, v31
	v_exp_f32_e32 v25, v25
	s_nop 0
	v_add_f32_e32 v25, 1.0, v25
	v_rcp_f32_e32 v29, v25
	s_nop 0
	v_pk_mul_f32 v[28:29], v[30:31], v[28:29]
	s_nop 0
	v_pk_mul_f32 v[26:27], v[28:29], v[26:27]
	s_nop 0
	v_cvt_pk_f16_f32 v25, v26, v27
	v_mul_f32_e32 v26, 0xbfb8aa3b, v20
	v_mul_f32_e32 v27, 0xbfb8aa3b, v21
	v_exp_f32_e32 v26, v26
	v_exp_f32_e32 v27, v27
	v_add_f32_e32 v26, 1.0, v26
	v_add_f32_e32 v27, 1.0, v27
	v_rcp_f32_e32 v26, v26
	v_rcp_f32_e32 v27, v27
	s_nop 0
	v_pk_mul_f32 v[20:21], v[20:21], v[26:27]
	s_nop 0
	v_pk_mul_f32 v[16:17], v[20:21], v[16:17]
	s_nop 0
	v_cvt_pk_f16_f32 v26, v16, v17
	v_mul_f32_e32 v16, 0xbfb8aa3b, v22
	v_mul_f32_e32 v17, 0xbfb8aa3b, v23
	v_exp_f32_e32 v16, v16
	v_exp_f32_e32 v17, v17
	v_add_f32_e32 v16, 1.0, v16
	v_add_f32_e32 v17, 1.0, v17
	v_rcp_f32_e32 v16, v16
	v_rcp_f32_e32 v17, v17
	s_nop 0
	v_pk_mul_f32 v[16:17], v[22:23], v[16:17]
	s_nop 0
	v_pk_mul_f32 v[16:17], v[16:17], v[18:19]
	s_nop 0
	v_cvt_pk_f16_f32 v27, v16, v17
	v_add_u32_e32 v16, 0x6e000, v32
	v_mov_b32_e32 v17, v33
	v_lshl_add_u64 v[16:17], v[16:17], 1, s[86:87]
	v_lshl_add_u64 v[16:17], v[16:17], 0, v[114:115]
	global_store_dwordx4 v[16:17], v[24:27], off
	v_mul_f32_e32 v16, 0xbfb8aa3b, v12
	v_mul_f32_e32 v17, 0xbfb8aa3b, v13
	v_exp_f32_e32 v16, v16
	v_exp_f32_e32 v17, v17
	v_add_u32_e32 v32, 0x79000, v32
	v_add_f32_e32 v16, 1.0, v16
	v_add_f32_e32 v17, 1.0, v17
	v_rcp_f32_e32 v16, v16
	v_rcp_f32_e32 v17, v17
	s_nop 0
	v_pk_mul_f32 v[12:13], v[12:13], v[16:17]
	s_nop 0
	v_pk_mul_f32 v[8:9], v[12:13], v[8:9]
	s_nop 0
	v_cvt_pk_f16_f32 v8, v8, v9
	v_mul_f32_e32 v9, 0xbfb8aa3b, v14
	v_exp_f32_e32 v9, v9
	s_nop 0
	v_add_f32_e32 v9, 1.0, v9
	v_rcp_f32_e32 v12, v9
	v_mul_f32_e32 v9, 0xbfb8aa3b, v15
	v_exp_f32_e32 v9, v9
	s_nop 0
	v_add_f32_e32 v9, 1.0, v9
	v_rcp_f32_e32 v13, v9
	s_nop 0
	v_pk_mul_f32 v[12:13], v[14:15], v[12:13]
	s_nop 0
	v_pk_mul_f32 v[10:11], v[12:13], v[10:11]
	s_nop 0
	v_cvt_pk_f16_f32 v9, v10, v11
	v_mul_f32_e32 v10, 0xbfb8aa3b, v4
	v_mul_f32_e32 v11, 0xbfb8aa3b, v5
	v_exp_f32_e32 v10, v10
	v_exp_f32_e32 v11, v11
	v_add_f32_e32 v10, 1.0, v10
	v_add_f32_e32 v11, 1.0, v11
	v_rcp_f32_e32 v10, v10
	v_rcp_f32_e32 v11, v11
	s_nop 0
	v_pk_mul_f32 v[4:5], v[4:5], v[10:11]
	s_nop 0
	v_pk_mul_f32 v[0:1], v[4:5], v[0:1]
	s_nop 0
	v_cvt_pk_f16_f32 v10, v0, v1
	v_mul_f32_e32 v0, 0xbfb8aa3b, v6
	v_mul_f32_e32 v1, 0xbfb8aa3b, v7
	v_exp_f32_e32 v0, v0
	v_exp_f32_e32 v1, v1
	v_add_f32_e32 v0, 1.0, v0
	v_add_f32_e32 v1, 1.0, v1
	v_rcp_f32_e32 v0, v0
	v_rcp_f32_e32 v1, v1
	s_nop 0
	v_pk_mul_f32 v[0:1], v[6:7], v[0:1]
	s_nop 0
	v_pk_mul_f32 v[0:1], v[0:1], v[2:3]
	s_nop 0
	v_cvt_pk_f16_f32 v11, v0, v1
	v_lshl_add_u64 v[0:1], v[32:33], 1, s[86:87]
	v_lshl_add_u64 v[0:1], v[0:1], 0, v[114:115]
	global_store_dwordx4 v[0:1], v[8:11], off
	s_cbranch_vccnz .LBB0_749
	s_andn2_b64 vcc, exec, s[0:1]
	s_cbranch_vccnz .LBB0_748
	s_barrier
	s_branch .LBB0_748

; __device__ __forceinline__ void phase_norm(const float* src32, const h16* src16, const float* ln, const float* modl, int shi, int sci, h16* dst) {
;     ...
;         for (int u = 0; u < 2; ++u) {
;             const int row = row0 + u * half;
;             if (row < M_TOK) {
;                 float ss = 0.f;
; #pragma unroll
;                 for (int i = 0; i < 4; ++i) ss += vc[u][i][0] * vc[u][i][0] + vc[u][i][1] * vc[u][i][1] + vc[u][i][2] * vc[u][i][2] + vc[u][i][3] * vc[u][i][3];
;                 ss = wave_sum(ss, lane);
;                 const float rstd = rsqrtf(ss * (1.0f / 1024.0f) + 1e-6f);
;                 const int b = row >> 12;
;                 const float* sh = modl + b * 9216 + shi * 1024; const float* sc = modl + b * 9216 + sci * 1024;
; #pragma unroll
;                 for (int i = 0; i < 4; ++i) {
;                     const int col = src32 ? (4 * lane + 256 * i) : (16 * lane + 4 * i);
;                     const f32x4 gv = *(const f32x4*)(ln + col), sv = *(const f32x4*)(sh + col), cv = *(const f32x4*)(sc + col);
;                     h16x4 o;
; #pragma unroll
;                     for (int j = 0; j < 4; ++j) o[j] = (h16)(vc[u][i][j] * rstd * gv[j] * (1.0f + cv[j]) + sv[j]);
;                     gst((h16x4*)(dst + (unsigned)row * DM + col), o);
;                 }
.LBB0_786:
	s_waitcnt vmcnt(0)
	v_mov_b32_e32 v92, v59
	v_mov_b32_e32 v93, v63
	v_mov_b32_e32 v90, v58
	v_mov_b32_e32 v91, v62
	v_pk_mul_f32 v[92:93], v[92:93], v[92:93]
	v_mov_b32_e32 v94, v29
	v_pk_fma_f32 v[90:91], v[90:91], v[90:91], v[92:93]
	v_mov_b32_e32 v92, v60
	v_mov_b32_e32 v93, v64
	v_pk_fma_f32 v[90:91], v[92:93], v[92:93], v[90:91]
	v_mov_b32_e32 v92, v61
	v_mov_b32_e32 v93, v65
	v_mov_b32_e32 v95, v55
	v_pk_fma_f32 v[90:91], v[92:93], v[92:93], v[90:91]
	v_mov_b32_e32 v92, v28
	v_mov_b32_e32 v93, v54
	v_pk_mul_f32 v[94:95], v[94:95], v[94:95]
	v_add_f32_e32 v32, v90, v91
	v_pk_fma_f32 v[92:93], v[92:93], v[92:93], v[94:95]
	v_mov_b32_e32 v94, v30
	v_mov_b32_e32 v95, v56
	v_pk_fma_f32 v[92:93], v[94:95], v[94:95], v[92:93]
	v_mov_b32_e32 v94, v31
	v_mov_b32_e32 v95, v57
	v_pk_fma_f32 v[92:93], v[94:95], v[94:95], v[92:93]
	s_mov_b32 s6, 0x800000
	v_add_f32_e32 v32, v93, v32
	v_add_f32_e32 v32, v92, v32
	ds_bpermute_b32 v86, v71, v32
	global_load_dwordx4 v[90:93], v[72:73], off
	s_waitcnt lgkmcnt(0)
	v_add_f32_e32 v32, v32, v86
	ds_bpermute_b32 v86, v75, v32
	s_waitcnt lgkmcnt(0)
	v_add_f32_e32 v32, v32, v86
	ds_bpermute_b32 v86, v79, v32
	s_waitcnt lgkmcnt(0)
	v_add_f32_e32 v32, v32, v86
	ds_bpermute_b32 v86, v83, v32
	s_waitcnt lgkmcnt(0)
	v_add_f32_e32 v32, v32, v86
	ds_bpermute_b32 v86, v87, v32
	s_waitcnt lgkmcnt(0)
	v_add_f32_e32 v32, v32, v86
	ds_bpermute_b32 v86, v88, v32
	s_waitcnt lgkmcnt(0)
	v_add_f32_e32 v32, v32, v86
	v_fmamk_f32 v32, v32, 0x3a800000, v193
	v_cmp_gt_f32_e32 vcc, s6, v32
	v_mul_f32_e32 v86, 0x4b800000, v32
	s_ashr_i32 s6, s8, 12
	v_cndmask_b32_e32 v32, v32, v86, vcc
	s_mulk_i32 s6, 0x2400
	v_rsq_f32_e32 v32, v32
	s_ashr_i32 s7, s6, 31
	s_lshl_b64 s[6:7], s[6:7], 2
	v_readlane_b32 s8, v255, 13
	s_add_u32 s10, s8, s6
	v_readlane_b32 s6, v255, 15
	s_addc_u32 s11, s6, s7
	v_mul_f32_e32 v86, 0x45800000, v32
	s_add_u32 s8, s10, 0x1000
	v_cndmask_b32_e32 v86, v32, v86, vcc
	s_addc_u32 s9, s11, 0
	v_lshlrev_b32_e32 v32, 2, v70
	v_lshl_add_u64 v[94:95], s[10:11], 0, v[32:33]
	v_lshl_add_u64 v[98:99], s[8:9], 0, v[32:33]
	global_load_dwordx4 v[94:97], v[94:95], off
	v_pk_mul_f32 v[62:63], v[62:63], v[86:87] op_sel_hi:[1,0]
	global_load_dwordx4 v[98:101], v[98:99], off
	s_add_i32 s20, s2, s3
	v_pk_mul_f32 v[64:65], v[64:65], v[86:87] op_sel_hi:[1,0]
	s_lshl_b64 s[6:7], s[20:21], 1
	s_add_u32 s6, s84, s6
	s_addc_u32 s7, s85, s7
	v_pk_mul_f32 v[58:59], v[58:59], v[86:87] op_sel_hi:[1,0]
	v_pk_mul_f32 v[60:61], v[60:61], v[86:87] op_sel_hi:[1,0]
	v_pk_mul_f32 v[54:55], v[54:55], v[86:87] op_sel_hi:[1,0]
	v_pk_mul_f32 v[56:57], v[56:57], v[86:87] op_sel_hi:[1,0]
	v_pk_mul_f32 v[28:29], v[28:29], v[86:87] op_sel_hi:[1,0]
	s_cmpk_gt_i32 s12, 0x7fff
	s_waitcnt vmcnt(0)
	v_pk_mul_f32 v[62:63], v[90:91], v[62:63]
	v_pk_mul_f32 v[64:65], v[92:93], v[64:65]
	s_waitcnt lgkmcnt(0)
	v_pk_add_f32 v[90:91], v[98:99], 1.0 op_sel_hi:[1,0]
	s_nop 0
	v_pk_fma_f32 v[62:63], v[90:91], v[62:63], v[94:95]
	v_pk_add_f32 v[90:91], v[100:101], 1.0 op_sel_hi:[1,0]
	v_cvt_pk_f16_f32 v62, v62, v63
	v_pk_fma_f32 v[64:65], v[90:91], v[64:65], v[96:97]
	s_nop 0
	v_cvt_pk_f16_f32 v63, v64, v65
	v_lshlrev_b32_e32 v64, 1, v70
	global_store_dwordx2 v64, v[62:63], s[6:7]
	v_lshlrev_b32_e32 v62, 2, v74
	v_mov_b32_e32 v63, v33
	v_lshl_add_u64 v[94:95], s[10:11], 0, v[62:63]
	v_lshl_add_u64 v[98:99], s[8:9], 0, v[62:63]
	global_load_dwordx4 v[90:93], v[76:77], off
	s_waitcnt vmcnt(0)
	v_pk_mul_f32 v[58:59], v[90:91], v[58:59]
	global_load_dwordx4 v[94:97], v[94:95], off
	v_pk_mul_f32 v[60:61], v[92:93], v[60:61]
	global_load_dwordx4 v[98:101], v[98:99], off
	s_waitcnt vmcnt(0) lgkmcnt(0)
	v_pk_add_f32 v[90:91], v[98:99], 1.0 op_sel_hi:[1,0]
	s_nop 0
	v_pk_fma_f32 v[58:59], v[90:91], v[58:59], v[94:95]
	v_pk_add_f32 v[90:91], v[100:101], 1.0 op_sel_hi:[1,0]
	v_cvt_pk_f16_f32 v58, v58, v59
	v_pk_fma_f32 v[60:61], v[90:91], v[60:61], v[96:97]
	s_nop 0
	v_cvt_pk_f16_f32 v59, v60, v61
	v_lshlrev_b32_e32 v60, 1, v74
	global_store_dwordx2 v60, v[58:59], s[6:7]
	v_lshlrev_b32_e32 v58, 2, v78
	v_mov_b32_e32 v59, v33
	v_lshl_add_u64 v[94:95], s[10:11], 0, v[58:59]
	v_lshl_add_u64 v[98:99], s[8:9], 0, v[58:59]
	global_load_dwordx4 v[90:93], v[80:81], off
	s_waitcnt vmcnt(0)
	v_pk_mul_f32 v[54:55], v[90:91], v[54:55]
	global_load_dwordx4 v[94:97], v[94:95], off
	v_pk_mul_f32 v[56:57], v[92:93], v[56:57]
	global_load_dwordx4 v[98:101], v[98:99], off
	s_waitcnt vmcnt(0) lgkmcnt(0)
	v_pk_add_f32 v[90:91], v[98:99], 1.0 op_sel_hi:[1,0]
	s_nop 0
	v_pk_fma_f32 v[54:55], v[54:55], v[90:91], v[94:95]
	v_pk_add_f32 v[90:91], v[100:101], 1.0 op_sel_hi:[1,0]
	v_cvt_pk_f16_f32 v54, v54, v55
	v_pk_fma_f32 v[56:57], v[56:57], v[90:91], v[96:97]
	s_nop 0
	v_cvt_pk_f16_f32 v55, v56, v57
	v_lshlrev_b32_e32 v56, 1, v78
	global_store_dwordx2 v56, v[54:55], s[6:7]
	v_lshlrev_b32_e32 v54, 2, v82
	v_mov_b32_e32 v55, v33
	v_lshl_add_u64 v[94:95], s[10:11], 0, v[54:55]
	v_lshl_add_u64 v[98:99], s[8:9], 0, v[54:55]
	global_load_dwordx4 v[90:93], v[84:85], off
	s_waitcnt vmcnt(0)
	v_pk_mul_f32 v[28:29], v[28:29], v[90:91]
	global_load_dwordx4 v[94:97], v[94:95], off
	s_nop 0
	global_load_dwordx4 v[98:101], v[98:99], off
	s_waitcnt vmcnt(0) lgkmcnt(0)
	v_pk_add_f32 v[90:91], v[98:99], 1.0 op_sel_hi:[1,0]
	s_nop 0
	v_pk_fma_f32 v[28:29], v[28:29], v[90:91], v[94:95]
	s_nop 0
	v_cvt_pk_f16_f32 v90, v28, v29
	v_pk_mul_f32 v[28:29], v[30:31], v[86:87] op_sel_hi:[1,0]
	v_pk_add_f32 v[30:31], v[100:101], 1.0 op_sel_hi:[1,0]
	v_pk_mul_f32 v[28:29], v[28:29], v[92:93]
	s_nop 0
	v_pk_fma_f32 v[28:29], v[28:29], v[30:31], v[96:97]
	s_nop 0
	v_cvt_pk_f16_f32 v91, v28, v29
	v_lshlrev_b32_e32 v28, 1, v82
	global_store_dwordx2 v28, v[90:91], s[6:7]
	s_cbranch_scc1 .LBB0_775
; __device__ __forceinline__ void phase_norm(const float* src32, const h16* src16, const float* ln, const float* modl, int shi, int sci, h16* dst) {
;     ...
;         for (int u = 0; u < 2; ++u) {
;             const int row = row0 + u * half;
;             if (row < M_TOK) {
;                 float ss = 0.f;
; #pragma unroll
;                 for (int i = 0; i < 4; ++i) ss += vc[u][i][0] * vc[u][i][0] + vc[u][i][1] * vc[u][i][1] + vc[u][i][2] * vc[u][i][2] + vc[u][i][3] * vc[u][i][3];
;                 ss = wave_sum(ss, lane);
;                 const float rstd = rsqrtf(ss * (1.0f / 1024.0f) + 1e-6f);
;                 const int b = row >> 12;
;                 const float* sh = modl + b * 9216 + shi * 1024; const float* sc = modl + b * 9216 + sci * 1024;
; #pragma unroll
;                 for (int i = 0; i < 4; ++i) {
;                     const int col = src32 ? (4 * lane + 256 * i) : (16 * lane + 4 * i);
;                     const f32x4 gv = *(const f32x4*)(ln + col), sv = *(const f32x4*)(sh + col), cv = *(const f32x4*)(sc + col);
;                     h16x4 o;
; #pragma unroll
;                     for (int j = 0; j < 4; ++j) o[j] = (h16)(vc[u][i][j] * rstd * gv[j] * (1.0f + cv[j]) + sv[j]);
;                     gst((h16x4*)(dst + (unsigned)row * DM + col), o);
;                 }
	s_ashr_i32 s6, s12, 12
	s_mulk_i32 s6, 0x2400
	s_ashr_i32 s7, s6, 31
	s_lshl_b64 s[6:7], s[6:7], 2
	v_readlane_b32 s8, v255, 13
	s_add_u32 s6, s8, s6
	v_readlane_b32 s8, v255, 15
	s_addc_u32 s7, s8, s7
	s_add_u32 s8, s6, 0x1000
	s_addc_u32 s9, s7, 0
	v_lshl_add_u64 v[30:31], s[8:9], 0, v[32:33]
	global_load_dwordx4 v[90:93], v[72:73], off
	global_load_dwordx4 v[94:97], v[30:31], off
	v_lshl_add_u64 v[30:31], s[6:7], 0, v[32:33]
	global_load_dwordx4 v[98:101], v[30:31], off
	v_mov_b32_e32 v102, v9
	v_mov_b32_e32 v103, v13
	v_mov_b32_e32 v30, v8
	v_mov_b32_e32 v31, v12
	v_pk_mul_f32 v[102:103], v[102:103], v[102:103]
	v_mov_b32_e32 v104, v1
	v_pk_fma_f32 v[30:31], v[30:31], v[30:31], v[102:103]
	v_mov_b32_e32 v102, v10
	v_mov_b32_e32 v103, v14
	v_pk_fma_f32 v[30:31], v[102:103], v[102:103], v[30:31]
	v_mov_b32_e32 v102, v11
	v_mov_b32_e32 v103, v15
	v_mov_b32_e32 v105, v5
	v_pk_fma_f32 v[30:31], v[102:103], v[102:103], v[30:31]
	v_mov_b32_e32 v102, v0
	v_mov_b32_e32 v103, v4
	v_pk_mul_f32 v[104:105], v[104:105], v[104:105]
	v_add_f32_e32 v29, v30, v31
	v_pk_fma_f32 v[102:103], v[102:103], v[102:103], v[104:105]
	v_mov_b32_e32 v104, v2
	v_mov_b32_e32 v105, v6
	v_pk_fma_f32 v[102:103], v[104:105], v[104:105], v[102:103]
	v_mov_b32_e32 v104, v3
	v_mov_b32_e32 v105, v7
	v_pk_fma_f32 v[102:103], v[104:105], v[104:105], v[102:103]
	s_add_i32 s20, s13, s3
	v_add_f32_e32 v29, v103, v29
	v_add_f32_e32 v29, v102, v29
	ds_bpermute_b32 v30, v71, v29
	s_lshl_b64 s[10:11], s[20:21], 1
	s_mov_b32 s20, 0x800000
	s_add_u32 s10, s84, s10
	s_addc_u32 s11, s85, s11
	s_waitcnt lgkmcnt(0)
	v_add_f32_e32 v29, v29, v30
	ds_bpermute_b32 v30, v75, v29
	s_waitcnt lgkmcnt(0)
	v_add_f32_e32 v29, v29, v30
	ds_bpermute_b32 v30, v79, v29
	s_waitcnt lgkmcnt(0)
	v_add_f32_e32 v29, v29, v30
	ds_bpermute_b32 v30, v83, v29
	s_waitcnt lgkmcnt(0)
	v_add_f32_e32 v29, v29, v30
	ds_bpermute_b32 v30, v87, v29
	s_waitcnt lgkmcnt(0)
	v_add_f32_e32 v29, v29, v30
	ds_bpermute_b32 v30, v88, v29
	s_waitcnt lgkmcnt(0)
	v_add_f32_e32 v29, v29, v30
	v_fmamk_f32 v29, v29, 0x3a800000, v193
	v_mul_f32_e32 v30, 0x4b800000, v29
	v_cmp_gt_f32_e32 vcc, s20, v29
	s_nop 1
	v_cndmask_b32_e32 v29, v29, v30, vcc
	v_rsq_f32_e32 v29, v29
	v_lshl_add_u64 v[30:31], s[8:9], 0, v[62:63]
	v_mul_f32_e32 v32, 0x45800000, v29
	v_cndmask_b32_e32 v32, v29, v32, vcc
	v_pk_mul_f32 v[12:13], v[12:13], v[32:33] op_sel_hi:[1,0]
	v_pk_mul_f32 v[14:15], v[14:15], v[32:33] op_sel_hi:[1,0]
	s_waitcnt vmcnt(0)
	v_pk_mul_f32 v[12:13], v[90:91], v[12:13]
	v_pk_mul_f32 v[14:15], v[92:93], v[14:15]
	v_pk_add_f32 v[90:91], v[94:95], 1.0 op_sel_hi:[1,0]
	v_pk_add_f32 v[92:93], v[96:97], 1.0 op_sel_hi:[1,0]
	v_pk_fma_f32 v[12:13], v[90:91], v[12:13], v[98:99]
	v_pk_fma_f32 v[14:15], v[92:93], v[14:15], v[100:101]
	v_cvt_pk_f16_f32 v12, v12, v13
	v_cvt_pk_f16_f32 v13, v14, v15
	global_store_dwordx2 v64, v[12:13], s[10:11]
	global_load_dwordx4 v[12:15], v[76:77], off
	s_nop 0
	global_load_dwordx4 v[90:93], v[30:31], off
	v_lshl_add_u64 v[30:31], s[6:7], 0, v[62:63]
	global_load_dwordx4 v[62:65], v[30:31], off
	v_pk_mul_f32 v[8:9], v[8:9], v[32:33] op_sel_hi:[1,0]
	v_pk_mul_f32 v[10:11], v[10:11], v[32:33] op_sel_hi:[1,0]
	v_lshl_add_u64 v[30:31], s[8:9], 0, v[58:59]
	v_pk_mul_f32 v[4:5], v[4:5], v[32:33] op_sel_hi:[1,0]
	v_pk_mul_f32 v[6:7], v[6:7], v[32:33] op_sel_hi:[1,0]
	v_pk_mul_f32 v[0:1], v[0:1], v[32:33] op_sel_hi:[1,0]
	v_pk_mul_f32 v[2:3], v[2:3], v[32:33] op_sel_hi:[1,0]
	s_waitcnt vmcnt(0)
	v_pk_mul_f32 v[8:9], v[12:13], v[8:9]
	s_waitcnt lgkmcnt(0)
	v_pk_add_f32 v[12:13], v[90:91], 1.0 op_sel_hi:[1,0]
	v_pk_mul_f32 v[10:11], v[14:15], v[10:11]
	v_pk_add_f32 v[14:15], v[92:93], 1.0 op_sel_hi:[1,0]
	v_pk_fma_f32 v[8:9], v[12:13], v[8:9], v[62:63]
	v_pk_fma_f32 v[10:11], v[14:15], v[10:11], v[64:65]
	v_cvt_pk_f16_f32 v8, v8, v9
	v_cvt_pk_f16_f32 v9, v10, v11
	global_store_dwordx2 v60, v[8:9], s[10:11]
	global_load_dwordx4 v[8:11], v[80:81], off
	s_nop 0
	global_load_dwordx4 v[12:15], v[30:31], off
	v_lshl_add_u64 v[30:31], s[6:7], 0, v[58:59]
	global_load_dwordx4 v[58:61], v[30:31], off
	v_lshl_add_u64 v[30:31], s[8:9], 0, v[54:55]
	s_waitcnt vmcnt(0)
	v_pk_mul_f32 v[4:5], v[8:9], v[4:5]
	s_waitcnt lgkmcnt(0)
	v_pk_add_f32 v[8:9], v[12:13], 1.0 op_sel_hi:[1,0]
	v_pk_mul_f32 v[6:7], v[10:11], v[6:7]
	v_pk_add_f32 v[10:11], v[14:15], 1.0 op_sel_hi:[1,0]
	v_pk_fma_f32 v[4:5], v[4:5], v[8:9], v[58:59]
	v_pk_fma_f32 v[6:7], v[6:7], v[10:11], v[60:61]
	v_cvt_pk_f16_f32 v4, v4, v5
	v_cvt_pk_f16_f32 v5, v6, v7
	global_store_dwordx2 v56, v[4:5], s[10:11]
	global_load_dwordx4 v[4:7], v[84:85], off
	s_nop 0
	global_load_dwordx4 v[8:11], v[30:31], off
	v_lshl_add_u64 v[12:13], s[6:7], 0, v[54:55]
	global_load_dwordx4 v[12:15], v[12:13], off
	s_waitcnt vmcnt(0)
	v_pk_mul_f32 v[0:1], v[0:1], v[4:5]
	s_waitcnt lgkmcnt(0)
	v_pk_add_f32 v[4:5], v[8:9], 1.0 op_sel_hi:[1,0]
	v_pk_mul_f32 v[2:3], v[2:3], v[6:7]
	v_pk_add_f32 v[6:7], v[10:11], 1.0 op_sel_hi:[1,0]
	v_pk_fma_f32 v[0:1], v[0:1], v[4:5], v[12:13]
	v_pk_fma_f32 v[2:3], v[2:3], v[6:7], v[14:15]
	v_cvt_pk_f16_f32 v0, v0, v1
	v_cvt_pk_f16_f32 v1, v2, v3
	global_store_dwordx2 v28, v[0:1], s[10:11]
	s_branch .LBB0_775

;     __device__ __forceinline__ void operator()(const f32x4 (&acc)[2][2][4][2], const Unit& u, int wr, int wc, int fr, int fq) const {
;     ...
;         } else if (wc == 0 && fq < 2) {
; #pragma unroll
;             for (int ai = 0; ai < 2; ++ai)
; #pragma unroll
;                 for (int m = 0; m < 4; ++m)
; #pragma unroll
;                     for (int n = 0; n < 2; ++n) *(f32x4*)(bd + (unsigned)(row0 + ai * HALF + m * 16) * 16 + 8 * fq + 4 * n) = acc[ai][0][m][n];
;         }
.LBB0_922:
	s_and_saveexec_b64 s[26:27], s[12:13]
	s_cbranch_execz .LBB0_924
	v_lshlrev_b32_e32 v32, 4, v151
	v_lshl_add_u64 v[144:145], v[32:33], 2, v[138:139]
	global_store_dwordx4 v[144:145], v[126:129], off
	global_store_dwordx4 v[144:145], v[122:125], off offset:16
	global_store_dwordx4 v[144:145], v[110:113], off offset:1024
	global_store_dwordx4 v[144:145], v[106:109], off offset:1040
	global_store_dwordx4 v[144:145], v[94:97], off offset:2048
	global_store_dwordx4 v[144:145], v[90:93], off offset:2064
	global_store_dwordx4 v[144:145], v[78:81], off offset:3072
	global_store_dwordx4 v[144:145], v[74:77], off offset:3088
	v_add_u32_e32 v144, 0x800, v32
	v_mov_b32_e32 v145, v33
	v_lshl_add_u64 v[144:145], v[144:145], 2, v[138:139]
	global_store_dwordx4 v[144:145], v[62:65], off
	global_store_dwordx4 v[144:145], v[58:61], off offset:16
	v_add_u32_e32 v144, 0x900, v32
	v_mov_b32_e32 v145, v33
	v_lshl_add_u64 v[144:145], v[144:145], 2, v[138:139]
	global_store_dwordx4 v[144:145], v[46:49], off
	global_store_dwordx4 v[144:145], v[42:45], off offset:16
	v_add_u32_e32 v144, 0xa00, v32
	v_mov_b32_e32 v145, v33
	v_lshl_add_u64 v[144:145], v[144:145], 2, v[138:139]
	v_add_u32_e32 v32, 0xb00, v32
	global_store_dwordx4 v[144:145], v[28:31], off
	global_store_dwordx4 v[144:145], v[24:27], off offset:16
	v_lshl_add_u64 v[144:145], v[32:33], 2, v[138:139]
	global_store_dwordx4 v[144:145], v[12:15], off
	global_store_dwordx4 v[144:145], v[8:11], off offset:16

; __device__ __forceinline__ float sigm_f(float x) { return __builtin_amdgcn_rcpf(1.0f + fexp(-x)); }
;     __device__ __forceinline__ void operator()(const f32x4 (&acc)[2][2][4][2], const Unit& u, int wr, int wc, int fr, int fq) const {
;         const int row0 = u.pm * BM + wr * 64 + fr;
;         if (u.pn < nmain) {
;             const int col0 = u.pn * BM + wc * 32 + 8 * fq;
; #pragma unroll
;             for (int ai = 0; ai < 2; ++ai)
; #pragma unroll
;                 for (int m = 0; m < 4; ++m)
; #pragma unroll
;                     for (int bj = 0; bj < 2; ++bj) {
;                         h16x8 o;
; #pragma unroll
;                         for (int n = 0; n < 2; ++n)
; #pragma unroll
;                             for (int j = 0; j < 4; ++j) { float v = acc[ai][bj][m][n][j]; if (act) v = sigm_f(v); o[4 * n + j] = (h16)v; }
;                         *(h16x8*)(O + (unsigned)(row0 + ai * HALF + m * 16) * ldc + col0 + bj * HALF) = o;
;                         if (halo && m == 3 && fr >= 13 && u.pn < 12) {
;                             const int row = row0 + ai * HALF + 48, nc = ((row & 4095) >> 6) + 1;
;                             if (nc < 64) *(h16x8*)(halo + ((unsigned)((row >> 12) * 64 + nc) * 3 + (fr - 13)) * 3072 + col0 + bj * HALF) = o;
;                         }
;                     }
.LBB0_925:
	v_mul_f32_e32 v152, 0xbfb8aa3b, v126
	v_exp_f32_e32 v152, v152
	v_lshl_or_b32 v144, s93, 8, v149
	v_ashrrev_i32_e32 v145, 31, v144
	s_cmp_gt_i32 s93, 11
	v_add_f32_e32 v152, 1.0, v152
	v_rcp_f32_e32 v152, v152
	s_cselect_b64 s[26:27], -1, 0
	s_lshr_b32 s0, s17, 6
	s_and_b32 s1, s0, 63
	v_cndmask_b32_e64 v126, v126, v152, s[4:5]
	v_mul_f32_e32 v152, 0xbfb8aa3b, v127
	v_exp_f32_e32 v152, v152
	s_cmp_lg_u32 s1, 63
	s_cselect_b64 s[28:29], -1, 0
	s_mul_i32 s0, s0, 3
	v_add_f32_e32 v152, 1.0, v152
	v_rcp_f32_e32 v152, v152
	s_or_b64 s[26:27], s[14:15], s[26:27]
	v_add3_u32 v32, s0, 3, v148
	s_movk_i32 s0, 0xc00
	v_cndmask_b32_e64 v152, v127, v152, s[4:5]
	v_mul_f32_e32 v127, 0xbfb8aa3b, v128
	v_exp_f32_e32 v127, v127
	v_cvt_pk_f16_f32 v126, v126, v152
	s_xor_b64 s[26:27], s[26:27], -1
	v_mul_lo_u32 v32, v32, s0
	v_add_f32_e32 v127, 1.0, v127
	v_rcp_f32_e32 v127, v127
	s_and_b64 s[28:29], s[26:27], s[28:29]
	v_cndmask_b32_e64 v127, v128, v127, s[4:5]
	v_mul_f32_e32 v128, 0xbfb8aa3b, v129
	v_exp_f32_e32 v128, v128
	s_nop 0
	v_add_f32_e32 v128, 1.0, v128
	v_rcp_f32_e32 v128, v128
	s_nop 0
	v_cndmask_b32_e64 v153, v129, v128, s[4:5]
	v_mul_f32_e32 v128, 0xbfb8aa3b, v122
	v_exp_f32_e32 v128, v128
	v_cvt_pk_f16_f32 v127, v127, v153
	v_add_f32_e32 v128, 1.0, v128
	v_rcp_f32_e32 v128, v128
	s_nop 0
	v_cndmask_b32_e64 v122, v122, v128, s[4:5]
	v_mul_f32_e32 v128, 0xbfb8aa3b, v123
	v_exp_f32_e32 v128, v128
	s_nop 0
	v_add_f32_e32 v128, 1.0, v128
	v_rcp_f32_e32 v128, v128
	s_nop 0
	v_cndmask_b32_e64 v123, v123, v128, s[4:5]
	v_mul_f32_e32 v128, 0xbfb8aa3b, v124
	v_exp_f32_e32 v128, v128
	s_nop 0
	v_add_f32_e32 v128, 1.0, v128
	v_rcp_f32_e32 v128, v128
	s_nop 0
	v_cndmask_b32_e64 v124, v124, v128, s[4:5]
	v_mul_f32_e32 v128, 0xbfb8aa3b, v125
	v_exp_f32_e32 v128, v128
	s_nop 0
	v_add_f32_e32 v128, 1.0, v128
	v_rcp_f32_e32 v128, v128
	s_nop 0
	v_cndmask_b32_e64 v125, v125, v128, s[4:5]
	v_cvt_pk_f16_f32 v129, v124, v125
	v_mul_lo_u32 v124, v151, s78
	v_mov_b32_e32 v125, v33
	v_lshl_add_u64 v[152:153], v[124:125], 1, s[8:9]
	v_mul_f32_e32 v125, 0xbfb8aa3b, v118
	v_exp_f32_e32 v125, v125
	v_cvt_pk_f16_f32 v128, v122, v123
	v_lshlrev_b64 v[122:123], 1, v[144:145]
	v_lshl_add_u64 v[152:153], v[152:153], 0, v[122:123]
	v_add_f32_e32 v125, 1.0, v125
	v_rcp_f32_e32 v125, v125
	global_store_dwordx4 v[152:153], v[126:129], off
	v_cndmask_b32_e64 v118, v118, v125, s[4:5]
	v_mul_f32_e32 v125, 0xbfb8aa3b, v119
	v_exp_f32_e32 v125, v125
	s_nop 0
	v_add_f32_e32 v125, 1.0, v125
	v_rcp_f32_e32 v125, v125
	s_nop 0
	v_cndmask_b32_e64 v119, v119, v125, s[4:5]
	v_mul_f32_e32 v125, 0xbfb8aa3b, v120
	v_exp_f32_e32 v125, v125
	s_nop 0
	v_add_f32_e32 v125, 1.0, v125
	v_rcp_f32_e32 v125, v125
	s_nop 0
	v_cndmask_b32_e64 v120, v120, v125, s[4:5]
	v_mul_f32_e32 v125, 0xbfb8aa3b, v121
	v_exp_f32_e32 v125, v125
	s_nop 0
	v_add_f32_e32 v125, 1.0, v125
	v_rcp_f32_e32 v125, v125
	s_nop 0
	v_cndmask_b32_e64 v121, v121, v125, s[4:5]
	v_mul_f32_e32 v125, 0xbfb8aa3b, v114
	v_exp_f32_e32 v125, v125
	s_nop 0
	v_add_f32_e32 v125, 1.0, v125
	v_rcp_f32_e32 v125, v125
	s_nop 0
	v_cndmask_b32_e64 v114, v114, v125, s[4:5]
	v_mul_f32_e32 v125, 0xbfb8aa3b, v115
	v_exp_f32_e32 v125, v125
	s_nop 0
	v_add_f32_e32 v125, 1.0, v125
	v_rcp_f32_e32 v125, v125
	s_nop 0
	v_cndmask_b32_e64 v115, v115, v125, s[4:5]
	v_mul_f32_e32 v125, 0xbfb8aa3b, v116
	v_exp_f32_e32 v125, v125
	s_nop 0
	v_add_f32_e32 v125, 1.0, v125
	v_rcp_f32_e32 v125, v125
	s_nop 0
	v_cndmask_b32_e64 v116, v116, v125, s[4:5]
	v_mul_f32_e32 v125, 0xbfb8aa3b, v117
	v_exp_f32_e32 v125, v125
	s_nop 0
	v_add_f32_e32 v125, 1.0, v125
	v_rcp_f32_e32 v125, v125
	s_nop 0
	v_cndmask_b32_e64 v117, v117, v125, s[4:5]
	v_cvt_pk_f16_f32 v117, v116, v117
	v_cvt_pk_f16_f32 v116, v114, v115
	v_cvt_pk_f16_f32 v115, v120, v121
	v_cvt_pk_f16_f32 v114, v118, v119
	global_store_dwordx4 v[152:153], v[114:117], off offset:256
	s_nop 1
	v_mul_f32_e32 v114, 0xbfb8aa3b, v110
	v_exp_f32_e32 v114, v114
	s_nop 0
	v_add_f32_e32 v114, 1.0, v114
	v_rcp_f32_e32 v114, v114
	s_nop 0
	v_cndmask_b32_e64 v114, v110, v114, s[4:5]
	v_mul_f32_e32 v110, 0xbfb8aa3b, v111
	v_exp_f32_e32 v110, v110
	s_nop 0
	v_add_f32_e32 v110, 1.0, v110
	v_rcp_f32_e32 v110, v110
	s_nop 0
	v_cndmask_b32_e64 v115, v111, v110, s[4:5]
	v_mul_f32_e32 v110, 0xbfb8aa3b, v112
	v_exp_f32_e32 v110, v110
	s_nop 0
	v_add_f32_e32 v110, 1.0, v110
	v_rcp_f32_e32 v110, v110
	s_nop 0
	v_cndmask_b32_e64 v112, v112, v110, s[4:5]
	v_mul_f32_e32 v110, 0xbfb8aa3b, v113
	v_exp_f32_e32 v110, v110
	s_nop 0
	v_add_f32_e32 v110, 1.0, v110
	v_rcp_f32_e32 v110, v110
	s_nop 0
	v_cndmask_b32_e64 v113, v113, v110, s[4:5]
	v_mul_f32_e32 v110, 0xbfb8aa3b, v106
	v_exp_f32_e32 v110, v110
	s_nop 0
	v_add_f32_e32 v110, 1.0, v110
	v_rcp_f32_e32 v110, v110
	s_nop 0
	v_cndmask_b32_e64 v106, v106, v110, s[4:5]
	v_mul_f32_e32 v110, 0xbfb8aa3b, v107
	v_exp_f32_e32 v110, v110
	s_nop 0
	v_add_f32_e32 v110, 1.0, v110
	v_rcp_f32_e32 v110, v110
	s_nop 0
	v_cndmask_b32_e64 v107, v107, v110, s[4:5]
	v_mul_f32_e32 v110, 0xbfb8aa3b, v108
	v_exp_f32_e32 v110, v110
	s_nop 0
	v_add_f32_e32 v110, 1.0, v110
	v_rcp_f32_e32 v110, v110
	s_nop 0
	v_cndmask_b32_e64 v108, v108, v110, s[4:5]
	v_mul_f32_e32 v110, 0xbfb8aa3b, v109
	v_exp_f32_e32 v110, v110
	s_nop 0
	v_add_f32_e32 v110, 1.0, v110
	v_rcp_f32_e32 v110, v110
	s_nop 0
	v_cndmask_b32_e64 v109, v109, v110, s[4:5]
	v_cvt_pk_f16_f32 v110, v106, v107
	v_add_u32_e32 v106, s92, v124
	v_mov_b32_e32 v107, v33
	v_cvt_pk_f16_f32 v111, v108, v109
	v_cvt_pk_f16_f32 v109, v112, v113
	v_lshl_add_u64 v[112:113], v[106:107], 1, s[8:9]
	v_mul_f32_e32 v107, 0xbfb8aa3b, v102
	v_exp_f32_e32 v107, v107
; __device__ __forceinline__ float sigm_f(float x) { return __builtin_amdgcn_rcpf(1.0f + fexp(-x)); }
;     __device__ __forceinline__ void operator()(const f32x4 (&acc)[2][2][4][2], const Unit& u, int wr, int wc, int fr, int fq) const {
;         const int row0 = u.pm * BM + wr * 64 + fr;
;         if (u.pn < nmain) {
;             const int col0 = u.pn * BM + wc * 32 + 8 * fq;
; #pragma unroll
;             for (int ai = 0; ai < 2; ++ai)
; #pragma unroll
;                 for (int m = 0; m < 4; ++m)
; #pragma unroll
;                     for (int bj = 0; bj < 2; ++bj) {
;                         h16x8 o;
; #pragma unroll
;                         for (int n = 0; n < 2; ++n)
; #pragma unroll
;                             for (int j = 0; j < 4; ++j) { float v = acc[ai][bj][m][n][j]; if (act) v = sigm_f(v); o[4 * n + j] = (h16)v; }
;                         *(h16x8*)(O + (unsigned)(row0 + ai * HALF + m * 16) * ldc + col0 + bj * HALF) = o;
;                         if (halo && m == 3 && fr >= 13 && u.pn < 12) {
;                             const int row = row0 + ai * HALF + 48, nc = ((row & 4095) >> 6) + 1;
;                             if (nc < 64) *(h16x8*)(halo + ((unsigned)((row >> 12) * 64 + nc) * 3 + (fr - 13)) * 3072 + col0 + bj * HALF) = o;
;                         }
;                     }
	v_lshl_add_u64 v[112:113], v[112:113], 0, v[122:123]
	v_cvt_pk_f16_f32 v108, v114, v115
	global_store_dwordx4 v[112:113], v[108:111], off
	v_add_f32_e32 v107, 1.0, v107
	v_rcp_f32_e32 v107, v107
	s_nop 0
	v_cndmask_b32_e64 v102, v102, v107, s[4:5]
	v_mul_f32_e32 v107, 0xbfb8aa3b, v103
	v_exp_f32_e32 v107, v107
	s_nop 0
	v_add_f32_e32 v107, 1.0, v107
	v_rcp_f32_e32 v107, v107
	s_nop 0
	v_cndmask_b32_e64 v103, v103, v107, s[4:5]
	v_mul_f32_e32 v107, 0xbfb8aa3b, v104
	v_exp_f32_e32 v107, v107
	s_nop 0
	v_add_f32_e32 v107, 1.0, v107
	v_rcp_f32_e32 v107, v107
	s_nop 0
	v_cndmask_b32_e64 v104, v104, v107, s[4:5]
	v_mul_f32_e32 v107, 0xbfb8aa3b, v105
	v_exp_f32_e32 v107, v107
	s_nop 0
	v_add_f32_e32 v107, 1.0, v107
	v_rcp_f32_e32 v107, v107
	s_nop 0
	v_cndmask_b32_e64 v105, v105, v107, s[4:5]
	v_mul_f32_e32 v107, 0xbfb8aa3b, v98
	v_exp_f32_e32 v107, v107
	s_nop 0
	v_add_f32_e32 v107, 1.0, v107
	v_rcp_f32_e32 v107, v107
	s_nop 0
	v_cndmask_b32_e64 v98, v98, v107, s[4:5]
	v_mul_f32_e32 v107, 0xbfb8aa3b, v99
	v_exp_f32_e32 v107, v107
	s_nop 0
	v_add_f32_e32 v107, 1.0, v107
	v_rcp_f32_e32 v107, v107
	s_nop 0
	v_cndmask_b32_e64 v99, v99, v107, s[4:5]
	v_mul_f32_e32 v107, 0xbfb8aa3b, v100
	v_exp_f32_e32 v107, v107
	s_nop 0
	v_add_f32_e32 v107, 1.0, v107
	v_rcp_f32_e32 v107, v107
	s_nop 0
	v_cndmask_b32_e64 v100, v100, v107, s[4:5]
	v_mul_f32_e32 v107, 0xbfb8aa3b, v101
	v_exp_f32_e32 v107, v107
	s_nop 0
	v_add_f32_e32 v107, 1.0, v107
	v_rcp_f32_e32 v107, v107
	s_nop 0
	v_cndmask_b32_e64 v101, v101, v107, s[4:5]
	v_cvt_pk_f16_f32 v101, v100, v101
	v_cvt_pk_f16_f32 v100, v98, v99
	v_cvt_pk_f16_f32 v99, v104, v105
	v_cvt_pk_f16_f32 v98, v102, v103
	global_store_dwordx4 v[112:113], v[98:101], off offset:256
	s_nop 1
	v_mul_f32_e32 v98, 0xbfb8aa3b, v94
	v_exp_f32_e32 v98, v98
	s_nop 0
	v_add_f32_e32 v98, 1.0, v98
	v_rcp_f32_e32 v98, v98
	s_nop 0
	v_cndmask_b32_e64 v98, v94, v98, s[4:5]
	v_mul_f32_e32 v94, 0xbfb8aa3b, v95
	v_exp_f32_e32 v94, v94
	s_nop 0
	v_add_f32_e32 v94, 1.0, v94
	v_rcp_f32_e32 v94, v94
	s_nop 0
	v_cndmask_b32_e64 v99, v95, v94, s[4:5]
	v_mul_f32_e32 v94, 0xbfb8aa3b, v96
	v_exp_f32_e32 v94, v94
	s_nop 0
	v_add_f32_e32 v94, 1.0, v94
	v_rcp_f32_e32 v94, v94
	s_nop 0
	v_cndmask_b32_e64 v96, v96, v94, s[4:5]
	v_mul_f32_e32 v94, 0xbfb8aa3b, v97
	v_exp_f32_e32 v94, v94
	s_nop 0
	v_add_f32_e32 v94, 1.0, v94
	v_rcp_f32_e32 v94, v94
	s_nop 0
	v_cndmask_b32_e64 v97, v97, v94, s[4:5]
	v_mul_f32_e32 v94, 0xbfb8aa3b, v90
	v_exp_f32_e32 v94, v94
	s_nop 0
	v_add_f32_e32 v94, 1.0, v94
	v_rcp_f32_e32 v94, v94
	s_nop 0
	v_cndmask_b32_e64 v90, v90, v94, s[4:5]
	v_mul_f32_e32 v94, 0xbfb8aa3b, v91
	v_exp_f32_e32 v94, v94
	s_nop 0
	v_add_f32_e32 v94, 1.0, v94
	v_rcp_f32_e32 v94, v94
	s_nop 0
	v_cndmask_b32_e64 v91, v91, v94, s[4:5]
	v_mul_f32_e32 v94, 0xbfb8aa3b, v92
	v_exp_f32_e32 v94, v94
	s_nop 0
	v_add_f32_e32 v94, 1.0, v94
	v_rcp_f32_e32 v94, v94
	s_nop 0
	v_cndmask_b32_e64 v92, v92, v94, s[4:5]
	v_mul_f32_e32 v94, 0xbfb8aa3b, v93
	v_exp_f32_e32 v94, v94
	s_nop 0
	v_add_f32_e32 v94, 1.0, v94
	v_rcp_f32_e32 v94, v94
	s_nop 0
	v_cndmask_b32_e64 v93, v93, v94, s[4:5]
	v_cvt_pk_f16_f32 v94, v90, v91
	v_add_u32_e32 v90, s92, v106
	v_mov_b32_e32 v91, v33
	v_cvt_pk_f16_f32 v95, v92, v93
	v_cvt_pk_f16_f32 v93, v96, v97
	v_lshl_add_u64 v[96:97], v[90:91], 1, s[8:9]
	v_mul_f32_e32 v91, 0xbfb8aa3b, v86
	v_exp_f32_e32 v91, v91
	v_lshl_add_u64 v[96:97], v[96:97], 0, v[122:123]
	v_cvt_pk_f16_f32 v92, v98, v99
	global_store_dwordx4 v[96:97], v[92:95], off
	v_add_f32_e32 v91, 1.0, v91
	v_rcp_f32_e32 v91, v91
	s_nop 0
	v_cndmask_b32_e64 v86, v86, v91, s[4:5]
	v_mul_f32_e32 v91, 0xbfb8aa3b, v87
	v_exp_f32_e32 v91, v91
	s_nop 0
	v_add_f32_e32 v91, 1.0, v91
	v_rcp_f32_e32 v91, v91
	s_nop 0
	v_cndmask_b32_e64 v87, v87, v91, s[4:5]
	v_mul_f32_e32 v91, 0xbfb8aa3b, v88
	v_exp_f32_e32 v91, v91
	s_nop 0
	v_add_f32_e32 v91, 1.0, v91
	v_rcp_f32_e32 v91, v91
	s_nop 0
	v_cndmask_b32_e64 v88, v88, v91, s[4:5]
	v_mul_f32_e32 v91, 0xbfb8aa3b, v89
	v_exp_f32_e32 v91, v91
	s_nop 0
	v_add_f32_e32 v91, 1.0, v91
	v_rcp_f32_e32 v91, v91
	s_nop 0
	v_cndmask_b32_e64 v89, v89, v91, s[4:5]
	v_mul_f32_e32 v91, 0xbfb8aa3b, v82
	v_exp_f32_e32 v91, v91
	s_nop 0
	v_add_f32_e32 v91, 1.0, v91
	v_rcp_f32_e32 v91, v91
	s_nop 0
	v_cndmask_b32_e64 v82, v82, v91, s[4:5]
	v_mul_f32_e32 v91, 0xbfb8aa3b, v83
	v_exp_f32_e32 v91, v91
	s_nop 0
	v_add_f32_e32 v91, 1.0, v91
	v_rcp_f32_e32 v91, v91
	s_nop 0
	v_cndmask_b32_e64 v83, v83, v91, s[4:5]
	v_mul_f32_e32 v91, 0xbfb8aa3b, v84
	v_exp_f32_e32 v91, v91
	s_nop 0
	v_add_f32_e32 v91, 1.0, v91
	v_rcp_f32_e32 v91, v91
	s_nop 0
	v_cndmask_b32_e64 v84, v84, v91, s[4:5]
	v_mul_f32_e32 v91, 0xbfb8aa3b, v85
	v_exp_f32_e32 v91, v91
	s_nop 0
	v_add_f32_e32 v91, 1.0, v91
	v_rcp_f32_e32 v91, v91
	s_nop 0
	v_cndmask_b32_e64 v85, v85, v91, s[4:5]
	v_cvt_pk_f16_f32 v85, v84, v85
	v_cvt_pk_f16_f32 v84, v82, v83
	v_cvt_pk_f16_f32 v83, v88, v89
	v_cvt_pk_f16_f32 v82, v86, v87
	global_store_dwordx4 v[96:97], v[82:85], off offset:256
	s_nop 1
	v_mul_f32_e32 v82, 0xbfb8aa3b, v78
	v_exp_f32_e32 v82, v82
	s_nop 0
	v_add_f32_e32 v82, 1.0, v82
	v_rcp_f32_e32 v82, v82
	s_nop 0
	v_cndmask_b32_e64 v78, v78, v82, s[4:5]
	v_mul_f32_e32 v82, 0xbfb8aa3b, v79
	v_exp_f32_e32 v82, v82
	s_nop 0
	v_add_f32_e32 v82, 1.0, v82
	v_rcp_f32_e32 v82, v82
	s_nop 0
	v_cndmask_b32_e64 v79, v79, v82, s[4:5]
	v_mul_f32_e32 v82, 0xbfb8aa3b, v80
	v_exp_f32_e32 v82, v82
	s_nop 0
	v_add_f32_e32 v82, 1.0, v82
	v_rcp_f32_e32 v82, v82
	s_nop 0
	v_cndmask_b32_e64 v80, v80, v82, s[4:5]
	v_mul_f32_e32 v82, 0xbfb8aa3b, v81
	v_exp_f32_e32 v82, v82
	s_nop 0
	v_add_f32_e32 v82, 1.0, v82
	v_rcp_f32_e32 v82, v82
	s_nop 0
	v_cndmask_b32_e64 v81, v81, v82, s[4:5]
	v_mul_f32_e32 v82, 0xbfb8aa3b, v74
	v_exp_f32_e32 v82, v82
	s_nop 0
	v_add_f32_e32 v82, 1.0, v82
	v_rcp_f32_e32 v82, v82
	s_nop 0
	v_cndmask_b32_e64 v74, v74, v82, s[4:5]
	v_mul_f32_e32 v82, 0xbfb8aa3b, v75
	v_exp_f32_e32 v82, v82
	s_nop 0
	v_add_f32_e32 v82, 1.0, v82
	v_rcp_f32_e32 v82, v82
	s_nop 0
	v_cndmask_b32_e64 v75, v75, v82, s[4:5]
	v_mul_f32_e32 v82, 0xbfb8aa3b, v76
	v_exp_f32_e32 v82, v82
	s_nop 0
	v_add_f32_e32 v82, 1.0, v82
	v_rcp_f32_e32 v82, v82
	s_nop 0
	v_cndmask_b32_e64 v76, v76, v82, s[4:5]
	v_mul_f32_e32 v82, 0xbfb8aa3b, v77
	v_exp_f32_e32 v82, v82
	s_nop 0
	v_add_f32_e32 v82, 1.0, v82
	v_rcp_f32_e32 v82, v82
	s_nop 0
	v_cndmask_b32_e64 v77, v77, v82, s[4:5]
	v_cvt_pk_f16_f32 v77, v76, v77
	v_cvt_pk_f16_f32 v76, v74, v75
	v_cvt_pk_f16_f32 v74, v78, v79
	v_add_u32_e32 v78, s92, v90
	v_mov_b32_e32 v79, v33
	v_cvt_pk_f16_f32 v75, v80, v81
	v_lshl_add_u64 v[80:81], v[78:79], 1, s[8:9]
	v_lshl_add_u64 v[80:81], v[80:81], 0, v[122:123]
	global_store_dwordx4 v[80:81], v[74:77], off
	s_and_saveexec_b64 s[30:31], s[28:29]
	s_cbranch_execz .LBB0_927
	v_readlane_b32 s0, v255, 30
	v_readlane_b32 s1, v255, 31
	s_nop 1
	v_lshl_add_u64 v[82:83], v[32:33], 1, s[0:1]
	v_lshl_add_u64 v[82:83], v[144:145], 1, v[82:83]
	global_store_dwordx4 v[82:83], v[74:77], off
; __device__ __forceinline__ float sigm_f(float x) { return __builtin_amdgcn_rcpf(1.0f + fexp(-x)); }
;     __device__ __forceinline__ void operator()(const f32x4 (&acc)[2][2][4][2], const Unit& u, int wr, int wc, int fr, int fq) const {
;         const int row0 = u.pm * BM + wr * 64 + fr;
;         if (u.pn < nmain) {
;             const int col0 = u.pn * BM + wc * 32 + 8 * fq;
; #pragma unroll
;             for (int ai = 0; ai < 2; ++ai)
; #pragma unroll
;                 for (int m = 0; m < 4; ++m)
; #pragma unroll
;                     for (int bj = 0; bj < 2; ++bj) {
;                         h16x8 o;
; #pragma unroll
;                         for (int n = 0; n < 2; ++n)
; #pragma unroll
;                             for (int j = 0; j < 4; ++j) { float v = acc[ai][bj][m][n][j]; if (act) v = sigm_f(v); o[4 * n + j] = (h16)v; }
;                         *(h16x8*)(O + (unsigned)(row0 + ai * HALF + m * 16) * ldc + col0 + bj * HALF) = o;
;                         if (halo && m == 3 && fr >= 13 && u.pn < 12) {
;                             const int row = row0 + ai * HALF + 48, nc = ((row & 4095) >> 6) + 1;
;                             if (nc < 64) *(h16x8*)(halo + ((unsigned)((row >> 12) * 64 + nc) * 3 + (fr - 13)) * 3072 + col0 + bj * HALF) = o;
;                         }
;                     }
.LBB0_927:
	s_or_b64 exec, exec, s[30:31]
	s_nop 0
	v_mul_f32_e32 v74, 0xbfb8aa3b, v70
	v_exp_f32_e32 v74, v74
	s_nop 0
	v_add_f32_e32 v74, 1.0, v74
	v_rcp_f32_e32 v74, v74
	s_nop 0
	v_cndmask_b32_e64 v70, v70, v74, s[4:5]
	v_mul_f32_e32 v74, 0xbfb8aa3b, v71
	v_exp_f32_e32 v74, v74
	s_nop 0
	v_add_f32_e32 v74, 1.0, v74
	v_rcp_f32_e32 v74, v74
	s_nop 0
	v_cndmask_b32_e64 v71, v71, v74, s[4:5]
	v_mul_f32_e32 v74, 0xbfb8aa3b, v72
	v_exp_f32_e32 v74, v74
	s_nop 0
	v_add_f32_e32 v74, 1.0, v74
	v_rcp_f32_e32 v74, v74
	s_nop 0
	v_cndmask_b32_e64 v72, v72, v74, s[4:5]
	v_mul_f32_e32 v74, 0xbfb8aa3b, v73
	v_exp_f32_e32 v74, v74
	s_nop 0
	v_add_f32_e32 v74, 1.0, v74
	v_rcp_f32_e32 v74, v74
	s_nop 0
	v_cndmask_b32_e64 v73, v73, v74, s[4:5]
	v_mul_f32_e32 v74, 0xbfb8aa3b, v66
	v_exp_f32_e32 v74, v74
	s_nop 0
	v_add_f32_e32 v74, 1.0, v74
	v_rcp_f32_e32 v74, v74
	s_nop 0
	v_cndmask_b32_e64 v66, v66, v74, s[4:5]
	v_mul_f32_e32 v74, 0xbfb8aa3b, v67
	v_exp_f32_e32 v74, v74
	s_nop 0
	v_add_f32_e32 v74, 1.0, v74
	v_rcp_f32_e32 v74, v74
	s_nop 0
	v_cndmask_b32_e64 v67, v67, v74, s[4:5]
	v_mul_f32_e32 v74, 0xbfb8aa3b, v68
	v_exp_f32_e32 v74, v74
	s_nop 0
	v_add_f32_e32 v74, 1.0, v74
	v_rcp_f32_e32 v74, v74
	s_nop 0
	v_cndmask_b32_e64 v68, v68, v74, s[4:5]
	v_mul_f32_e32 v74, 0xbfb8aa3b, v69
	v_exp_f32_e32 v74, v74
	s_nop 0
	v_add_f32_e32 v74, 1.0, v74
	v_rcp_f32_e32 v74, v74
	s_nop 0
	v_cndmask_b32_e64 v69, v69, v74, s[4:5]
	v_cvt_pk_f16_f32 v69, v68, v69
	v_cvt_pk_f16_f32 v68, v66, v67
	v_cvt_pk_f16_f32 v67, v72, v73
	v_cvt_pk_f16_f32 v66, v70, v71
	global_store_dwordx4 v[80:81], v[66:69], off offset:256
	s_and_saveexec_b64 s[30:31], s[28:29]
	s_cbranch_execz .LBB0_929
	v_readlane_b32 s0, v255, 30
	v_readlane_b32 s1, v255, 31
	s_nop 1
	v_lshl_add_u64 v[70:71], v[32:33], 1, s[0:1]
	v_lshl_add_u64 v[70:71], v[144:145], 1, v[70:71]
	global_store_dwordx4 v[70:71], v[66:69], off offset:256
.LBB0_929:
	s_or_b64 exec, exec, s[30:31]
	v_add_u32_e32 v32, 0x80, v151
	v_lshrrev_b32_e32 v32, 6, v32
	v_and_b32_e32 v66, 63, v32
	v_cmp_ne_u32_e32 vcc, 63, v66
	v_mul_f32_e32 v66, 0xbfb8aa3b, v62
	v_exp_f32_e32 v66, v66
	v_and_b32_e32 v32, 0x3fffff, v32
	v_add_u32_e32 v32, 1, v32
	v_mad_u32_u24 v32, v32, 3, v148
	v_add_f32_e32 v66, 1.0, v66
	v_rcp_f32_e32 v66, v66
	s_movk_i32 s0, 0xc00
	v_mul_lo_u32 v32, v32, s0
	s_mul_i32 s0, s78, 0x50
	v_cndmask_b32_e64 v66, v62, v66, s[4:5]
	v_mul_f32_e32 v62, 0xbfb8aa3b, v63
	v_exp_f32_e32 v62, v62
	s_and_b64 s[26:27], s[26:27], vcc
	v_add_f32_e32 v62, 1.0, v62
	v_rcp_f32_e32 v62, v62
	s_nop 0
	v_cndmask_b32_e64 v67, v63, v62, s[4:5]
	v_mul_f32_e32 v62, 0xbfb8aa3b, v64
	v_exp_f32_e32 v62, v62
	s_nop 0
	v_add_f32_e32 v62, 1.0, v62
	v_rcp_f32_e32 v62, v62
	s_nop 0
	v_cndmask_b32_e64 v64, v64, v62, s[4:5]
	v_mul_f32_e32 v62, 0xbfb8aa3b, v65
	v_exp_f32_e32 v62, v62
	s_nop 0
	v_add_f32_e32 v62, 1.0, v62
	v_rcp_f32_e32 v62, v62
	s_nop 0
	v_cndmask_b32_e64 v65, v65, v62, s[4:5]
	v_mul_f32_e32 v62, 0xbfb8aa3b, v58
	v_exp_f32_e32 v62, v62
	s_nop 0
	v_add_f32_e32 v62, 1.0, v62
	v_rcp_f32_e32 v62, v62
	s_nop 0
	v_cndmask_b32_e64 v58, v58, v62, s[4:5]
	v_mul_f32_e32 v62, 0xbfb8aa3b, v59
	v_exp_f32_e32 v62, v62
	s_nop 0
	v_add_f32_e32 v62, 1.0, v62
	v_rcp_f32_e32 v62, v62
	s_nop 0
	v_cndmask_b32_e64 v59, v59, v62, s[4:5]
	v_mul_f32_e32 v62, 0xbfb8aa3b, v60
	v_exp_f32_e32 v62, v62
	s_nop 0
	v_add_f32_e32 v62, 1.0, v62
	v_rcp_f32_e32 v62, v62
	s_nop 0
	v_cndmask_b32_e64 v60, v60, v62, s[4:5]
	v_mul_f32_e32 v62, 0xbfb8aa3b, v61
	v_exp_f32_e32 v62, v62
	s_nop 0
	v_add_f32_e32 v62, 1.0, v62
	v_rcp_f32_e32 v62, v62
	s_nop 0
	v_cndmask_b32_e64 v61, v61, v62, s[4:5]
	v_cvt_pk_f16_f32 v62, v58, v59
	v_add_u32_e32 v58, s0, v78
	v_mov_b32_e32 v59, v33
	v_cvt_pk_f16_f32 v63, v60, v61
	v_cvt_pk_f16_f32 v61, v64, v65
	v_lshl_add_u64 v[64:65], v[58:59], 1, s[8:9]
	v_mul_f32_e32 v59, 0xbfb8aa3b, v54
	v_exp_f32_e32 v59, v59
	v_lshl_add_u64 v[64:65], v[64:65], 0, v[122:123]
	v_cvt_pk_f16_f32 v60, v66, v67
	global_store_dwordx4 v[64:65], v[60:63], off
	v_add_f32_e32 v59, 1.0, v59
	v_rcp_f32_e32 v59, v59
	s_nop 0
	v_cndmask_b32_e64 v54, v54, v59, s[4:5]
	v_mul_f32_e32 v59, 0xbfb8aa3b, v55
	v_exp_f32_e32 v59, v59
	s_nop 0
	v_add_f32_e32 v59, 1.0, v59
	v_rcp_f32_e32 v59, v59
	s_nop 0
	v_cndmask_b32_e64 v55, v55, v59, s[4:5]
	v_mul_f32_e32 v59, 0xbfb8aa3b, v56
	v_exp_f32_e32 v59, v59
	s_nop 0
	v_add_f32_e32 v59, 1.0, v59
	v_rcp_f32_e32 v59, v59
	s_nop 0
	v_cndmask_b32_e64 v56, v56, v59, s[4:5]
	v_mul_f32_e32 v59, 0xbfb8aa3b, v57
	v_exp_f32_e32 v59, v59
	s_nop 0
	v_add_f32_e32 v59, 1.0, v59
	v_rcp_f32_e32 v59, v59
	s_nop 0
	v_cndmask_b32_e64 v57, v57, v59, s[4:5]
	v_mul_f32_e32 v59, 0xbfb8aa3b, v50
	v_exp_f32_e32 v59, v59
	s_nop 0
	v_add_f32_e32 v59, 1.0, v59
	v_rcp_f32_e32 v59, v59
	s_nop 0
	v_cndmask_b32_e64 v50, v50, v59, s[4:5]
	v_mul_f32_e32 v59, 0xbfb8aa3b, v51
	v_exp_f32_e32 v59, v59
	s_nop 0
	v_add_f32_e32 v59, 1.0, v59
	v_rcp_f32_e32 v59, v59
	s_nop 0
	v_cndmask_b32_e64 v51, v51, v59, s[4:5]
	v_mul_f32_e32 v59, 0xbfb8aa3b, v52
	v_exp_f32_e32 v59, v59
	s_nop 0
	v_add_f32_e32 v59, 1.0, v59
	v_rcp_f32_e32 v59, v59
	s_nop 0
	v_cndmask_b32_e64 v52, v52, v59, s[4:5]
	v_mul_f32_e32 v59, 0xbfb8aa3b, v53
	v_exp_f32_e32 v59, v59
	s_nop 0
	v_add_f32_e32 v59, 1.0, v59
	v_rcp_f32_e32 v59, v59
	s_nop 0
	v_cndmask_b32_e64 v53, v53, v59, s[4:5]
	v_cvt_pk_f16_f32 v53, v52, v53
	v_cvt_pk_f16_f32 v52, v50, v51
	v_cvt_pk_f16_f32 v51, v56, v57
	v_cvt_pk_f16_f32 v50, v54, v55
	global_store_dwordx4 v[64:65], v[50:53], off offset:256
	s_nop 1
	v_mul_f32_e32 v50, 0xbfb8aa3b, v46
	v_exp_f32_e32 v50, v50
	s_nop 0
	v_add_f32_e32 v50, 1.0, v50
	v_rcp_f32_e32 v50, v50
	s_nop 0
; __device__ __forceinline__ float sigm_f(float x) { return __builtin_amdgcn_rcpf(1.0f + fexp(-x)); }
;     __device__ __forceinline__ void operator()(const f32x4 (&acc)[2][2][4][2], const Unit& u, int wr, int wc, int fr, int fq) const {
;         const int row0 = u.pm * BM + wr * 64 + fr;
;         if (u.pn < nmain) {
;             const int col0 = u.pn * BM + wc * 32 + 8 * fq;
; #pragma unroll
;             for (int ai = 0; ai < 2; ++ai)
; #pragma unroll
;                 for (int m = 0; m < 4; ++m)
; #pragma unroll
;                     for (int bj = 0; bj < 2; ++bj) {
;                         h16x8 o;
; #pragma unroll
;                         for (int n = 0; n < 2; ++n)
; #pragma unroll
;                             for (int j = 0; j < 4; ++j) { float v = acc[ai][bj][m][n][j]; if (act) v = sigm_f(v); o[4 * n + j] = (h16)v; }
;                         *(h16x8*)(O + (unsigned)(row0 + ai * HALF + m * 16) * ldc + col0 + bj * HALF) = o;
	v_cndmask_b32_e64 v50, v46, v50, s[4:5]
	v_mul_f32_e32 v46, 0xbfb8aa3b, v47
	v_exp_f32_e32 v46, v46
	s_nop 0
	v_add_f32_e32 v46, 1.0, v46
	v_rcp_f32_e32 v46, v46
	s_nop 0
	v_cndmask_b32_e64 v51, v47, v46, s[4:5]
	v_mul_f32_e32 v46, 0xbfb8aa3b, v48
	v_exp_f32_e32 v46, v46
	s_nop 0
	v_add_f32_e32 v46, 1.0, v46
	v_rcp_f32_e32 v46, v46
	s_nop 0
	v_cndmask_b32_e64 v48, v48, v46, s[4:5]
	v_mul_f32_e32 v46, 0xbfb8aa3b, v49
	v_exp_f32_e32 v46, v46
	s_nop 0
	v_add_f32_e32 v46, 1.0, v46
	v_rcp_f32_e32 v46, v46
	s_nop 0
	v_cndmask_b32_e64 v49, v49, v46, s[4:5]
	v_mul_f32_e32 v46, 0xbfb8aa3b, v42
	v_exp_f32_e32 v46, v46
	s_nop 0
	v_add_f32_e32 v46, 1.0, v46
	v_rcp_f32_e32 v46, v46
	s_nop 0
	v_cndmask_b32_e64 v42, v42, v46, s[4:5]
	v_mul_f32_e32 v46, 0xbfb8aa3b, v43
	v_exp_f32_e32 v46, v46
	s_nop 0
	v_add_f32_e32 v46, 1.0, v46
	v_rcp_f32_e32 v46, v46
	s_nop 0
	v_cndmask_b32_e64 v43, v43, v46, s[4:5]
	v_mul_f32_e32 v46, 0xbfb8aa3b, v44
	v_exp_f32_e32 v46, v46
	s_nop 0
	v_add_f32_e32 v46, 1.0, v46
	v_rcp_f32_e32 v46, v46
	s_nop 0
	v_cndmask_b32_e64 v44, v44, v46, s[4:5]
	v_mul_f32_e32 v46, 0xbfb8aa3b, v45
	v_exp_f32_e32 v46, v46
	s_nop 0
	v_add_f32_e32 v46, 1.0, v46
	v_rcp_f32_e32 v46, v46
	s_nop 0
	v_cndmask_b32_e64 v45, v45, v46, s[4:5]
	v_cvt_pk_f16_f32 v46, v42, v43
	v_add_u32_e32 v42, s92, v58
	v_mov_b32_e32 v43, v33
	v_cvt_pk_f16_f32 v47, v44, v45
	v_cvt_pk_f16_f32 v45, v48, v49
	v_lshl_add_u64 v[48:49], v[42:43], 1, s[8:9]
	v_mul_f32_e32 v43, 0xbfb8aa3b, v38
	v_exp_f32_e32 v43, v43
	v_lshl_add_u64 v[48:49], v[48:49], 0, v[122:123]
	v_cvt_pk_f16_f32 v44, v50, v51
	global_store_dwordx4 v[48:49], v[44:47], off
	v_add_f32_e32 v43, 1.0, v43
	v_rcp_f32_e32 v43, v43
	s_nop 0
	v_cndmask_b32_e64 v38, v38, v43, s[4:5]
	v_mul_f32_e32 v43, 0xbfb8aa3b, v39
	v_exp_f32_e32 v43, v43
	s_nop 0
	v_add_f32_e32 v43, 1.0, v43
	v_rcp_f32_e32 v43, v43
	s_nop 0
	v_cndmask_b32_e64 v39, v39, v43, s[4:5]
	v_mul_f32_e32 v43, 0xbfb8aa3b, v40
	v_exp_f32_e32 v43, v43
	s_nop 0
	v_add_f32_e32 v43, 1.0, v43
	v_rcp_f32_e32 v43, v43
	s_nop 0
	v_cndmask_b32_e64 v40, v40, v43, s[4:5]
	v_mul_f32_e32 v43, 0xbfb8aa3b, v41
	v_exp_f32_e32 v43, v43
	s_nop 0
	v_add_f32_e32 v43, 1.0, v43
	v_rcp_f32_e32 v43, v43
	s_nop 0
	v_cndmask_b32_e64 v41, v41, v43, s[4:5]
	v_mul_f32_e32 v43, 0xbfb8aa3b, v34
	v_exp_f32_e32 v43, v43
	s_nop 0
	v_add_f32_e32 v43, 1.0, v43
	v_rcp_f32_e32 v43, v43
	s_nop 0
	v_cndmask_b32_e64 v34, v34, v43, s[4:5]
	v_mul_f32_e32 v43, 0xbfb8aa3b, v35
	v_exp_f32_e32 v43, v43
	s_nop 0
	v_add_f32_e32 v43, 1.0, v43
	v_rcp_f32_e32 v43, v43
	s_nop 0
	v_cndmask_b32_e64 v35, v35, v43, s[4:5]
	v_mul_f32_e32 v43, 0xbfb8aa3b, v36
	v_exp_f32_e32 v43, v43
	s_nop 0
	v_add_f32_e32 v43, 1.0, v43
	v_rcp_f32_e32 v43, v43
	s_nop 0
	v_cndmask_b32_e64 v36, v36, v43, s[4:5]
	v_mul_f32_e32 v43, 0xbfb8aa3b, v37
	v_exp_f32_e32 v43, v43
	s_nop 0
	v_add_f32_e32 v43, 1.0, v43
	v_rcp_f32_e32 v43, v43
	s_nop 0
	v_cndmask_b32_e64 v37, v37, v43, s[4:5]
	v_cvt_pk_f16_f32 v37, v36, v37
	v_cvt_pk_f16_f32 v36, v34, v35
	v_cvt_pk_f16_f32 v35, v40, v41
	v_cvt_pk_f16_f32 v34, v38, v39
	global_store_dwordx4 v[48:49], v[34:37], off offset:256
	s_nop 1
	v_mul_f32_e32 v34, 0xbfb8aa3b, v28
	v_exp_f32_e32 v34, v34
	s_nop 0
	v_add_f32_e32 v34, 1.0, v34
	v_rcp_f32_e32 v34, v34
	s_nop 0
	v_cndmask_b32_e64 v34, v28, v34, s[4:5]
	v_mul_f32_e32 v28, 0xbfb8aa3b, v29
	v_exp_f32_e32 v28, v28
	s_nop 0
	v_add_f32_e32 v28, 1.0, v28
	v_rcp_f32_e32 v28, v28
	s_nop 0
	v_cndmask_b32_e64 v35, v29, v28, s[4:5]
	v_mul_f32_e32 v28, 0xbfb8aa3b, v30
	v_exp_f32_e32 v28, v28
	s_nop 0
	v_add_f32_e32 v28, 1.0, v28
	v_rcp_f32_e32 v28, v28
	s_nop 0
	v_cndmask_b32_e64 v30, v30, v28, s[4:5]
	v_mul_f32_e32 v28, 0xbfb8aa3b, v31
	v_exp_f32_e32 v28, v28
	s_nop 0
	v_add_f32_e32 v28, 1.0, v28
	v_rcp_f32_e32 v28, v28
	s_nop 0
	v_cndmask_b32_e64 v31, v31, v28, s[4:5]
	v_mul_f32_e32 v28, 0xbfb8aa3b, v24
	v_exp_f32_e32 v28, v28
	s_nop 0
	v_add_f32_e32 v28, 1.0, v28
	v_rcp_f32_e32 v28, v28
	s_nop 0
	v_cndmask_b32_e64 v24, v24, v28, s[4:5]
	v_mul_f32_e32 v28, 0xbfb8aa3b, v25
	v_exp_f32_e32 v28, v28
	s_nop 0
	v_add_f32_e32 v28, 1.0, v28
	v_rcp_f32_e32 v28, v28
	s_nop 0
	v_cndmask_b32_e64 v25, v25, v28, s[4:5]
	v_mul_f32_e32 v28, 0xbfb8aa3b, v26
	v_exp_f32_e32 v28, v28
	s_nop 0
	v_add_f32_e32 v28, 1.0, v28
	v_rcp_f32_e32 v28, v28
	s_nop 0
	v_cndmask_b32_e64 v26, v26, v28, s[4:5]
	v_mul_f32_e32 v28, 0xbfb8aa3b, v27
	v_exp_f32_e32 v28, v28
	s_nop 0
	v_add_f32_e32 v28, 1.0, v28
	v_rcp_f32_e32 v28, v28
	s_nop 0
	v_cndmask_b32_e64 v27, v27, v28, s[4:5]
	v_cvt_pk_f16_f32 v28, v24, v25
	v_add_u32_e32 v24, s92, v42
	v_mov_b32_e32 v25, v33
	v_cvt_pk_f16_f32 v29, v26, v27
	v_cvt_pk_f16_f32 v27, v30, v31
	v_lshl_add_u64 v[30:31], v[24:25], 1, s[8:9]
	v_mul_f32_e32 v25, 0xbfb8aa3b, v20
	v_exp_f32_e32 v25, v25
	v_lshl_add_u64 v[30:31], v[30:31], 0, v[122:123]
	v_cvt_pk_f16_f32 v26, v34, v35
	global_store_dwordx4 v[30:31], v[26:29], off
	v_add_f32_e32 v25, 1.0, v25
	v_rcp_f32_e32 v25, v25
	s_nop 0
	v_cndmask_b32_e64 v20, v20, v25, s[4:5]
	v_mul_f32_e32 v25, 0xbfb8aa3b, v21
	v_exp_f32_e32 v25, v25
	s_nop 0
; __device__ __forceinline__ float sigm_f(float x) { return __builtin_amdgcn_rcpf(1.0f + fexp(-x)); }
;     __device__ __forceinline__ void operator()(const f32x4 (&acc)[2][2][4][2], const Unit& u, int wr, int wc, int fr, int fq) const {
;         const int row0 = u.pm * BM + wr * 64 + fr;
;         if (u.pn < nmain) {
;             const int col0 = u.pn * BM + wc * 32 + 8 * fq;
; #pragma unroll
;             for (int ai = 0; ai < 2; ++ai)
; #pragma unroll
;                 for (int m = 0; m < 4; ++m)
; #pragma unroll
;                     for (int bj = 0; bj < 2; ++bj) {
;                         h16x8 o;
; #pragma unroll
;                         for (int n = 0; n < 2; ++n)
; #pragma unroll
;                             for (int j = 0; j < 4; ++j) { float v = acc[ai][bj][m][n][j]; if (act) v = sigm_f(v); o[4 * n + j] = (h16)v; }
;                         *(h16x8*)(O + (unsigned)(row0 + ai * HALF + m * 16) * ldc + col0 + bj * HALF) = o;
;                         if (halo && m == 3 && fr >= 13 && u.pn < 12) {
;                             const int row = row0 + ai * HALF + 48, nc = ((row & 4095) >> 6) + 1;
;                             if (nc < 64) *(h16x8*)(halo + ((unsigned)((row >> 12) * 64 + nc) * 3 + (fr - 13)) * 3072 + col0 + bj * HALF) = o;
;                         }
;                     }
	v_add_f32_e32 v25, 1.0, v25
	v_rcp_f32_e32 v25, v25
	s_nop 0
	v_cndmask_b32_e64 v21, v21, v25, s[4:5]
	v_mul_f32_e32 v25, 0xbfb8aa3b, v22
	v_exp_f32_e32 v25, v25
	s_nop 0
	v_add_f32_e32 v25, 1.0, v25
	v_rcp_f32_e32 v25, v25
	s_nop 0
	v_cndmask_b32_e64 v22, v22, v25, s[4:5]
	v_mul_f32_e32 v25, 0xbfb8aa3b, v23
	v_exp_f32_e32 v25, v25
	s_nop 0
	v_add_f32_e32 v25, 1.0, v25
	v_rcp_f32_e32 v25, v25
	s_nop 0
	v_cndmask_b32_e64 v23, v23, v25, s[4:5]
	v_mul_f32_e32 v25, 0xbfb8aa3b, v16
	v_exp_f32_e32 v25, v25
	s_nop 0
	v_add_f32_e32 v25, 1.0, v25
	v_rcp_f32_e32 v25, v25
	s_nop 0
	v_cndmask_b32_e64 v16, v16, v25, s[4:5]
	v_mul_f32_e32 v25, 0xbfb8aa3b, v17
	v_exp_f32_e32 v25, v25
	s_nop 0
	v_add_f32_e32 v25, 1.0, v25
	v_rcp_f32_e32 v25, v25
	s_nop 0
	v_cndmask_b32_e64 v17, v17, v25, s[4:5]
	v_mul_f32_e32 v25, 0xbfb8aa3b, v18
	v_exp_f32_e32 v25, v25
	s_nop 0
	v_add_f32_e32 v25, 1.0, v25
	v_rcp_f32_e32 v25, v25
	s_nop 0
	v_cndmask_b32_e64 v18, v18, v25, s[4:5]
	v_mul_f32_e32 v25, 0xbfb8aa3b, v19
	v_exp_f32_e32 v25, v25
	s_nop 0
	v_add_f32_e32 v25, 1.0, v25
	v_rcp_f32_e32 v25, v25
	s_nop 0
	v_cndmask_b32_e64 v19, v19, v25, s[4:5]
	v_cvt_pk_f16_f32 v19, v18, v19
	v_cvt_pk_f16_f32 v18, v16, v17
	v_cvt_pk_f16_f32 v17, v22, v23
	v_cvt_pk_f16_f32 v16, v20, v21
	global_store_dwordx4 v[30:31], v[16:19], off offset:256
	s_nop 1
	v_mul_f32_e32 v16, 0xbfb8aa3b, v12
	v_exp_f32_e32 v16, v16
	s_nop 0
	v_add_f32_e32 v16, 1.0, v16
	v_rcp_f32_e32 v16, v16
	s_nop 0
	v_cndmask_b32_e64 v12, v12, v16, s[4:5]
	v_mul_f32_e32 v16, 0xbfb8aa3b, v13
	v_exp_f32_e32 v16, v16
	s_nop 0
	v_add_f32_e32 v16, 1.0, v16
	v_rcp_f32_e32 v16, v16
	s_nop 0
	v_cndmask_b32_e64 v13, v13, v16, s[4:5]
	v_mul_f32_e32 v16, 0xbfb8aa3b, v14
	v_exp_f32_e32 v16, v16
	s_nop 0
	v_add_f32_e32 v16, 1.0, v16
	v_rcp_f32_e32 v16, v16
	s_nop 0
	v_cndmask_b32_e64 v14, v14, v16, s[4:5]
	v_mul_f32_e32 v16, 0xbfb8aa3b, v15
	v_exp_f32_e32 v16, v16
	s_nop 0
	v_add_f32_e32 v16, 1.0, v16
	v_rcp_f32_e32 v16, v16
	s_nop 0
	v_cndmask_b32_e64 v15, v15, v16, s[4:5]
	v_mul_f32_e32 v16, 0xbfb8aa3b, v8
	v_exp_f32_e32 v16, v16
	s_nop 0
	v_add_f32_e32 v16, 1.0, v16
	v_rcp_f32_e32 v16, v16
	s_nop 0
	v_cndmask_b32_e64 v8, v8, v16, s[4:5]
	v_mul_f32_e32 v16, 0xbfb8aa3b, v9
	v_exp_f32_e32 v16, v16
	s_nop 0
	v_add_f32_e32 v16, 1.0, v16
	v_rcp_f32_e32 v16, v16
	s_nop 0
	v_cndmask_b32_e64 v9, v9, v16, s[4:5]
	v_mul_f32_e32 v16, 0xbfb8aa3b, v10
	v_exp_f32_e32 v16, v16
	s_nop 0
	v_add_f32_e32 v16, 1.0, v16
	v_rcp_f32_e32 v16, v16
	s_nop 0
	v_cndmask_b32_e64 v10, v10, v16, s[4:5]
	v_mul_f32_e32 v16, 0xbfb8aa3b, v11
	v_exp_f32_e32 v16, v16
	s_nop 0
	v_add_f32_e32 v16, 1.0, v16
	v_rcp_f32_e32 v16, v16
	s_nop 0
	v_cndmask_b32_e64 v11, v11, v16, s[4:5]
	v_cvt_pk_f16_f32 v11, v10, v11
	v_cvt_pk_f16_f32 v10, v8, v9
	v_cvt_pk_f16_f32 v8, v12, v13
	v_add_u32_e32 v12, s92, v24
	v_mov_b32_e32 v13, v33
	v_lshl_add_u64 v[12:13], v[12:13], 1, s[8:9]
	v_cvt_pk_f16_f32 v9, v14, v15
	v_lshl_add_u64 v[12:13], v[12:13], 0, v[122:123]
	global_store_dwordx4 v[12:13], v[8:11], off
	s_and_saveexec_b64 s[28:29], s[26:27]
	s_cbranch_execz .LBB0_931
	v_readlane_b32 s0, v255, 30
	v_readlane_b32 s1, v255, 31
	s_nop 1
	v_lshl_add_u64 v[14:15], v[32:33], 1, s[0:1]
	v_lshl_add_u64 v[14:15], v[144:145], 1, v[14:15]
	global_store_dwordx4 v[14:15], v[8:11], off
.LBB0_931:
	s_or_b64 exec, exec, s[28:29]
	s_nop 0
	v_mul_f32_e32 v8, 0xbfb8aa3b, v4
	v_exp_f32_e32 v8, v8
	s_nop 0
	v_add_f32_e32 v8, 1.0, v8
	v_rcp_f32_e32 v8, v8
	s_nop 0
	v_cndmask_b32_e64 v4, v4, v8, s[4:5]
	v_mul_f32_e32 v8, 0xbfb8aa3b, v5
	v_exp_f32_e32 v8, v8
	s_nop 0
	v_add_f32_e32 v8, 1.0, v8
	v_rcp_f32_e32 v8, v8
	s_nop 0
	v_cndmask_b32_e64 v5, v5, v8, s[4:5]
	v_mul_f32_e32 v8, 0xbfb8aa3b, v6
	v_exp_f32_e32 v8, v8
	s_nop 0
	v_add_f32_e32 v8, 1.0, v8
	v_rcp_f32_e32 v8, v8
	s_nop 0
	v_cndmask_b32_e64 v6, v6, v8, s[4:5]
	v_mul_f32_e32 v8, 0xbfb8aa3b, v7
	v_exp_f32_e32 v8, v8
	s_nop 0
	v_add_f32_e32 v8, 1.0, v8
	v_rcp_f32_e32 v8, v8
	s_nop 0
	v_cndmask_b32_e64 v7, v7, v8, s[4:5]
	v_mul_f32_e32 v8, 0xbfb8aa3b, v0
	v_exp_f32_e32 v8, v8
	s_nop 0
	v_add_f32_e32 v8, 1.0, v8
	v_rcp_f32_e32 v8, v8
	s_nop 0
	v_cndmask_b32_e64 v0, v0, v8, s[4:5]
	v_mul_f32_e32 v8, 0xbfb8aa3b, v1
	v_exp_f32_e32 v8, v8
	s_nop 0
	v_add_f32_e32 v8, 1.0, v8
	v_rcp_f32_e32 v8, v8
	s_nop 0
	v_cndmask_b32_e64 v1, v1, v8, s[4:5]
	v_mul_f32_e32 v8, 0xbfb8aa3b, v2
	v_exp_f32_e32 v8, v8
	s_nop 0
	v_add_f32_e32 v8, 1.0, v8
	v_rcp_f32_e32 v8, v8
	s_nop 0
	v_cndmask_b32_e64 v2, v2, v8, s[4:5]
	v_mul_f32_e32 v8, 0xbfb8aa3b, v3
	v_exp_f32_e32 v8, v8
	s_nop 0
	v_add_f32_e32 v8, 1.0, v8
	v_rcp_f32_e32 v8, v8
	s_nop 0
	v_cndmask_b32_e64 v3, v3, v8, s[4:5]
	v_cvt_pk_f16_f32 v3, v2, v3
	v_cvt_pk_f16_f32 v2, v0, v1
	v_cvt_pk_f16_f32 v1, v6, v7
	v_cvt_pk_f16_f32 v0, v4, v5
	global_store_dwordx4 v[12:13], v[0:3], off offset:256
	s_and_saveexec_b64 s[28:29], s[26:27]
	s_cbranch_execz .LBB0_933
	v_readlane_b32 s0, v255, 30
	v_readlane_b32 s1, v255, 31
	s_nop 1
	v_lshl_add_u64 v[4:5], v[32:33], 1, s[0:1]
	v_lshl_add_u64 v[4:5], v[144:145], 1, v[4:5]
	global_store_dwordx4 v[4:5], v[0:3], off offset:256
